# convert_weights transposes: all 32 loads of an item in flight (unroll x2) on top of PJ tail deferral
# baseline (speedup 1.0000x reference)
.LBB0_64:
	s_lshl_b32 s12, s6, 1
	s_lshl_b32 s11, s5, 1
	v_or_b32_e32 v21, s12, v2
	v_or_b32_e32 v0, s11, v3
	v_add_u32_e32 v26, s1, v21
	v_add_u32_e32 v23, s3, v0
	v_mad_u64_u32 v[26:27], s[14:15], v26, s16, v[24:25]
	v_mad_u64_u32 v[28:29], s[14:15], v23, s16, v[24:25]
	global_load_dword v100, v[26:27], off
	global_load_dword v101, v[28:29], off
	v_mad_u64_u32 v[116:117], s[14:15], v21, s77, v[6:7]
	v_mad_u64_u32 v[118:119], s[14:15], v0, s77, v[6:7]
	s_add_i32 s14, s12, 4
	s_add_i32 s13, s11, 4
	v_or_b32_e32 v21, s14, v2
	v_or_b32_e32 v0, s13, v3
	s_add_i32 s13, s11, 8
	s_add_i32 s6, s6, 16
	s_add_i32 s5, s5, 16
	s_add_i32 s7, s7, -16
	v_add_u32_e32 v26, s1, v21
	v_add_u32_e32 v23, s3, v0
	v_mad_u64_u32 v[26:27], s[14:15], v26, s16, v[24:25]
	v_mad_u64_u32 v[28:29], s[14:15], v23, s16, v[24:25]
	global_load_dword v102, v[26:27], off
	global_load_dword v103, v[28:29], off
	v_mad_u64_u32 v[120:121], s[14:15], v21, s77, v[6:7]
	v_mad_u64_u32 v[122:123], s[14:15], v0, s77, v[6:7]
	s_add_i32 s14, s12, 8
	s_nop 0
	v_or_b32_e32 v21, s14, v2
	v_or_b32_e32 v0, s13, v3
	s_add_i32 s13, s11, 12
	v_add_u32_e32 v26, s1, v21
	v_add_u32_e32 v23, s3, v0
	v_mad_u64_u32 v[26:27], s[14:15], v26, s16, v[24:25]
	v_mad_u64_u32 v[28:29], s[14:15], v23, s16, v[24:25]
	global_load_dword v104, v[26:27], off
	global_load_dword v105, v[28:29], off
	v_mad_u64_u32 v[124:125], s[14:15], v21, s77, v[6:7]
	v_mad_u64_u32 v[126:127], s[14:15], v0, s77, v[6:7]
	s_add_i32 s14, s12, 12
	s_nop 0
	v_or_b32_e32 v21, s14, v2
	v_or_b32_e32 v0, s13, v3
	s_add_i32 s13, s11, 16
	v_add_u32_e32 v26, s1, v21
	v_add_u32_e32 v23, s3, v0
	v_mad_u64_u32 v[26:27], s[14:15], v26, s16, v[24:25]
	v_mad_u64_u32 v[28:29], s[14:15], v23, s16, v[24:25]
	global_load_dword v106, v[26:27], off
	global_load_dword v107, v[28:29], off
	v_mad_u64_u32 v[128:129], s[14:15], v21, s77, v[6:7]
	v_mad_u64_u32 v[130:131], s[14:15], v0, s77, v[6:7]
	s_add_i32 s14, s12, 16
	s_nop 0
	v_or_b32_e32 v21, s14, v2
	v_or_b32_e32 v0, s13, v3
	s_add_i32 s13, s11, 20
	v_add_u32_e32 v26, s1, v21
	v_add_u32_e32 v23, s3, v0
	v_mad_u64_u32 v[26:27], s[14:15], v26, s16, v[24:25]
	v_mad_u64_u32 v[28:29], s[14:15], v23, s16, v[24:25]
	global_load_dword v108, v[26:27], off
	global_load_dword v109, v[28:29], off
	v_mad_u64_u32 v[132:133], s[14:15], v21, s77, v[6:7]
	v_mad_u64_u32 v[134:135], s[14:15], v0, s77, v[6:7]
	s_add_i32 s14, s12, 20
	s_nop 0
	v_or_b32_e32 v21, s14, v2
	v_or_b32_e32 v0, s13, v3
	s_add_i32 s13, s11, 24
	s_add_i32 s11, s11, 28
	v_add_u32_e32 v26, s1, v21
	v_add_u32_e32 v23, s3, v0
	v_mad_u64_u32 v[26:27], s[14:15], v26, s16, v[24:25]
	v_mad_u64_u32 v[28:29], s[14:15], v23, s16, v[24:25]
	global_load_dword v110, v[26:27], off
	global_load_dword v111, v[28:29], off
	v_mad_u64_u32 v[136:137], s[14:15], v21, s77, v[6:7]
	v_mad_u64_u32 v[138:139], s[14:15], v0, s77, v[6:7]
	s_add_i32 s14, s12, 24
	s_nop 0
	v_or_b32_e32 v21, s14, v2
	v_or_b32_e32 v0, s13, v3
	s_add_i32 s12, s12, 28
	s_cmp_lg_u32 s7, 0
	v_add_u32_e32 v26, s1, v21
	v_add_u32_e32 v23, s3, v0
	v_mad_u64_u32 v[26:27], s[14:15], v26, s16, v[24:25]
	v_mad_u64_u32 v[28:29], s[14:15], v23, s16, v[24:25]
	global_load_dword v112, v[26:27], off
	global_load_dword v113, v[28:29], off
	v_mad_u64_u32 v[140:141], s[14:15], v21, s77, v[6:7]
	v_or_b32_e32 v21, s12, v2
	v_mad_u64_u32 v[142:143], s[14:15], v0, s77, v[6:7]
	v_or_b32_e32 v0, s11, v3
	v_add_u32_e32 v26, s1, v21
	v_add_u32_e32 v23, s3, v0
	v_mad_u64_u32 v[26:27], s[12:13], v26, s16, v[24:25]
	v_mad_u64_u32 v[28:29], s[12:13], v23, s16, v[24:25]
	global_load_dword v114, v[26:27], off
	global_load_dword v115, v[28:29], off
	v_mad_u64_u32 v[144:145], s[12:13], v21, s77, v[6:7]
	v_mad_u64_u32 v[146:147], s[12:13], v0, s77, v[6:7]
	s_lshl_b32 s12, s6, 1
	s_lshl_b32 s11, s5, 1
	v_or_b32_e32 v21, s12, v2
	v_or_b32_e32 v0, s11, v3
	v_add_u32_e32 v26, s1, v21
	v_add_u32_e32 v23, s3, v0
	v_mad_u64_u32 v[26:27], s[14:15], v26, s16, v[24:25]
	v_mad_u64_u32 v[28:29], s[14:15], v23, s16, v[24:25]
	global_load_dword v148, v[26:27], off
	global_load_dword v149, v[28:29], off
	v_mad_u64_u32 v[164:165], s[14:15], v21, s77, v[6:7]
	v_mad_u64_u32 v[166:167], s[14:15], v0, s77, v[6:7]
	s_add_i32 s14, s12, 4
	s_add_i32 s13, s11, 4
	v_or_b32_e32 v21, s14, v2
	v_or_b32_e32 v0, s13, v3
	s_add_i32 s13, s11, 8
	s_add_i32 s6, s6, 16
	s_add_i32 s5, s5, 16
	s_add_i32 s7, s7, -16
	v_add_u32_e32 v26, s1, v21
	v_add_u32_e32 v23, s3, v0
	v_mad_u64_u32 v[26:27], s[14:15], v26, s16, v[24:25]
	v_mad_u64_u32 v[28:29], s[14:15], v23, s16, v[24:25]
	global_load_dword v150, v[26:27], off
	global_load_dword v151, v[28:29], off
	v_mad_u64_u32 v[168:169], s[14:15], v21, s77, v[6:7]
	v_mad_u64_u32 v[170:171], s[14:15], v0, s77, v[6:7]
	s_add_i32 s14, s12, 8
	s_nop 0
	v_or_b32_e32 v21, s14, v2
	v_or_b32_e32 v0, s13, v3
	s_add_i32 s13, s11, 12
	v_add_u32_e32 v26, s1, v21
	v_add_u32_e32 v23, s3, v0
	v_mad_u64_u32 v[26:27], s[14:15], v26, s16, v[24:25]
	v_mad_u64_u32 v[28:29], s[14:15], v23, s16, v[24:25]
	global_load_dword v152, v[26:27], off
	global_load_dword v153, v[28:29], off
	v_mad_u64_u32 v[172:173], s[14:15], v21, s77, v[6:7]
	v_mad_u64_u32 v[174:175], s[14:15], v0, s77, v[6:7]
	s_add_i32 s14, s12, 12
	s_nop 0
	v_or_b32_e32 v21, s14, v2
	v_or_b32_e32 v0, s13, v3
	s_add_i32 s13, s11, 16
	v_add_u32_e32 v26, s1, v21
	v_add_u32_e32 v23, s3, v0
	v_mad_u64_u32 v[26:27], s[14:15], v26, s16, v[24:25]
	v_mad_u64_u32 v[28:29], s[14:15], v23, s16, v[24:25]
	global_load_dword v154, v[26:27], off
	global_load_dword v155, v[28:29], off
	v_mad_u64_u32 v[176:177], s[14:15], v21, s77, v[6:7]
	v_mad_u64_u32 v[178:179], s[14:15], v0, s77, v[6:7]
	s_add_i32 s14, s12, 16
	s_nop 0
	v_or_b32_e32 v21, s14, v2
	v_or_b32_e32 v0, s13, v3
	s_add_i32 s13, s11, 20
	v_add_u32_e32 v26, s1, v21
	v_add_u32_e32 v23, s3, v0
	v_mad_u64_u32 v[26:27], s[14:15], v26, s16, v[24:25]
	v_mad_u64_u32 v[28:29], s[14:15], v23, s16, v[24:25]
	global_load_dword v156, v[26:27], off
	global_load_dword v157, v[28:29], off
	v_mad_u64_u32 v[180:181], s[14:15], v21, s77, v[6:7]
	v_mad_u64_u32 v[182:183], s[14:15], v0, s77, v[6:7]
	s_add_i32 s14, s12, 20
	s_nop 0
	v_or_b32_e32 v21, s14, v2
	v_or_b32_e32 v0, s13, v3
	s_add_i32 s13, s11, 24
	s_add_i32 s11, s11, 28
	v_add_u32_e32 v26, s1, v21
	v_add_u32_e32 v23, s3, v0
	v_mad_u64_u32 v[26:27], s[14:15], v26, s16, v[24:25]
	v_mad_u64_u32 v[28:29], s[14:15], v23, s16, v[24:25]
	global_load_dword v158, v[26:27], off
	global_load_dword v159, v[28:29], off
	v_mad_u64_u32 v[184:185], s[14:15], v21, s77, v[6:7]
	v_mad_u64_u32 v[186:187], s[14:15], v0, s77, v[6:7]
	s_add_i32 s14, s12, 24
	s_nop 0
	v_or_b32_e32 v21, s14, v2
	v_or_b32_e32 v0, s13, v3
	s_add_i32 s12, s12, 28
	s_cmp_lg_u32 s7, 0
	v_add_u32_e32 v26, s1, v21
	v_add_u32_e32 v23, s3, v0
	v_mad_u64_u32 v[26:27], s[14:15], v26, s16, v[24:25]
	v_mad_u64_u32 v[28:29], s[14:15], v23, s16, v[24:25]
	global_load_dword v160, v[26:27], off
	global_load_dword v161, v[28:29], off
	v_mad_u64_u32 v[188:189], s[14:15], v21, s77, v[6:7]
	v_or_b32_e32 v21, s12, v2
	v_mad_u64_u32 v[190:191], s[14:15], v0, s77, v[6:7]
	v_or_b32_e32 v0, s11, v3
	v_add_u32_e32 v26, s1, v21
	v_add_u32_e32 v23, s3, v0
	v_mad_u64_u32 v[26:27], s[12:13], v26, s16, v[24:25]
	v_mad_u64_u32 v[28:29], s[12:13], v23, s16, v[24:25]
	global_load_dword v162, v[26:27], off
	global_load_dword v163, v[28:29], off
	v_mad_u64_u32 v[192:193], s[12:13], v21, s77, v[6:7]
	v_mad_u64_u32 v[196:197], s[12:13], v0, s77, v[6:7]
	s_waitcnt vmcnt(0)
	ds_write_b32 v116, v100
	ds_write_b32 v118, v101
	ds_write_b32 v120, v102
	ds_write_b32 v122, v103
	ds_write_b32 v124, v104
	ds_write_b32 v126, v105
	ds_write_b32 v128, v106
	ds_write_b32 v130, v107
	ds_write_b32 v132, v108
	ds_write_b32 v134, v109
	ds_write_b32 v136, v110
	ds_write_b32 v138, v111
	ds_write_b32 v140, v112
	ds_write_b32 v142, v113
	ds_write_b32 v144, v114
	ds_write_b32 v146, v115
	ds_write_b32 v164, v148
	ds_write_b32 v166, v149
	ds_write_b32 v168, v150
	ds_write_b32 v170, v151
	ds_write_b32 v172, v152
	ds_write_b32 v174, v153
	ds_write_b32 v176, v154
	ds_write_b32 v178, v155
	ds_write_b32 v180, v156
	ds_write_b32 v182, v157
	ds_write_b32 v184, v158
	ds_write_b32 v186, v159
	ds_write_b32 v188, v160
	ds_write_b32 v190, v161
	ds_write_b32 v192, v162
	ds_write_b32 v196, v163
	s_cbranch_scc1 .LBB0_64
	s_mov_b32 s1, s4
	s_lshl_b64 s[0:1], s[0:1], 11
	s_add_u32 s0, s72, s0
	v_readlane_b32 s3, v249, 35
	s_addc_u32 s1, s3, s1
	s_and_b32 s2, 0xffff, s2
	s_lshl_b32 s2, s2, 1
	s_add_u32 s0, s0, s2
	s_addc_u32 s1, s1, 0
	s_mov_b64 s[2:3], 0

.LBB0_68:
	s_lshl_b32 s11, s5, 1
	s_lshl_b32 s7, s2, 1
	v_or_b32_e32 v21, s11, v2
	v_or_b32_e32 v0, s7, v3
	v_add_u32_e32 v28, s0, v21
	v_add_u32_e32 v26, s3, v0
	v_ashrrev_i32_e32 v29, 31, v28
	v_ashrrev_i32_e32 v27, 31, v26
	v_lshlrev_b64 v[28:29], 12, v[28:29]
	v_lshlrev_b64 v[26:27], 12, v[26:27]
	v_lshl_add_u64 v[28:29], v[24:25], 0, v[28:29]
	v_lshl_add_u64 v[26:27], v[24:25], 0, v[26:27]
	global_load_dword v100, v[28:29], off
	global_load_dword v101, v[26:27], off
	v_mad_u64_u32 v[116:117], s[12:13], v21, s77, v[6:7]
	v_mad_u64_u32 v[118:119], s[12:13], v0, s77, v[6:7]
	s_add_i32 s13, s11, 4
	s_add_i32 s12, s7, 4
	v_or_b32_e32 v21, s13, v2
	v_or_b32_e32 v0, s12, v3
	s_add_i32 s5, s5, 16
	s_add_i32 s2, s2, 16
	s_add_i32 s6, s6, -16
	v_add_u32_e32 v28, s0, v21
	v_add_u32_e32 v26, s3, v0
	v_ashrrev_i32_e32 v29, 31, v28
	v_ashrrev_i32_e32 v27, 31, v26
	v_lshlrev_b64 v[28:29], 12, v[28:29]
	v_lshlrev_b64 v[26:27], 12, v[26:27]
	v_lshl_add_u64 v[28:29], v[24:25], 0, v[28:29]
	v_lshl_add_u64 v[26:27], v[24:25], 0, v[26:27]
	global_load_dword v102, v[28:29], off
	global_load_dword v103, v[26:27], off
	v_mad_u64_u32 v[120:121], s[12:13], v21, s77, v[6:7]
	v_mad_u64_u32 v[122:123], s[12:13], v0, s77, v[6:7]
	s_add_i32 s13, s11, 8
	s_add_i32 s12, s7, 8
	v_or_b32_e32 v21, s13, v2
	v_or_b32_e32 v0, s12, v3
	v_add_u32_e32 v28, s0, v21
	v_add_u32_e32 v26, s3, v0
	v_ashrrev_i32_e32 v29, 31, v28
	v_ashrrev_i32_e32 v27, 31, v26
	v_lshlrev_b64 v[28:29], 12, v[28:29]
	v_lshlrev_b64 v[26:27], 12, v[26:27]
	v_lshl_add_u64 v[28:29], v[24:25], 0, v[28:29]
	v_lshl_add_u64 v[26:27], v[24:25], 0, v[26:27]
	global_load_dword v104, v[28:29], off
	global_load_dword v105, v[26:27], off
	v_mad_u64_u32 v[124:125], s[12:13], v21, s77, v[6:7]
	v_mad_u64_u32 v[126:127], s[12:13], v0, s77, v[6:7]
	s_add_i32 s13, s11, 12
	s_add_i32 s12, s7, 12
	v_or_b32_e32 v21, s13, v2
	v_or_b32_e32 v0, s12, v3
	v_add_u32_e32 v28, s0, v21
	v_add_u32_e32 v26, s3, v0
	v_ashrrev_i32_e32 v29, 31, v28
	v_ashrrev_i32_e32 v27, 31, v26
	v_lshlrev_b64 v[28:29], 12, v[28:29]
	v_lshlrev_b64 v[26:27], 12, v[26:27]
	v_lshl_add_u64 v[28:29], v[24:25], 0, v[28:29]
	v_lshl_add_u64 v[26:27], v[24:25], 0, v[26:27]
	global_load_dword v106, v[28:29], off
	global_load_dword v107, v[26:27], off
	v_mad_u64_u32 v[128:129], s[12:13], v21, s77, v[6:7]
	v_mad_u64_u32 v[130:131], s[12:13], v0, s77, v[6:7]
	s_add_i32 s13, s11, 16
	s_add_i32 s12, s7, 16
	v_or_b32_e32 v21, s13, v2
	v_or_b32_e32 v0, s12, v3
	v_add_u32_e32 v28, s0, v21
	v_add_u32_e32 v26, s3, v0
	v_ashrrev_i32_e32 v29, 31, v28
	v_ashrrev_i32_e32 v27, 31, v26
	v_lshlrev_b64 v[28:29], 12, v[28:29]
	v_lshlrev_b64 v[26:27], 12, v[26:27]
	v_lshl_add_u64 v[28:29], v[24:25], 0, v[28:29]
	v_lshl_add_u64 v[26:27], v[24:25], 0, v[26:27]
	global_load_dword v108, v[28:29], off
	global_load_dword v109, v[26:27], off
	v_mad_u64_u32 v[132:133], s[12:13], v21, s77, v[6:7]
	v_mad_u64_u32 v[134:135], s[12:13], v0, s77, v[6:7]
	s_add_i32 s13, s11, 20
	s_add_i32 s12, s7, 20
	v_or_b32_e32 v21, s13, v2
	v_or_b32_e32 v0, s12, v3
	v_add_u32_e32 v28, s0, v21
	v_add_u32_e32 v26, s3, v0
	v_ashrrev_i32_e32 v29, 31, v28
	v_ashrrev_i32_e32 v27, 31, v26
	v_lshlrev_b64 v[28:29], 12, v[28:29]
	v_lshlrev_b64 v[26:27], 12, v[26:27]
	v_lshl_add_u64 v[28:29], v[24:25], 0, v[28:29]
	v_lshl_add_u64 v[26:27], v[24:25], 0, v[26:27]
	global_load_dword v110, v[28:29], off
	global_load_dword v111, v[26:27], off
	v_mad_u64_u32 v[136:137], s[12:13], v21, s77, v[6:7]
	v_mad_u64_u32 v[138:139], s[12:13], v0, s77, v[6:7]
	s_add_i32 s13, s11, 24
	s_add_i32 s12, s7, 24
	v_or_b32_e32 v21, s13, v2
	v_or_b32_e32 v0, s12, v3
	s_add_i32 s11, s11, 28
	s_add_i32 s7, s7, 28
	s_cmp_lg_u32 s6, 0
	v_add_u32_e32 v28, s0, v21
	v_add_u32_e32 v26, s3, v0
	v_ashrrev_i32_e32 v29, 31, v28
	v_ashrrev_i32_e32 v27, 31, v26
	v_lshlrev_b64 v[28:29], 12, v[28:29]
	v_lshlrev_b64 v[26:27], 12, v[26:27]
	v_lshl_add_u64 v[28:29], v[24:25], 0, v[28:29]
	v_lshl_add_u64 v[26:27], v[24:25], 0, v[26:27]
	global_load_dword v112, v[28:29], off
	global_load_dword v113, v[26:27], off
	v_mad_u64_u32 v[140:141], s[12:13], v21, s77, v[6:7]
	v_mad_u64_u32 v[142:143], s[12:13], v0, s77, v[6:7]
	v_or_b32_e32 v21, s11, v2
	v_or_b32_e32 v0, s7, v3
	v_add_u32_e32 v28, s0, v21
	v_add_u32_e32 v26, s3, v0
	v_ashrrev_i32_e32 v29, 31, v28
	v_ashrrev_i32_e32 v27, 31, v26
	v_lshlrev_b64 v[28:29], 12, v[28:29]
	v_lshlrev_b64 v[26:27], 12, v[26:27]
	v_lshl_add_u64 v[28:29], v[24:25], 0, v[28:29]
	v_lshl_add_u64 v[26:27], v[24:25], 0, v[26:27]
	global_load_dword v114, v[28:29], off
	global_load_dword v115, v[26:27], off
	v_mad_u64_u32 v[144:145], s[12:13], v21, s77, v[6:7]
	v_mad_u64_u32 v[146:147], s[12:13], v0, s77, v[6:7]
	s_lshl_b32 s11, s5, 1
	s_lshl_b32 s7, s2, 1
	v_or_b32_e32 v21, s11, v2
	v_or_b32_e32 v0, s7, v3
	v_add_u32_e32 v28, s0, v21
	v_add_u32_e32 v26, s3, v0
	v_ashrrev_i32_e32 v29, 31, v28
	v_ashrrev_i32_e32 v27, 31, v26
	v_lshlrev_b64 v[28:29], 12, v[28:29]
	v_lshlrev_b64 v[26:27], 12, v[26:27]
	v_lshl_add_u64 v[28:29], v[24:25], 0, v[28:29]
	v_lshl_add_u64 v[26:27], v[24:25], 0, v[26:27]
	global_load_dword v148, v[28:29], off
	global_load_dword v149, v[26:27], off
	v_mad_u64_u32 v[164:165], s[12:13], v21, s77, v[6:7]
	v_mad_u64_u32 v[166:167], s[12:13], v0, s77, v[6:7]
	s_add_i32 s13, s11, 4
	s_add_i32 s12, s7, 4
	v_or_b32_e32 v21, s13, v2
	v_or_b32_e32 v0, s12, v3
	s_add_i32 s5, s5, 16
	s_add_i32 s2, s2, 16
	s_add_i32 s6, s6, -16
	v_add_u32_e32 v28, s0, v21
	v_add_u32_e32 v26, s3, v0
	v_ashrrev_i32_e32 v29, 31, v28
	v_ashrrev_i32_e32 v27, 31, v26
	v_lshlrev_b64 v[28:29], 12, v[28:29]
	v_lshlrev_b64 v[26:27], 12, v[26:27]
	v_lshl_add_u64 v[28:29], v[24:25], 0, v[28:29]
	v_lshl_add_u64 v[26:27], v[24:25], 0, v[26:27]
	global_load_dword v150, v[28:29], off
	global_load_dword v151, v[26:27], off
	v_mad_u64_u32 v[168:169], s[12:13], v21, s77, v[6:7]
	v_mad_u64_u32 v[170:171], s[12:13], v0, s77, v[6:7]
	s_add_i32 s13, s11, 8
	s_add_i32 s12, s7, 8
	v_or_b32_e32 v21, s13, v2
	v_or_b32_e32 v0, s12, v3
	v_add_u32_e32 v28, s0, v21
	v_add_u32_e32 v26, s3, v0
	v_ashrrev_i32_e32 v29, 31, v28
	v_ashrrev_i32_e32 v27, 31, v26
	v_lshlrev_b64 v[28:29], 12, v[28:29]
	v_lshlrev_b64 v[26:27], 12, v[26:27]
	v_lshl_add_u64 v[28:29], v[24:25], 0, v[28:29]
	v_lshl_add_u64 v[26:27], v[24:25], 0, v[26:27]
	global_load_dword v152, v[28:29], off
	global_load_dword v153, v[26:27], off
	v_mad_u64_u32 v[172:173], s[12:13], v21, s77, v[6:7]
	v_mad_u64_u32 v[174:175], s[12:13], v0, s77, v[6:7]
	s_add_i32 s13, s11, 12
	s_add_i32 s12, s7, 12
	v_or_b32_e32 v21, s13, v2
	v_or_b32_e32 v0, s12, v3
	v_add_u32_e32 v28, s0, v21
	v_add_u32_e32 v26, s3, v0
	v_ashrrev_i32_e32 v29, 31, v28
	v_ashrrev_i32_e32 v27, 31, v26
	v_lshlrev_b64 v[28:29], 12, v[28:29]
	v_lshlrev_b64 v[26:27], 12, v[26:27]
	v_lshl_add_u64 v[28:29], v[24:25], 0, v[28:29]
	v_lshl_add_u64 v[26:27], v[24:25], 0, v[26:27]
	global_load_dword v154, v[28:29], off
	global_load_dword v155, v[26:27], off
	v_mad_u64_u32 v[176:177], s[12:13], v21, s77, v[6:7]
	v_mad_u64_u32 v[178:179], s[12:13], v0, s77, v[6:7]
	s_add_i32 s13, s11, 16
	s_add_i32 s12, s7, 16
	v_or_b32_e32 v21, s13, v2
	v_or_b32_e32 v0, s12, v3
	v_add_u32_e32 v28, s0, v21
	v_add_u32_e32 v26, s3, v0
	v_ashrrev_i32_e32 v29, 31, v28
	v_ashrrev_i32_e32 v27, 31, v26
	v_lshlrev_b64 v[28:29], 12, v[28:29]
	v_lshlrev_b64 v[26:27], 12, v[26:27]
	v_lshl_add_u64 v[28:29], v[24:25], 0, v[28:29]
	v_lshl_add_u64 v[26:27], v[24:25], 0, v[26:27]
	global_load_dword v156, v[28:29], off
	global_load_dword v157, v[26:27], off
	v_mad_u64_u32 v[180:181], s[12:13], v21, s77, v[6:7]
	v_mad_u64_u32 v[182:183], s[12:13], v0, s77, v[6:7]
	s_add_i32 s13, s11, 20
	s_add_i32 s12, s7, 20
	v_or_b32_e32 v21, s13, v2
	v_or_b32_e32 v0, s12, v3
	v_add_u32_e32 v28, s0, v21
	v_add_u32_e32 v26, s3, v0
	v_ashrrev_i32_e32 v29, 31, v28
	v_ashrrev_i32_e32 v27, 31, v26
	v_lshlrev_b64 v[28:29], 12, v[28:29]
	v_lshlrev_b64 v[26:27], 12, v[26:27]
	v_lshl_add_u64 v[28:29], v[24:25], 0, v[28:29]
	v_lshl_add_u64 v[26:27], v[24:25], 0, v[26:27]
	global_load_dword v158, v[28:29], off
	global_load_dword v159, v[26:27], off
	v_mad_u64_u32 v[184:185], s[12:13], v21, s77, v[6:7]
	v_mad_u64_u32 v[186:187], s[12:13], v0, s77, v[6:7]
	s_add_i32 s13, s11, 24
	s_add_i32 s12, s7, 24
	v_or_b32_e32 v21, s13, v2
	v_or_b32_e32 v0, s12, v3
	s_add_i32 s11, s11, 28
	s_add_i32 s7, s7, 28
	s_cmp_lg_u32 s6, 0
	v_add_u32_e32 v28, s0, v21
	v_add_u32_e32 v26, s3, v0
	v_ashrrev_i32_e32 v29, 31, v28
	v_ashrrev_i32_e32 v27, 31, v26
	v_lshlrev_b64 v[28:29], 12, v[28:29]
	v_lshlrev_b64 v[26:27], 12, v[26:27]
	v_lshl_add_u64 v[28:29], v[24:25], 0, v[28:29]
	v_lshl_add_u64 v[26:27], v[24:25], 0, v[26:27]
	global_load_dword v160, v[28:29], off
	global_load_dword v161, v[26:27], off
	v_mad_u64_u32 v[188:189], s[12:13], v21, s77, v[6:7]
	v_mad_u64_u32 v[190:191], s[12:13], v0, s77, v[6:7]
	v_or_b32_e32 v21, s11, v2
	v_or_b32_e32 v0, s7, v3
	v_add_u32_e32 v28, s0, v21
	v_add_u32_e32 v26, s3, v0
	v_ashrrev_i32_e32 v29, 31, v28
	v_ashrrev_i32_e32 v27, 31, v26
	v_lshlrev_b64 v[28:29], 12, v[28:29]
	v_lshlrev_b64 v[26:27], 12, v[26:27]
	v_lshl_add_u64 v[28:29], v[24:25], 0, v[28:29]
	v_lshl_add_u64 v[26:27], v[24:25], 0, v[26:27]
	global_load_dword v162, v[28:29], off
	global_load_dword v163, v[26:27], off
	v_mad_u64_u32 v[192:193], s[12:13], v21, s77, v[6:7]
	v_mad_u64_u32 v[196:197], s[12:13], v0, s77, v[6:7]
	s_waitcnt vmcnt(0)
	ds_write_b32 v116, v100
	ds_write_b32 v118, v101
	ds_write_b32 v120, v102
	ds_write_b32 v122, v103
	ds_write_b32 v124, v104
	ds_write_b32 v126, v105
	ds_write_b32 v128, v106
	ds_write_b32 v130, v107
	ds_write_b32 v132, v108
	ds_write_b32 v134, v109
	ds_write_b32 v136, v110
	ds_write_b32 v138, v111
	ds_write_b32 v140, v112
	ds_write_b32 v142, v113
	ds_write_b32 v144, v114
	ds_write_b32 v146, v115
	ds_write_b32 v164, v148
	ds_write_b32 v166, v149
	ds_write_b32 v168, v150
	ds_write_b32 v170, v151
	ds_write_b32 v172, v152
	ds_write_b32 v174, v153
	ds_write_b32 v176, v154
	ds_write_b32 v178, v155
	ds_write_b32 v180, v156
	ds_write_b32 v182, v157
	ds_write_b32 v184, v158
	ds_write_b32 v186, v159
	ds_write_b32 v188, v160
	ds_write_b32 v190, v161
	ds_write_b32 v192, v162
	ds_write_b32 v196, v163
	s_cbranch_scc1 .LBB0_68
	s_lshl_b32 s1, s1, 11
	v_readlane_b32 s2, v249, 48
	s_add_u32 s2, s2, s1
	v_readlane_b32 s1, v249, 49
	s_addc_u32 s3, s1, 0
	s_mov_b32 s1, s4
	s_lshl_b64 s[0:1], s[0:1], 1
	s_add_u32 s0, s2, s0
	s_addc_u32 s1, s3, s1

.LBB0_73:
	s_lshl_b32 s13, s7, 1
	s_lshl_b32 s12, s5, 1
	v_or_b32_e32 v23, s13, v2
	v_or_b32_e32 v21, s12, v3
	v_add_u32_e32 v0, s3, v23
	v_add_u32_e32 v26, s6, v21
	v_mov_b32_e32 v27, v1
	v_lshlrev_b64 v[28:29], 12, v[0:1]
	v_lshlrev_b64 v[26:27], 12, v[26:27]
	v_lshl_add_u64 v[28:29], v[24:25], 0, v[28:29]
	v_lshl_add_u64 v[26:27], v[24:25], 0, v[26:27]
	global_load_dword v100, v[28:29], off
	global_load_dword v101, v[26:27], off
	v_mad_u64_u32 v[116:117], s[14:15], v23, s77, v[6:7]
	v_mad_u64_u32 v[118:119], s[14:15], v21, s77, v[6:7]
	s_add_i32 s15, s13, 4
	s_add_i32 s14, s12, 4
	v_or_b32_e32 v23, s15, v2
	v_or_b32_e32 v21, s14, v3
	v_mov_b32_e32 v27, v1
	s_add_i32 s7, s7, 16
	s_add_i32 s5, s5, 16
	s_add_i32 s11, s11, -16
	v_add_u32_e32 v0, s3, v23
	v_add_u32_e32 v26, s6, v21
	v_lshlrev_b64 v[28:29], 12, v[0:1]
	v_lshlrev_b64 v[26:27], 12, v[26:27]
	v_lshl_add_u64 v[28:29], v[24:25], 0, v[28:29]
	v_lshl_add_u64 v[26:27], v[24:25], 0, v[26:27]
	global_load_dword v102, v[28:29], off
	global_load_dword v103, v[26:27], off
	v_mad_u64_u32 v[120:121], s[14:15], v23, s77, v[6:7]
	v_mad_u64_u32 v[122:123], s[14:15], v21, s77, v[6:7]
	s_add_i32 s15, s13, 8
	s_add_i32 s14, s12, 8
	v_or_b32_e32 v23, s15, v2
	v_or_b32_e32 v21, s14, v3
	v_mov_b32_e32 v27, v1
	v_add_u32_e32 v0, s3, v23
	v_add_u32_e32 v26, s6, v21
	v_lshlrev_b64 v[28:29], 12, v[0:1]
	v_lshlrev_b64 v[26:27], 12, v[26:27]
	v_lshl_add_u64 v[28:29], v[24:25], 0, v[28:29]
	v_lshl_add_u64 v[26:27], v[24:25], 0, v[26:27]
	global_load_dword v104, v[28:29], off
	global_load_dword v105, v[26:27], off
	v_mad_u64_u32 v[124:125], s[14:15], v23, s77, v[6:7]
	v_mad_u64_u32 v[126:127], s[14:15], v21, s77, v[6:7]
	s_add_i32 s15, s13, 12
	s_add_i32 s14, s12, 12
	v_or_b32_e32 v23, s15, v2
	v_or_b32_e32 v21, s14, v3
	v_mov_b32_e32 v27, v1
	v_add_u32_e32 v0, s3, v23
	v_add_u32_e32 v26, s6, v21
	v_lshlrev_b64 v[28:29], 12, v[0:1]
	v_lshlrev_b64 v[26:27], 12, v[26:27]
	v_lshl_add_u64 v[28:29], v[24:25], 0, v[28:29]
	v_lshl_add_u64 v[26:27], v[24:25], 0, v[26:27]
	global_load_dword v106, v[28:29], off
	global_load_dword v107, v[26:27], off
	v_mad_u64_u32 v[128:129], s[14:15], v23, s77, v[6:7]
	v_mad_u64_u32 v[130:131], s[14:15], v21, s77, v[6:7]
	s_add_i32 s15, s13, 16
	s_add_i32 s14, s12, 16
	v_or_b32_e32 v23, s15, v2
	v_or_b32_e32 v21, s14, v3
	v_mov_b32_e32 v27, v1
	v_add_u32_e32 v0, s3, v23
	v_add_u32_e32 v26, s6, v21
	v_lshlrev_b64 v[28:29], 12, v[0:1]
	v_lshlrev_b64 v[26:27], 12, v[26:27]
	v_lshl_add_u64 v[28:29], v[24:25], 0, v[28:29]
	v_lshl_add_u64 v[26:27], v[24:25], 0, v[26:27]
	global_load_dword v108, v[28:29], off
	global_load_dword v109, v[26:27], off
	v_mad_u64_u32 v[132:133], s[14:15], v23, s77, v[6:7]
	v_mad_u64_u32 v[134:135], s[14:15], v21, s77, v[6:7]
	s_add_i32 s15, s13, 20
	s_add_i32 s14, s12, 20
	v_or_b32_e32 v23, s15, v2
	v_or_b32_e32 v21, s14, v3
	v_mov_b32_e32 v27, v1
	v_add_u32_e32 v0, s3, v23
	v_add_u32_e32 v26, s6, v21
	v_lshlrev_b64 v[28:29], 12, v[0:1]
	v_lshlrev_b64 v[26:27], 12, v[26:27]
	v_lshl_add_u64 v[28:29], v[24:25], 0, v[28:29]
	v_lshl_add_u64 v[26:27], v[24:25], 0, v[26:27]
	global_load_dword v110, v[28:29], off
	global_load_dword v111, v[26:27], off
	v_mad_u64_u32 v[136:137], s[14:15], v23, s77, v[6:7]
	v_mad_u64_u32 v[138:139], s[14:15], v21, s77, v[6:7]
	s_add_i32 s15, s13, 24
	s_add_i32 s14, s12, 24
	v_or_b32_e32 v23, s15, v2
	v_or_b32_e32 v21, s14, v3
	v_mov_b32_e32 v27, v1
	s_add_i32 s13, s13, 28
	s_add_i32 s12, s12, 28
	s_cmp_lg_u32 s11, 0
	v_add_u32_e32 v0, s3, v23
	v_add_u32_e32 v26, s6, v21
	v_lshlrev_b64 v[28:29], 12, v[0:1]
	v_lshlrev_b64 v[26:27], 12, v[26:27]
	v_lshl_add_u64 v[28:29], v[24:25], 0, v[28:29]
	v_lshl_add_u64 v[26:27], v[24:25], 0, v[26:27]
	global_load_dword v112, v[28:29], off
	global_load_dword v113, v[26:27], off
	v_mad_u64_u32 v[140:141], s[14:15], v23, s77, v[6:7]
	v_or_b32_e32 v23, s13, v2
	v_mad_u64_u32 v[142:143], s[14:15], v21, s77, v[6:7]
	v_or_b32_e32 v21, s12, v3
	v_mov_b32_e32 v27, v1
	v_add_u32_e32 v0, s3, v23
	v_add_u32_e32 v26, s6, v21
	v_lshlrev_b64 v[28:29], 12, v[0:1]
	v_lshlrev_b64 v[26:27], 12, v[26:27]
	v_lshl_add_u64 v[28:29], v[24:25], 0, v[28:29]
	v_lshl_add_u64 v[26:27], v[24:25], 0, v[26:27]
	global_load_dword v114, v[28:29], off
	global_load_dword v115, v[26:27], off
	v_mad_u64_u32 v[144:145], s[12:13], v23, s77, v[6:7]
	v_mad_u64_u32 v[146:147], s[12:13], v21, s77, v[6:7]
	s_lshl_b32 s13, s7, 1
	s_lshl_b32 s12, s5, 1
	v_or_b32_e32 v23, s13, v2
	v_or_b32_e32 v21, s12, v3
	v_add_u32_e32 v0, s3, v23
	v_add_u32_e32 v26, s6, v21
	v_mov_b32_e32 v27, v1
	v_lshlrev_b64 v[28:29], 12, v[0:1]
	v_lshlrev_b64 v[26:27], 12, v[26:27]
	v_lshl_add_u64 v[28:29], v[24:25], 0, v[28:29]
	v_lshl_add_u64 v[26:27], v[24:25], 0, v[26:27]
	global_load_dword v148, v[28:29], off
	global_load_dword v149, v[26:27], off
	v_mad_u64_u32 v[164:165], s[14:15], v23, s77, v[6:7]
	v_mad_u64_u32 v[166:167], s[14:15], v21, s77, v[6:7]
	s_add_i32 s15, s13, 4
	s_add_i32 s14, s12, 4
	v_or_b32_e32 v23, s15, v2
	v_or_b32_e32 v21, s14, v3
	v_mov_b32_e32 v27, v1
	s_add_i32 s7, s7, 16
	s_add_i32 s5, s5, 16
	s_add_i32 s11, s11, -16
	v_add_u32_e32 v0, s3, v23
	v_add_u32_e32 v26, s6, v21
	v_lshlrev_b64 v[28:29], 12, v[0:1]
	v_lshlrev_b64 v[26:27], 12, v[26:27]
	v_lshl_add_u64 v[28:29], v[24:25], 0, v[28:29]
	v_lshl_add_u64 v[26:27], v[24:25], 0, v[26:27]
	global_load_dword v150, v[28:29], off
	global_load_dword v151, v[26:27], off
	v_mad_u64_u32 v[168:169], s[14:15], v23, s77, v[6:7]
	v_mad_u64_u32 v[170:171], s[14:15], v21, s77, v[6:7]
	s_add_i32 s15, s13, 8
	s_add_i32 s14, s12, 8
	v_or_b32_e32 v23, s15, v2
	v_or_b32_e32 v21, s14, v3
	v_mov_b32_e32 v27, v1
	v_add_u32_e32 v0, s3, v23
	v_add_u32_e32 v26, s6, v21
	v_lshlrev_b64 v[28:29], 12, v[0:1]
	v_lshlrev_b64 v[26:27], 12, v[26:27]
	v_lshl_add_u64 v[28:29], v[24:25], 0, v[28:29]
	v_lshl_add_u64 v[26:27], v[24:25], 0, v[26:27]
	global_load_dword v152, v[28:29], off
	global_load_dword v153, v[26:27], off
	v_mad_u64_u32 v[172:173], s[14:15], v23, s77, v[6:7]
	v_mad_u64_u32 v[174:175], s[14:15], v21, s77, v[6:7]
	s_add_i32 s15, s13, 12
	s_add_i32 s14, s12, 12
	v_or_b32_e32 v23, s15, v2
	v_or_b32_e32 v21, s14, v3
	v_mov_b32_e32 v27, v1
	v_add_u32_e32 v0, s3, v23
	v_add_u32_e32 v26, s6, v21
	v_lshlrev_b64 v[28:29], 12, v[0:1]
	v_lshlrev_b64 v[26:27], 12, v[26:27]
	v_lshl_add_u64 v[28:29], v[24:25], 0, v[28:29]
	v_lshl_add_u64 v[26:27], v[24:25], 0, v[26:27]
	global_load_dword v154, v[28:29], off
	global_load_dword v155, v[26:27], off
	v_mad_u64_u32 v[176:177], s[14:15], v23, s77, v[6:7]
	v_mad_u64_u32 v[178:179], s[14:15], v21, s77, v[6:7]
	s_add_i32 s15, s13, 16
	s_add_i32 s14, s12, 16
	v_or_b32_e32 v23, s15, v2
	v_or_b32_e32 v21, s14, v3
	v_mov_b32_e32 v27, v1
	v_add_u32_e32 v0, s3, v23
	v_add_u32_e32 v26, s6, v21
	v_lshlrev_b64 v[28:29], 12, v[0:1]
	v_lshlrev_b64 v[26:27], 12, v[26:27]
	v_lshl_add_u64 v[28:29], v[24:25], 0, v[28:29]
	v_lshl_add_u64 v[26:27], v[24:25], 0, v[26:27]
	global_load_dword v156, v[28:29], off
	global_load_dword v157, v[26:27], off
	v_mad_u64_u32 v[180:181], s[14:15], v23, s77, v[6:7]
	v_mad_u64_u32 v[182:183], s[14:15], v21, s77, v[6:7]
	s_add_i32 s15, s13, 20
	s_add_i32 s14, s12, 20
	v_or_b32_e32 v23, s15, v2
	v_or_b32_e32 v21, s14, v3
	v_mov_b32_e32 v27, v1
	v_add_u32_e32 v0, s3, v23
	v_add_u32_e32 v26, s6, v21
	v_lshlrev_b64 v[28:29], 12, v[0:1]
	v_lshlrev_b64 v[26:27], 12, v[26:27]
	v_lshl_add_u64 v[28:29], v[24:25], 0, v[28:29]
	v_lshl_add_u64 v[26:27], v[24:25], 0, v[26:27]
	global_load_dword v158, v[28:29], off
	global_load_dword v159, v[26:27], off
	v_mad_u64_u32 v[184:185], s[14:15], v23, s77, v[6:7]
	v_mad_u64_u32 v[186:187], s[14:15], v21, s77, v[6:7]
	s_add_i32 s15, s13, 24
	s_add_i32 s14, s12, 24
	v_or_b32_e32 v23, s15, v2
	v_or_b32_e32 v21, s14, v3
	v_mov_b32_e32 v27, v1
	s_add_i32 s13, s13, 28
	s_add_i32 s12, s12, 28
	s_cmp_lg_u32 s11, 0
	v_add_u32_e32 v0, s3, v23
	v_add_u32_e32 v26, s6, v21
	v_lshlrev_b64 v[28:29], 12, v[0:1]
	v_lshlrev_b64 v[26:27], 12, v[26:27]
	v_lshl_add_u64 v[28:29], v[24:25], 0, v[28:29]
	v_lshl_add_u64 v[26:27], v[24:25], 0, v[26:27]
	global_load_dword v160, v[28:29], off
	global_load_dword v161, v[26:27], off
	v_mad_u64_u32 v[188:189], s[14:15], v23, s77, v[6:7]
	v_or_b32_e32 v23, s13, v2
	v_mad_u64_u32 v[190:191], s[14:15], v21, s77, v[6:7]
	v_or_b32_e32 v21, s12, v3
	v_mov_b32_e32 v27, v1
	v_add_u32_e32 v0, s3, v23
	v_add_u32_e32 v26, s6, v21
	v_lshlrev_b64 v[28:29], 12, v[0:1]
	v_lshlrev_b64 v[26:27], 12, v[26:27]
	v_lshl_add_u64 v[28:29], v[24:25], 0, v[28:29]
	v_lshl_add_u64 v[26:27], v[24:25], 0, v[26:27]
	global_load_dword v162, v[28:29], off
	global_load_dword v163, v[26:27], off
	v_mad_u64_u32 v[192:193], s[12:13], v23, s77, v[6:7]
	v_mad_u64_u32 v[196:197], s[12:13], v21, s77, v[6:7]
	s_waitcnt vmcnt(0)
	ds_write_b32 v116, v100
	ds_write_b32 v118, v101
	ds_write_b32 v120, v102
	ds_write_b32 v122, v103
	ds_write_b32 v124, v104
	ds_write_b32 v126, v105
	ds_write_b32 v128, v106
	ds_write_b32 v130, v107
	ds_write_b32 v132, v108
	ds_write_b32 v134, v109
	ds_write_b32 v136, v110
	ds_write_b32 v138, v111
	ds_write_b32 v140, v112
	ds_write_b32 v142, v113
	ds_write_b32 v144, v114
	ds_write_b32 v146, v115
	ds_write_b32 v164, v148
	ds_write_b32 v166, v149
	ds_write_b32 v168, v150
	ds_write_b32 v170, v151
	ds_write_b32 v172, v152
	ds_write_b32 v174, v153
	ds_write_b32 v176, v154
	ds_write_b32 v178, v155
	ds_write_b32 v180, v156
	ds_write_b32 v182, v157
	ds_write_b32 v184, v158
	ds_write_b32 v186, v159
	ds_write_b32 v188, v160
	ds_write_b32 v190, v161
	ds_write_b32 v192, v162
	ds_write_b32 v196, v163
	s_cbranch_scc1 .LBB0_73
	s_lshl_b64 s[0:1], s[0:1], 20
	v_readlane_b32 s5, v253, 4
	s_add_u32 s0, s5, s0
	v_readlane_b32 s5, v253, 5
	s_addc_u32 s1, s5, s1
	s_lshl_b32 s2, s2, 10
	s_add_u32 s0, s0, s2
	s_addc_u32 s1, s1, 0
	s_lshl_b32 s2, s3, 1
	s_add_u32 s0, s0, s2
	s_addc_u32 s1, s1, 0
	v_mov_b32_e32 v0, v37
	v_mov_b32_e32 v24, v36
	v_mov_b32_e32 v26, v35
	v_mov_b32_e32 v28, v34

.LBB0_78:
	s_lshl_b32 s11, s5, 1
	s_lshl_b32 s7, s3, 1
	v_or_b32_e32 v21, s11, v2
	v_or_b32_e32 v0, s7, v3
	v_add_u32_e32 v28, s0, v21
	v_add_u32_e32 v26, s2, v0
	v_ashrrev_i32_e32 v29, 31, v28
	v_ashrrev_i32_e32 v27, 31, v26
	v_lshlrev_b64 v[28:29], 11, v[28:29]
	v_lshlrev_b64 v[26:27], 11, v[26:27]
	v_lshl_add_u64 v[28:29], v[24:25], 0, v[28:29]
	v_lshl_add_u64 v[26:27], v[24:25], 0, v[26:27]
	global_load_dword v100, v[28:29], off
	global_load_dword v101, v[26:27], off
	v_mad_u64_u32 v[116:117], s[12:13], v21, s77, v[6:7]
	v_mad_u64_u32 v[118:119], s[12:13], v0, s77, v[6:7]
	s_add_i32 s13, s11, 4
	s_add_i32 s12, s7, 4
	v_or_b32_e32 v21, s13, v2
	v_or_b32_e32 v0, s12, v3
	s_add_i32 s5, s5, 16
	s_add_i32 s3, s3, 16
	s_add_i32 s6, s6, -16
	v_add_u32_e32 v28, s0, v21
	v_add_u32_e32 v26, s2, v0
	v_ashrrev_i32_e32 v29, 31, v28
	v_ashrrev_i32_e32 v27, 31, v26
	v_lshlrev_b64 v[28:29], 11, v[28:29]
	v_lshlrev_b64 v[26:27], 11, v[26:27]
	v_lshl_add_u64 v[28:29], v[24:25], 0, v[28:29]
	v_lshl_add_u64 v[26:27], v[24:25], 0, v[26:27]
	global_load_dword v102, v[28:29], off
	global_load_dword v103, v[26:27], off
	v_mad_u64_u32 v[120:121], s[12:13], v21, s77, v[6:7]
	v_mad_u64_u32 v[122:123], s[12:13], v0, s77, v[6:7]
	s_add_i32 s13, s11, 8
	s_add_i32 s12, s7, 8
	v_or_b32_e32 v21, s13, v2
	v_or_b32_e32 v0, s12, v3
	v_add_u32_e32 v28, s0, v21
	v_add_u32_e32 v26, s2, v0
	v_ashrrev_i32_e32 v29, 31, v28
	v_ashrrev_i32_e32 v27, 31, v26
	v_lshlrev_b64 v[28:29], 11, v[28:29]
	v_lshlrev_b64 v[26:27], 11, v[26:27]
	v_lshl_add_u64 v[28:29], v[24:25], 0, v[28:29]
	v_lshl_add_u64 v[26:27], v[24:25], 0, v[26:27]
	global_load_dword v104, v[28:29], off
	global_load_dword v105, v[26:27], off
	v_mad_u64_u32 v[124:125], s[12:13], v21, s77, v[6:7]
	v_mad_u64_u32 v[126:127], s[12:13], v0, s77, v[6:7]
	s_add_i32 s13, s11, 12
	s_add_i32 s12, s7, 12
	v_or_b32_e32 v21, s13, v2
	v_or_b32_e32 v0, s12, v3
	v_add_u32_e32 v28, s0, v21
	v_add_u32_e32 v26, s2, v0
	v_ashrrev_i32_e32 v29, 31, v28
	v_ashrrev_i32_e32 v27, 31, v26
	v_lshlrev_b64 v[28:29], 11, v[28:29]
	v_lshlrev_b64 v[26:27], 11, v[26:27]
	v_lshl_add_u64 v[28:29], v[24:25], 0, v[28:29]
	v_lshl_add_u64 v[26:27], v[24:25], 0, v[26:27]
	global_load_dword v106, v[28:29], off
	global_load_dword v107, v[26:27], off
	v_mad_u64_u32 v[128:129], s[12:13], v21, s77, v[6:7]
	v_mad_u64_u32 v[130:131], s[12:13], v0, s77, v[6:7]
	s_add_i32 s13, s11, 16
	s_add_i32 s12, s7, 16
	v_or_b32_e32 v21, s13, v2
	v_or_b32_e32 v0, s12, v3
	v_add_u32_e32 v28, s0, v21
	v_add_u32_e32 v26, s2, v0
	v_ashrrev_i32_e32 v29, 31, v28
	v_ashrrev_i32_e32 v27, 31, v26
	v_lshlrev_b64 v[28:29], 11, v[28:29]
	v_lshlrev_b64 v[26:27], 11, v[26:27]
	v_lshl_add_u64 v[28:29], v[24:25], 0, v[28:29]
	v_lshl_add_u64 v[26:27], v[24:25], 0, v[26:27]
	global_load_dword v108, v[28:29], off
	global_load_dword v109, v[26:27], off
	v_mad_u64_u32 v[132:133], s[12:13], v21, s77, v[6:7]
	v_mad_u64_u32 v[134:135], s[12:13], v0, s77, v[6:7]
	s_add_i32 s13, s11, 20
	s_add_i32 s12, s7, 20
	v_or_b32_e32 v21, s13, v2
	v_or_b32_e32 v0, s12, v3
	v_add_u32_e32 v28, s0, v21
	v_add_u32_e32 v26, s2, v0
	v_ashrrev_i32_e32 v29, 31, v28
	v_ashrrev_i32_e32 v27, 31, v26
	v_lshlrev_b64 v[28:29], 11, v[28:29]
	v_lshlrev_b64 v[26:27], 11, v[26:27]
	v_lshl_add_u64 v[28:29], v[24:25], 0, v[28:29]
	v_lshl_add_u64 v[26:27], v[24:25], 0, v[26:27]
	global_load_dword v110, v[28:29], off
	global_load_dword v111, v[26:27], off
	v_mad_u64_u32 v[136:137], s[12:13], v21, s77, v[6:7]
	v_mad_u64_u32 v[138:139], s[12:13], v0, s77, v[6:7]
	s_add_i32 s13, s11, 24
	s_add_i32 s12, s7, 24
	v_or_b32_e32 v21, s13, v2
	v_or_b32_e32 v0, s12, v3
	s_add_i32 s11, s11, 28
	s_add_i32 s7, s7, 28
	s_cmp_lg_u32 s6, 0
	v_add_u32_e32 v28, s0, v21
	v_add_u32_e32 v26, s2, v0
	v_ashrrev_i32_e32 v29, 31, v28
	v_ashrrev_i32_e32 v27, 31, v26
	v_lshlrev_b64 v[28:29], 11, v[28:29]
	v_lshlrev_b64 v[26:27], 11, v[26:27]
	v_lshl_add_u64 v[28:29], v[24:25], 0, v[28:29]
	v_lshl_add_u64 v[26:27], v[24:25], 0, v[26:27]
	global_load_dword v112, v[28:29], off
	global_load_dword v113, v[26:27], off
	v_mad_u64_u32 v[140:141], s[12:13], v21, s77, v[6:7]
	v_mad_u64_u32 v[142:143], s[12:13], v0, s77, v[6:7]
	v_or_b32_e32 v21, s11, v2
	v_or_b32_e32 v0, s7, v3
	v_add_u32_e32 v28, s0, v21
	v_add_u32_e32 v26, s2, v0
	v_ashrrev_i32_e32 v29, 31, v28
	v_ashrrev_i32_e32 v27, 31, v26
	v_lshlrev_b64 v[28:29], 11, v[28:29]
	v_lshlrev_b64 v[26:27], 11, v[26:27]
	v_lshl_add_u64 v[28:29], v[24:25], 0, v[28:29]
	v_lshl_add_u64 v[26:27], v[24:25], 0, v[26:27]
	global_load_dword v114, v[28:29], off
	global_load_dword v115, v[26:27], off
	v_mad_u64_u32 v[144:145], s[12:13], v21, s77, v[6:7]
	v_mad_u64_u32 v[146:147], s[12:13], v0, s77, v[6:7]
	s_lshl_b32 s11, s5, 1
	s_lshl_b32 s7, s3, 1
	v_or_b32_e32 v21, s11, v2
	v_or_b32_e32 v0, s7, v3
	v_add_u32_e32 v28, s0, v21
	v_add_u32_e32 v26, s2, v0
	v_ashrrev_i32_e32 v29, 31, v28
	v_ashrrev_i32_e32 v27, 31, v26
	v_lshlrev_b64 v[28:29], 11, v[28:29]
	v_lshlrev_b64 v[26:27], 11, v[26:27]
	v_lshl_add_u64 v[28:29], v[24:25], 0, v[28:29]
	v_lshl_add_u64 v[26:27], v[24:25], 0, v[26:27]
	global_load_dword v148, v[28:29], off
	global_load_dword v149, v[26:27], off
	v_mad_u64_u32 v[164:165], s[12:13], v21, s77, v[6:7]
	v_mad_u64_u32 v[166:167], s[12:13], v0, s77, v[6:7]
	s_add_i32 s13, s11, 4
	s_add_i32 s12, s7, 4
	v_or_b32_e32 v21, s13, v2
	v_or_b32_e32 v0, s12, v3
	s_add_i32 s5, s5, 16
	s_add_i32 s3, s3, 16
	s_add_i32 s6, s6, -16
	v_add_u32_e32 v28, s0, v21
	v_add_u32_e32 v26, s2, v0
	v_ashrrev_i32_e32 v29, 31, v28
	v_ashrrev_i32_e32 v27, 31, v26
	v_lshlrev_b64 v[28:29], 11, v[28:29]
	v_lshlrev_b64 v[26:27], 11, v[26:27]
	v_lshl_add_u64 v[28:29], v[24:25], 0, v[28:29]
	v_lshl_add_u64 v[26:27], v[24:25], 0, v[26:27]
	global_load_dword v150, v[28:29], off
	global_load_dword v151, v[26:27], off
	v_mad_u64_u32 v[168:169], s[12:13], v21, s77, v[6:7]
	v_mad_u64_u32 v[170:171], s[12:13], v0, s77, v[6:7]
	s_add_i32 s13, s11, 8
	s_add_i32 s12, s7, 8
	v_or_b32_e32 v21, s13, v2
	v_or_b32_e32 v0, s12, v3
	v_add_u32_e32 v28, s0, v21
	v_add_u32_e32 v26, s2, v0
	v_ashrrev_i32_e32 v29, 31, v28
	v_ashrrev_i32_e32 v27, 31, v26
	v_lshlrev_b64 v[28:29], 11, v[28:29]
	v_lshlrev_b64 v[26:27], 11, v[26:27]
	v_lshl_add_u64 v[28:29], v[24:25], 0, v[28:29]
	v_lshl_add_u64 v[26:27], v[24:25], 0, v[26:27]
	global_load_dword v152, v[28:29], off
	global_load_dword v153, v[26:27], off
	v_mad_u64_u32 v[172:173], s[12:13], v21, s77, v[6:7]
	v_mad_u64_u32 v[174:175], s[12:13], v0, s77, v[6:7]
	s_add_i32 s13, s11, 12
	s_add_i32 s12, s7, 12
	v_or_b32_e32 v21, s13, v2
	v_or_b32_e32 v0, s12, v3
	v_add_u32_e32 v28, s0, v21
	v_add_u32_e32 v26, s2, v0
	v_ashrrev_i32_e32 v29, 31, v28
	v_ashrrev_i32_e32 v27, 31, v26
	v_lshlrev_b64 v[28:29], 11, v[28:29]
	v_lshlrev_b64 v[26:27], 11, v[26:27]
	v_lshl_add_u64 v[28:29], v[24:25], 0, v[28:29]
	v_lshl_add_u64 v[26:27], v[24:25], 0, v[26:27]
	global_load_dword v154, v[28:29], off
	global_load_dword v155, v[26:27], off
	v_mad_u64_u32 v[176:177], s[12:13], v21, s77, v[6:7]
	v_mad_u64_u32 v[178:179], s[12:13], v0, s77, v[6:7]
	s_add_i32 s13, s11, 16
	s_add_i32 s12, s7, 16
	v_or_b32_e32 v21, s13, v2
	v_or_b32_e32 v0, s12, v3
	v_add_u32_e32 v28, s0, v21
	v_add_u32_e32 v26, s2, v0
	v_ashrrev_i32_e32 v29, 31, v28
	v_ashrrev_i32_e32 v27, 31, v26
	v_lshlrev_b64 v[28:29], 11, v[28:29]
	v_lshlrev_b64 v[26:27], 11, v[26:27]
	v_lshl_add_u64 v[28:29], v[24:25], 0, v[28:29]
	v_lshl_add_u64 v[26:27], v[24:25], 0, v[26:27]
	global_load_dword v156, v[28:29], off
	global_load_dword v157, v[26:27], off
	v_mad_u64_u32 v[180:181], s[12:13], v21, s77, v[6:7]
	v_mad_u64_u32 v[182:183], s[12:13], v0, s77, v[6:7]
	s_add_i32 s13, s11, 20
	s_add_i32 s12, s7, 20
	v_or_b32_e32 v21, s13, v2
	v_or_b32_e32 v0, s12, v3
	v_add_u32_e32 v28, s0, v21
	v_add_u32_e32 v26, s2, v0
	v_ashrrev_i32_e32 v29, 31, v28
	v_ashrrev_i32_e32 v27, 31, v26
	v_lshlrev_b64 v[28:29], 11, v[28:29]
	v_lshlrev_b64 v[26:27], 11, v[26:27]
	v_lshl_add_u64 v[28:29], v[24:25], 0, v[28:29]
	v_lshl_add_u64 v[26:27], v[24:25], 0, v[26:27]
	global_load_dword v158, v[28:29], off
	global_load_dword v159, v[26:27], off
	v_mad_u64_u32 v[184:185], s[12:13], v21, s77, v[6:7]
	v_mad_u64_u32 v[186:187], s[12:13], v0, s77, v[6:7]
	s_add_i32 s13, s11, 24
	s_add_i32 s12, s7, 24
	v_or_b32_e32 v21, s13, v2
	v_or_b32_e32 v0, s12, v3
	s_add_i32 s11, s11, 28
	s_add_i32 s7, s7, 28
	s_cmp_lg_u32 s6, 0
	v_add_u32_e32 v28, s0, v21
	v_add_u32_e32 v26, s2, v0
	v_ashrrev_i32_e32 v29, 31, v28
	v_ashrrev_i32_e32 v27, 31, v26
	v_lshlrev_b64 v[28:29], 11, v[28:29]
	v_lshlrev_b64 v[26:27], 11, v[26:27]
	v_lshl_add_u64 v[28:29], v[24:25], 0, v[28:29]
	v_lshl_add_u64 v[26:27], v[24:25], 0, v[26:27]
	global_load_dword v160, v[28:29], off
	global_load_dword v161, v[26:27], off
	v_mad_u64_u32 v[188:189], s[12:13], v21, s77, v[6:7]
	v_mad_u64_u32 v[190:191], s[12:13], v0, s77, v[6:7]
	v_or_b32_e32 v21, s11, v2
	v_or_b32_e32 v0, s7, v3
	v_add_u32_e32 v28, s0, v21
	v_add_u32_e32 v26, s2, v0
	v_ashrrev_i32_e32 v29, 31, v28
	v_ashrrev_i32_e32 v27, 31, v26
	v_lshlrev_b64 v[28:29], 11, v[28:29]
	v_lshlrev_b64 v[26:27], 11, v[26:27]
	v_lshl_add_u64 v[28:29], v[24:25], 0, v[28:29]
	v_lshl_add_u64 v[26:27], v[24:25], 0, v[26:27]
	global_load_dword v162, v[28:29], off
	global_load_dword v163, v[26:27], off
	v_mad_u64_u32 v[192:193], s[12:13], v21, s77, v[6:7]
	v_mad_u64_u32 v[196:197], s[12:13], v0, s77, v[6:7]
	s_waitcnt vmcnt(0)
	ds_write_b32 v116, v100
	ds_write_b32 v118, v101
	ds_write_b32 v120, v102
	ds_write_b32 v122, v103
	ds_write_b32 v124, v104
	ds_write_b32 v126, v105
	ds_write_b32 v128, v106
	ds_write_b32 v130, v107
	ds_write_b32 v132, v108
	ds_write_b32 v134, v109
	ds_write_b32 v136, v110
	ds_write_b32 v138, v111
	ds_write_b32 v140, v112
	ds_write_b32 v142, v113
	ds_write_b32 v144, v114
	ds_write_b32 v146, v115
	ds_write_b32 v164, v148
	ds_write_b32 v166, v149
	ds_write_b32 v168, v150
	ds_write_b32 v170, v151
	ds_write_b32 v172, v152
	ds_write_b32 v174, v153
	ds_write_b32 v176, v154
	ds_write_b32 v178, v155
	ds_write_b32 v180, v156
	ds_write_b32 v182, v157
	ds_write_b32 v184, v158
	ds_write_b32 v186, v159
	ds_write_b32 v188, v160
	ds_write_b32 v190, v161
	ds_write_b32 v192, v162
	ds_write_b32 v196, v163
	s_cbranch_scc1 .LBB0_78
	s_lshl_b32 s1, s1, 10
	s_add_u32 s2, s73, s1
	v_readlane_b32 s1, v250, 13
	s_addc_u32 s3, s1, 0
	s_mov_b32 s1, s4
	s_lshl_b64 s[0:1], s[0:1], 1
	s_add_u32 s0, s2, s0
	s_addc_u32 s1, s3, s1
	v_mov_b32_e32 v0, v37
	v_mov_b32_e32 v24, v36
	v_mov_b32_e32 v26, v35
	v_mov_b32_e32 v28, v34

.LBB0_87:
	s_lshl_b32 s12, s5, 1
	s_lshl_b32 s11, s2, 1
	v_or_b32_e32 v21, s12, v2
	v_or_b32_e32 v0, s11, v3
	v_add_u32_e32 v28, s6, v21
	v_add_u32_e32 v26, s3, v0
	v_ashrrev_i32_e32 v29, 31, v28
	v_ashrrev_i32_e32 v27, 31, v26
	v_lshlrev_b64 v[28:29], 12, v[28:29]
	v_lshlrev_b64 v[26:27], 12, v[26:27]
	v_lshl_add_u64 v[28:29], v[24:25], 0, v[28:29]
	v_lshl_add_u64 v[26:27], v[24:25], 0, v[26:27]
	global_load_dword v100, v[28:29], off
	global_load_dword v101, v[26:27], off
	v_mad_u64_u32 v[116:117], s[14:15], v21, s77, v[6:7]
	v_mad_u64_u32 v[118:119], s[14:15], v0, s77, v[6:7]
	s_add_i32 s14, s12, 4
	s_add_i32 s13, s11, 4
	v_or_b32_e32 v21, s14, v2
	v_or_b32_e32 v0, s13, v3
	s_add_i32 s13, s11, 8
	s_add_i32 s5, s5, 16
	s_add_i32 s2, s2, 16
	s_add_i32 s7, s7, -16
	v_add_u32_e32 v28, s6, v21
	v_add_u32_e32 v26, s3, v0
	v_ashrrev_i32_e32 v29, 31, v28
	v_ashrrev_i32_e32 v27, 31, v26
	v_lshlrev_b64 v[28:29], 12, v[28:29]
	v_lshlrev_b64 v[26:27], 12, v[26:27]
	v_lshl_add_u64 v[28:29], v[24:25], 0, v[28:29]
	v_lshl_add_u64 v[26:27], v[24:25], 0, v[26:27]
	global_load_dword v102, v[28:29], off
	global_load_dword v103, v[26:27], off
	v_mad_u64_u32 v[120:121], s[14:15], v21, s77, v[6:7]
	v_mad_u64_u32 v[122:123], s[14:15], v0, s77, v[6:7]
	s_add_i32 s14, s12, 8
	s_nop 0
	v_or_b32_e32 v21, s14, v2
	v_or_b32_e32 v0, s13, v3
	s_add_i32 s13, s11, 12
	v_add_u32_e32 v28, s6, v21
	v_add_u32_e32 v26, s3, v0
	v_ashrrev_i32_e32 v29, 31, v28
	v_ashrrev_i32_e32 v27, 31, v26
	v_lshlrev_b64 v[28:29], 12, v[28:29]
	v_lshlrev_b64 v[26:27], 12, v[26:27]
	v_lshl_add_u64 v[28:29], v[24:25], 0, v[28:29]
	v_lshl_add_u64 v[26:27], v[24:25], 0, v[26:27]
	global_load_dword v104, v[28:29], off
	global_load_dword v105, v[26:27], off
	v_mad_u64_u32 v[124:125], s[14:15], v21, s77, v[6:7]
	v_mad_u64_u32 v[126:127], s[14:15], v0, s77, v[6:7]
	s_add_i32 s14, s12, 12
	s_nop 0
	v_or_b32_e32 v21, s14, v2
	v_or_b32_e32 v0, s13, v3
	s_add_i32 s13, s11, 16
	v_add_u32_e32 v28, s6, v21
	v_add_u32_e32 v26, s3, v0
	v_ashrrev_i32_e32 v29, 31, v28
	v_ashrrev_i32_e32 v27, 31, v26
	v_lshlrev_b64 v[28:29], 12, v[28:29]
	v_lshlrev_b64 v[26:27], 12, v[26:27]
	v_lshl_add_u64 v[28:29], v[24:25], 0, v[28:29]
	v_lshl_add_u64 v[26:27], v[24:25], 0, v[26:27]
	global_load_dword v106, v[28:29], off
	global_load_dword v107, v[26:27], off
	v_mad_u64_u32 v[128:129], s[14:15], v21, s77, v[6:7]
	v_mad_u64_u32 v[130:131], s[14:15], v0, s77, v[6:7]
	s_add_i32 s14, s12, 16
	s_nop 0
	v_or_b32_e32 v21, s14, v2
	v_or_b32_e32 v0, s13, v3
	s_add_i32 s13, s11, 20
	v_add_u32_e32 v28, s6, v21
	v_add_u32_e32 v26, s3, v0
	v_ashrrev_i32_e32 v29, 31, v28
	v_ashrrev_i32_e32 v27, 31, v26
	v_lshlrev_b64 v[28:29], 12, v[28:29]
	v_lshlrev_b64 v[26:27], 12, v[26:27]
	v_lshl_add_u64 v[28:29], v[24:25], 0, v[28:29]
	v_lshl_add_u64 v[26:27], v[24:25], 0, v[26:27]
	global_load_dword v108, v[28:29], off
	global_load_dword v109, v[26:27], off
	v_mad_u64_u32 v[132:133], s[14:15], v21, s77, v[6:7]
	v_mad_u64_u32 v[134:135], s[14:15], v0, s77, v[6:7]
	s_add_i32 s14, s12, 20
	s_nop 0
	v_or_b32_e32 v21, s14, v2
	v_or_b32_e32 v0, s13, v3
	s_add_i32 s13, s11, 24
	s_add_i32 s11, s11, 28
	v_add_u32_e32 v28, s6, v21
	v_add_u32_e32 v26, s3, v0
	v_ashrrev_i32_e32 v29, 31, v28
	v_ashrrev_i32_e32 v27, 31, v26
	v_lshlrev_b64 v[28:29], 12, v[28:29]
	v_lshlrev_b64 v[26:27], 12, v[26:27]
	v_lshl_add_u64 v[28:29], v[24:25], 0, v[28:29]
	v_lshl_add_u64 v[26:27], v[24:25], 0, v[26:27]
	global_load_dword v110, v[28:29], off
	global_load_dword v111, v[26:27], off
	v_mad_u64_u32 v[136:137], s[14:15], v21, s77, v[6:7]
	v_mad_u64_u32 v[138:139], s[14:15], v0, s77, v[6:7]
	s_add_i32 s14, s12, 24
	s_nop 0
	v_or_b32_e32 v21, s14, v2
	v_or_b32_e32 v0, s13, v3
	s_add_i32 s12, s12, 28
	s_cmp_lg_u32 s7, 0
	v_add_u32_e32 v28, s6, v21
	v_add_u32_e32 v26, s3, v0
	v_ashrrev_i32_e32 v29, 31, v28
	v_ashrrev_i32_e32 v27, 31, v26
	v_lshlrev_b64 v[28:29], 12, v[28:29]
	v_lshlrev_b64 v[26:27], 12, v[26:27]
	v_lshl_add_u64 v[28:29], v[24:25], 0, v[28:29]
	v_lshl_add_u64 v[26:27], v[24:25], 0, v[26:27]
	global_load_dword v112, v[28:29], off
	global_load_dword v113, v[26:27], off
	v_mad_u64_u32 v[140:141], s[14:15], v21, s77, v[6:7]
	v_mad_u64_u32 v[142:143], s[14:15], v0, s77, v[6:7]
	v_or_b32_e32 v21, s12, v2
	v_or_b32_e32 v0, s11, v3
	v_add_u32_e32 v28, s6, v21
	v_add_u32_e32 v26, s3, v0
	v_ashrrev_i32_e32 v29, 31, v28
	v_ashrrev_i32_e32 v27, 31, v26
	v_lshlrev_b64 v[28:29], 12, v[28:29]
	v_lshlrev_b64 v[26:27], 12, v[26:27]
	v_lshl_add_u64 v[28:29], v[24:25], 0, v[28:29]
	v_lshl_add_u64 v[26:27], v[24:25], 0, v[26:27]
	global_load_dword v114, v[28:29], off
	global_load_dword v115, v[26:27], off
	v_mad_u64_u32 v[144:145], s[12:13], v21, s77, v[6:7]
	v_mad_u64_u32 v[146:147], s[12:13], v0, s77, v[6:7]
	s_lshl_b32 s12, s5, 1
	s_lshl_b32 s11, s2, 1
	v_or_b32_e32 v21, s12, v2
	v_or_b32_e32 v0, s11, v3
	v_add_u32_e32 v28, s6, v21
	v_add_u32_e32 v26, s3, v0
	v_ashrrev_i32_e32 v29, 31, v28
	v_ashrrev_i32_e32 v27, 31, v26
	v_lshlrev_b64 v[28:29], 12, v[28:29]
	v_lshlrev_b64 v[26:27], 12, v[26:27]
	v_lshl_add_u64 v[28:29], v[24:25], 0, v[28:29]
	v_lshl_add_u64 v[26:27], v[24:25], 0, v[26:27]
	global_load_dword v148, v[28:29], off
	global_load_dword v149, v[26:27], off
	v_mad_u64_u32 v[164:165], s[14:15], v21, s77, v[6:7]
	v_mad_u64_u32 v[166:167], s[14:15], v0, s77, v[6:7]
	s_add_i32 s14, s12, 4
	s_add_i32 s13, s11, 4
	v_or_b32_e32 v21, s14, v2
	v_or_b32_e32 v0, s13, v3
	s_add_i32 s13, s11, 8
	s_add_i32 s5, s5, 16
	s_add_i32 s2, s2, 16
	s_add_i32 s7, s7, -16
	v_add_u32_e32 v28, s6, v21
	v_add_u32_e32 v26, s3, v0
	v_ashrrev_i32_e32 v29, 31, v28
	v_ashrrev_i32_e32 v27, 31, v26
	v_lshlrev_b64 v[28:29], 12, v[28:29]
	v_lshlrev_b64 v[26:27], 12, v[26:27]
	v_lshl_add_u64 v[28:29], v[24:25], 0, v[28:29]
	v_lshl_add_u64 v[26:27], v[24:25], 0, v[26:27]
	global_load_dword v150, v[28:29], off
	global_load_dword v151, v[26:27], off
	v_mad_u64_u32 v[168:169], s[14:15], v21, s77, v[6:7]
	v_mad_u64_u32 v[170:171], s[14:15], v0, s77, v[6:7]
	s_add_i32 s14, s12, 8
	s_nop 0
	v_or_b32_e32 v21, s14, v2
	v_or_b32_e32 v0, s13, v3
	s_add_i32 s13, s11, 12
	v_add_u32_e32 v28, s6, v21
	v_add_u32_e32 v26, s3, v0
	v_ashrrev_i32_e32 v29, 31, v28
	v_ashrrev_i32_e32 v27, 31, v26
	v_lshlrev_b64 v[28:29], 12, v[28:29]
	v_lshlrev_b64 v[26:27], 12, v[26:27]
	v_lshl_add_u64 v[28:29], v[24:25], 0, v[28:29]
	v_lshl_add_u64 v[26:27], v[24:25], 0, v[26:27]
	global_load_dword v152, v[28:29], off
	global_load_dword v153, v[26:27], off
	v_mad_u64_u32 v[172:173], s[14:15], v21, s77, v[6:7]
	v_mad_u64_u32 v[174:175], s[14:15], v0, s77, v[6:7]
	s_add_i32 s14, s12, 12
	s_nop 0
	v_or_b32_e32 v21, s14, v2
	v_or_b32_e32 v0, s13, v3
	s_add_i32 s13, s11, 16
	v_add_u32_e32 v28, s6, v21
	v_add_u32_e32 v26, s3, v0
	v_ashrrev_i32_e32 v29, 31, v28
	v_ashrrev_i32_e32 v27, 31, v26
	v_lshlrev_b64 v[28:29], 12, v[28:29]
	v_lshlrev_b64 v[26:27], 12, v[26:27]
	v_lshl_add_u64 v[28:29], v[24:25], 0, v[28:29]
	v_lshl_add_u64 v[26:27], v[24:25], 0, v[26:27]
	global_load_dword v154, v[28:29], off
	global_load_dword v155, v[26:27], off
	v_mad_u64_u32 v[176:177], s[14:15], v21, s77, v[6:7]
	v_mad_u64_u32 v[178:179], s[14:15], v0, s77, v[6:7]
	s_add_i32 s14, s12, 16
	s_nop 0
	v_or_b32_e32 v21, s14, v2
	v_or_b32_e32 v0, s13, v3
	s_add_i32 s13, s11, 20
	v_add_u32_e32 v28, s6, v21
	v_add_u32_e32 v26, s3, v0
	v_ashrrev_i32_e32 v29, 31, v28
	v_ashrrev_i32_e32 v27, 31, v26
	v_lshlrev_b64 v[28:29], 12, v[28:29]
	v_lshlrev_b64 v[26:27], 12, v[26:27]
	v_lshl_add_u64 v[28:29], v[24:25], 0, v[28:29]
	v_lshl_add_u64 v[26:27], v[24:25], 0, v[26:27]
	global_load_dword v156, v[28:29], off
	global_load_dword v157, v[26:27], off
	v_mad_u64_u32 v[180:181], s[14:15], v21, s77, v[6:7]
	v_mad_u64_u32 v[182:183], s[14:15], v0, s77, v[6:7]
	s_add_i32 s14, s12, 20
	s_nop 0
	v_or_b32_e32 v21, s14, v2
	v_or_b32_e32 v0, s13, v3
	s_add_i32 s13, s11, 24
	s_add_i32 s11, s11, 28
	v_add_u32_e32 v28, s6, v21
	v_add_u32_e32 v26, s3, v0
	v_ashrrev_i32_e32 v29, 31, v28
	v_ashrrev_i32_e32 v27, 31, v26
	v_lshlrev_b64 v[28:29], 12, v[28:29]
	v_lshlrev_b64 v[26:27], 12, v[26:27]
	v_lshl_add_u64 v[28:29], v[24:25], 0, v[28:29]
	v_lshl_add_u64 v[26:27], v[24:25], 0, v[26:27]
	global_load_dword v158, v[28:29], off
	global_load_dword v159, v[26:27], off
	v_mad_u64_u32 v[184:185], s[14:15], v21, s77, v[6:7]
	v_mad_u64_u32 v[186:187], s[14:15], v0, s77, v[6:7]
	s_add_i32 s14, s12, 24
	s_nop 0
	v_or_b32_e32 v21, s14, v2
	v_or_b32_e32 v0, s13, v3
	s_add_i32 s12, s12, 28
	s_cmp_lg_u32 s7, 0
	v_add_u32_e32 v28, s6, v21
	v_add_u32_e32 v26, s3, v0
	v_ashrrev_i32_e32 v29, 31, v28
	v_ashrrev_i32_e32 v27, 31, v26
	v_lshlrev_b64 v[28:29], 12, v[28:29]
	v_lshlrev_b64 v[26:27], 12, v[26:27]
	v_lshl_add_u64 v[28:29], v[24:25], 0, v[28:29]
	v_lshl_add_u64 v[26:27], v[24:25], 0, v[26:27]
	global_load_dword v160, v[28:29], off
	global_load_dword v161, v[26:27], off
	v_mad_u64_u32 v[188:189], s[14:15], v21, s77, v[6:7]
	v_mad_u64_u32 v[190:191], s[14:15], v0, s77, v[6:7]
	v_or_b32_e32 v21, s12, v2
	v_or_b32_e32 v0, s11, v3
	v_add_u32_e32 v28, s6, v21
	v_add_u32_e32 v26, s3, v0
	v_ashrrev_i32_e32 v29, 31, v28
	v_ashrrev_i32_e32 v27, 31, v26
	v_lshlrev_b64 v[28:29], 12, v[28:29]
	v_lshlrev_b64 v[26:27], 12, v[26:27]
	v_lshl_add_u64 v[28:29], v[24:25], 0, v[28:29]
	v_lshl_add_u64 v[26:27], v[24:25], 0, v[26:27]
	global_load_dword v162, v[28:29], off
	global_load_dword v163, v[26:27], off
	v_mad_u64_u32 v[192:193], s[12:13], v21, s77, v[6:7]
	v_mad_u64_u32 v[196:197], s[12:13], v0, s77, v[6:7]
	s_waitcnt vmcnt(0)
	ds_write_b32 v116, v100
	ds_write_b32 v118, v101
	ds_write_b32 v120, v102
	ds_write_b32 v122, v103
	ds_write_b32 v124, v104
	ds_write_b32 v126, v105
	ds_write_b32 v128, v106
	ds_write_b32 v130, v107
	ds_write_b32 v132, v108
	ds_write_b32 v134, v109
	ds_write_b32 v136, v110
	ds_write_b32 v138, v111
	ds_write_b32 v140, v112
	ds_write_b32 v142, v113
	ds_write_b32 v144, v114
	ds_write_b32 v146, v115
	ds_write_b32 v164, v148
	ds_write_b32 v166, v149
	ds_write_b32 v168, v150
	ds_write_b32 v170, v151
	ds_write_b32 v172, v152
	ds_write_b32 v174, v153
	ds_write_b32 v176, v154
	ds_write_b32 v178, v155
	ds_write_b32 v180, v156
	ds_write_b32 v182, v157
	ds_write_b32 v184, v158
	ds_write_b32 v186, v159
	ds_write_b32 v188, v160
	ds_write_b32 v190, v161
	ds_write_b32 v192, v162
	ds_write_b32 v196, v163
	s_cbranch_scc1 .LBB0_87
	s_mov_b32 s7, s4
	s_lshl_b64 s[2:3], s[6:7], 1
	s_add_u32 s0, s0, s2
	s_addc_u32 s1, s1, s3
	v_mov_b32_e32 v0, v41
	v_mov_b32_e32 v24, v40
	v_mov_b32_e32 v26, v39
	v_mov_b32_e32 v28, v38

.LBB0_92:
	s_lshl_b32 s11, s5, 1
	s_lshl_b32 s7, s3, 1
	v_or_b32_e32 v21, s11, v2
	v_or_b32_e32 v0, s7, v3
	v_add_u32_e32 v26, s0, v21
	v_add_u32_e32 v23, s2, v0
	v_mad_u64_u32 v[26:27], s[12:13], v26, s61, v[24:25]
	v_mad_u64_u32 v[28:29], s[12:13], v23, s61, v[24:25]
	global_load_dword v100, v[26:27], off
	global_load_dword v101, v[28:29], off
	v_mad_u64_u32 v[116:117], s[12:13], v21, s77, v[6:7]
	v_mad_u64_u32 v[118:119], s[12:13], v0, s77, v[6:7]
	s_add_i32 s13, s11, 4
	s_add_i32 s12, s7, 4
	v_or_b32_e32 v21, s13, v2
	v_or_b32_e32 v0, s12, v3
	s_add_i32 s5, s5, 16
	s_add_i32 s3, s3, 16
	s_add_i32 s6, s6, -16
	v_add_u32_e32 v26, s0, v21
	v_add_u32_e32 v23, s2, v0
	v_mad_u64_u32 v[26:27], s[12:13], v26, s61, v[24:25]
	v_mad_u64_u32 v[28:29], s[12:13], v23, s61, v[24:25]
	global_load_dword v102, v[26:27], off
	global_load_dword v103, v[28:29], off
	v_mad_u64_u32 v[120:121], s[12:13], v21, s77, v[6:7]
	v_mad_u64_u32 v[122:123], s[12:13], v0, s77, v[6:7]
	s_add_i32 s13, s11, 8
	s_add_i32 s12, s7, 8
	v_or_b32_e32 v21, s13, v2
	v_or_b32_e32 v0, s12, v3
	v_add_u32_e32 v26, s0, v21
	v_add_u32_e32 v23, s2, v0
	v_mad_u64_u32 v[26:27], s[12:13], v26, s61, v[24:25]
	v_mad_u64_u32 v[28:29], s[12:13], v23, s61, v[24:25]
	global_load_dword v104, v[26:27], off
	global_load_dword v105, v[28:29], off
	v_mad_u64_u32 v[124:125], s[12:13], v21, s77, v[6:7]
	v_mad_u64_u32 v[126:127], s[12:13], v0, s77, v[6:7]
	s_add_i32 s13, s11, 12
	s_add_i32 s12, s7, 12
	v_or_b32_e32 v21, s13, v2
	v_or_b32_e32 v0, s12, v3
	v_add_u32_e32 v26, s0, v21
	v_add_u32_e32 v23, s2, v0
	v_mad_u64_u32 v[26:27], s[12:13], v26, s61, v[24:25]
	v_mad_u64_u32 v[28:29], s[12:13], v23, s61, v[24:25]
	global_load_dword v106, v[26:27], off
	global_load_dword v107, v[28:29], off
	v_mad_u64_u32 v[128:129], s[12:13], v21, s77, v[6:7]
	v_mad_u64_u32 v[130:131], s[12:13], v0, s77, v[6:7]
	s_add_i32 s13, s11, 16
	s_add_i32 s12, s7, 16
	v_or_b32_e32 v21, s13, v2
	v_or_b32_e32 v0, s12, v3
	v_add_u32_e32 v26, s0, v21
	v_add_u32_e32 v23, s2, v0
	v_mad_u64_u32 v[26:27], s[12:13], v26, s61, v[24:25]
	v_mad_u64_u32 v[28:29], s[12:13], v23, s61, v[24:25]
	global_load_dword v108, v[26:27], off
	global_load_dword v109, v[28:29], off
	v_mad_u64_u32 v[132:133], s[12:13], v21, s77, v[6:7]
	v_mad_u64_u32 v[134:135], s[12:13], v0, s77, v[6:7]
	s_add_i32 s13, s11, 20
	s_add_i32 s12, s7, 20
	v_or_b32_e32 v21, s13, v2
	v_or_b32_e32 v0, s12, v3
	v_add_u32_e32 v26, s0, v21
	v_add_u32_e32 v23, s2, v0
	v_mad_u64_u32 v[26:27], s[12:13], v26, s61, v[24:25]
	v_mad_u64_u32 v[28:29], s[12:13], v23, s61, v[24:25]
	global_load_dword v110, v[26:27], off
	global_load_dword v111, v[28:29], off
	v_mad_u64_u32 v[136:137], s[12:13], v21, s77, v[6:7]
	v_mad_u64_u32 v[138:139], s[12:13], v0, s77, v[6:7]
	s_add_i32 s13, s11, 24
	s_add_i32 s12, s7, 24
	v_or_b32_e32 v21, s13, v2
	v_or_b32_e32 v0, s12, v3
	s_add_i32 s11, s11, 28
	s_add_i32 s7, s7, 28
	s_cmp_lg_u32 s6, 0
	v_add_u32_e32 v26, s0, v21
	v_add_u32_e32 v23, s2, v0
	v_mad_u64_u32 v[26:27], s[12:13], v26, s61, v[24:25]
	v_mad_u64_u32 v[28:29], s[12:13], v23, s61, v[24:25]
	global_load_dword v112, v[26:27], off
	global_load_dword v113, v[28:29], off
	v_mad_u64_u32 v[140:141], s[12:13], v21, s77, v[6:7]
	v_or_b32_e32 v21, s11, v2
	v_mad_u64_u32 v[142:143], s[12:13], v0, s77, v[6:7]
	v_or_b32_e32 v0, s7, v3
	v_add_u32_e32 v26, s0, v21
	v_add_u32_e32 v23, s2, v0
	v_mad_u64_u32 v[26:27], s[12:13], v26, s61, v[24:25]
	v_mad_u64_u32 v[28:29], s[12:13], v23, s61, v[24:25]
	global_load_dword v114, v[26:27], off
	global_load_dword v115, v[28:29], off
	v_mad_u64_u32 v[144:145], s[12:13], v21, s77, v[6:7]
	v_mad_u64_u32 v[146:147], s[12:13], v0, s77, v[6:7]
	s_lshl_b32 s11, s5, 1
	s_lshl_b32 s7, s3, 1
	v_or_b32_e32 v21, s11, v2
	v_or_b32_e32 v0, s7, v3
	v_add_u32_e32 v26, s0, v21
	v_add_u32_e32 v23, s2, v0
	v_mad_u64_u32 v[26:27], s[12:13], v26, s61, v[24:25]
	v_mad_u64_u32 v[28:29], s[12:13], v23, s61, v[24:25]
	global_load_dword v148, v[26:27], off
	global_load_dword v149, v[28:29], off
	v_mad_u64_u32 v[164:165], s[12:13], v21, s77, v[6:7]
	v_mad_u64_u32 v[166:167], s[12:13], v0, s77, v[6:7]
	s_add_i32 s13, s11, 4
	s_add_i32 s12, s7, 4
	v_or_b32_e32 v21, s13, v2
	v_or_b32_e32 v0, s12, v3
	s_add_i32 s5, s5, 16
	s_add_i32 s3, s3, 16
	s_add_i32 s6, s6, -16
	v_add_u32_e32 v26, s0, v21
	v_add_u32_e32 v23, s2, v0
	v_mad_u64_u32 v[26:27], s[12:13], v26, s61, v[24:25]
	v_mad_u64_u32 v[28:29], s[12:13], v23, s61, v[24:25]
	global_load_dword v150, v[26:27], off
	global_load_dword v151, v[28:29], off
	v_mad_u64_u32 v[168:169], s[12:13], v21, s77, v[6:7]
	v_mad_u64_u32 v[170:171], s[12:13], v0, s77, v[6:7]
	s_add_i32 s13, s11, 8
	s_add_i32 s12, s7, 8
	v_or_b32_e32 v21, s13, v2
	v_or_b32_e32 v0, s12, v3
	v_add_u32_e32 v26, s0, v21
	v_add_u32_e32 v23, s2, v0
	v_mad_u64_u32 v[26:27], s[12:13], v26, s61, v[24:25]
	v_mad_u64_u32 v[28:29], s[12:13], v23, s61, v[24:25]
	global_load_dword v152, v[26:27], off
	global_load_dword v153, v[28:29], off
	v_mad_u64_u32 v[172:173], s[12:13], v21, s77, v[6:7]
	v_mad_u64_u32 v[174:175], s[12:13], v0, s77, v[6:7]
	s_add_i32 s13, s11, 12
	s_add_i32 s12, s7, 12
	v_or_b32_e32 v21, s13, v2
	v_or_b32_e32 v0, s12, v3
	v_add_u32_e32 v26, s0, v21
	v_add_u32_e32 v23, s2, v0
	v_mad_u64_u32 v[26:27], s[12:13], v26, s61, v[24:25]
	v_mad_u64_u32 v[28:29], s[12:13], v23, s61, v[24:25]
	global_load_dword v154, v[26:27], off
	global_load_dword v155, v[28:29], off
	v_mad_u64_u32 v[176:177], s[12:13], v21, s77, v[6:7]
	v_mad_u64_u32 v[178:179], s[12:13], v0, s77, v[6:7]
	s_add_i32 s13, s11, 16
	s_add_i32 s12, s7, 16
	v_or_b32_e32 v21, s13, v2
	v_or_b32_e32 v0, s12, v3
	v_add_u32_e32 v26, s0, v21
	v_add_u32_e32 v23, s2, v0
	v_mad_u64_u32 v[26:27], s[12:13], v26, s61, v[24:25]
	v_mad_u64_u32 v[28:29], s[12:13], v23, s61, v[24:25]
	global_load_dword v156, v[26:27], off
	global_load_dword v157, v[28:29], off
	v_mad_u64_u32 v[180:181], s[12:13], v21, s77, v[6:7]
	v_mad_u64_u32 v[182:183], s[12:13], v0, s77, v[6:7]
	s_add_i32 s13, s11, 20
	s_add_i32 s12, s7, 20
	v_or_b32_e32 v21, s13, v2
	v_or_b32_e32 v0, s12, v3
	v_add_u32_e32 v26, s0, v21
	v_add_u32_e32 v23, s2, v0
	v_mad_u64_u32 v[26:27], s[12:13], v26, s61, v[24:25]
	v_mad_u64_u32 v[28:29], s[12:13], v23, s61, v[24:25]
	global_load_dword v158, v[26:27], off
	global_load_dword v159, v[28:29], off
	v_mad_u64_u32 v[184:185], s[12:13], v21, s77, v[6:7]
	v_mad_u64_u32 v[186:187], s[12:13], v0, s77, v[6:7]
	s_add_i32 s13, s11, 24
	s_add_i32 s12, s7, 24
	v_or_b32_e32 v21, s13, v2
	v_or_b32_e32 v0, s12, v3
	s_add_i32 s11, s11, 28
	s_add_i32 s7, s7, 28
	s_cmp_lg_u32 s6, 0
	v_add_u32_e32 v26, s0, v21
	v_add_u32_e32 v23, s2, v0
	v_mad_u64_u32 v[26:27], s[12:13], v26, s61, v[24:25]
	v_mad_u64_u32 v[28:29], s[12:13], v23, s61, v[24:25]
	global_load_dword v160, v[26:27], off
	global_load_dword v161, v[28:29], off
	v_mad_u64_u32 v[188:189], s[12:13], v21, s77, v[6:7]
	v_or_b32_e32 v21, s11, v2
	v_mad_u64_u32 v[190:191], s[12:13], v0, s77, v[6:7]
	v_or_b32_e32 v0, s7, v3
	v_add_u32_e32 v26, s0, v21
	v_add_u32_e32 v23, s2, v0
	v_mad_u64_u32 v[26:27], s[12:13], v26, s61, v[24:25]
	v_mad_u64_u32 v[28:29], s[12:13], v23, s61, v[24:25]
	global_load_dword v162, v[26:27], off
	global_load_dword v163, v[28:29], off
	v_mad_u64_u32 v[192:193], s[12:13], v21, s77, v[6:7]
	v_mad_u64_u32 v[196:197], s[12:13], v0, s77, v[6:7]
	s_waitcnt vmcnt(0)
	ds_write_b32 v116, v100
	ds_write_b32 v118, v101
	ds_write_b32 v120, v102
	ds_write_b32 v122, v103
	ds_write_b32 v124, v104
	ds_write_b32 v126, v105
	ds_write_b32 v128, v106
	ds_write_b32 v130, v107
	ds_write_b32 v132, v108
	ds_write_b32 v134, v109
	ds_write_b32 v136, v110
	ds_write_b32 v138, v111
	ds_write_b32 v140, v112
	ds_write_b32 v142, v113
	ds_write_b32 v144, v114
	ds_write_b32 v146, v115
	ds_write_b32 v164, v148
	ds_write_b32 v166, v149
	ds_write_b32 v168, v150
	ds_write_b32 v170, v151
	ds_write_b32 v172, v152
	ds_write_b32 v174, v153
	ds_write_b32 v176, v154
	ds_write_b32 v178, v155
	ds_write_b32 v180, v156
	ds_write_b32 v182, v157
	ds_write_b32 v184, v158
	ds_write_b32 v186, v159
	ds_write_b32 v188, v160
	ds_write_b32 v190, v161
	ds_write_b32 v192, v162
	ds_write_b32 v196, v163
	s_cbranch_scc1 .LBB0_92
	s_mulk_i32 s1, 0x6000
	s_add_u32 s1, s50, s1
	s_addc_u32 s2, s51, 0
	s_lshl_b32 s0, s0, 1
	s_add_u32 s0, s1, s0
	s_addc_u32 s1, s2, 0
	v_mov_b32_e32 v0, v45
	v_mov_b32_e32 v24, v44
	v_mov_b32_e32 v26, v43
	v_mov_b32_e32 v28, v42

.LBB0_97:
	s_lshl_b32 s11, s5, 1
	s_lshl_b32 s7, s2, 1
	v_or_b32_e32 v23, s11, v2
	v_or_b32_e32 v21, s7, v3
	v_add_u32_e32 v0, s1, v23
	v_add_u32_e32 v26, s3, v21
	v_mov_b32_e32 v27, v1
	v_lshlrev_b64 v[28:29], 14, v[0:1]
	v_lshlrev_b64 v[26:27], 14, v[26:27]
	v_lshl_add_u64 v[28:29], v[24:25], 0, v[28:29]
	v_lshl_add_u64 v[26:27], v[24:25], 0, v[26:27]
	global_load_dword v100, v[28:29], off
	global_load_dword v101, v[26:27], off
	v_mad_u64_u32 v[116:117], s[12:13], v23, s77, v[6:7]
	v_mad_u64_u32 v[118:119], s[12:13], v21, s77, v[6:7]
	s_add_i32 s13, s11, 4
	s_add_i32 s12, s7, 4
	v_or_b32_e32 v23, s13, v2
	v_or_b32_e32 v21, s12, v3
	v_mov_b32_e32 v27, v1
	s_add_i32 s5, s5, 16
	s_add_i32 s2, s2, 16
	s_add_i32 s6, s6, -16
	v_add_u32_e32 v0, s1, v23
	v_add_u32_e32 v26, s3, v21
	v_lshlrev_b64 v[28:29], 14, v[0:1]
	v_lshlrev_b64 v[26:27], 14, v[26:27]
	v_lshl_add_u64 v[28:29], v[24:25], 0, v[28:29]
	v_lshl_add_u64 v[26:27], v[24:25], 0, v[26:27]
	global_load_dword v102, v[28:29], off
	global_load_dword v103, v[26:27], off
	v_mad_u64_u32 v[120:121], s[12:13], v23, s77, v[6:7]
	v_mad_u64_u32 v[122:123], s[12:13], v21, s77, v[6:7]
	s_add_i32 s13, s11, 8
	s_add_i32 s12, s7, 8
	v_or_b32_e32 v23, s13, v2
	v_or_b32_e32 v21, s12, v3
	v_mov_b32_e32 v27, v1
	v_add_u32_e32 v0, s1, v23
	v_add_u32_e32 v26, s3, v21
	v_lshlrev_b64 v[28:29], 14, v[0:1]
	v_lshlrev_b64 v[26:27], 14, v[26:27]
	v_lshl_add_u64 v[28:29], v[24:25], 0, v[28:29]
	v_lshl_add_u64 v[26:27], v[24:25], 0, v[26:27]
	global_load_dword v104, v[28:29], off
	global_load_dword v105, v[26:27], off
	v_mad_u64_u32 v[124:125], s[12:13], v23, s77, v[6:7]
	v_mad_u64_u32 v[126:127], s[12:13], v21, s77, v[6:7]
	s_add_i32 s13, s11, 12
	s_add_i32 s12, s7, 12
	v_or_b32_e32 v23, s13, v2
	v_or_b32_e32 v21, s12, v3
	v_mov_b32_e32 v27, v1
	v_add_u32_e32 v0, s1, v23
	v_add_u32_e32 v26, s3, v21
	v_lshlrev_b64 v[28:29], 14, v[0:1]
	v_lshlrev_b64 v[26:27], 14, v[26:27]
	v_lshl_add_u64 v[28:29], v[24:25], 0, v[28:29]
	v_lshl_add_u64 v[26:27], v[24:25], 0, v[26:27]
	global_load_dword v106, v[28:29], off
	global_load_dword v107, v[26:27], off
	v_mad_u64_u32 v[128:129], s[12:13], v23, s77, v[6:7]
	v_mad_u64_u32 v[130:131], s[12:13], v21, s77, v[6:7]
	s_add_i32 s13, s11, 16
	s_add_i32 s12, s7, 16
	v_or_b32_e32 v23, s13, v2
	v_or_b32_e32 v21, s12, v3
	v_mov_b32_e32 v27, v1
	v_add_u32_e32 v0, s1, v23
	v_add_u32_e32 v26, s3, v21
	v_lshlrev_b64 v[28:29], 14, v[0:1]
	v_lshlrev_b64 v[26:27], 14, v[26:27]
	v_lshl_add_u64 v[28:29], v[24:25], 0, v[28:29]
	v_lshl_add_u64 v[26:27], v[24:25], 0, v[26:27]
	global_load_dword v108, v[28:29], off
	global_load_dword v109, v[26:27], off
	v_mad_u64_u32 v[132:133], s[12:13], v23, s77, v[6:7]
	v_mad_u64_u32 v[134:135], s[12:13], v21, s77, v[6:7]
	s_add_i32 s13, s11, 20
	s_add_i32 s12, s7, 20
	v_or_b32_e32 v23, s13, v2
	v_or_b32_e32 v21, s12, v3
	v_mov_b32_e32 v27, v1
	v_add_u32_e32 v0, s1, v23
	v_add_u32_e32 v26, s3, v21
	v_lshlrev_b64 v[28:29], 14, v[0:1]
	v_lshlrev_b64 v[26:27], 14, v[26:27]
	v_lshl_add_u64 v[28:29], v[24:25], 0, v[28:29]
	v_lshl_add_u64 v[26:27], v[24:25], 0, v[26:27]
	global_load_dword v110, v[28:29], off
	global_load_dword v111, v[26:27], off
	v_mad_u64_u32 v[136:137], s[12:13], v23, s77, v[6:7]
	v_mad_u64_u32 v[138:139], s[12:13], v21, s77, v[6:7]
	s_add_i32 s13, s11, 24
	s_add_i32 s12, s7, 24
	v_or_b32_e32 v23, s13, v2
	v_or_b32_e32 v21, s12, v3
	v_mov_b32_e32 v27, v1
	s_add_i32 s11, s11, 28
	s_add_i32 s7, s7, 28
	s_cmp_lg_u32 s6, 0
	v_add_u32_e32 v0, s1, v23
	v_add_u32_e32 v26, s3, v21
	v_lshlrev_b64 v[28:29], 14, v[0:1]
	v_lshlrev_b64 v[26:27], 14, v[26:27]
	v_lshl_add_u64 v[28:29], v[24:25], 0, v[28:29]
	v_lshl_add_u64 v[26:27], v[24:25], 0, v[26:27]
	global_load_dword v112, v[28:29], off
	global_load_dword v113, v[26:27], off
	v_mad_u64_u32 v[140:141], s[12:13], v23, s77, v[6:7]
	v_or_b32_e32 v23, s11, v2
	v_mad_u64_u32 v[142:143], s[12:13], v21, s77, v[6:7]
	v_or_b32_e32 v21, s7, v3
	v_mov_b32_e32 v27, v1
	v_add_u32_e32 v0, s1, v23
	v_add_u32_e32 v26, s3, v21
	v_lshlrev_b64 v[28:29], 14, v[0:1]
	v_lshlrev_b64 v[26:27], 14, v[26:27]
	v_lshl_add_u64 v[28:29], v[24:25], 0, v[28:29]
	v_lshl_add_u64 v[26:27], v[24:25], 0, v[26:27]
	global_load_dword v114, v[28:29], off
	global_load_dword v115, v[26:27], off
	v_mad_u64_u32 v[144:145], s[12:13], v23, s77, v[6:7]
	v_mad_u64_u32 v[146:147], s[12:13], v21, s77, v[6:7]
	s_lshl_b32 s11, s5, 1
	s_lshl_b32 s7, s2, 1
	v_or_b32_e32 v23, s11, v2
	v_or_b32_e32 v21, s7, v3
	v_add_u32_e32 v0, s1, v23
	v_add_u32_e32 v26, s3, v21
	v_mov_b32_e32 v27, v1
	v_lshlrev_b64 v[28:29], 14, v[0:1]
	v_lshlrev_b64 v[26:27], 14, v[26:27]
	v_lshl_add_u64 v[28:29], v[24:25], 0, v[28:29]
	v_lshl_add_u64 v[26:27], v[24:25], 0, v[26:27]
	global_load_dword v148, v[28:29], off
	global_load_dword v149, v[26:27], off
	v_mad_u64_u32 v[164:165], s[12:13], v23, s77, v[6:7]
	v_mad_u64_u32 v[166:167], s[12:13], v21, s77, v[6:7]
	s_add_i32 s13, s11, 4
	s_add_i32 s12, s7, 4
	v_or_b32_e32 v23, s13, v2
	v_or_b32_e32 v21, s12, v3
	v_mov_b32_e32 v27, v1
	s_add_i32 s5, s5, 16
	s_add_i32 s2, s2, 16
	s_add_i32 s6, s6, -16
	v_add_u32_e32 v0, s1, v23
	v_add_u32_e32 v26, s3, v21
	v_lshlrev_b64 v[28:29], 14, v[0:1]
	v_lshlrev_b64 v[26:27], 14, v[26:27]
	v_lshl_add_u64 v[28:29], v[24:25], 0, v[28:29]
	v_lshl_add_u64 v[26:27], v[24:25], 0, v[26:27]
	global_load_dword v150, v[28:29], off
	global_load_dword v151, v[26:27], off
	v_mad_u64_u32 v[168:169], s[12:13], v23, s77, v[6:7]
	v_mad_u64_u32 v[170:171], s[12:13], v21, s77, v[6:7]
	s_add_i32 s13, s11, 8
	s_add_i32 s12, s7, 8
	v_or_b32_e32 v23, s13, v2
	v_or_b32_e32 v21, s12, v3
	v_mov_b32_e32 v27, v1
	v_add_u32_e32 v0, s1, v23
	v_add_u32_e32 v26, s3, v21
	v_lshlrev_b64 v[28:29], 14, v[0:1]
	v_lshlrev_b64 v[26:27], 14, v[26:27]
	v_lshl_add_u64 v[28:29], v[24:25], 0, v[28:29]
	v_lshl_add_u64 v[26:27], v[24:25], 0, v[26:27]
	global_load_dword v152, v[28:29], off
	global_load_dword v153, v[26:27], off
	v_mad_u64_u32 v[172:173], s[12:13], v23, s77, v[6:7]
	v_mad_u64_u32 v[174:175], s[12:13], v21, s77, v[6:7]
	s_add_i32 s13, s11, 12
	s_add_i32 s12, s7, 12
	v_or_b32_e32 v23, s13, v2
	v_or_b32_e32 v21, s12, v3
	v_mov_b32_e32 v27, v1
	v_add_u32_e32 v0, s1, v23
	v_add_u32_e32 v26, s3, v21
	v_lshlrev_b64 v[28:29], 14, v[0:1]
	v_lshlrev_b64 v[26:27], 14, v[26:27]
	v_lshl_add_u64 v[28:29], v[24:25], 0, v[28:29]
	v_lshl_add_u64 v[26:27], v[24:25], 0, v[26:27]
	global_load_dword v154, v[28:29], off
	global_load_dword v155, v[26:27], off
	v_mad_u64_u32 v[176:177], s[12:13], v23, s77, v[6:7]
	v_mad_u64_u32 v[178:179], s[12:13], v21, s77, v[6:7]
	s_add_i32 s13, s11, 16
	s_add_i32 s12, s7, 16
	v_or_b32_e32 v23, s13, v2
	v_or_b32_e32 v21, s12, v3
	v_mov_b32_e32 v27, v1
	v_add_u32_e32 v0, s1, v23
	v_add_u32_e32 v26, s3, v21
	v_lshlrev_b64 v[28:29], 14, v[0:1]
	v_lshlrev_b64 v[26:27], 14, v[26:27]
	v_lshl_add_u64 v[28:29], v[24:25], 0, v[28:29]
	v_lshl_add_u64 v[26:27], v[24:25], 0, v[26:27]
	global_load_dword v156, v[28:29], off
	global_load_dword v157, v[26:27], off
	v_mad_u64_u32 v[180:181], s[12:13], v23, s77, v[6:7]
	v_mad_u64_u32 v[182:183], s[12:13], v21, s77, v[6:7]
	s_add_i32 s13, s11, 20
	s_add_i32 s12, s7, 20
	v_or_b32_e32 v23, s13, v2
	v_or_b32_e32 v21, s12, v3
	v_mov_b32_e32 v27, v1
	v_add_u32_e32 v0, s1, v23
	v_add_u32_e32 v26, s3, v21
	v_lshlrev_b64 v[28:29], 14, v[0:1]
	v_lshlrev_b64 v[26:27], 14, v[26:27]
	v_lshl_add_u64 v[28:29], v[24:25], 0, v[28:29]
	v_lshl_add_u64 v[26:27], v[24:25], 0, v[26:27]
	global_load_dword v158, v[28:29], off
	global_load_dword v159, v[26:27], off
	v_mad_u64_u32 v[184:185], s[12:13], v23, s77, v[6:7]
	v_mad_u64_u32 v[186:187], s[12:13], v21, s77, v[6:7]
	s_add_i32 s13, s11, 24
	s_add_i32 s12, s7, 24
	v_or_b32_e32 v23, s13, v2
	v_or_b32_e32 v21, s12, v3
	v_mov_b32_e32 v27, v1
	s_add_i32 s11, s11, 28
	s_add_i32 s7, s7, 28
	s_cmp_lg_u32 s6, 0
	v_add_u32_e32 v0, s1, v23
	v_add_u32_e32 v26, s3, v21
	v_lshlrev_b64 v[28:29], 14, v[0:1]
	v_lshlrev_b64 v[26:27], 14, v[26:27]
	v_lshl_add_u64 v[28:29], v[24:25], 0, v[28:29]
	v_lshl_add_u64 v[26:27], v[24:25], 0, v[26:27]
	global_load_dword v160, v[28:29], off
	global_load_dword v161, v[26:27], off
	v_mad_u64_u32 v[188:189], s[12:13], v23, s77, v[6:7]
	v_or_b32_e32 v23, s11, v2
	v_mad_u64_u32 v[190:191], s[12:13], v21, s77, v[6:7]
	v_or_b32_e32 v21, s7, v3
	v_mov_b32_e32 v27, v1
	v_add_u32_e32 v0, s1, v23
	v_add_u32_e32 v26, s3, v21
	v_lshlrev_b64 v[28:29], 14, v[0:1]
	v_lshlrev_b64 v[26:27], 14, v[26:27]
	v_lshl_add_u64 v[28:29], v[24:25], 0, v[28:29]
	v_lshl_add_u64 v[26:27], v[24:25], 0, v[26:27]
	global_load_dword v162, v[28:29], off
	global_load_dword v163, v[26:27], off
	v_mad_u64_u32 v[192:193], s[12:13], v23, s77, v[6:7]
	v_mad_u64_u32 v[196:197], s[12:13], v21, s77, v[6:7]
	s_waitcnt vmcnt(0)
	ds_write_b32 v116, v100
	ds_write_b32 v118, v101
	ds_write_b32 v120, v102
	ds_write_b32 v122, v103
	ds_write_b32 v124, v104
	ds_write_b32 v126, v105
	ds_write_b32 v128, v106
	ds_write_b32 v130, v107
	ds_write_b32 v132, v108
	ds_write_b32 v134, v109
	ds_write_b32 v136, v110
	ds_write_b32 v138, v111
	ds_write_b32 v140, v112
	ds_write_b32 v142, v113
	ds_write_b32 v144, v114
	ds_write_b32 v146, v115
	ds_write_b32 v164, v148
	ds_write_b32 v166, v149
	ds_write_b32 v168, v150
	ds_write_b32 v170, v151
	ds_write_b32 v172, v152
	ds_write_b32 v174, v153
	ds_write_b32 v176, v154
	ds_write_b32 v178, v155
	ds_write_b32 v180, v156
	ds_write_b32 v182, v157
	ds_write_b32 v184, v158
	ds_write_b32 v186, v159
	ds_write_b32 v188, v160
	ds_write_b32 v190, v161
	ds_write_b32 v192, v162
	ds_write_b32 v196, v163
	s_cbranch_scc1 .LBB0_97
	v_readlane_b32 s12, v249, 0
	s_lshl_b32 s0, s0, 11
	v_readlane_b32 s18, v249, 6
	v_readlane_b32 s19, v249, 7
	s_add_u32 s0, s18, s0
	s_addc_u32 s2, s19, 0
	s_lshl_b32 s1, s1, 1
	s_add_u32 s0, s0, s1
	s_addc_u32 s1, s2, 0
	s_add_u32 s0, s0, 0x680000
	s_addc_u32 s1, s1, 0
	v_mov_b32_e32 v0, v33
	v_mov_b32_e32 v24, v32
	v_mov_b32_e32 v26, v31
	v_mov_b32_e32 v28, v30
	v_readlane_b32 s13, v249, 1
	v_readlane_b32 s14, v249, 2
	v_readlane_b32 s15, v249, 3
	v_readlane_b32 s16, v249, 4
	v_readlane_b32 s17, v249, 5

.LBB0_102:
	s_lshl_b32 s12, s3, 1
	s_lshl_b32 s11, s2, 1
	v_or_b32_e32 v21, s12, v2
	v_or_b32_e32 v0, s11, v3
	v_add_u32_e32 v26, s0, v21
	v_add_u32_e32 v23, s1, v0
	v_mad_i64_i32 v[26:27], s[14:15], v26, s62, v[24:25]
	v_mad_i64_i32 v[28:29], s[14:15], v23, s62, v[24:25]
	global_load_dword v100, v[26:27], off
	global_load_dword v101, v[28:29], off
	v_mad_u64_u32 v[116:117], s[14:15], v21, s77, v[6:7]
	v_mad_u64_u32 v[118:119], s[14:15], v0, s77, v[6:7]
	s_add_i32 s14, s12, 4
	s_add_i32 s13, s11, 4
	v_or_b32_e32 v21, s14, v2
	v_or_b32_e32 v0, s13, v3
	s_add_i32 s13, s11, 8
	s_add_i32 s3, s3, 16
	s_add_i32 s2, s2, 16
	s_add_i32 s5, s5, -16
	v_add_u32_e32 v26, s0, v21
	v_add_u32_e32 v23, s1, v0
	v_mad_i64_i32 v[26:27], s[14:15], v26, s62, v[24:25]
	v_mad_i64_i32 v[28:29], s[14:15], v23, s62, v[24:25]
	global_load_dword v102, v[26:27], off
	global_load_dword v103, v[28:29], off
	v_mad_u64_u32 v[120:121], s[14:15], v21, s77, v[6:7]
	v_mad_u64_u32 v[122:123], s[14:15], v0, s77, v[6:7]
	s_add_i32 s14, s12, 8
	s_nop 0
	v_or_b32_e32 v21, s14, v2
	v_or_b32_e32 v0, s13, v3
	s_add_i32 s13, s11, 12
	v_add_u32_e32 v26, s0, v21
	v_add_u32_e32 v23, s1, v0
	v_mad_i64_i32 v[26:27], s[14:15], v26, s62, v[24:25]
	v_mad_i64_i32 v[28:29], s[14:15], v23, s62, v[24:25]
	global_load_dword v104, v[26:27], off
	global_load_dword v105, v[28:29], off
	v_mad_u64_u32 v[124:125], s[14:15], v21, s77, v[6:7]
	v_mad_u64_u32 v[126:127], s[14:15], v0, s77, v[6:7]
	s_add_i32 s14, s12, 12
	s_nop 0
	v_or_b32_e32 v21, s14, v2
	v_or_b32_e32 v0, s13, v3
	s_add_i32 s13, s11, 16
	v_add_u32_e32 v26, s0, v21
	v_add_u32_e32 v23, s1, v0
	v_mad_i64_i32 v[26:27], s[14:15], v26, s62, v[24:25]
	v_mad_i64_i32 v[28:29], s[14:15], v23, s62, v[24:25]
	global_load_dword v106, v[26:27], off
	global_load_dword v107, v[28:29], off
	v_mad_u64_u32 v[128:129], s[14:15], v21, s77, v[6:7]
	v_mad_u64_u32 v[130:131], s[14:15], v0, s77, v[6:7]
	s_add_i32 s14, s12, 16
	s_nop 0
	v_or_b32_e32 v21, s14, v2
	v_or_b32_e32 v0, s13, v3
	s_add_i32 s13, s11, 20
	v_add_u32_e32 v26, s0, v21
	v_add_u32_e32 v23, s1, v0
	v_mad_i64_i32 v[26:27], s[14:15], v26, s62, v[24:25]
	v_mad_i64_i32 v[28:29], s[14:15], v23, s62, v[24:25]
	global_load_dword v108, v[26:27], off
	global_load_dword v109, v[28:29], off
	v_mad_u64_u32 v[132:133], s[14:15], v21, s77, v[6:7]
	v_mad_u64_u32 v[134:135], s[14:15], v0, s77, v[6:7]
	s_add_i32 s14, s12, 20
	s_nop 0
	v_or_b32_e32 v21, s14, v2
	v_or_b32_e32 v0, s13, v3
	s_add_i32 s13, s11, 24
	s_add_i32 s11, s11, 28
	v_add_u32_e32 v26, s0, v21
	v_add_u32_e32 v23, s1, v0
	v_mad_i64_i32 v[26:27], s[14:15], v26, s62, v[24:25]
	v_mad_i64_i32 v[28:29], s[14:15], v23, s62, v[24:25]
	global_load_dword v110, v[26:27], off
	global_load_dword v111, v[28:29], off
	v_mad_u64_u32 v[136:137], s[14:15], v21, s77, v[6:7]
	v_mad_u64_u32 v[138:139], s[14:15], v0, s77, v[6:7]
	s_add_i32 s14, s12, 24
	s_nop 0
	v_or_b32_e32 v21, s14, v2
	v_or_b32_e32 v0, s13, v3
	s_add_i32 s12, s12, 28
	s_cmp_lg_u32 s5, 0
	v_add_u32_e32 v26, s0, v21
	v_add_u32_e32 v23, s1, v0
	v_mad_i64_i32 v[26:27], s[14:15], v26, s62, v[24:25]
	v_mad_i64_i32 v[28:29], s[14:15], v23, s62, v[24:25]
	global_load_dword v112, v[26:27], off
	global_load_dword v113, v[28:29], off
	v_mad_u64_u32 v[140:141], s[14:15], v21, s77, v[6:7]
	v_or_b32_e32 v21, s12, v2
	v_mad_u64_u32 v[142:143], s[14:15], v0, s77, v[6:7]
	v_or_b32_e32 v0, s11, v3
	v_add_u32_e32 v26, s0, v21
	v_add_u32_e32 v23, s1, v0
	v_mad_i64_i32 v[26:27], s[12:13], v26, s62, v[24:25]
	v_mad_i64_i32 v[28:29], s[12:13], v23, s62, v[24:25]
	global_load_dword v114, v[26:27], off
	global_load_dword v115, v[28:29], off
	v_mad_u64_u32 v[144:145], s[12:13], v21, s77, v[6:7]
	v_mad_u64_u32 v[146:147], s[12:13], v0, s77, v[6:7]
	s_lshl_b32 s12, s3, 1
	s_lshl_b32 s11, s2, 1
	v_or_b32_e32 v21, s12, v2
	v_or_b32_e32 v0, s11, v3
	v_add_u32_e32 v26, s0, v21
	v_add_u32_e32 v23, s1, v0
	v_mad_i64_i32 v[26:27], s[14:15], v26, s62, v[24:25]
	v_mad_i64_i32 v[28:29], s[14:15], v23, s62, v[24:25]
	global_load_dword v148, v[26:27], off
	global_load_dword v149, v[28:29], off
	v_mad_u64_u32 v[164:165], s[14:15], v21, s77, v[6:7]
	v_mad_u64_u32 v[166:167], s[14:15], v0, s77, v[6:7]
	s_add_i32 s14, s12, 4
	s_add_i32 s13, s11, 4
	v_or_b32_e32 v21, s14, v2
	v_or_b32_e32 v0, s13, v3
	s_add_i32 s13, s11, 8
	s_add_i32 s3, s3, 16
	s_add_i32 s2, s2, 16
	s_add_i32 s5, s5, -16
	v_add_u32_e32 v26, s0, v21
	v_add_u32_e32 v23, s1, v0
	v_mad_i64_i32 v[26:27], s[14:15], v26, s62, v[24:25]
	v_mad_i64_i32 v[28:29], s[14:15], v23, s62, v[24:25]
	global_load_dword v150, v[26:27], off
	global_load_dword v151, v[28:29], off
	v_mad_u64_u32 v[168:169], s[14:15], v21, s77, v[6:7]
	v_mad_u64_u32 v[170:171], s[14:15], v0, s77, v[6:7]
	s_add_i32 s14, s12, 8
	s_nop 0
	v_or_b32_e32 v21, s14, v2
	v_or_b32_e32 v0, s13, v3
	s_add_i32 s13, s11, 12
	v_add_u32_e32 v26, s0, v21
	v_add_u32_e32 v23, s1, v0
	v_mad_i64_i32 v[26:27], s[14:15], v26, s62, v[24:25]
	v_mad_i64_i32 v[28:29], s[14:15], v23, s62, v[24:25]
	global_load_dword v152, v[26:27], off
	global_load_dword v153, v[28:29], off
	v_mad_u64_u32 v[172:173], s[14:15], v21, s77, v[6:7]
	v_mad_u64_u32 v[174:175], s[14:15], v0, s77, v[6:7]
	s_add_i32 s14, s12, 12
	s_nop 0
	v_or_b32_e32 v21, s14, v2
	v_or_b32_e32 v0, s13, v3
	s_add_i32 s13, s11, 16
	v_add_u32_e32 v26, s0, v21
	v_add_u32_e32 v23, s1, v0
	v_mad_i64_i32 v[26:27], s[14:15], v26, s62, v[24:25]
	v_mad_i64_i32 v[28:29], s[14:15], v23, s62, v[24:25]
	global_load_dword v154, v[26:27], off
	global_load_dword v155, v[28:29], off
	v_mad_u64_u32 v[176:177], s[14:15], v21, s77, v[6:7]
	v_mad_u64_u32 v[178:179], s[14:15], v0, s77, v[6:7]
	s_add_i32 s14, s12, 16
	s_nop 0
	v_or_b32_e32 v21, s14, v2
	v_or_b32_e32 v0, s13, v3
	s_add_i32 s13, s11, 20
	v_add_u32_e32 v26, s0, v21
	v_add_u32_e32 v23, s1, v0
	v_mad_i64_i32 v[26:27], s[14:15], v26, s62, v[24:25]
	v_mad_i64_i32 v[28:29], s[14:15], v23, s62, v[24:25]
	global_load_dword v156, v[26:27], off
	global_load_dword v157, v[28:29], off
	v_mad_u64_u32 v[180:181], s[14:15], v21, s77, v[6:7]
	v_mad_u64_u32 v[182:183], s[14:15], v0, s77, v[6:7]
	s_add_i32 s14, s12, 20
	s_nop 0
	v_or_b32_e32 v21, s14, v2
	v_or_b32_e32 v0, s13, v3
	s_add_i32 s13, s11, 24
	s_add_i32 s11, s11, 28
	v_add_u32_e32 v26, s0, v21
	v_add_u32_e32 v23, s1, v0
	v_mad_i64_i32 v[26:27], s[14:15], v26, s62, v[24:25]
	v_mad_i64_i32 v[28:29], s[14:15], v23, s62, v[24:25]
	global_load_dword v158, v[26:27], off
	global_load_dword v159, v[28:29], off
	v_mad_u64_u32 v[184:185], s[14:15], v21, s77, v[6:7]
	v_mad_u64_u32 v[186:187], s[14:15], v0, s77, v[6:7]
	s_add_i32 s14, s12, 24
	s_nop 0
	v_or_b32_e32 v21, s14, v2
	v_or_b32_e32 v0, s13, v3
	s_add_i32 s12, s12, 28
	s_cmp_lg_u32 s5, 0
	v_add_u32_e32 v26, s0, v21
	v_add_u32_e32 v23, s1, v0
	v_mad_i64_i32 v[26:27], s[14:15], v26, s62, v[24:25]
	v_mad_i64_i32 v[28:29], s[14:15], v23, s62, v[24:25]
	global_load_dword v160, v[26:27], off
	global_load_dword v161, v[28:29], off
	v_mad_u64_u32 v[188:189], s[14:15], v21, s77, v[6:7]
	v_or_b32_e32 v21, s12, v2
	v_mad_u64_u32 v[190:191], s[14:15], v0, s77, v[6:7]
	v_or_b32_e32 v0, s11, v3
	v_add_u32_e32 v26, s0, v21
	v_add_u32_e32 v23, s1, v0
	v_mad_i64_i32 v[26:27], s[12:13], v26, s62, v[24:25]
	v_mad_i64_i32 v[28:29], s[12:13], v23, s62, v[24:25]
	global_load_dword v162, v[26:27], off
	global_load_dword v163, v[28:29], off
	v_mad_u64_u32 v[192:193], s[12:13], v21, s77, v[6:7]
	v_mad_u64_u32 v[196:197], s[12:13], v0, s77, v[6:7]
	s_waitcnt vmcnt(0)
	ds_write_b32 v116, v100
	ds_write_b32 v118, v101
	ds_write_b32 v120, v102
	ds_write_b32 v122, v103
	ds_write_b32 v124, v104
	ds_write_b32 v126, v105
	ds_write_b32 v128, v106
	ds_write_b32 v130, v107
	ds_write_b32 v132, v108
	ds_write_b32 v134, v109
	ds_write_b32 v136, v110
	ds_write_b32 v138, v111
	ds_write_b32 v140, v112
	ds_write_b32 v142, v113
	ds_write_b32 v144, v114
	ds_write_b32 v146, v115
	ds_write_b32 v164, v148
	ds_write_b32 v166, v149
	ds_write_b32 v168, v150
	ds_write_b32 v170, v151
	ds_write_b32 v172, v152
	ds_write_b32 v174, v153
	ds_write_b32 v176, v154
	ds_write_b32 v178, v155
	ds_write_b32 v180, v156
	ds_write_b32 v182, v157
	ds_write_b32 v184, v158
	ds_write_b32 v186, v159
	ds_write_b32 v188, v160
	ds_write_b32 v190, v161
	ds_write_b32 v192, v162
	ds_write_b32 v196, v163
	s_cbranch_scc1 .LBB0_102
	v_readlane_b32 s12, v249, 0
	s_lshl_b64 s[2:3], s[6:7], 11
	v_readlane_b32 s18, v249, 6
	v_readlane_b32 s19, v249, 7
	s_add_u32 s2, s18, s2
	s_addc_u32 s3, s19, s3
	s_ashr_i32 s1, s0, 31
	s_lshl_b64 s[0:1], s[0:1], 1
	s_add_u32 s0, s2, s0
	s_addc_u32 s1, s3, s1
	v_mov_b32_e32 v0, v33
	v_mov_b32_e32 v24, v32
	v_mov_b32_e32 v26, v31
	v_mov_b32_e32 v28, v30
	v_readlane_b32 s13, v249, 1
	v_readlane_b32 s14, v249, 2
	v_readlane_b32 s15, v249, 3
	v_readlane_b32 s16, v249, 4
	v_readlane_b32 s17, v249, 5
	s_branch .LBB0_51

.LBB0_154:
	s_lshl_b32 s13, s7, 1
	s_lshl_b32 s12, s5, 1
	v_or_b32_e32 v19, s13, v2
	v_or_b32_e32 v17, s12, v3
	v_add_u32_e32 v0, s3, v19
	v_add_u32_e32 v22, s6, v17
	v_mov_b32_e32 v23, v1
	v_lshlrev_b64 v[24:25], 12, v[0:1]
	v_lshlrev_b64 v[22:23], 12, v[22:23]
	v_lshl_add_u64 v[24:25], v[20:21], 0, v[24:25]
	v_lshl_add_u64 v[22:23], v[20:21], 0, v[22:23]
	global_load_dword v100, v[24:25], off
	global_load_dword v101, v[22:23], off
	v_mad_u64_u32 v[116:117], s[14:15], v19, s77, v[4:5]
	v_mad_u64_u32 v[118:119], s[14:15], v17, s77, v[4:5]
	s_add_i32 s15, s13, 4
	s_add_i32 s14, s12, 4
	v_or_b32_e32 v19, s15, v2
	v_or_b32_e32 v17, s14, v3
	v_mov_b32_e32 v23, v1
	s_add_i32 s7, s7, 16
	s_add_i32 s5, s5, 16
	s_add_i32 s11, s11, -16
	v_add_u32_e32 v0, s3, v19
	v_add_u32_e32 v22, s6, v17
	v_lshlrev_b64 v[24:25], 12, v[0:1]
	v_lshlrev_b64 v[22:23], 12, v[22:23]
	v_lshl_add_u64 v[24:25], v[20:21], 0, v[24:25]
	v_lshl_add_u64 v[22:23], v[20:21], 0, v[22:23]
	global_load_dword v102, v[24:25], off
	global_load_dword v103, v[22:23], off
	v_mad_u64_u32 v[120:121], s[14:15], v19, s77, v[4:5]
	v_mad_u64_u32 v[122:123], s[14:15], v17, s77, v[4:5]
	s_add_i32 s15, s13, 8
	s_add_i32 s14, s12, 8
	v_or_b32_e32 v19, s15, v2
	v_or_b32_e32 v17, s14, v3
	v_mov_b32_e32 v23, v1
	v_add_u32_e32 v0, s3, v19
	v_add_u32_e32 v22, s6, v17
	v_lshlrev_b64 v[24:25], 12, v[0:1]
	v_lshlrev_b64 v[22:23], 12, v[22:23]
	v_lshl_add_u64 v[24:25], v[20:21], 0, v[24:25]
	v_lshl_add_u64 v[22:23], v[20:21], 0, v[22:23]
	global_load_dword v104, v[24:25], off
	global_load_dword v105, v[22:23], off
	v_mad_u64_u32 v[124:125], s[14:15], v19, s77, v[4:5]
	v_mad_u64_u32 v[126:127], s[14:15], v17, s77, v[4:5]
	s_add_i32 s15, s13, 12
	s_add_i32 s14, s12, 12
	v_or_b32_e32 v19, s15, v2
	v_or_b32_e32 v17, s14, v3
	v_mov_b32_e32 v23, v1
	v_add_u32_e32 v0, s3, v19
	v_add_u32_e32 v22, s6, v17
	v_lshlrev_b64 v[24:25], 12, v[0:1]
	v_lshlrev_b64 v[22:23], 12, v[22:23]
	v_lshl_add_u64 v[24:25], v[20:21], 0, v[24:25]
	v_lshl_add_u64 v[22:23], v[20:21], 0, v[22:23]
	global_load_dword v106, v[24:25], off
	global_load_dword v107, v[22:23], off
	v_mad_u64_u32 v[128:129], s[14:15], v19, s77, v[4:5]
	v_mad_u64_u32 v[130:131], s[14:15], v17, s77, v[4:5]
	s_add_i32 s15, s13, 16
	s_add_i32 s14, s12, 16
	v_or_b32_e32 v19, s15, v2
	v_or_b32_e32 v17, s14, v3
	v_mov_b32_e32 v23, v1
	v_add_u32_e32 v0, s3, v19
	v_add_u32_e32 v22, s6, v17
	v_lshlrev_b64 v[24:25], 12, v[0:1]
	v_lshlrev_b64 v[22:23], 12, v[22:23]
	v_lshl_add_u64 v[24:25], v[20:21], 0, v[24:25]
	v_lshl_add_u64 v[22:23], v[20:21], 0, v[22:23]
	global_load_dword v108, v[24:25], off
	global_load_dword v109, v[22:23], off
	v_mad_u64_u32 v[132:133], s[14:15], v19, s77, v[4:5]
	v_mad_u64_u32 v[134:135], s[14:15], v17, s77, v[4:5]
	s_add_i32 s15, s13, 20
	s_add_i32 s14, s12, 20
	v_or_b32_e32 v19, s15, v2
	v_or_b32_e32 v17, s14, v3
	v_mov_b32_e32 v23, v1
	v_add_u32_e32 v0, s3, v19
	v_add_u32_e32 v22, s6, v17
	v_lshlrev_b64 v[24:25], 12, v[0:1]
	v_lshlrev_b64 v[22:23], 12, v[22:23]
	v_lshl_add_u64 v[24:25], v[20:21], 0, v[24:25]
	v_lshl_add_u64 v[22:23], v[20:21], 0, v[22:23]
	global_load_dword v110, v[24:25], off
	global_load_dword v111, v[22:23], off
	v_mad_u64_u32 v[136:137], s[14:15], v19, s77, v[4:5]
	v_mad_u64_u32 v[138:139], s[14:15], v17, s77, v[4:5]
	s_add_i32 s15, s13, 24
	s_add_i32 s14, s12, 24
	v_or_b32_e32 v19, s15, v2
	v_or_b32_e32 v17, s14, v3
	v_mov_b32_e32 v23, v1
	s_add_i32 s13, s13, 28
	s_add_i32 s12, s12, 28
	s_cmp_lg_u32 s11, 0
	v_add_u32_e32 v0, s3, v19
	v_add_u32_e32 v22, s6, v17
	v_lshlrev_b64 v[24:25], 12, v[0:1]
	v_lshlrev_b64 v[22:23], 12, v[22:23]
	v_lshl_add_u64 v[24:25], v[20:21], 0, v[24:25]
	v_lshl_add_u64 v[22:23], v[20:21], 0, v[22:23]
	global_load_dword v112, v[24:25], off
	global_load_dword v113, v[22:23], off
	v_mad_u64_u32 v[140:141], s[14:15], v19, s77, v[4:5]
	v_or_b32_e32 v19, s13, v2
	v_mad_u64_u32 v[142:143], s[14:15], v17, s77, v[4:5]
	v_or_b32_e32 v17, s12, v3
	v_mov_b32_e32 v23, v1
	v_add_u32_e32 v0, s3, v19
	v_add_u32_e32 v22, s6, v17
	v_lshlrev_b64 v[24:25], 12, v[0:1]
	v_lshlrev_b64 v[22:23], 12, v[22:23]
	v_lshl_add_u64 v[24:25], v[20:21], 0, v[24:25]
	v_lshl_add_u64 v[22:23], v[20:21], 0, v[22:23]
	global_load_dword v114, v[24:25], off
	global_load_dword v115, v[22:23], off
	v_mad_u64_u32 v[144:145], s[12:13], v19, s77, v[4:5]
	v_mad_u64_u32 v[146:147], s[12:13], v17, s77, v[4:5]
	s_lshl_b32 s13, s7, 1
	s_lshl_b32 s12, s5, 1
	v_or_b32_e32 v19, s13, v2
	v_or_b32_e32 v17, s12, v3
	v_add_u32_e32 v0, s3, v19
	v_add_u32_e32 v22, s6, v17
	v_mov_b32_e32 v23, v1
	v_lshlrev_b64 v[24:25], 12, v[0:1]
	v_lshlrev_b64 v[22:23], 12, v[22:23]
	v_lshl_add_u64 v[24:25], v[20:21], 0, v[24:25]
	v_lshl_add_u64 v[22:23], v[20:21], 0, v[22:23]
	global_load_dword v148, v[24:25], off
	global_load_dword v149, v[22:23], off
	v_mad_u64_u32 v[164:165], s[14:15], v19, s77, v[4:5]
	v_mad_u64_u32 v[166:167], s[14:15], v17, s77, v[4:5]
	s_add_i32 s15, s13, 4
	s_add_i32 s14, s12, 4
	v_or_b32_e32 v19, s15, v2
	v_or_b32_e32 v17, s14, v3
	v_mov_b32_e32 v23, v1
	s_add_i32 s7, s7, 16
	s_add_i32 s5, s5, 16
	s_add_i32 s11, s11, -16
	v_add_u32_e32 v0, s3, v19
	v_add_u32_e32 v22, s6, v17
	v_lshlrev_b64 v[24:25], 12, v[0:1]
	v_lshlrev_b64 v[22:23], 12, v[22:23]
	v_lshl_add_u64 v[24:25], v[20:21], 0, v[24:25]
	v_lshl_add_u64 v[22:23], v[20:21], 0, v[22:23]
	global_load_dword v150, v[24:25], off
	global_load_dword v151, v[22:23], off
	v_mad_u64_u32 v[168:169], s[14:15], v19, s77, v[4:5]
	v_mad_u64_u32 v[170:171], s[14:15], v17, s77, v[4:5]
	s_add_i32 s15, s13, 8
	s_add_i32 s14, s12, 8
	v_or_b32_e32 v19, s15, v2
	v_or_b32_e32 v17, s14, v3
	v_mov_b32_e32 v23, v1
	v_add_u32_e32 v0, s3, v19
	v_add_u32_e32 v22, s6, v17
	v_lshlrev_b64 v[24:25], 12, v[0:1]
	v_lshlrev_b64 v[22:23], 12, v[22:23]
	v_lshl_add_u64 v[24:25], v[20:21], 0, v[24:25]
	v_lshl_add_u64 v[22:23], v[20:21], 0, v[22:23]
	global_load_dword v152, v[24:25], off
	global_load_dword v153, v[22:23], off
	v_mad_u64_u32 v[172:173], s[14:15], v19, s77, v[4:5]
	v_mad_u64_u32 v[174:175], s[14:15], v17, s77, v[4:5]
	s_add_i32 s15, s13, 12
	s_add_i32 s14, s12, 12
	v_or_b32_e32 v19, s15, v2
	v_or_b32_e32 v17, s14, v3
	v_mov_b32_e32 v23, v1
	v_add_u32_e32 v0, s3, v19
	v_add_u32_e32 v22, s6, v17
	v_lshlrev_b64 v[24:25], 12, v[0:1]
	v_lshlrev_b64 v[22:23], 12, v[22:23]
	v_lshl_add_u64 v[24:25], v[20:21], 0, v[24:25]
	v_lshl_add_u64 v[22:23], v[20:21], 0, v[22:23]
	global_load_dword v154, v[24:25], off
	global_load_dword v155, v[22:23], off
	v_mad_u64_u32 v[176:177], s[14:15], v19, s77, v[4:5]
	v_mad_u64_u32 v[178:179], s[14:15], v17, s77, v[4:5]
	s_add_i32 s15, s13, 16
	s_add_i32 s14, s12, 16
	v_or_b32_e32 v19, s15, v2
	v_or_b32_e32 v17, s14, v3
	v_mov_b32_e32 v23, v1
	v_add_u32_e32 v0, s3, v19
	v_add_u32_e32 v22, s6, v17
	v_lshlrev_b64 v[24:25], 12, v[0:1]
	v_lshlrev_b64 v[22:23], 12, v[22:23]
	v_lshl_add_u64 v[24:25], v[20:21], 0, v[24:25]
	v_lshl_add_u64 v[22:23], v[20:21], 0, v[22:23]
	global_load_dword v156, v[24:25], off
	global_load_dword v157, v[22:23], off
	v_mad_u64_u32 v[180:181], s[14:15], v19, s77, v[4:5]
	v_mad_u64_u32 v[182:183], s[14:15], v17, s77, v[4:5]
	s_add_i32 s15, s13, 20
	s_add_i32 s14, s12, 20
	v_or_b32_e32 v19, s15, v2
	v_or_b32_e32 v17, s14, v3
	v_mov_b32_e32 v23, v1
	v_add_u32_e32 v0, s3, v19
	v_add_u32_e32 v22, s6, v17
	v_lshlrev_b64 v[24:25], 12, v[0:1]
	v_lshlrev_b64 v[22:23], 12, v[22:23]
	v_lshl_add_u64 v[24:25], v[20:21], 0, v[24:25]
	v_lshl_add_u64 v[22:23], v[20:21], 0, v[22:23]
	global_load_dword v158, v[24:25], off
	global_load_dword v159, v[22:23], off
	v_mad_u64_u32 v[184:185], s[14:15], v19, s77, v[4:5]
	v_mad_u64_u32 v[186:187], s[14:15], v17, s77, v[4:5]
	s_add_i32 s15, s13, 24
	s_add_i32 s14, s12, 24
	v_or_b32_e32 v19, s15, v2
	v_or_b32_e32 v17, s14, v3
	v_mov_b32_e32 v23, v1
	s_add_i32 s13, s13, 28
	s_add_i32 s12, s12, 28
	s_cmp_lg_u32 s11, 0
	v_add_u32_e32 v0, s3, v19
	v_add_u32_e32 v22, s6, v17
	v_lshlrev_b64 v[24:25], 12, v[0:1]
	v_lshlrev_b64 v[22:23], 12, v[22:23]
	v_lshl_add_u64 v[24:25], v[20:21], 0, v[24:25]
	v_lshl_add_u64 v[22:23], v[20:21], 0, v[22:23]
	global_load_dword v160, v[24:25], off
	global_load_dword v161, v[22:23], off
	v_mad_u64_u32 v[188:189], s[14:15], v19, s77, v[4:5]
	v_or_b32_e32 v19, s13, v2
	v_mad_u64_u32 v[190:191], s[14:15], v17, s77, v[4:5]
	v_or_b32_e32 v17, s12, v3
	v_mov_b32_e32 v23, v1
	v_add_u32_e32 v0, s3, v19
	v_add_u32_e32 v22, s6, v17
	v_lshlrev_b64 v[24:25], 12, v[0:1]
	v_lshlrev_b64 v[22:23], 12, v[22:23]
	v_lshl_add_u64 v[24:25], v[20:21], 0, v[24:25]
	v_lshl_add_u64 v[22:23], v[20:21], 0, v[22:23]
	global_load_dword v162, v[24:25], off
	global_load_dword v163, v[22:23], off
	v_mad_u64_u32 v[192:193], s[12:13], v19, s77, v[4:5]
	v_mad_u64_u32 v[196:197], s[12:13], v17, s77, v[4:5]
	s_waitcnt vmcnt(0)
	ds_write_b32 v116, v100
	ds_write_b32 v118, v101
	ds_write_b32 v120, v102
	ds_write_b32 v122, v103
	ds_write_b32 v124, v104
	ds_write_b32 v126, v105
	ds_write_b32 v128, v106
	ds_write_b32 v130, v107
	ds_write_b32 v132, v108
	ds_write_b32 v134, v109
	ds_write_b32 v136, v110
	ds_write_b32 v138, v111
	ds_write_b32 v140, v112
	ds_write_b32 v142, v113
	ds_write_b32 v144, v114
	ds_write_b32 v146, v115
	ds_write_b32 v164, v148
	ds_write_b32 v166, v149
	ds_write_b32 v168, v150
	ds_write_b32 v170, v151
	ds_write_b32 v172, v152
	ds_write_b32 v174, v153
	ds_write_b32 v176, v154
	ds_write_b32 v178, v155
	ds_write_b32 v180, v156
	ds_write_b32 v182, v157
	ds_write_b32 v184, v158
	ds_write_b32 v186, v159
	ds_write_b32 v188, v160
	ds_write_b32 v190, v161
	ds_write_b32 v192, v162
	ds_write_b32 v196, v163
	s_cbranch_scc1 .LBB0_154
	s_lshl_b64 s[0:1], s[0:1], 20
	v_readlane_b32 s5, v253, 4
	s_add_u32 s0, s5, s0
	v_readlane_b32 s5, v253, 5
	s_addc_u32 s1, s5, s1
	s_lshl_b32 s2, s2, 10
	s_add_u32 s0, s0, s2
	s_addc_u32 s1, s1, 0
	s_lshl_b32 s2, s3, 1
	s_add_u32 s0, s0, s2
	s_addc_u32 s1, s1, 0
	s_mov_b64 s[2:3], 0

.LBB0_158:
	s_lshl_b32 s11, s5, 1
	s_lshl_b32 s7, s3, 1
	v_or_b32_e32 v17, s11, v2
	v_or_b32_e32 v0, s7, v3
	v_add_u32_e32 v24, s0, v17
	v_add_u32_e32 v22, s2, v0
	v_ashrrev_i32_e32 v25, 31, v24
	v_ashrrev_i32_e32 v23, 31, v22
	v_lshlrev_b64 v[24:25], 11, v[24:25]
	v_lshlrev_b64 v[22:23], 11, v[22:23]
	v_lshl_add_u64 v[24:25], v[20:21], 0, v[24:25]
	v_lshl_add_u64 v[22:23], v[20:21], 0, v[22:23]
	global_load_dword v100, v[24:25], off
	global_load_dword v101, v[22:23], off
	v_mad_u64_u32 v[116:117], s[12:13], v17, s77, v[4:5]
	v_mad_u64_u32 v[118:119], s[12:13], v0, s77, v[4:5]
	s_add_i32 s13, s11, 4
	s_add_i32 s12, s7, 4
	v_or_b32_e32 v17, s13, v2
	v_or_b32_e32 v0, s12, v3
	s_add_i32 s5, s5, 16
	s_add_i32 s3, s3, 16
	s_add_i32 s6, s6, -16
	v_add_u32_e32 v24, s0, v17
	v_add_u32_e32 v22, s2, v0
	v_ashrrev_i32_e32 v25, 31, v24
	v_ashrrev_i32_e32 v23, 31, v22
	v_lshlrev_b64 v[24:25], 11, v[24:25]
	v_lshlrev_b64 v[22:23], 11, v[22:23]
	v_lshl_add_u64 v[24:25], v[20:21], 0, v[24:25]
	v_lshl_add_u64 v[22:23], v[20:21], 0, v[22:23]
	global_load_dword v102, v[24:25], off
	global_load_dword v103, v[22:23], off
	v_mad_u64_u32 v[120:121], s[12:13], v17, s77, v[4:5]
	v_mad_u64_u32 v[122:123], s[12:13], v0, s77, v[4:5]
	s_add_i32 s13, s11, 8
	s_add_i32 s12, s7, 8
	v_or_b32_e32 v17, s13, v2
	v_or_b32_e32 v0, s12, v3
	v_add_u32_e32 v24, s0, v17
	v_add_u32_e32 v22, s2, v0
	v_ashrrev_i32_e32 v25, 31, v24
	v_ashrrev_i32_e32 v23, 31, v22
	v_lshlrev_b64 v[24:25], 11, v[24:25]
	v_lshlrev_b64 v[22:23], 11, v[22:23]
	v_lshl_add_u64 v[24:25], v[20:21], 0, v[24:25]
	v_lshl_add_u64 v[22:23], v[20:21], 0, v[22:23]
	global_load_dword v104, v[24:25], off
	global_load_dword v105, v[22:23], off
	v_mad_u64_u32 v[124:125], s[12:13], v17, s77, v[4:5]
	v_mad_u64_u32 v[126:127], s[12:13], v0, s77, v[4:5]
	s_add_i32 s13, s11, 12
	s_add_i32 s12, s7, 12
	v_or_b32_e32 v17, s13, v2
	v_or_b32_e32 v0, s12, v3
	v_add_u32_e32 v24, s0, v17
	v_add_u32_e32 v22, s2, v0
	v_ashrrev_i32_e32 v25, 31, v24
	v_ashrrev_i32_e32 v23, 31, v22
	v_lshlrev_b64 v[24:25], 11, v[24:25]
	v_lshlrev_b64 v[22:23], 11, v[22:23]
	v_lshl_add_u64 v[24:25], v[20:21], 0, v[24:25]
	v_lshl_add_u64 v[22:23], v[20:21], 0, v[22:23]
	global_load_dword v106, v[24:25], off
	global_load_dword v107, v[22:23], off
	v_mad_u64_u32 v[128:129], s[12:13], v17, s77, v[4:5]
	v_mad_u64_u32 v[130:131], s[12:13], v0, s77, v[4:5]
	s_add_i32 s13, s11, 16
	s_add_i32 s12, s7, 16
	v_or_b32_e32 v17, s13, v2
	v_or_b32_e32 v0, s12, v3
	v_add_u32_e32 v24, s0, v17
	v_add_u32_e32 v22, s2, v0
	v_ashrrev_i32_e32 v25, 31, v24
	v_ashrrev_i32_e32 v23, 31, v22
	v_lshlrev_b64 v[24:25], 11, v[24:25]
	v_lshlrev_b64 v[22:23], 11, v[22:23]
	v_lshl_add_u64 v[24:25], v[20:21], 0, v[24:25]
	v_lshl_add_u64 v[22:23], v[20:21], 0, v[22:23]
	global_load_dword v108, v[24:25], off
	global_load_dword v109, v[22:23], off
	v_mad_u64_u32 v[132:133], s[12:13], v17, s77, v[4:5]
	v_mad_u64_u32 v[134:135], s[12:13], v0, s77, v[4:5]
	s_add_i32 s13, s11, 20
	s_add_i32 s12, s7, 20
	v_or_b32_e32 v17, s13, v2
	v_or_b32_e32 v0, s12, v3
	v_add_u32_e32 v24, s0, v17
	v_add_u32_e32 v22, s2, v0
	v_ashrrev_i32_e32 v25, 31, v24
	v_ashrrev_i32_e32 v23, 31, v22
	v_lshlrev_b64 v[24:25], 11, v[24:25]
	v_lshlrev_b64 v[22:23], 11, v[22:23]
	v_lshl_add_u64 v[24:25], v[20:21], 0, v[24:25]
	v_lshl_add_u64 v[22:23], v[20:21], 0, v[22:23]
	global_load_dword v110, v[24:25], off
	global_load_dword v111, v[22:23], off
	v_mad_u64_u32 v[136:137], s[12:13], v17, s77, v[4:5]
	v_mad_u64_u32 v[138:139], s[12:13], v0, s77, v[4:5]
	s_add_i32 s13, s11, 24
	s_add_i32 s12, s7, 24
	v_or_b32_e32 v17, s13, v2
	v_or_b32_e32 v0, s12, v3
	s_add_i32 s11, s11, 28
	s_add_i32 s7, s7, 28
	s_cmp_lg_u32 s6, 0
	v_add_u32_e32 v24, s0, v17
	v_add_u32_e32 v22, s2, v0
	v_ashrrev_i32_e32 v25, 31, v24
	v_ashrrev_i32_e32 v23, 31, v22
	v_lshlrev_b64 v[24:25], 11, v[24:25]
	v_lshlrev_b64 v[22:23], 11, v[22:23]
	v_lshl_add_u64 v[24:25], v[20:21], 0, v[24:25]
	v_lshl_add_u64 v[22:23], v[20:21], 0, v[22:23]
	global_load_dword v112, v[24:25], off
	global_load_dword v113, v[22:23], off
	v_mad_u64_u32 v[140:141], s[12:13], v17, s77, v[4:5]
	v_mad_u64_u32 v[142:143], s[12:13], v0, s77, v[4:5]
	v_or_b32_e32 v17, s11, v2
	v_or_b32_e32 v0, s7, v3
	v_add_u32_e32 v24, s0, v17
	v_add_u32_e32 v22, s2, v0
	v_ashrrev_i32_e32 v25, 31, v24
	v_ashrrev_i32_e32 v23, 31, v22
	v_lshlrev_b64 v[24:25], 11, v[24:25]
	v_lshlrev_b64 v[22:23], 11, v[22:23]
	v_lshl_add_u64 v[24:25], v[20:21], 0, v[24:25]
	v_lshl_add_u64 v[22:23], v[20:21], 0, v[22:23]
	global_load_dword v114, v[24:25], off
	global_load_dword v115, v[22:23], off
	v_mad_u64_u32 v[144:145], s[12:13], v17, s77, v[4:5]
	v_mad_u64_u32 v[146:147], s[12:13], v0, s77, v[4:5]
	s_lshl_b32 s11, s5, 1
	s_lshl_b32 s7, s3, 1
	v_or_b32_e32 v17, s11, v2
	v_or_b32_e32 v0, s7, v3
	v_add_u32_e32 v24, s0, v17
	v_add_u32_e32 v22, s2, v0
	v_ashrrev_i32_e32 v25, 31, v24
	v_ashrrev_i32_e32 v23, 31, v22
	v_lshlrev_b64 v[24:25], 11, v[24:25]
	v_lshlrev_b64 v[22:23], 11, v[22:23]
	v_lshl_add_u64 v[24:25], v[20:21], 0, v[24:25]
	v_lshl_add_u64 v[22:23], v[20:21], 0, v[22:23]
	global_load_dword v148, v[24:25], off
	global_load_dword v149, v[22:23], off
	v_mad_u64_u32 v[164:165], s[12:13], v17, s77, v[4:5]
	v_mad_u64_u32 v[166:167], s[12:13], v0, s77, v[4:5]
	s_add_i32 s13, s11, 4
	s_add_i32 s12, s7, 4
	v_or_b32_e32 v17, s13, v2
	v_or_b32_e32 v0, s12, v3
	s_add_i32 s5, s5, 16
	s_add_i32 s3, s3, 16
	s_add_i32 s6, s6, -16
	v_add_u32_e32 v24, s0, v17
	v_add_u32_e32 v22, s2, v0
	v_ashrrev_i32_e32 v25, 31, v24
	v_ashrrev_i32_e32 v23, 31, v22
	v_lshlrev_b64 v[24:25], 11, v[24:25]
	v_lshlrev_b64 v[22:23], 11, v[22:23]
	v_lshl_add_u64 v[24:25], v[20:21], 0, v[24:25]
	v_lshl_add_u64 v[22:23], v[20:21], 0, v[22:23]
	global_load_dword v150, v[24:25], off
	global_load_dword v151, v[22:23], off
	v_mad_u64_u32 v[168:169], s[12:13], v17, s77, v[4:5]
	v_mad_u64_u32 v[170:171], s[12:13], v0, s77, v[4:5]
	s_add_i32 s13, s11, 8
	s_add_i32 s12, s7, 8
	v_or_b32_e32 v17, s13, v2
	v_or_b32_e32 v0, s12, v3
	v_add_u32_e32 v24, s0, v17
	v_add_u32_e32 v22, s2, v0
	v_ashrrev_i32_e32 v25, 31, v24
	v_ashrrev_i32_e32 v23, 31, v22
	v_lshlrev_b64 v[24:25], 11, v[24:25]
	v_lshlrev_b64 v[22:23], 11, v[22:23]
	v_lshl_add_u64 v[24:25], v[20:21], 0, v[24:25]
	v_lshl_add_u64 v[22:23], v[20:21], 0, v[22:23]
	global_load_dword v152, v[24:25], off
	global_load_dword v153, v[22:23], off
	v_mad_u64_u32 v[172:173], s[12:13], v17, s77, v[4:5]
	v_mad_u64_u32 v[174:175], s[12:13], v0, s77, v[4:5]
	s_add_i32 s13, s11, 12
	s_add_i32 s12, s7, 12
	v_or_b32_e32 v17, s13, v2
	v_or_b32_e32 v0, s12, v3
	v_add_u32_e32 v24, s0, v17
	v_add_u32_e32 v22, s2, v0
	v_ashrrev_i32_e32 v25, 31, v24
	v_ashrrev_i32_e32 v23, 31, v22
	v_lshlrev_b64 v[24:25], 11, v[24:25]
	v_lshlrev_b64 v[22:23], 11, v[22:23]
	v_lshl_add_u64 v[24:25], v[20:21], 0, v[24:25]
	v_lshl_add_u64 v[22:23], v[20:21], 0, v[22:23]
	global_load_dword v154, v[24:25], off
	global_load_dword v155, v[22:23], off
	v_mad_u64_u32 v[176:177], s[12:13], v17, s77, v[4:5]
	v_mad_u64_u32 v[178:179], s[12:13], v0, s77, v[4:5]
	s_add_i32 s13, s11, 16
	s_add_i32 s12, s7, 16
	v_or_b32_e32 v17, s13, v2
	v_or_b32_e32 v0, s12, v3
	v_add_u32_e32 v24, s0, v17
	v_add_u32_e32 v22, s2, v0
	v_ashrrev_i32_e32 v25, 31, v24
	v_ashrrev_i32_e32 v23, 31, v22
	v_lshlrev_b64 v[24:25], 11, v[24:25]
	v_lshlrev_b64 v[22:23], 11, v[22:23]
	v_lshl_add_u64 v[24:25], v[20:21], 0, v[24:25]
	v_lshl_add_u64 v[22:23], v[20:21], 0, v[22:23]
	global_load_dword v156, v[24:25], off
	global_load_dword v157, v[22:23], off
	v_mad_u64_u32 v[180:181], s[12:13], v17, s77, v[4:5]
	v_mad_u64_u32 v[182:183], s[12:13], v0, s77, v[4:5]
	s_add_i32 s13, s11, 20
	s_add_i32 s12, s7, 20
	v_or_b32_e32 v17, s13, v2
	v_or_b32_e32 v0, s12, v3
	v_add_u32_e32 v24, s0, v17
	v_add_u32_e32 v22, s2, v0
	v_ashrrev_i32_e32 v25, 31, v24
	v_ashrrev_i32_e32 v23, 31, v22
	v_lshlrev_b64 v[24:25], 11, v[24:25]
	v_lshlrev_b64 v[22:23], 11, v[22:23]
	v_lshl_add_u64 v[24:25], v[20:21], 0, v[24:25]
	v_lshl_add_u64 v[22:23], v[20:21], 0, v[22:23]
	global_load_dword v158, v[24:25], off
	global_load_dword v159, v[22:23], off
	v_mad_u64_u32 v[184:185], s[12:13], v17, s77, v[4:5]
	v_mad_u64_u32 v[186:187], s[12:13], v0, s77, v[4:5]
	s_add_i32 s13, s11, 24
	s_add_i32 s12, s7, 24
	v_or_b32_e32 v17, s13, v2
	v_or_b32_e32 v0, s12, v3
	s_add_i32 s11, s11, 28
	s_add_i32 s7, s7, 28
	s_cmp_lg_u32 s6, 0
	v_add_u32_e32 v24, s0, v17
	v_add_u32_e32 v22, s2, v0
	v_ashrrev_i32_e32 v25, 31, v24
	v_ashrrev_i32_e32 v23, 31, v22
	v_lshlrev_b64 v[24:25], 11, v[24:25]
	v_lshlrev_b64 v[22:23], 11, v[22:23]
	v_lshl_add_u64 v[24:25], v[20:21], 0, v[24:25]
	v_lshl_add_u64 v[22:23], v[20:21], 0, v[22:23]
	global_load_dword v160, v[24:25], off
	global_load_dword v161, v[22:23], off
	v_mad_u64_u32 v[188:189], s[12:13], v17, s77, v[4:5]
	v_mad_u64_u32 v[190:191], s[12:13], v0, s77, v[4:5]
	v_or_b32_e32 v17, s11, v2
	v_or_b32_e32 v0, s7, v3
	v_add_u32_e32 v24, s0, v17
	v_add_u32_e32 v22, s2, v0
	v_ashrrev_i32_e32 v25, 31, v24
	v_ashrrev_i32_e32 v23, 31, v22
	v_lshlrev_b64 v[24:25], 11, v[24:25]
	v_lshlrev_b64 v[22:23], 11, v[22:23]
	v_lshl_add_u64 v[24:25], v[20:21], 0, v[24:25]
	v_lshl_add_u64 v[22:23], v[20:21], 0, v[22:23]
	global_load_dword v162, v[24:25], off
	global_load_dword v163, v[22:23], off
	v_mad_u64_u32 v[192:193], s[12:13], v17, s77, v[4:5]
	v_mad_u64_u32 v[196:197], s[12:13], v0, s77, v[4:5]
	s_waitcnt vmcnt(0)
	ds_write_b32 v116, v100
	ds_write_b32 v118, v101
	ds_write_b32 v120, v102
	ds_write_b32 v122, v103
	ds_write_b32 v124, v104
	ds_write_b32 v126, v105
	ds_write_b32 v128, v106
	ds_write_b32 v130, v107
	ds_write_b32 v132, v108
	ds_write_b32 v134, v109
	ds_write_b32 v136, v110
	ds_write_b32 v138, v111
	ds_write_b32 v140, v112
	ds_write_b32 v142, v113
	ds_write_b32 v144, v114
	ds_write_b32 v146, v115
	ds_write_b32 v164, v148
	ds_write_b32 v166, v149
	ds_write_b32 v168, v150
	ds_write_b32 v170, v151
	ds_write_b32 v172, v152
	ds_write_b32 v174, v153
	ds_write_b32 v176, v154
	ds_write_b32 v178, v155
	ds_write_b32 v180, v156
	ds_write_b32 v182, v157
	ds_write_b32 v184, v158
	ds_write_b32 v186, v159
	ds_write_b32 v188, v160
	ds_write_b32 v190, v161
	ds_write_b32 v192, v162
	ds_write_b32 v196, v163
	s_cbranch_scc1 .LBB0_158
	s_lshl_b32 s1, s1, 10
	s_add_u32 s2, s73, s1
	v_readlane_b32 s1, v250, 13
	s_addc_u32 s3, s1, 0
	s_mov_b32 s1, s4
	s_lshl_b64 s[0:1], s[0:1], 1
	s_add_u32 s0, s2, s0
	s_addc_u32 s1, s3, s1

.LBB0_167:
	s_lshl_b32 s12, s5, 1
	s_lshl_b32 s11, s2, 1
	v_or_b32_e32 v17, s12, v2
	v_or_b32_e32 v0, s11, v3
	v_add_u32_e32 v24, s6, v17
	v_add_u32_e32 v22, s3, v0
	v_ashrrev_i32_e32 v25, 31, v24
	v_ashrrev_i32_e32 v23, 31, v22
	v_lshlrev_b64 v[24:25], 12, v[24:25]
	v_lshlrev_b64 v[22:23], 12, v[22:23]
	v_lshl_add_u64 v[24:25], v[20:21], 0, v[24:25]
	v_lshl_add_u64 v[22:23], v[20:21], 0, v[22:23]
	global_load_dword v100, v[24:25], off
	global_load_dword v101, v[22:23], off
	v_mad_u64_u32 v[116:117], s[14:15], v17, s77, v[4:5]
	v_mad_u64_u32 v[118:119], s[14:15], v0, s77, v[4:5]
	s_add_i32 s14, s12, 4
	s_add_i32 s13, s11, 4
	v_or_b32_e32 v17, s14, v2
	v_or_b32_e32 v0, s13, v3
	s_add_i32 s13, s11, 8
	s_add_i32 s5, s5, 16
	s_add_i32 s2, s2, 16
	s_add_i32 s7, s7, -16
	v_add_u32_e32 v24, s6, v17
	v_add_u32_e32 v22, s3, v0
	v_ashrrev_i32_e32 v25, 31, v24
	v_ashrrev_i32_e32 v23, 31, v22
	v_lshlrev_b64 v[24:25], 12, v[24:25]
	v_lshlrev_b64 v[22:23], 12, v[22:23]
	v_lshl_add_u64 v[24:25], v[20:21], 0, v[24:25]
	v_lshl_add_u64 v[22:23], v[20:21], 0, v[22:23]
	global_load_dword v102, v[24:25], off
	global_load_dword v103, v[22:23], off
	v_mad_u64_u32 v[120:121], s[14:15], v17, s77, v[4:5]
	v_mad_u64_u32 v[122:123], s[14:15], v0, s77, v[4:5]
	s_add_i32 s14, s12, 8
	s_nop 0
	v_or_b32_e32 v17, s14, v2
	v_or_b32_e32 v0, s13, v3
	s_add_i32 s13, s11, 12
	v_add_u32_e32 v24, s6, v17
	v_add_u32_e32 v22, s3, v0
	v_ashrrev_i32_e32 v25, 31, v24
	v_ashrrev_i32_e32 v23, 31, v22
	v_lshlrev_b64 v[24:25], 12, v[24:25]
	v_lshlrev_b64 v[22:23], 12, v[22:23]
	v_lshl_add_u64 v[24:25], v[20:21], 0, v[24:25]
	v_lshl_add_u64 v[22:23], v[20:21], 0, v[22:23]
	global_load_dword v104, v[24:25], off
	global_load_dword v105, v[22:23], off
	v_mad_u64_u32 v[124:125], s[14:15], v17, s77, v[4:5]
	v_mad_u64_u32 v[126:127], s[14:15], v0, s77, v[4:5]
	s_add_i32 s14, s12, 12
	s_nop 0
	v_or_b32_e32 v17, s14, v2
	v_or_b32_e32 v0, s13, v3
	s_add_i32 s13, s11, 16
	v_add_u32_e32 v24, s6, v17
	v_add_u32_e32 v22, s3, v0
	v_ashrrev_i32_e32 v25, 31, v24
	v_ashrrev_i32_e32 v23, 31, v22
	v_lshlrev_b64 v[24:25], 12, v[24:25]
	v_lshlrev_b64 v[22:23], 12, v[22:23]
	v_lshl_add_u64 v[24:25], v[20:21], 0, v[24:25]
	v_lshl_add_u64 v[22:23], v[20:21], 0, v[22:23]
	global_load_dword v106, v[24:25], off
	global_load_dword v107, v[22:23], off
	v_mad_u64_u32 v[128:129], s[14:15], v17, s77, v[4:5]
	v_mad_u64_u32 v[130:131], s[14:15], v0, s77, v[4:5]
	s_add_i32 s14, s12, 16
	s_nop 0
	v_or_b32_e32 v17, s14, v2
	v_or_b32_e32 v0, s13, v3
	s_add_i32 s13, s11, 20
	v_add_u32_e32 v24, s6, v17
	v_add_u32_e32 v22, s3, v0
	v_ashrrev_i32_e32 v25, 31, v24
	v_ashrrev_i32_e32 v23, 31, v22
	v_lshlrev_b64 v[24:25], 12, v[24:25]
	v_lshlrev_b64 v[22:23], 12, v[22:23]
	v_lshl_add_u64 v[24:25], v[20:21], 0, v[24:25]
	v_lshl_add_u64 v[22:23], v[20:21], 0, v[22:23]
	global_load_dword v108, v[24:25], off
	global_load_dword v109, v[22:23], off
	v_mad_u64_u32 v[132:133], s[14:15], v17, s77, v[4:5]
	v_mad_u64_u32 v[134:135], s[14:15], v0, s77, v[4:5]
	s_add_i32 s14, s12, 20
	s_nop 0
	v_or_b32_e32 v17, s14, v2
	v_or_b32_e32 v0, s13, v3
	s_add_i32 s13, s11, 24
	s_add_i32 s11, s11, 28
	v_add_u32_e32 v24, s6, v17
	v_add_u32_e32 v22, s3, v0
	v_ashrrev_i32_e32 v25, 31, v24
	v_ashrrev_i32_e32 v23, 31, v22
	v_lshlrev_b64 v[24:25], 12, v[24:25]
	v_lshlrev_b64 v[22:23], 12, v[22:23]
	v_lshl_add_u64 v[24:25], v[20:21], 0, v[24:25]
	v_lshl_add_u64 v[22:23], v[20:21], 0, v[22:23]
	global_load_dword v110, v[24:25], off
	global_load_dword v111, v[22:23], off
	v_mad_u64_u32 v[136:137], s[14:15], v17, s77, v[4:5]
	v_mad_u64_u32 v[138:139], s[14:15], v0, s77, v[4:5]
	s_add_i32 s14, s12, 24
	s_nop 0
	v_or_b32_e32 v17, s14, v2
	v_or_b32_e32 v0, s13, v3
	s_add_i32 s12, s12, 28
	s_cmp_lg_u32 s7, 0
	v_add_u32_e32 v24, s6, v17
	v_add_u32_e32 v22, s3, v0
	v_ashrrev_i32_e32 v25, 31, v24
	v_ashrrev_i32_e32 v23, 31, v22
	v_lshlrev_b64 v[24:25], 12, v[24:25]
	v_lshlrev_b64 v[22:23], 12, v[22:23]
	v_lshl_add_u64 v[24:25], v[20:21], 0, v[24:25]
	v_lshl_add_u64 v[22:23], v[20:21], 0, v[22:23]
	global_load_dword v112, v[24:25], off
	global_load_dword v113, v[22:23], off
	v_mad_u64_u32 v[140:141], s[14:15], v17, s77, v[4:5]
	v_mad_u64_u32 v[142:143], s[14:15], v0, s77, v[4:5]
	v_or_b32_e32 v17, s12, v2
	v_or_b32_e32 v0, s11, v3
	v_add_u32_e32 v24, s6, v17
	v_add_u32_e32 v22, s3, v0
	v_ashrrev_i32_e32 v25, 31, v24
	v_ashrrev_i32_e32 v23, 31, v22
	v_lshlrev_b64 v[24:25], 12, v[24:25]
	v_lshlrev_b64 v[22:23], 12, v[22:23]
	v_lshl_add_u64 v[24:25], v[20:21], 0, v[24:25]
	v_lshl_add_u64 v[22:23], v[20:21], 0, v[22:23]
	global_load_dword v114, v[24:25], off
	global_load_dword v115, v[22:23], off
	v_mad_u64_u32 v[144:145], s[12:13], v17, s77, v[4:5]
	v_mad_u64_u32 v[146:147], s[12:13], v0, s77, v[4:5]
	s_lshl_b32 s12, s5, 1
	s_lshl_b32 s11, s2, 1
	v_or_b32_e32 v17, s12, v2
	v_or_b32_e32 v0, s11, v3
	v_add_u32_e32 v24, s6, v17
	v_add_u32_e32 v22, s3, v0
	v_ashrrev_i32_e32 v25, 31, v24
	v_ashrrev_i32_e32 v23, 31, v22
	v_lshlrev_b64 v[24:25], 12, v[24:25]
	v_lshlrev_b64 v[22:23], 12, v[22:23]
	v_lshl_add_u64 v[24:25], v[20:21], 0, v[24:25]
	v_lshl_add_u64 v[22:23], v[20:21], 0, v[22:23]
	global_load_dword v148, v[24:25], off
	global_load_dword v149, v[22:23], off
	v_mad_u64_u32 v[164:165], s[14:15], v17, s77, v[4:5]
	v_mad_u64_u32 v[166:167], s[14:15], v0, s77, v[4:5]
	s_add_i32 s14, s12, 4
	s_add_i32 s13, s11, 4
	v_or_b32_e32 v17, s14, v2
	v_or_b32_e32 v0, s13, v3
	s_add_i32 s13, s11, 8
	s_add_i32 s5, s5, 16
	s_add_i32 s2, s2, 16
	s_add_i32 s7, s7, -16
	v_add_u32_e32 v24, s6, v17
	v_add_u32_e32 v22, s3, v0
	v_ashrrev_i32_e32 v25, 31, v24
	v_ashrrev_i32_e32 v23, 31, v22
	v_lshlrev_b64 v[24:25], 12, v[24:25]
	v_lshlrev_b64 v[22:23], 12, v[22:23]
	v_lshl_add_u64 v[24:25], v[20:21], 0, v[24:25]
	v_lshl_add_u64 v[22:23], v[20:21], 0, v[22:23]
	global_load_dword v150, v[24:25], off
	global_load_dword v151, v[22:23], off
	v_mad_u64_u32 v[168:169], s[14:15], v17, s77, v[4:5]
	v_mad_u64_u32 v[170:171], s[14:15], v0, s77, v[4:5]
	s_add_i32 s14, s12, 8
	s_nop 0
	v_or_b32_e32 v17, s14, v2
	v_or_b32_e32 v0, s13, v3
	s_add_i32 s13, s11, 12
	v_add_u32_e32 v24, s6, v17
	v_add_u32_e32 v22, s3, v0
	v_ashrrev_i32_e32 v25, 31, v24
	v_ashrrev_i32_e32 v23, 31, v22
	v_lshlrev_b64 v[24:25], 12, v[24:25]
	v_lshlrev_b64 v[22:23], 12, v[22:23]
	v_lshl_add_u64 v[24:25], v[20:21], 0, v[24:25]
	v_lshl_add_u64 v[22:23], v[20:21], 0, v[22:23]
	global_load_dword v152, v[24:25], off
	global_load_dword v153, v[22:23], off
	v_mad_u64_u32 v[172:173], s[14:15], v17, s77, v[4:5]
	v_mad_u64_u32 v[174:175], s[14:15], v0, s77, v[4:5]
	s_add_i32 s14, s12, 12
	s_nop 0
	v_or_b32_e32 v17, s14, v2
	v_or_b32_e32 v0, s13, v3
	s_add_i32 s13, s11, 16
	v_add_u32_e32 v24, s6, v17
	v_add_u32_e32 v22, s3, v0
	v_ashrrev_i32_e32 v25, 31, v24
	v_ashrrev_i32_e32 v23, 31, v22
	v_lshlrev_b64 v[24:25], 12, v[24:25]
	v_lshlrev_b64 v[22:23], 12, v[22:23]
	v_lshl_add_u64 v[24:25], v[20:21], 0, v[24:25]
	v_lshl_add_u64 v[22:23], v[20:21], 0, v[22:23]
	global_load_dword v154, v[24:25], off
	global_load_dword v155, v[22:23], off
	v_mad_u64_u32 v[176:177], s[14:15], v17, s77, v[4:5]
	v_mad_u64_u32 v[178:179], s[14:15], v0, s77, v[4:5]
	s_add_i32 s14, s12, 16
	s_nop 0
	v_or_b32_e32 v17, s14, v2
	v_or_b32_e32 v0, s13, v3
	s_add_i32 s13, s11, 20
	v_add_u32_e32 v24, s6, v17
	v_add_u32_e32 v22, s3, v0
	v_ashrrev_i32_e32 v25, 31, v24
	v_ashrrev_i32_e32 v23, 31, v22
	v_lshlrev_b64 v[24:25], 12, v[24:25]
	v_lshlrev_b64 v[22:23], 12, v[22:23]
	v_lshl_add_u64 v[24:25], v[20:21], 0, v[24:25]
	v_lshl_add_u64 v[22:23], v[20:21], 0, v[22:23]
	global_load_dword v156, v[24:25], off
	global_load_dword v157, v[22:23], off
	v_mad_u64_u32 v[180:181], s[14:15], v17, s77, v[4:5]
	v_mad_u64_u32 v[182:183], s[14:15], v0, s77, v[4:5]
	s_add_i32 s14, s12, 20
	s_nop 0
	v_or_b32_e32 v17, s14, v2
	v_or_b32_e32 v0, s13, v3
	s_add_i32 s13, s11, 24
	s_add_i32 s11, s11, 28
	v_add_u32_e32 v24, s6, v17
	v_add_u32_e32 v22, s3, v0
	v_ashrrev_i32_e32 v25, 31, v24
	v_ashrrev_i32_e32 v23, 31, v22
	v_lshlrev_b64 v[24:25], 12, v[24:25]
	v_lshlrev_b64 v[22:23], 12, v[22:23]
	v_lshl_add_u64 v[24:25], v[20:21], 0, v[24:25]
	v_lshl_add_u64 v[22:23], v[20:21], 0, v[22:23]
	global_load_dword v158, v[24:25], off
	global_load_dword v159, v[22:23], off
	v_mad_u64_u32 v[184:185], s[14:15], v17, s77, v[4:5]
	v_mad_u64_u32 v[186:187], s[14:15], v0, s77, v[4:5]
	s_add_i32 s14, s12, 24
	s_nop 0
	v_or_b32_e32 v17, s14, v2
	v_or_b32_e32 v0, s13, v3
	s_add_i32 s12, s12, 28
	s_cmp_lg_u32 s7, 0
	v_add_u32_e32 v24, s6, v17
	v_add_u32_e32 v22, s3, v0
	v_ashrrev_i32_e32 v25, 31, v24
	v_ashrrev_i32_e32 v23, 31, v22
	v_lshlrev_b64 v[24:25], 12, v[24:25]
	v_lshlrev_b64 v[22:23], 12, v[22:23]
	v_lshl_add_u64 v[24:25], v[20:21], 0, v[24:25]
	v_lshl_add_u64 v[22:23], v[20:21], 0, v[22:23]
	global_load_dword v160, v[24:25], off
	global_load_dword v161, v[22:23], off
	v_mad_u64_u32 v[188:189], s[14:15], v17, s77, v[4:5]
	v_mad_u64_u32 v[190:191], s[14:15], v0, s77, v[4:5]
	v_or_b32_e32 v17, s12, v2
	v_or_b32_e32 v0, s11, v3
	v_add_u32_e32 v24, s6, v17
	v_add_u32_e32 v22, s3, v0
	v_ashrrev_i32_e32 v25, 31, v24
	v_ashrrev_i32_e32 v23, 31, v22
	v_lshlrev_b64 v[24:25], 12, v[24:25]
	v_lshlrev_b64 v[22:23], 12, v[22:23]
	v_lshl_add_u64 v[24:25], v[20:21], 0, v[24:25]
	v_lshl_add_u64 v[22:23], v[20:21], 0, v[22:23]
	global_load_dword v162, v[24:25], off
	global_load_dword v163, v[22:23], off
	v_mad_u64_u32 v[192:193], s[12:13], v17, s77, v[4:5]
	v_mad_u64_u32 v[196:197], s[12:13], v0, s77, v[4:5]
	s_waitcnt vmcnt(0)
	ds_write_b32 v116, v100
	ds_write_b32 v118, v101
	ds_write_b32 v120, v102
	ds_write_b32 v122, v103
	ds_write_b32 v124, v104
	ds_write_b32 v126, v105
	ds_write_b32 v128, v106
	ds_write_b32 v130, v107
	ds_write_b32 v132, v108
	ds_write_b32 v134, v109
	ds_write_b32 v136, v110
	ds_write_b32 v138, v111
	ds_write_b32 v140, v112
	ds_write_b32 v142, v113
	ds_write_b32 v144, v114
	ds_write_b32 v146, v115
	ds_write_b32 v164, v148
	ds_write_b32 v166, v149
	ds_write_b32 v168, v150
	ds_write_b32 v170, v151
	ds_write_b32 v172, v152
	ds_write_b32 v174, v153
	ds_write_b32 v176, v154
	ds_write_b32 v178, v155
	ds_write_b32 v180, v156
	ds_write_b32 v182, v157
	ds_write_b32 v184, v158
	ds_write_b32 v186, v159
	ds_write_b32 v188, v160
	ds_write_b32 v190, v161
	ds_write_b32 v192, v162
	ds_write_b32 v196, v163
	s_cbranch_scc1 .LBB0_167
	s_mov_b32 s7, s4
	s_lshl_b64 s[2:3], s[6:7], 1
	s_add_u32 s0, s0, s2
	s_addc_u32 s1, s1, s3
	v_mov_b32_e32 v0, v33
	v_mov_b32_e32 v20, v32
	v_mov_b32_e32 v22, v31
	v_mov_b32_e32 v24, v30

.LBB0_172:
	s_lshl_b32 s11, s5, 1
	s_lshl_b32 s7, s3, 1
	v_or_b32_e32 v17, s11, v2
	v_or_b32_e32 v0, s7, v3
	v_add_u32_e32 v22, s0, v17
	v_add_u32_e32 v19, s2, v0
	v_mad_u64_u32 v[22:23], s[12:13], v22, s61, v[20:21]
	v_mad_u64_u32 v[24:25], s[12:13], v19, s61, v[20:21]
	global_load_dword v100, v[22:23], off
	global_load_dword v101, v[24:25], off
	v_mad_u64_u32 v[116:117], s[12:13], v17, s77, v[4:5]
	v_mad_u64_u32 v[118:119], s[12:13], v0, s77, v[4:5]
	s_add_i32 s13, s11, 4
	s_add_i32 s12, s7, 4
	v_or_b32_e32 v17, s13, v2
	v_or_b32_e32 v0, s12, v3
	s_add_i32 s5, s5, 16
	s_add_i32 s3, s3, 16
	s_add_i32 s6, s6, -16
	v_add_u32_e32 v22, s0, v17
	v_add_u32_e32 v19, s2, v0
	v_mad_u64_u32 v[22:23], s[12:13], v22, s61, v[20:21]
	v_mad_u64_u32 v[24:25], s[12:13], v19, s61, v[20:21]
	global_load_dword v102, v[22:23], off
	global_load_dword v103, v[24:25], off
	v_mad_u64_u32 v[120:121], s[12:13], v17, s77, v[4:5]
	v_mad_u64_u32 v[122:123], s[12:13], v0, s77, v[4:5]
	s_add_i32 s13, s11, 8
	s_add_i32 s12, s7, 8
	v_or_b32_e32 v17, s13, v2
	v_or_b32_e32 v0, s12, v3
	v_add_u32_e32 v22, s0, v17
	v_add_u32_e32 v19, s2, v0
	v_mad_u64_u32 v[22:23], s[12:13], v22, s61, v[20:21]
	v_mad_u64_u32 v[24:25], s[12:13], v19, s61, v[20:21]
	global_load_dword v104, v[22:23], off
	global_load_dword v105, v[24:25], off
	v_mad_u64_u32 v[124:125], s[12:13], v17, s77, v[4:5]
	v_mad_u64_u32 v[126:127], s[12:13], v0, s77, v[4:5]
	s_add_i32 s13, s11, 12
	s_add_i32 s12, s7, 12
	v_or_b32_e32 v17, s13, v2
	v_or_b32_e32 v0, s12, v3
	v_add_u32_e32 v22, s0, v17
	v_add_u32_e32 v19, s2, v0
	v_mad_u64_u32 v[22:23], s[12:13], v22, s61, v[20:21]
	v_mad_u64_u32 v[24:25], s[12:13], v19, s61, v[20:21]
	global_load_dword v106, v[22:23], off
	global_load_dword v107, v[24:25], off
	v_mad_u64_u32 v[128:129], s[12:13], v17, s77, v[4:5]
	v_mad_u64_u32 v[130:131], s[12:13], v0, s77, v[4:5]
	s_add_i32 s13, s11, 16
	s_add_i32 s12, s7, 16
	v_or_b32_e32 v17, s13, v2
	v_or_b32_e32 v0, s12, v3
	v_add_u32_e32 v22, s0, v17
	v_add_u32_e32 v19, s2, v0
	v_mad_u64_u32 v[22:23], s[12:13], v22, s61, v[20:21]
	v_mad_u64_u32 v[24:25], s[12:13], v19, s61, v[20:21]
	global_load_dword v108, v[22:23], off
	global_load_dword v109, v[24:25], off
	v_mad_u64_u32 v[132:133], s[12:13], v17, s77, v[4:5]
	v_mad_u64_u32 v[134:135], s[12:13], v0, s77, v[4:5]
	s_add_i32 s13, s11, 20
	s_add_i32 s12, s7, 20
	v_or_b32_e32 v17, s13, v2
	v_or_b32_e32 v0, s12, v3
	v_add_u32_e32 v22, s0, v17
	v_add_u32_e32 v19, s2, v0
	v_mad_u64_u32 v[22:23], s[12:13], v22, s61, v[20:21]
	v_mad_u64_u32 v[24:25], s[12:13], v19, s61, v[20:21]
	global_load_dword v110, v[22:23], off
	global_load_dword v111, v[24:25], off
	v_mad_u64_u32 v[136:137], s[12:13], v17, s77, v[4:5]
	v_mad_u64_u32 v[138:139], s[12:13], v0, s77, v[4:5]
	s_add_i32 s13, s11, 24
	s_add_i32 s12, s7, 24
	v_or_b32_e32 v17, s13, v2
	v_or_b32_e32 v0, s12, v3
	s_add_i32 s11, s11, 28
	s_add_i32 s7, s7, 28
	s_cmp_lg_u32 s6, 0
	v_add_u32_e32 v22, s0, v17
	v_add_u32_e32 v19, s2, v0
	v_mad_u64_u32 v[22:23], s[12:13], v22, s61, v[20:21]
	v_mad_u64_u32 v[24:25], s[12:13], v19, s61, v[20:21]
	global_load_dword v112, v[22:23], off
	global_load_dword v113, v[24:25], off
	v_mad_u64_u32 v[140:141], s[12:13], v17, s77, v[4:5]
	v_or_b32_e32 v17, s11, v2
	v_mad_u64_u32 v[142:143], s[12:13], v0, s77, v[4:5]
	v_or_b32_e32 v0, s7, v3
	v_add_u32_e32 v22, s0, v17
	v_add_u32_e32 v19, s2, v0
	v_mad_u64_u32 v[22:23], s[12:13], v22, s61, v[20:21]
	v_mad_u64_u32 v[24:25], s[12:13], v19, s61, v[20:21]
	global_load_dword v114, v[22:23], off
	global_load_dword v115, v[24:25], off
	v_mad_u64_u32 v[144:145], s[12:13], v17, s77, v[4:5]
	v_mad_u64_u32 v[146:147], s[12:13], v0, s77, v[4:5]
	s_lshl_b32 s11, s5, 1
	s_lshl_b32 s7, s3, 1
	v_or_b32_e32 v17, s11, v2
	v_or_b32_e32 v0, s7, v3
	v_add_u32_e32 v22, s0, v17
	v_add_u32_e32 v19, s2, v0
	v_mad_u64_u32 v[22:23], s[12:13], v22, s61, v[20:21]
	v_mad_u64_u32 v[24:25], s[12:13], v19, s61, v[20:21]
	global_load_dword v148, v[22:23], off
	global_load_dword v149, v[24:25], off
	v_mad_u64_u32 v[164:165], s[12:13], v17, s77, v[4:5]
	v_mad_u64_u32 v[166:167], s[12:13], v0, s77, v[4:5]
	s_add_i32 s13, s11, 4
	s_add_i32 s12, s7, 4
	v_or_b32_e32 v17, s13, v2
	v_or_b32_e32 v0, s12, v3
	s_add_i32 s5, s5, 16
	s_add_i32 s3, s3, 16
	s_add_i32 s6, s6, -16
	v_add_u32_e32 v22, s0, v17
	v_add_u32_e32 v19, s2, v0
	v_mad_u64_u32 v[22:23], s[12:13], v22, s61, v[20:21]
	v_mad_u64_u32 v[24:25], s[12:13], v19, s61, v[20:21]
	global_load_dword v150, v[22:23], off
	global_load_dword v151, v[24:25], off
	v_mad_u64_u32 v[168:169], s[12:13], v17, s77, v[4:5]
	v_mad_u64_u32 v[170:171], s[12:13], v0, s77, v[4:5]
	s_add_i32 s13, s11, 8
	s_add_i32 s12, s7, 8
	v_or_b32_e32 v17, s13, v2
	v_or_b32_e32 v0, s12, v3
	v_add_u32_e32 v22, s0, v17
	v_add_u32_e32 v19, s2, v0
	v_mad_u64_u32 v[22:23], s[12:13], v22, s61, v[20:21]
	v_mad_u64_u32 v[24:25], s[12:13], v19, s61, v[20:21]
	global_load_dword v152, v[22:23], off
	global_load_dword v153, v[24:25], off
	v_mad_u64_u32 v[172:173], s[12:13], v17, s77, v[4:5]
	v_mad_u64_u32 v[174:175], s[12:13], v0, s77, v[4:5]
	s_add_i32 s13, s11, 12
	s_add_i32 s12, s7, 12
	v_or_b32_e32 v17, s13, v2
	v_or_b32_e32 v0, s12, v3
	v_add_u32_e32 v22, s0, v17
	v_add_u32_e32 v19, s2, v0
	v_mad_u64_u32 v[22:23], s[12:13], v22, s61, v[20:21]
	v_mad_u64_u32 v[24:25], s[12:13], v19, s61, v[20:21]
	global_load_dword v154, v[22:23], off
	global_load_dword v155, v[24:25], off
	v_mad_u64_u32 v[176:177], s[12:13], v17, s77, v[4:5]
	v_mad_u64_u32 v[178:179], s[12:13], v0, s77, v[4:5]
	s_add_i32 s13, s11, 16
	s_add_i32 s12, s7, 16
	v_or_b32_e32 v17, s13, v2
	v_or_b32_e32 v0, s12, v3
	v_add_u32_e32 v22, s0, v17
	v_add_u32_e32 v19, s2, v0
	v_mad_u64_u32 v[22:23], s[12:13], v22, s61, v[20:21]
	v_mad_u64_u32 v[24:25], s[12:13], v19, s61, v[20:21]
	global_load_dword v156, v[22:23], off
	global_load_dword v157, v[24:25], off
	v_mad_u64_u32 v[180:181], s[12:13], v17, s77, v[4:5]
	v_mad_u64_u32 v[182:183], s[12:13], v0, s77, v[4:5]
	s_add_i32 s13, s11, 20
	s_add_i32 s12, s7, 20
	v_or_b32_e32 v17, s13, v2
	v_or_b32_e32 v0, s12, v3
	v_add_u32_e32 v22, s0, v17
	v_add_u32_e32 v19, s2, v0
	v_mad_u64_u32 v[22:23], s[12:13], v22, s61, v[20:21]
	v_mad_u64_u32 v[24:25], s[12:13], v19, s61, v[20:21]
	global_load_dword v158, v[22:23], off
	global_load_dword v159, v[24:25], off
	v_mad_u64_u32 v[184:185], s[12:13], v17, s77, v[4:5]
	v_mad_u64_u32 v[186:187], s[12:13], v0, s77, v[4:5]
	s_add_i32 s13, s11, 24
	s_add_i32 s12, s7, 24
	v_or_b32_e32 v17, s13, v2
	v_or_b32_e32 v0, s12, v3
	s_add_i32 s11, s11, 28
	s_add_i32 s7, s7, 28
	s_cmp_lg_u32 s6, 0
	v_add_u32_e32 v22, s0, v17
	v_add_u32_e32 v19, s2, v0
	v_mad_u64_u32 v[22:23], s[12:13], v22, s61, v[20:21]
	v_mad_u64_u32 v[24:25], s[12:13], v19, s61, v[20:21]
	global_load_dword v160, v[22:23], off
	global_load_dword v161, v[24:25], off
	v_mad_u64_u32 v[188:189], s[12:13], v17, s77, v[4:5]
	v_or_b32_e32 v17, s11, v2
	v_mad_u64_u32 v[190:191], s[12:13], v0, s77, v[4:5]
	v_or_b32_e32 v0, s7, v3
	v_add_u32_e32 v22, s0, v17
	v_add_u32_e32 v19, s2, v0
	v_mad_u64_u32 v[22:23], s[12:13], v22, s61, v[20:21]
	v_mad_u64_u32 v[24:25], s[12:13], v19, s61, v[20:21]
	global_load_dword v162, v[22:23], off
	global_load_dword v163, v[24:25], off
	v_mad_u64_u32 v[192:193], s[12:13], v17, s77, v[4:5]
	v_mad_u64_u32 v[196:197], s[12:13], v0, s77, v[4:5]
	s_waitcnt vmcnt(0)
	ds_write_b32 v116, v100
	ds_write_b32 v118, v101
	ds_write_b32 v120, v102
	ds_write_b32 v122, v103
	ds_write_b32 v124, v104
	ds_write_b32 v126, v105
	ds_write_b32 v128, v106
	ds_write_b32 v130, v107
	ds_write_b32 v132, v108
	ds_write_b32 v134, v109
	ds_write_b32 v136, v110
	ds_write_b32 v138, v111
	ds_write_b32 v140, v112
	ds_write_b32 v142, v113
	ds_write_b32 v144, v114
	ds_write_b32 v146, v115
	ds_write_b32 v164, v148
	ds_write_b32 v166, v149
	ds_write_b32 v168, v150
	ds_write_b32 v170, v151
	ds_write_b32 v172, v152
	ds_write_b32 v174, v153
	ds_write_b32 v176, v154
	ds_write_b32 v178, v155
	ds_write_b32 v180, v156
	ds_write_b32 v182, v157
	ds_write_b32 v184, v158
	ds_write_b32 v186, v159
	ds_write_b32 v188, v160
	ds_write_b32 v190, v161
	ds_write_b32 v192, v162
	ds_write_b32 v196, v163
	s_cbranch_scc1 .LBB0_172
	s_mulk_i32 s1, 0x6000
	s_add_u32 s1, s50, s1
	s_addc_u32 s2, s51, 0
	s_lshl_b32 s0, s0, 1
	s_add_u32 s0, s1, s0
	s_addc_u32 s1, s2, 0
	v_mov_b32_e32 v0, v37
	v_mov_b32_e32 v20, v36
	v_mov_b32_e32 v22, v35
	v_mov_b32_e32 v24, v34

.LBB0_177:
	s_lshl_b32 s11, s5, 1
	s_lshl_b32 s7, s2, 1
	v_or_b32_e32 v19, s11, v2
	v_or_b32_e32 v17, s7, v3
	v_add_u32_e32 v0, s1, v19
	v_add_u32_e32 v22, s3, v17
	v_mov_b32_e32 v23, v1
	v_lshlrev_b64 v[24:25], 14, v[0:1]
	v_lshlrev_b64 v[22:23], 14, v[22:23]
	v_lshl_add_u64 v[24:25], v[20:21], 0, v[24:25]
	v_lshl_add_u64 v[22:23], v[20:21], 0, v[22:23]
	global_load_dword v100, v[24:25], off
	global_load_dword v101, v[22:23], off
	v_mad_u64_u32 v[116:117], s[12:13], v19, s77, v[4:5]
	v_mad_u64_u32 v[118:119], s[12:13], v17, s77, v[4:5]
	s_add_i32 s13, s11, 4
	s_add_i32 s12, s7, 4
	v_or_b32_e32 v19, s13, v2
	v_or_b32_e32 v17, s12, v3
	v_mov_b32_e32 v23, v1
	s_add_i32 s5, s5, 16
	s_add_i32 s2, s2, 16
	s_add_i32 s6, s6, -16
	v_add_u32_e32 v0, s1, v19
	v_add_u32_e32 v22, s3, v17
	v_lshlrev_b64 v[24:25], 14, v[0:1]
	v_lshlrev_b64 v[22:23], 14, v[22:23]
	v_lshl_add_u64 v[24:25], v[20:21], 0, v[24:25]
	v_lshl_add_u64 v[22:23], v[20:21], 0, v[22:23]
	global_load_dword v102, v[24:25], off
	global_load_dword v103, v[22:23], off
	v_mad_u64_u32 v[120:121], s[12:13], v19, s77, v[4:5]
	v_mad_u64_u32 v[122:123], s[12:13], v17, s77, v[4:5]
	s_add_i32 s13, s11, 8
	s_add_i32 s12, s7, 8
	v_or_b32_e32 v19, s13, v2
	v_or_b32_e32 v17, s12, v3
	v_mov_b32_e32 v23, v1
	v_add_u32_e32 v0, s1, v19
	v_add_u32_e32 v22, s3, v17
	v_lshlrev_b64 v[24:25], 14, v[0:1]
	v_lshlrev_b64 v[22:23], 14, v[22:23]
	v_lshl_add_u64 v[24:25], v[20:21], 0, v[24:25]
	v_lshl_add_u64 v[22:23], v[20:21], 0, v[22:23]
	global_load_dword v104, v[24:25], off
	global_load_dword v105, v[22:23], off
	v_mad_u64_u32 v[124:125], s[12:13], v19, s77, v[4:5]
	v_mad_u64_u32 v[126:127], s[12:13], v17, s77, v[4:5]
	s_add_i32 s13, s11, 12
	s_add_i32 s12, s7, 12
	v_or_b32_e32 v19, s13, v2
	v_or_b32_e32 v17, s12, v3
	v_mov_b32_e32 v23, v1
	v_add_u32_e32 v0, s1, v19
	v_add_u32_e32 v22, s3, v17
	v_lshlrev_b64 v[24:25], 14, v[0:1]
	v_lshlrev_b64 v[22:23], 14, v[22:23]
	v_lshl_add_u64 v[24:25], v[20:21], 0, v[24:25]
	v_lshl_add_u64 v[22:23], v[20:21], 0, v[22:23]
	global_load_dword v106, v[24:25], off
	global_load_dword v107, v[22:23], off
	v_mad_u64_u32 v[128:129], s[12:13], v19, s77, v[4:5]
	v_mad_u64_u32 v[130:131], s[12:13], v17, s77, v[4:5]
	s_add_i32 s13, s11, 16
	s_add_i32 s12, s7, 16
	v_or_b32_e32 v19, s13, v2
	v_or_b32_e32 v17, s12, v3
	v_mov_b32_e32 v23, v1
	v_add_u32_e32 v0, s1, v19
	v_add_u32_e32 v22, s3, v17
	v_lshlrev_b64 v[24:25], 14, v[0:1]
	v_lshlrev_b64 v[22:23], 14, v[22:23]
	v_lshl_add_u64 v[24:25], v[20:21], 0, v[24:25]
	v_lshl_add_u64 v[22:23], v[20:21], 0, v[22:23]
	global_load_dword v108, v[24:25], off
	global_load_dword v109, v[22:23], off
	v_mad_u64_u32 v[132:133], s[12:13], v19, s77, v[4:5]
	v_mad_u64_u32 v[134:135], s[12:13], v17, s77, v[4:5]
	s_add_i32 s13, s11, 20
	s_add_i32 s12, s7, 20
	v_or_b32_e32 v19, s13, v2
	v_or_b32_e32 v17, s12, v3
	v_mov_b32_e32 v23, v1
	v_add_u32_e32 v0, s1, v19
	v_add_u32_e32 v22, s3, v17
	v_lshlrev_b64 v[24:25], 14, v[0:1]
	v_lshlrev_b64 v[22:23], 14, v[22:23]
	v_lshl_add_u64 v[24:25], v[20:21], 0, v[24:25]
	v_lshl_add_u64 v[22:23], v[20:21], 0, v[22:23]
	global_load_dword v110, v[24:25], off
	global_load_dword v111, v[22:23], off
	v_mad_u64_u32 v[136:137], s[12:13], v19, s77, v[4:5]
	v_mad_u64_u32 v[138:139], s[12:13], v17, s77, v[4:5]
	s_add_i32 s13, s11, 24
	s_add_i32 s12, s7, 24
	v_or_b32_e32 v19, s13, v2
	v_or_b32_e32 v17, s12, v3
	v_mov_b32_e32 v23, v1
	s_add_i32 s11, s11, 28
	s_add_i32 s7, s7, 28
	s_cmp_lg_u32 s6, 0
	v_add_u32_e32 v0, s1, v19
	v_add_u32_e32 v22, s3, v17
	v_lshlrev_b64 v[24:25], 14, v[0:1]
	v_lshlrev_b64 v[22:23], 14, v[22:23]
	v_lshl_add_u64 v[24:25], v[20:21], 0, v[24:25]
	v_lshl_add_u64 v[22:23], v[20:21], 0, v[22:23]
	global_load_dword v112, v[24:25], off
	global_load_dword v113, v[22:23], off
	v_mad_u64_u32 v[140:141], s[12:13], v19, s77, v[4:5]
	v_or_b32_e32 v19, s11, v2
	v_mad_u64_u32 v[142:143], s[12:13], v17, s77, v[4:5]
	v_or_b32_e32 v17, s7, v3
	v_mov_b32_e32 v23, v1
	v_add_u32_e32 v0, s1, v19
	v_add_u32_e32 v22, s3, v17
	v_lshlrev_b64 v[24:25], 14, v[0:1]
	v_lshlrev_b64 v[22:23], 14, v[22:23]
	v_lshl_add_u64 v[24:25], v[20:21], 0, v[24:25]
	v_lshl_add_u64 v[22:23], v[20:21], 0, v[22:23]
	global_load_dword v114, v[24:25], off
	global_load_dword v115, v[22:23], off
	v_mad_u64_u32 v[144:145], s[12:13], v19, s77, v[4:5]
	v_mad_u64_u32 v[146:147], s[12:13], v17, s77, v[4:5]
	s_lshl_b32 s11, s5, 1
	s_lshl_b32 s7, s2, 1
	v_or_b32_e32 v19, s11, v2
	v_or_b32_e32 v17, s7, v3
	v_add_u32_e32 v0, s1, v19
	v_add_u32_e32 v22, s3, v17
	v_mov_b32_e32 v23, v1
	v_lshlrev_b64 v[24:25], 14, v[0:1]
	v_lshlrev_b64 v[22:23], 14, v[22:23]
	v_lshl_add_u64 v[24:25], v[20:21], 0, v[24:25]
	v_lshl_add_u64 v[22:23], v[20:21], 0, v[22:23]
	global_load_dword v148, v[24:25], off
	global_load_dword v149, v[22:23], off
	v_mad_u64_u32 v[164:165], s[12:13], v19, s77, v[4:5]
	v_mad_u64_u32 v[166:167], s[12:13], v17, s77, v[4:5]
	s_add_i32 s13, s11, 4
	s_add_i32 s12, s7, 4
	v_or_b32_e32 v19, s13, v2
	v_or_b32_e32 v17, s12, v3
	v_mov_b32_e32 v23, v1
	s_add_i32 s5, s5, 16
	s_add_i32 s2, s2, 16
	s_add_i32 s6, s6, -16
	v_add_u32_e32 v0, s1, v19
	v_add_u32_e32 v22, s3, v17
	v_lshlrev_b64 v[24:25], 14, v[0:1]
	v_lshlrev_b64 v[22:23], 14, v[22:23]
	v_lshl_add_u64 v[24:25], v[20:21], 0, v[24:25]
	v_lshl_add_u64 v[22:23], v[20:21], 0, v[22:23]
	global_load_dword v150, v[24:25], off
	global_load_dword v151, v[22:23], off
	v_mad_u64_u32 v[168:169], s[12:13], v19, s77, v[4:5]
	v_mad_u64_u32 v[170:171], s[12:13], v17, s77, v[4:5]
	s_add_i32 s13, s11, 8
	s_add_i32 s12, s7, 8
	v_or_b32_e32 v19, s13, v2
	v_or_b32_e32 v17, s12, v3
	v_mov_b32_e32 v23, v1
	v_add_u32_e32 v0, s1, v19
	v_add_u32_e32 v22, s3, v17
	v_lshlrev_b64 v[24:25], 14, v[0:1]
	v_lshlrev_b64 v[22:23], 14, v[22:23]
	v_lshl_add_u64 v[24:25], v[20:21], 0, v[24:25]
	v_lshl_add_u64 v[22:23], v[20:21], 0, v[22:23]
	global_load_dword v152, v[24:25], off
	global_load_dword v153, v[22:23], off
	v_mad_u64_u32 v[172:173], s[12:13], v19, s77, v[4:5]
	v_mad_u64_u32 v[174:175], s[12:13], v17, s77, v[4:5]
	s_add_i32 s13, s11, 12
	s_add_i32 s12, s7, 12
	v_or_b32_e32 v19, s13, v2
	v_or_b32_e32 v17, s12, v3
	v_mov_b32_e32 v23, v1
	v_add_u32_e32 v0, s1, v19
	v_add_u32_e32 v22, s3, v17
	v_lshlrev_b64 v[24:25], 14, v[0:1]
	v_lshlrev_b64 v[22:23], 14, v[22:23]
	v_lshl_add_u64 v[24:25], v[20:21], 0, v[24:25]
	v_lshl_add_u64 v[22:23], v[20:21], 0, v[22:23]
	global_load_dword v154, v[24:25], off
	global_load_dword v155, v[22:23], off
	v_mad_u64_u32 v[176:177], s[12:13], v19, s77, v[4:5]
	v_mad_u64_u32 v[178:179], s[12:13], v17, s77, v[4:5]
	s_add_i32 s13, s11, 16
	s_add_i32 s12, s7, 16
	v_or_b32_e32 v19, s13, v2
	v_or_b32_e32 v17, s12, v3
	v_mov_b32_e32 v23, v1
	v_add_u32_e32 v0, s1, v19
	v_add_u32_e32 v22, s3, v17
	v_lshlrev_b64 v[24:25], 14, v[0:1]
	v_lshlrev_b64 v[22:23], 14, v[22:23]
	v_lshl_add_u64 v[24:25], v[20:21], 0, v[24:25]
	v_lshl_add_u64 v[22:23], v[20:21], 0, v[22:23]
	global_load_dword v156, v[24:25], off
	global_load_dword v157, v[22:23], off
	v_mad_u64_u32 v[180:181], s[12:13], v19, s77, v[4:5]
	v_mad_u64_u32 v[182:183], s[12:13], v17, s77, v[4:5]
	s_add_i32 s13, s11, 20
	s_add_i32 s12, s7, 20
	v_or_b32_e32 v19, s13, v2
	v_or_b32_e32 v17, s12, v3
	v_mov_b32_e32 v23, v1
	v_add_u32_e32 v0, s1, v19
	v_add_u32_e32 v22, s3, v17
	v_lshlrev_b64 v[24:25], 14, v[0:1]
	v_lshlrev_b64 v[22:23], 14, v[22:23]
	v_lshl_add_u64 v[24:25], v[20:21], 0, v[24:25]
	v_lshl_add_u64 v[22:23], v[20:21], 0, v[22:23]
	global_load_dword v158, v[24:25], off
	global_load_dword v159, v[22:23], off
	v_mad_u64_u32 v[184:185], s[12:13], v19, s77, v[4:5]
	v_mad_u64_u32 v[186:187], s[12:13], v17, s77, v[4:5]
	s_add_i32 s13, s11, 24
	s_add_i32 s12, s7, 24
	v_or_b32_e32 v19, s13, v2
	v_or_b32_e32 v17, s12, v3
	v_mov_b32_e32 v23, v1
	s_add_i32 s11, s11, 28
	s_add_i32 s7, s7, 28
	s_cmp_lg_u32 s6, 0
	v_add_u32_e32 v0, s1, v19
	v_add_u32_e32 v22, s3, v17
	v_lshlrev_b64 v[24:25], 14, v[0:1]
	v_lshlrev_b64 v[22:23], 14, v[22:23]
	v_lshl_add_u64 v[24:25], v[20:21], 0, v[24:25]
	v_lshl_add_u64 v[22:23], v[20:21], 0, v[22:23]
	global_load_dword v160, v[24:25], off
	global_load_dword v161, v[22:23], off
	v_mad_u64_u32 v[188:189], s[12:13], v19, s77, v[4:5]
	v_or_b32_e32 v19, s11, v2
	v_mad_u64_u32 v[190:191], s[12:13], v17, s77, v[4:5]
	v_or_b32_e32 v17, s7, v3
	v_mov_b32_e32 v23, v1
	v_add_u32_e32 v0, s1, v19
	v_add_u32_e32 v22, s3, v17
	v_lshlrev_b64 v[24:25], 14, v[0:1]
	v_lshlrev_b64 v[22:23], 14, v[22:23]
	v_lshl_add_u64 v[24:25], v[20:21], 0, v[24:25]
	v_lshl_add_u64 v[22:23], v[20:21], 0, v[22:23]
	global_load_dword v162, v[24:25], off
	global_load_dword v163, v[22:23], off
	v_mad_u64_u32 v[192:193], s[12:13], v19, s77, v[4:5]
	v_mad_u64_u32 v[196:197], s[12:13], v17, s77, v[4:5]
	s_waitcnt vmcnt(0)
	ds_write_b32 v116, v100
	ds_write_b32 v118, v101
	ds_write_b32 v120, v102
	ds_write_b32 v122, v103
	ds_write_b32 v124, v104
	ds_write_b32 v126, v105
	ds_write_b32 v128, v106
	ds_write_b32 v130, v107
	ds_write_b32 v132, v108
	ds_write_b32 v134, v109
	ds_write_b32 v136, v110
	ds_write_b32 v138, v111
	ds_write_b32 v140, v112
	ds_write_b32 v142, v113
	ds_write_b32 v144, v114
	ds_write_b32 v146, v115
	ds_write_b32 v164, v148
	ds_write_b32 v166, v149
	ds_write_b32 v168, v150
	ds_write_b32 v170, v151
	ds_write_b32 v172, v152
	ds_write_b32 v174, v153
	ds_write_b32 v176, v154
	ds_write_b32 v178, v155
	ds_write_b32 v180, v156
	ds_write_b32 v182, v157
	ds_write_b32 v184, v158
	ds_write_b32 v186, v159
	ds_write_b32 v188, v160
	ds_write_b32 v190, v161
	ds_write_b32 v192, v162
	ds_write_b32 v196, v163
	s_cbranch_scc1 .LBB0_177
	s_lshl_b32 s0, s0, 11
	s_add_u32 s0, s18, s0
	s_addc_u32 s2, s19, 0
	s_lshl_b32 s1, s1, 1
	s_add_u32 s0, s0, s1
	s_addc_u32 s1, s2, 0
	s_add_u32 s0, s0, 0x680000
	s_addc_u32 s1, s1, 0
	v_mov_b32_e32 v0, v41
	v_mov_b32_e32 v20, v40
	v_mov_b32_e32 v22, v39
	v_mov_b32_e32 v24, v38

.LBB0_182:
	s_lshl_b32 s12, s3, 1
	s_lshl_b32 s11, s2, 1
	v_or_b32_e32 v17, s12, v2
	v_or_b32_e32 v0, s11, v3
	v_add_u32_e32 v22, s0, v17
	v_add_u32_e32 v19, s1, v0
	v_mad_i64_i32 v[22:23], s[14:15], v22, s62, v[20:21]
	v_mad_i64_i32 v[24:25], s[14:15], v19, s62, v[20:21]
	global_load_dword v100, v[22:23], off
	global_load_dword v101, v[24:25], off
	v_mad_u64_u32 v[116:117], s[14:15], v17, s77, v[4:5]
	v_mad_u64_u32 v[118:119], s[14:15], v0, s77, v[4:5]
	s_add_i32 s14, s12, 4
	s_add_i32 s13, s11, 4
	v_or_b32_e32 v17, s14, v2
	v_or_b32_e32 v0, s13, v3
	s_add_i32 s13, s11, 8
	s_add_i32 s3, s3, 16
	s_add_i32 s2, s2, 16
	s_add_i32 s5, s5, -16
	v_add_u32_e32 v22, s0, v17
	v_add_u32_e32 v19, s1, v0
	v_mad_i64_i32 v[22:23], s[14:15], v22, s62, v[20:21]
	v_mad_i64_i32 v[24:25], s[14:15], v19, s62, v[20:21]
	global_load_dword v102, v[22:23], off
	global_load_dword v103, v[24:25], off
	v_mad_u64_u32 v[120:121], s[14:15], v17, s77, v[4:5]
	v_mad_u64_u32 v[122:123], s[14:15], v0, s77, v[4:5]
	s_add_i32 s14, s12, 8
	s_nop 0
	v_or_b32_e32 v17, s14, v2
	v_or_b32_e32 v0, s13, v3
	s_add_i32 s13, s11, 12
	v_add_u32_e32 v22, s0, v17
	v_add_u32_e32 v19, s1, v0
	v_mad_i64_i32 v[22:23], s[14:15], v22, s62, v[20:21]
	v_mad_i64_i32 v[24:25], s[14:15], v19, s62, v[20:21]
	global_load_dword v104, v[22:23], off
	global_load_dword v105, v[24:25], off
	v_mad_u64_u32 v[124:125], s[14:15], v17, s77, v[4:5]
	v_mad_u64_u32 v[126:127], s[14:15], v0, s77, v[4:5]
	s_add_i32 s14, s12, 12
	s_nop 0
	v_or_b32_e32 v17, s14, v2
	v_or_b32_e32 v0, s13, v3
	s_add_i32 s13, s11, 16
	v_add_u32_e32 v22, s0, v17
	v_add_u32_e32 v19, s1, v0
	v_mad_i64_i32 v[22:23], s[14:15], v22, s62, v[20:21]
	v_mad_i64_i32 v[24:25], s[14:15], v19, s62, v[20:21]
	global_load_dword v106, v[22:23], off
	global_load_dword v107, v[24:25], off
	v_mad_u64_u32 v[128:129], s[14:15], v17, s77, v[4:5]
	v_mad_u64_u32 v[130:131], s[14:15], v0, s77, v[4:5]
	s_add_i32 s14, s12, 16
	s_nop 0
	v_or_b32_e32 v17, s14, v2
	v_or_b32_e32 v0, s13, v3
	s_add_i32 s13, s11, 20
	v_add_u32_e32 v22, s0, v17
	v_add_u32_e32 v19, s1, v0
	v_mad_i64_i32 v[22:23], s[14:15], v22, s62, v[20:21]
	v_mad_i64_i32 v[24:25], s[14:15], v19, s62, v[20:21]
	global_load_dword v108, v[22:23], off
	global_load_dword v109, v[24:25], off
	v_mad_u64_u32 v[132:133], s[14:15], v17, s77, v[4:5]
	v_mad_u64_u32 v[134:135], s[14:15], v0, s77, v[4:5]
	s_add_i32 s14, s12, 20
	s_nop 0
	v_or_b32_e32 v17, s14, v2
	v_or_b32_e32 v0, s13, v3
	s_add_i32 s13, s11, 24
	s_add_i32 s11, s11, 28
	v_add_u32_e32 v22, s0, v17
	v_add_u32_e32 v19, s1, v0
	v_mad_i64_i32 v[22:23], s[14:15], v22, s62, v[20:21]
	v_mad_i64_i32 v[24:25], s[14:15], v19, s62, v[20:21]
	global_load_dword v110, v[22:23], off
	global_load_dword v111, v[24:25], off
	v_mad_u64_u32 v[136:137], s[14:15], v17, s77, v[4:5]
	v_mad_u64_u32 v[138:139], s[14:15], v0, s77, v[4:5]
	s_add_i32 s14, s12, 24
	s_nop 0
	v_or_b32_e32 v17, s14, v2
	v_or_b32_e32 v0, s13, v3
	s_add_i32 s12, s12, 28
	s_cmp_lg_u32 s5, 0
	v_add_u32_e32 v22, s0, v17
	v_add_u32_e32 v19, s1, v0
	v_mad_i64_i32 v[22:23], s[14:15], v22, s62, v[20:21]
	v_mad_i64_i32 v[24:25], s[14:15], v19, s62, v[20:21]
	global_load_dword v112, v[22:23], off
	global_load_dword v113, v[24:25], off
	v_mad_u64_u32 v[140:141], s[14:15], v17, s77, v[4:5]
	v_or_b32_e32 v17, s12, v2
	v_mad_u64_u32 v[142:143], s[14:15], v0, s77, v[4:5]
	v_or_b32_e32 v0, s11, v3
	v_add_u32_e32 v22, s0, v17
	v_add_u32_e32 v19, s1, v0
	v_mad_i64_i32 v[22:23], s[12:13], v22, s62, v[20:21]
	v_mad_i64_i32 v[24:25], s[12:13], v19, s62, v[20:21]
	global_load_dword v114, v[22:23], off
	global_load_dword v115, v[24:25], off
	v_mad_u64_u32 v[144:145], s[12:13], v17, s77, v[4:5]
	v_mad_u64_u32 v[146:147], s[12:13], v0, s77, v[4:5]
	s_lshl_b32 s12, s3, 1
	s_lshl_b32 s11, s2, 1
	v_or_b32_e32 v17, s12, v2
	v_or_b32_e32 v0, s11, v3
	v_add_u32_e32 v22, s0, v17
	v_add_u32_e32 v19, s1, v0
	v_mad_i64_i32 v[22:23], s[14:15], v22, s62, v[20:21]
	v_mad_i64_i32 v[24:25], s[14:15], v19, s62, v[20:21]
	global_load_dword v148, v[22:23], off
	global_load_dword v149, v[24:25], off
	v_mad_u64_u32 v[164:165], s[14:15], v17, s77, v[4:5]
	v_mad_u64_u32 v[166:167], s[14:15], v0, s77, v[4:5]
	s_add_i32 s14, s12, 4
	s_add_i32 s13, s11, 4
	v_or_b32_e32 v17, s14, v2
	v_or_b32_e32 v0, s13, v3
	s_add_i32 s13, s11, 8
	s_add_i32 s3, s3, 16
	s_add_i32 s2, s2, 16
	s_add_i32 s5, s5, -16
	v_add_u32_e32 v22, s0, v17
	v_add_u32_e32 v19, s1, v0
	v_mad_i64_i32 v[22:23], s[14:15], v22, s62, v[20:21]
	v_mad_i64_i32 v[24:25], s[14:15], v19, s62, v[20:21]
	global_load_dword v150, v[22:23], off
	global_load_dword v151, v[24:25], off
	v_mad_u64_u32 v[168:169], s[14:15], v17, s77, v[4:5]
	v_mad_u64_u32 v[170:171], s[14:15], v0, s77, v[4:5]
	s_add_i32 s14, s12, 8
	s_nop 0
	v_or_b32_e32 v17, s14, v2
	v_or_b32_e32 v0, s13, v3
	s_add_i32 s13, s11, 12
	v_add_u32_e32 v22, s0, v17
	v_add_u32_e32 v19, s1, v0
	v_mad_i64_i32 v[22:23], s[14:15], v22, s62, v[20:21]
	v_mad_i64_i32 v[24:25], s[14:15], v19, s62, v[20:21]
	global_load_dword v152, v[22:23], off
	global_load_dword v153, v[24:25], off
	v_mad_u64_u32 v[172:173], s[14:15], v17, s77, v[4:5]
	v_mad_u64_u32 v[174:175], s[14:15], v0, s77, v[4:5]
	s_add_i32 s14, s12, 12
	s_nop 0
	v_or_b32_e32 v17, s14, v2
	v_or_b32_e32 v0, s13, v3
	s_add_i32 s13, s11, 16
	v_add_u32_e32 v22, s0, v17
	v_add_u32_e32 v19, s1, v0
	v_mad_i64_i32 v[22:23], s[14:15], v22, s62, v[20:21]
	v_mad_i64_i32 v[24:25], s[14:15], v19, s62, v[20:21]
	global_load_dword v154, v[22:23], off
	global_load_dword v155, v[24:25], off
	v_mad_u64_u32 v[176:177], s[14:15], v17, s77, v[4:5]
	v_mad_u64_u32 v[178:179], s[14:15], v0, s77, v[4:5]
	s_add_i32 s14, s12, 16
	s_nop 0
	v_or_b32_e32 v17, s14, v2
	v_or_b32_e32 v0, s13, v3
	s_add_i32 s13, s11, 20
	v_add_u32_e32 v22, s0, v17
	v_add_u32_e32 v19, s1, v0
	v_mad_i64_i32 v[22:23], s[14:15], v22, s62, v[20:21]
	v_mad_i64_i32 v[24:25], s[14:15], v19, s62, v[20:21]
	global_load_dword v156, v[22:23], off
	global_load_dword v157, v[24:25], off
	v_mad_u64_u32 v[180:181], s[14:15], v17, s77, v[4:5]
	v_mad_u64_u32 v[182:183], s[14:15], v0, s77, v[4:5]
	s_add_i32 s14, s12, 20
	s_nop 0
	v_or_b32_e32 v17, s14, v2
	v_or_b32_e32 v0, s13, v3
	s_add_i32 s13, s11, 24
	s_add_i32 s11, s11, 28
	v_add_u32_e32 v22, s0, v17
	v_add_u32_e32 v19, s1, v0
	v_mad_i64_i32 v[22:23], s[14:15], v22, s62, v[20:21]
	v_mad_i64_i32 v[24:25], s[14:15], v19, s62, v[20:21]
	global_load_dword v158, v[22:23], off
	global_load_dword v159, v[24:25], off
	v_mad_u64_u32 v[184:185], s[14:15], v17, s77, v[4:5]
	v_mad_u64_u32 v[186:187], s[14:15], v0, s77, v[4:5]
	s_add_i32 s14, s12, 24
	s_nop 0
	v_or_b32_e32 v17, s14, v2
	v_or_b32_e32 v0, s13, v3
	s_add_i32 s12, s12, 28
	s_cmp_lg_u32 s5, 0
	v_add_u32_e32 v22, s0, v17
	v_add_u32_e32 v19, s1, v0
	v_mad_i64_i32 v[22:23], s[14:15], v22, s62, v[20:21]
	v_mad_i64_i32 v[24:25], s[14:15], v19, s62, v[20:21]
	global_load_dword v160, v[22:23], off
	global_load_dword v161, v[24:25], off
	v_mad_u64_u32 v[188:189], s[14:15], v17, s77, v[4:5]
	v_or_b32_e32 v17, s12, v2
	v_mad_u64_u32 v[190:191], s[14:15], v0, s77, v[4:5]
	v_or_b32_e32 v0, s11, v3
	v_add_u32_e32 v22, s0, v17
	v_add_u32_e32 v19, s1, v0
	v_mad_i64_i32 v[22:23], s[12:13], v22, s62, v[20:21]
	v_mad_i64_i32 v[24:25], s[12:13], v19, s62, v[20:21]
	global_load_dword v162, v[22:23], off
	global_load_dword v163, v[24:25], off
	v_mad_u64_u32 v[192:193], s[12:13], v17, s77, v[4:5]
	v_mad_u64_u32 v[196:197], s[12:13], v0, s77, v[4:5]
	s_waitcnt vmcnt(0)
	ds_write_b32 v116, v100
	ds_write_b32 v118, v101
	ds_write_b32 v120, v102
	ds_write_b32 v122, v103
	ds_write_b32 v124, v104
	ds_write_b32 v126, v105
	ds_write_b32 v128, v106
	ds_write_b32 v130, v107
	ds_write_b32 v132, v108
	ds_write_b32 v134, v109
	ds_write_b32 v136, v110
	ds_write_b32 v138, v111
	ds_write_b32 v140, v112
	ds_write_b32 v142, v113
	ds_write_b32 v144, v114
	ds_write_b32 v146, v115
	ds_write_b32 v164, v148
	ds_write_b32 v166, v149
	ds_write_b32 v168, v150
	ds_write_b32 v170, v151
	ds_write_b32 v172, v152
	ds_write_b32 v174, v153
	ds_write_b32 v176, v154
	ds_write_b32 v178, v155
	ds_write_b32 v180, v156
	ds_write_b32 v182, v157
	ds_write_b32 v184, v158
	ds_write_b32 v186, v159
	ds_write_b32 v188, v160
	ds_write_b32 v190, v161
	ds_write_b32 v192, v162
	ds_write_b32 v196, v163
	s_cbranch_scc1 .LBB0_182
	s_lshl_b64 s[2:3], s[6:7], 11
	s_add_u32 s2, s18, s2
	s_addc_u32 s3, s19, s3
	s_ashr_i32 s1, s0, 31
	s_lshl_b64 s[0:1], s[0:1], 1
	s_add_u32 s0, s2, s0
	s_addc_u32 s1, s3, s1
	v_mov_b32_e32 v0, v41
	v_mov_b32_e32 v20, v40
	v_mov_b32_e32 v22, v39
	v_mov_b32_e32 v24, v38
	s_branch .LBB0_147

.LBB0_338:
	s_lshl_b32 s10, s6, 1
	s_lshl_b32 s9, s3, 1
	v_or_b32_e32 v17, s10, v2
	v_or_b32_e32 v0, s9, v3
	v_add_u32_e32 v22, s0, v17
	v_add_u32_e32 v20, s2, v0
	v_ashrrev_i32_e32 v23, 31, v22
	v_ashrrev_i32_e32 v21, 31, v20
	v_lshlrev_b64 v[22:23], 11, v[22:23]
	v_lshlrev_b64 v[20:21], 11, v[20:21]
	v_lshl_add_u64 v[22:23], v[18:19], 0, v[22:23]
	v_lshl_add_u64 v[20:21], v[18:19], 0, v[20:21]
	global_load_dword v100, v[22:23], off
	global_load_dword v101, v[20:21], off
	v_mad_u64_u32 v[116:117], s[12:13], v17, s77, v[6:7]
	v_mad_u64_u32 v[118:119], s[12:13], v0, s77, v[6:7]
	s_add_i32 s12, s10, 4
	s_add_i32 s11, s9, 4
	v_or_b32_e32 v17, s12, v2
	v_or_b32_e32 v0, s11, v3
	s_add_i32 s11, s9, 8
	s_add_i32 s6, s6, 16
	s_add_i32 s3, s3, 16
	s_add_i32 s7, s7, -16
	v_add_u32_e32 v22, s0, v17
	v_add_u32_e32 v20, s2, v0
	v_ashrrev_i32_e32 v23, 31, v22
	v_ashrrev_i32_e32 v21, 31, v20
	v_lshlrev_b64 v[22:23], 11, v[22:23]
	v_lshlrev_b64 v[20:21], 11, v[20:21]
	v_lshl_add_u64 v[22:23], v[18:19], 0, v[22:23]
	v_lshl_add_u64 v[20:21], v[18:19], 0, v[20:21]
	global_load_dword v102, v[22:23], off
	global_load_dword v103, v[20:21], off
	v_mad_u64_u32 v[120:121], s[12:13], v17, s77, v[6:7]
	v_mad_u64_u32 v[122:123], s[12:13], v0, s77, v[6:7]
	s_add_i32 s12, s10, 8
	s_nop 0
	v_or_b32_e32 v17, s12, v2
	v_or_b32_e32 v0, s11, v3
	s_add_i32 s11, s9, 12
	v_add_u32_e32 v22, s0, v17
	v_add_u32_e32 v20, s2, v0
	v_ashrrev_i32_e32 v23, 31, v22
	v_ashrrev_i32_e32 v21, 31, v20
	v_lshlrev_b64 v[22:23], 11, v[22:23]
	v_lshlrev_b64 v[20:21], 11, v[20:21]
	v_lshl_add_u64 v[22:23], v[18:19], 0, v[22:23]
	v_lshl_add_u64 v[20:21], v[18:19], 0, v[20:21]
	global_load_dword v104, v[22:23], off
	global_load_dword v105, v[20:21], off
	v_mad_u64_u32 v[124:125], s[12:13], v17, s77, v[6:7]
	v_mad_u64_u32 v[126:127], s[12:13], v0, s77, v[6:7]
	s_add_i32 s12, s10, 12
	s_nop 0
	v_or_b32_e32 v17, s12, v2
	v_or_b32_e32 v0, s11, v3
	s_add_i32 s11, s9, 16
	v_add_u32_e32 v22, s0, v17
	v_add_u32_e32 v20, s2, v0
	v_ashrrev_i32_e32 v23, 31, v22
	v_ashrrev_i32_e32 v21, 31, v20
	v_lshlrev_b64 v[22:23], 11, v[22:23]
	v_lshlrev_b64 v[20:21], 11, v[20:21]
	v_lshl_add_u64 v[22:23], v[18:19], 0, v[22:23]
	v_lshl_add_u64 v[20:21], v[18:19], 0, v[20:21]
	global_load_dword v106, v[22:23], off
	global_load_dword v107, v[20:21], off
	v_mad_u64_u32 v[128:129], s[12:13], v17, s77, v[6:7]
	v_mad_u64_u32 v[130:131], s[12:13], v0, s77, v[6:7]
	s_add_i32 s12, s10, 16
	s_nop 0
	v_or_b32_e32 v17, s12, v2
	v_or_b32_e32 v0, s11, v3
	s_add_i32 s11, s9, 20
	v_add_u32_e32 v22, s0, v17
	v_add_u32_e32 v20, s2, v0
	v_ashrrev_i32_e32 v23, 31, v22
	v_ashrrev_i32_e32 v21, 31, v20
	v_lshlrev_b64 v[22:23], 11, v[22:23]
	v_lshlrev_b64 v[20:21], 11, v[20:21]
	v_lshl_add_u64 v[22:23], v[18:19], 0, v[22:23]
	v_lshl_add_u64 v[20:21], v[18:19], 0, v[20:21]
	global_load_dword v108, v[22:23], off
	global_load_dword v109, v[20:21], off
	v_mad_u64_u32 v[132:133], s[12:13], v17, s77, v[6:7]
	v_mad_u64_u32 v[134:135], s[12:13], v0, s77, v[6:7]
	s_add_i32 s12, s10, 20
	s_nop 0
	v_or_b32_e32 v17, s12, v2
	v_or_b32_e32 v0, s11, v3
	s_add_i32 s11, s9, 24
	s_add_i32 s9, s9, 28
	v_add_u32_e32 v22, s0, v17
	v_add_u32_e32 v20, s2, v0
	v_ashrrev_i32_e32 v23, 31, v22
	v_ashrrev_i32_e32 v21, 31, v20
	v_lshlrev_b64 v[22:23], 11, v[22:23]
	v_lshlrev_b64 v[20:21], 11, v[20:21]
	v_lshl_add_u64 v[22:23], v[18:19], 0, v[22:23]
	v_lshl_add_u64 v[20:21], v[18:19], 0, v[20:21]
	global_load_dword v110, v[22:23], off
	global_load_dword v111, v[20:21], off
	v_mad_u64_u32 v[136:137], s[12:13], v17, s77, v[6:7]
	v_mad_u64_u32 v[138:139], s[12:13], v0, s77, v[6:7]
	s_add_i32 s12, s10, 24
	s_nop 0
	v_or_b32_e32 v17, s12, v2
	v_or_b32_e32 v0, s11, v3
	s_add_i32 s10, s10, 28
	s_cmp_lg_u32 s7, 0
	v_add_u32_e32 v22, s0, v17
	v_add_u32_e32 v20, s2, v0
	v_ashrrev_i32_e32 v23, 31, v22
	v_ashrrev_i32_e32 v21, 31, v20
	v_lshlrev_b64 v[22:23], 11, v[22:23]
	v_lshlrev_b64 v[20:21], 11, v[20:21]
	v_lshl_add_u64 v[22:23], v[18:19], 0, v[22:23]
	v_lshl_add_u64 v[20:21], v[18:19], 0, v[20:21]
	global_load_dword v112, v[22:23], off
	global_load_dword v113, v[20:21], off
	v_mad_u64_u32 v[140:141], s[12:13], v17, s77, v[6:7]
	v_mad_u64_u32 v[142:143], s[12:13], v0, s77, v[6:7]
	v_or_b32_e32 v17, s10, v2
	v_or_b32_e32 v0, s9, v3
	v_add_u32_e32 v22, s0, v17
	v_add_u32_e32 v20, s2, v0
	v_ashrrev_i32_e32 v23, 31, v22
	v_ashrrev_i32_e32 v21, 31, v20
	v_lshlrev_b64 v[22:23], 11, v[22:23]
	v_lshlrev_b64 v[20:21], 11, v[20:21]
	v_lshl_add_u64 v[22:23], v[18:19], 0, v[22:23]
	v_lshl_add_u64 v[20:21], v[18:19], 0, v[20:21]
	global_load_dword v114, v[22:23], off
	global_load_dword v115, v[20:21], off
	v_mad_u64_u32 v[144:145], s[10:11], v17, s77, v[6:7]
	v_mad_u64_u32 v[146:147], s[10:11], v0, s77, v[6:7]
	s_lshl_b32 s10, s6, 1
	s_lshl_b32 s9, s3, 1
	v_or_b32_e32 v17, s10, v2
	v_or_b32_e32 v0, s9, v3
	v_add_u32_e32 v22, s0, v17
	v_add_u32_e32 v20, s2, v0
	v_ashrrev_i32_e32 v23, 31, v22
	v_ashrrev_i32_e32 v21, 31, v20
	v_lshlrev_b64 v[22:23], 11, v[22:23]
	v_lshlrev_b64 v[20:21], 11, v[20:21]
	v_lshl_add_u64 v[22:23], v[18:19], 0, v[22:23]
	v_lshl_add_u64 v[20:21], v[18:19], 0, v[20:21]
	global_load_dword v148, v[22:23], off
	global_load_dword v149, v[20:21], off
	v_mad_u64_u32 v[164:165], s[12:13], v17, s77, v[6:7]
	v_mad_u64_u32 v[166:167], s[12:13], v0, s77, v[6:7]
	s_add_i32 s12, s10, 4
	s_add_i32 s11, s9, 4
	v_or_b32_e32 v17, s12, v2
	v_or_b32_e32 v0, s11, v3
	s_add_i32 s11, s9, 8
	s_add_i32 s6, s6, 16
	s_add_i32 s3, s3, 16
	s_add_i32 s7, s7, -16
	v_add_u32_e32 v22, s0, v17
	v_add_u32_e32 v20, s2, v0
	v_ashrrev_i32_e32 v23, 31, v22
	v_ashrrev_i32_e32 v21, 31, v20
	v_lshlrev_b64 v[22:23], 11, v[22:23]
	v_lshlrev_b64 v[20:21], 11, v[20:21]
	v_lshl_add_u64 v[22:23], v[18:19], 0, v[22:23]
	v_lshl_add_u64 v[20:21], v[18:19], 0, v[20:21]
	global_load_dword v150, v[22:23], off
	global_load_dword v151, v[20:21], off
	v_mad_u64_u32 v[168:169], s[12:13], v17, s77, v[6:7]
	v_mad_u64_u32 v[170:171], s[12:13], v0, s77, v[6:7]
	s_add_i32 s12, s10, 8
	s_nop 0
	v_or_b32_e32 v17, s12, v2
	v_or_b32_e32 v0, s11, v3
	s_add_i32 s11, s9, 12
	v_add_u32_e32 v22, s0, v17
	v_add_u32_e32 v20, s2, v0
	v_ashrrev_i32_e32 v23, 31, v22
	v_ashrrev_i32_e32 v21, 31, v20
	v_lshlrev_b64 v[22:23], 11, v[22:23]
	v_lshlrev_b64 v[20:21], 11, v[20:21]
	v_lshl_add_u64 v[22:23], v[18:19], 0, v[22:23]
	v_lshl_add_u64 v[20:21], v[18:19], 0, v[20:21]
	global_load_dword v152, v[22:23], off
	global_load_dword v153, v[20:21], off
	v_mad_u64_u32 v[172:173], s[12:13], v17, s77, v[6:7]
	v_mad_u64_u32 v[174:175], s[12:13], v0, s77, v[6:7]
	s_add_i32 s12, s10, 12
	s_nop 0
	v_or_b32_e32 v17, s12, v2
	v_or_b32_e32 v0, s11, v3
	s_add_i32 s11, s9, 16
	v_add_u32_e32 v22, s0, v17
	v_add_u32_e32 v20, s2, v0
	v_ashrrev_i32_e32 v23, 31, v22
	v_ashrrev_i32_e32 v21, 31, v20
	v_lshlrev_b64 v[22:23], 11, v[22:23]
	v_lshlrev_b64 v[20:21], 11, v[20:21]
	v_lshl_add_u64 v[22:23], v[18:19], 0, v[22:23]
	v_lshl_add_u64 v[20:21], v[18:19], 0, v[20:21]
	global_load_dword v154, v[22:23], off
	global_load_dword v155, v[20:21], off
	v_mad_u64_u32 v[176:177], s[12:13], v17, s77, v[6:7]
	v_mad_u64_u32 v[178:179], s[12:13], v0, s77, v[6:7]
	s_add_i32 s12, s10, 16
	s_nop 0
	v_or_b32_e32 v17, s12, v2
	v_or_b32_e32 v0, s11, v3
	s_add_i32 s11, s9, 20
	v_add_u32_e32 v22, s0, v17
	v_add_u32_e32 v20, s2, v0
	v_ashrrev_i32_e32 v23, 31, v22
	v_ashrrev_i32_e32 v21, 31, v20
	v_lshlrev_b64 v[22:23], 11, v[22:23]
	v_lshlrev_b64 v[20:21], 11, v[20:21]
	v_lshl_add_u64 v[22:23], v[18:19], 0, v[22:23]
	v_lshl_add_u64 v[20:21], v[18:19], 0, v[20:21]
	global_load_dword v156, v[22:23], off
	global_load_dword v157, v[20:21], off
	v_mad_u64_u32 v[180:181], s[12:13], v17, s77, v[6:7]
	v_mad_u64_u32 v[182:183], s[12:13], v0, s77, v[6:7]
	s_add_i32 s12, s10, 20
	s_nop 0
	v_or_b32_e32 v17, s12, v2
	v_or_b32_e32 v0, s11, v3
	s_add_i32 s11, s9, 24
	s_add_i32 s9, s9, 28
	v_add_u32_e32 v22, s0, v17
	v_add_u32_e32 v20, s2, v0
	v_ashrrev_i32_e32 v23, 31, v22
	v_ashrrev_i32_e32 v21, 31, v20
	v_lshlrev_b64 v[22:23], 11, v[22:23]
	v_lshlrev_b64 v[20:21], 11, v[20:21]
	v_lshl_add_u64 v[22:23], v[18:19], 0, v[22:23]
	v_lshl_add_u64 v[20:21], v[18:19], 0, v[20:21]
	global_load_dword v158, v[22:23], off
	global_load_dword v159, v[20:21], off
	v_mad_u64_u32 v[184:185], s[12:13], v17, s77, v[6:7]
	v_mad_u64_u32 v[186:187], s[12:13], v0, s77, v[6:7]
	s_add_i32 s12, s10, 24
	s_nop 0
	v_or_b32_e32 v17, s12, v2
	v_or_b32_e32 v0, s11, v3
	s_add_i32 s10, s10, 28
	s_cmp_lg_u32 s7, 0
	v_add_u32_e32 v22, s0, v17
	v_add_u32_e32 v20, s2, v0
	v_ashrrev_i32_e32 v23, 31, v22
	v_ashrrev_i32_e32 v21, 31, v20
	v_lshlrev_b64 v[22:23], 11, v[22:23]
	v_lshlrev_b64 v[20:21], 11, v[20:21]
	v_lshl_add_u64 v[22:23], v[18:19], 0, v[22:23]
	v_lshl_add_u64 v[20:21], v[18:19], 0, v[20:21]
	global_load_dword v160, v[22:23], off
	global_load_dword v161, v[20:21], off
	v_mad_u64_u32 v[188:189], s[12:13], v17, s77, v[6:7]
	v_mad_u64_u32 v[190:191], s[12:13], v0, s77, v[6:7]
	v_or_b32_e32 v17, s10, v2
	v_or_b32_e32 v0, s9, v3
	v_add_u32_e32 v22, s0, v17
	v_add_u32_e32 v20, s2, v0
	v_ashrrev_i32_e32 v23, 31, v22
	v_ashrrev_i32_e32 v21, 31, v20
	v_lshlrev_b64 v[22:23], 11, v[22:23]
	v_lshlrev_b64 v[20:21], 11, v[20:21]
	v_lshl_add_u64 v[22:23], v[18:19], 0, v[22:23]
	v_lshl_add_u64 v[20:21], v[18:19], 0, v[20:21]
	global_load_dword v162, v[22:23], off
	global_load_dword v163, v[20:21], off
	v_mad_u64_u32 v[192:193], s[10:11], v17, s77, v[6:7]
	v_mad_u64_u32 v[196:197], s[10:11], v0, s77, v[6:7]
	s_waitcnt vmcnt(0)
	ds_write_b32 v116, v100
	ds_write_b32 v118, v101
	ds_write_b32 v120, v102
	ds_write_b32 v122, v103
	ds_write_b32 v124, v104
	ds_write_b32 v126, v105
	ds_write_b32 v128, v106
	ds_write_b32 v130, v107
	ds_write_b32 v132, v108
	ds_write_b32 v134, v109
	ds_write_b32 v136, v110
	ds_write_b32 v138, v111
	ds_write_b32 v140, v112
	ds_write_b32 v142, v113
	ds_write_b32 v144, v114
	ds_write_b32 v146, v115
	ds_write_b32 v164, v148
	ds_write_b32 v166, v149
	ds_write_b32 v168, v150
	ds_write_b32 v170, v151
	ds_write_b32 v172, v152
	ds_write_b32 v174, v153
	ds_write_b32 v176, v154
	ds_write_b32 v178, v155
	ds_write_b32 v180, v156
	ds_write_b32 v182, v157
	ds_write_b32 v184, v158
	ds_write_b32 v186, v159
	ds_write_b32 v188, v160
	ds_write_b32 v190, v161
	ds_write_b32 v192, v162
	ds_write_b32 v196, v163
	s_cbranch_scc1 .LBB0_338
	s_lshl_b32 s1, s1, 10
	s_add_u32 s2, s73, s1
	v_readlane_b32 s1, v250, 13
	s_addc_u32 s3, s1, 0
	s_mov_b32 s1, s4
	s_lshl_b64 s[0:1], s[0:1], 1
	s_add_u32 s0, s2, s0
	s_addc_u32 s1, s3, s1
	s_mov_b64 s[2:3], 0

.LBB0_346:
	s_lshl_b32 s10, s5, 1
	s_lshl_b32 s9, s2, 1
	v_or_b32_e32 v17, s10, v2
	v_or_b32_e32 v0, s9, v3
	v_add_u32_e32 v22, s6, v17
	v_add_u32_e32 v20, s3, v0
	v_ashrrev_i32_e32 v23, 31, v22
	v_ashrrev_i32_e32 v21, 31, v20
	v_lshlrev_b64 v[22:23], 12, v[22:23]
	v_lshlrev_b64 v[20:21], 12, v[20:21]
	v_lshl_add_u64 v[22:23], v[18:19], 0, v[22:23]
	v_lshl_add_u64 v[20:21], v[18:19], 0, v[20:21]
	global_load_dword v100, v[22:23], off
	global_load_dword v101, v[20:21], off
	v_mad_u64_u32 v[116:117], s[12:13], v17, s77, v[6:7]
	v_mad_u64_u32 v[118:119], s[12:13], v0, s77, v[6:7]
	s_add_i32 s12, s10, 4
	s_add_i32 s11, s9, 4
	v_or_b32_e32 v17, s12, v2
	v_or_b32_e32 v0, s11, v3
	s_add_i32 s11, s9, 8
	s_add_i32 s5, s5, 16
	s_add_i32 s2, s2, 16
	s_add_i32 s7, s7, -16
	v_add_u32_e32 v22, s6, v17
	v_add_u32_e32 v20, s3, v0
	v_ashrrev_i32_e32 v23, 31, v22
	v_ashrrev_i32_e32 v21, 31, v20
	v_lshlrev_b64 v[22:23], 12, v[22:23]
	v_lshlrev_b64 v[20:21], 12, v[20:21]
	v_lshl_add_u64 v[22:23], v[18:19], 0, v[22:23]
	v_lshl_add_u64 v[20:21], v[18:19], 0, v[20:21]
	global_load_dword v102, v[22:23], off
	global_load_dword v103, v[20:21], off
	v_mad_u64_u32 v[120:121], s[12:13], v17, s77, v[6:7]
	v_mad_u64_u32 v[122:123], s[12:13], v0, s77, v[6:7]
	s_add_i32 s12, s10, 8
	s_nop 0
	v_or_b32_e32 v17, s12, v2
	v_or_b32_e32 v0, s11, v3
	s_add_i32 s11, s9, 12
	v_add_u32_e32 v22, s6, v17
	v_add_u32_e32 v20, s3, v0
	v_ashrrev_i32_e32 v23, 31, v22
	v_ashrrev_i32_e32 v21, 31, v20
	v_lshlrev_b64 v[22:23], 12, v[22:23]
	v_lshlrev_b64 v[20:21], 12, v[20:21]
	v_lshl_add_u64 v[22:23], v[18:19], 0, v[22:23]
	v_lshl_add_u64 v[20:21], v[18:19], 0, v[20:21]
	global_load_dword v104, v[22:23], off
	global_load_dword v105, v[20:21], off
	v_mad_u64_u32 v[124:125], s[12:13], v17, s77, v[6:7]
	v_mad_u64_u32 v[126:127], s[12:13], v0, s77, v[6:7]
	s_add_i32 s12, s10, 12
	s_nop 0
	v_or_b32_e32 v17, s12, v2
	v_or_b32_e32 v0, s11, v3
	s_add_i32 s11, s9, 16
	v_add_u32_e32 v22, s6, v17
	v_add_u32_e32 v20, s3, v0
	v_ashrrev_i32_e32 v23, 31, v22
	v_ashrrev_i32_e32 v21, 31, v20
	v_lshlrev_b64 v[22:23], 12, v[22:23]
	v_lshlrev_b64 v[20:21], 12, v[20:21]
	v_lshl_add_u64 v[22:23], v[18:19], 0, v[22:23]
	v_lshl_add_u64 v[20:21], v[18:19], 0, v[20:21]
	global_load_dword v106, v[22:23], off
	global_load_dword v107, v[20:21], off
	v_mad_u64_u32 v[128:129], s[12:13], v17, s77, v[6:7]
	v_mad_u64_u32 v[130:131], s[12:13], v0, s77, v[6:7]
	s_add_i32 s12, s10, 16
	s_nop 0
	v_or_b32_e32 v17, s12, v2
	v_or_b32_e32 v0, s11, v3
	s_add_i32 s11, s9, 20
	v_add_u32_e32 v22, s6, v17
	v_add_u32_e32 v20, s3, v0
	v_ashrrev_i32_e32 v23, 31, v22
	v_ashrrev_i32_e32 v21, 31, v20
	v_lshlrev_b64 v[22:23], 12, v[22:23]
	v_lshlrev_b64 v[20:21], 12, v[20:21]
	v_lshl_add_u64 v[22:23], v[18:19], 0, v[22:23]
	v_lshl_add_u64 v[20:21], v[18:19], 0, v[20:21]
	global_load_dword v108, v[22:23], off
	global_load_dword v109, v[20:21], off
	v_mad_u64_u32 v[132:133], s[12:13], v17, s77, v[6:7]
	v_mad_u64_u32 v[134:135], s[12:13], v0, s77, v[6:7]
	s_add_i32 s12, s10, 20
	s_nop 0
	v_or_b32_e32 v17, s12, v2
	v_or_b32_e32 v0, s11, v3
	s_add_i32 s11, s9, 24
	s_add_i32 s9, s9, 28
	v_add_u32_e32 v22, s6, v17
	v_add_u32_e32 v20, s3, v0
	v_ashrrev_i32_e32 v23, 31, v22
	v_ashrrev_i32_e32 v21, 31, v20
	v_lshlrev_b64 v[22:23], 12, v[22:23]
	v_lshlrev_b64 v[20:21], 12, v[20:21]
	v_lshl_add_u64 v[22:23], v[18:19], 0, v[22:23]
	v_lshl_add_u64 v[20:21], v[18:19], 0, v[20:21]
	global_load_dword v110, v[22:23], off
	global_load_dword v111, v[20:21], off
	v_mad_u64_u32 v[136:137], s[12:13], v17, s77, v[6:7]
	v_mad_u64_u32 v[138:139], s[12:13], v0, s77, v[6:7]
	s_add_i32 s12, s10, 24
	s_nop 0
	v_or_b32_e32 v17, s12, v2
	v_or_b32_e32 v0, s11, v3
	s_add_i32 s10, s10, 28
	s_cmp_lg_u32 s7, 0
	v_add_u32_e32 v22, s6, v17
	v_add_u32_e32 v20, s3, v0
	v_ashrrev_i32_e32 v23, 31, v22
	v_ashrrev_i32_e32 v21, 31, v20
	v_lshlrev_b64 v[22:23], 12, v[22:23]
	v_lshlrev_b64 v[20:21], 12, v[20:21]
	v_lshl_add_u64 v[22:23], v[18:19], 0, v[22:23]
	v_lshl_add_u64 v[20:21], v[18:19], 0, v[20:21]
	global_load_dword v112, v[22:23], off
	global_load_dword v113, v[20:21], off
	v_mad_u64_u32 v[140:141], s[12:13], v17, s77, v[6:7]
	v_mad_u64_u32 v[142:143], s[12:13], v0, s77, v[6:7]
	v_or_b32_e32 v17, s10, v2
	v_or_b32_e32 v0, s9, v3
	v_add_u32_e32 v22, s6, v17
	v_add_u32_e32 v20, s3, v0
	v_ashrrev_i32_e32 v23, 31, v22
	v_ashrrev_i32_e32 v21, 31, v20
	v_lshlrev_b64 v[22:23], 12, v[22:23]
	v_lshlrev_b64 v[20:21], 12, v[20:21]
	v_lshl_add_u64 v[22:23], v[18:19], 0, v[22:23]
	v_lshl_add_u64 v[20:21], v[18:19], 0, v[20:21]
	global_load_dword v114, v[22:23], off
	global_load_dword v115, v[20:21], off
	v_mad_u64_u32 v[144:145], s[10:11], v17, s77, v[6:7]
	v_mad_u64_u32 v[146:147], s[10:11], v0, s77, v[6:7]
	s_lshl_b32 s10, s5, 1
	s_lshl_b32 s9, s2, 1
	v_or_b32_e32 v17, s10, v2
	v_or_b32_e32 v0, s9, v3
	v_add_u32_e32 v22, s6, v17
	v_add_u32_e32 v20, s3, v0
	v_ashrrev_i32_e32 v23, 31, v22
	v_ashrrev_i32_e32 v21, 31, v20
	v_lshlrev_b64 v[22:23], 12, v[22:23]
	v_lshlrev_b64 v[20:21], 12, v[20:21]
	v_lshl_add_u64 v[22:23], v[18:19], 0, v[22:23]
	v_lshl_add_u64 v[20:21], v[18:19], 0, v[20:21]
	global_load_dword v148, v[22:23], off
	global_load_dword v149, v[20:21], off
	v_mad_u64_u32 v[164:165], s[12:13], v17, s77, v[6:7]
	v_mad_u64_u32 v[166:167], s[12:13], v0, s77, v[6:7]
	s_add_i32 s12, s10, 4
	s_add_i32 s11, s9, 4
	v_or_b32_e32 v17, s12, v2
	v_or_b32_e32 v0, s11, v3
	s_add_i32 s11, s9, 8
	s_add_i32 s5, s5, 16
	s_add_i32 s2, s2, 16
	s_add_i32 s7, s7, -16
	v_add_u32_e32 v22, s6, v17
	v_add_u32_e32 v20, s3, v0
	v_ashrrev_i32_e32 v23, 31, v22
	v_ashrrev_i32_e32 v21, 31, v20
	v_lshlrev_b64 v[22:23], 12, v[22:23]
	v_lshlrev_b64 v[20:21], 12, v[20:21]
	v_lshl_add_u64 v[22:23], v[18:19], 0, v[22:23]
	v_lshl_add_u64 v[20:21], v[18:19], 0, v[20:21]
	global_load_dword v150, v[22:23], off
	global_load_dword v151, v[20:21], off
	v_mad_u64_u32 v[168:169], s[12:13], v17, s77, v[6:7]
	v_mad_u64_u32 v[170:171], s[12:13], v0, s77, v[6:7]
	s_add_i32 s12, s10, 8
	s_nop 0
	v_or_b32_e32 v17, s12, v2
	v_or_b32_e32 v0, s11, v3
	s_add_i32 s11, s9, 12
	v_add_u32_e32 v22, s6, v17
	v_add_u32_e32 v20, s3, v0
	v_ashrrev_i32_e32 v23, 31, v22
	v_ashrrev_i32_e32 v21, 31, v20
	v_lshlrev_b64 v[22:23], 12, v[22:23]
	v_lshlrev_b64 v[20:21], 12, v[20:21]
	v_lshl_add_u64 v[22:23], v[18:19], 0, v[22:23]
	v_lshl_add_u64 v[20:21], v[18:19], 0, v[20:21]
	global_load_dword v152, v[22:23], off
	global_load_dword v153, v[20:21], off
	v_mad_u64_u32 v[172:173], s[12:13], v17, s77, v[6:7]
	v_mad_u64_u32 v[174:175], s[12:13], v0, s77, v[6:7]
	s_add_i32 s12, s10, 12
	s_nop 0
	v_or_b32_e32 v17, s12, v2
	v_or_b32_e32 v0, s11, v3
	s_add_i32 s11, s9, 16
	v_add_u32_e32 v22, s6, v17
	v_add_u32_e32 v20, s3, v0
	v_ashrrev_i32_e32 v23, 31, v22
	v_ashrrev_i32_e32 v21, 31, v20
	v_lshlrev_b64 v[22:23], 12, v[22:23]
	v_lshlrev_b64 v[20:21], 12, v[20:21]
	v_lshl_add_u64 v[22:23], v[18:19], 0, v[22:23]
	v_lshl_add_u64 v[20:21], v[18:19], 0, v[20:21]
	global_load_dword v154, v[22:23], off
	global_load_dword v155, v[20:21], off
	v_mad_u64_u32 v[176:177], s[12:13], v17, s77, v[6:7]
	v_mad_u64_u32 v[178:179], s[12:13], v0, s77, v[6:7]
	s_add_i32 s12, s10, 16
	s_nop 0
	v_or_b32_e32 v17, s12, v2
	v_or_b32_e32 v0, s11, v3
	s_add_i32 s11, s9, 20
	v_add_u32_e32 v22, s6, v17
	v_add_u32_e32 v20, s3, v0
	v_ashrrev_i32_e32 v23, 31, v22
	v_ashrrev_i32_e32 v21, 31, v20
	v_lshlrev_b64 v[22:23], 12, v[22:23]
	v_lshlrev_b64 v[20:21], 12, v[20:21]
	v_lshl_add_u64 v[22:23], v[18:19], 0, v[22:23]
	v_lshl_add_u64 v[20:21], v[18:19], 0, v[20:21]
	global_load_dword v156, v[22:23], off
	global_load_dword v157, v[20:21], off
	v_mad_u64_u32 v[180:181], s[12:13], v17, s77, v[6:7]
	v_mad_u64_u32 v[182:183], s[12:13], v0, s77, v[6:7]
	s_add_i32 s12, s10, 20
	s_nop 0
	v_or_b32_e32 v17, s12, v2
	v_or_b32_e32 v0, s11, v3
	s_add_i32 s11, s9, 24
	s_add_i32 s9, s9, 28
	v_add_u32_e32 v22, s6, v17
	v_add_u32_e32 v20, s3, v0
	v_ashrrev_i32_e32 v23, 31, v22
	v_ashrrev_i32_e32 v21, 31, v20
	v_lshlrev_b64 v[22:23], 12, v[22:23]
	v_lshlrev_b64 v[20:21], 12, v[20:21]
	v_lshl_add_u64 v[22:23], v[18:19], 0, v[22:23]
	v_lshl_add_u64 v[20:21], v[18:19], 0, v[20:21]
	global_load_dword v158, v[22:23], off
	global_load_dword v159, v[20:21], off
	v_mad_u64_u32 v[184:185], s[12:13], v17, s77, v[6:7]
	v_mad_u64_u32 v[186:187], s[12:13], v0, s77, v[6:7]
	s_add_i32 s12, s10, 24
	s_nop 0
	v_or_b32_e32 v17, s12, v2
	v_or_b32_e32 v0, s11, v3
	s_add_i32 s10, s10, 28
	s_cmp_lg_u32 s7, 0
	v_add_u32_e32 v22, s6, v17
	v_add_u32_e32 v20, s3, v0
	v_ashrrev_i32_e32 v23, 31, v22
	v_ashrrev_i32_e32 v21, 31, v20
	v_lshlrev_b64 v[22:23], 12, v[22:23]
	v_lshlrev_b64 v[20:21], 12, v[20:21]
	v_lshl_add_u64 v[22:23], v[18:19], 0, v[22:23]
	v_lshl_add_u64 v[20:21], v[18:19], 0, v[20:21]
	global_load_dword v160, v[22:23], off
	global_load_dword v161, v[20:21], off
	v_mad_u64_u32 v[188:189], s[12:13], v17, s77, v[6:7]
	v_mad_u64_u32 v[190:191], s[12:13], v0, s77, v[6:7]
	v_or_b32_e32 v17, s10, v2
	v_or_b32_e32 v0, s9, v3
	v_add_u32_e32 v22, s6, v17
	v_add_u32_e32 v20, s3, v0
	v_ashrrev_i32_e32 v23, 31, v22
	v_ashrrev_i32_e32 v21, 31, v20
	v_lshlrev_b64 v[22:23], 12, v[22:23]
	v_lshlrev_b64 v[20:21], 12, v[20:21]
	v_lshl_add_u64 v[22:23], v[18:19], 0, v[22:23]
	v_lshl_add_u64 v[20:21], v[18:19], 0, v[20:21]
	global_load_dword v162, v[22:23], off
	global_load_dword v163, v[20:21], off
	v_mad_u64_u32 v[192:193], s[10:11], v17, s77, v[6:7]
	v_mad_u64_u32 v[196:197], s[10:11], v0, s77, v[6:7]
	s_waitcnt vmcnt(0)
	ds_write_b32 v116, v100
	ds_write_b32 v118, v101
	ds_write_b32 v120, v102
	ds_write_b32 v122, v103
	ds_write_b32 v124, v104
	ds_write_b32 v126, v105
	ds_write_b32 v128, v106
	ds_write_b32 v130, v107
	ds_write_b32 v132, v108
	ds_write_b32 v134, v109
	ds_write_b32 v136, v110
	ds_write_b32 v138, v111
	ds_write_b32 v140, v112
	ds_write_b32 v142, v113
	ds_write_b32 v144, v114
	ds_write_b32 v146, v115
	ds_write_b32 v164, v148
	ds_write_b32 v166, v149
	ds_write_b32 v168, v150
	ds_write_b32 v170, v151
	ds_write_b32 v172, v152
	ds_write_b32 v174, v153
	ds_write_b32 v176, v154
	ds_write_b32 v178, v155
	ds_write_b32 v180, v156
	ds_write_b32 v182, v157
	ds_write_b32 v184, v158
	ds_write_b32 v186, v159
	ds_write_b32 v188, v160
	ds_write_b32 v190, v161
	ds_write_b32 v192, v162
	ds_write_b32 v196, v163
	s_cbranch_scc1 .LBB0_346
	s_mov_b32 s7, s4
	s_lshl_b64 s[2:3], s[6:7], 1
	s_add_u32 s0, s0, s2
	s_addc_u32 s1, s1, s3
	v_mov_b32_e32 v0, v31
	v_mov_b32_e32 v18, v30
	v_mov_b32_e32 v20, v29
	v_mov_b32_e32 v22, v28
	s_mov_b64 s[2:3], 0

.LBB0_350:
	s_lshl_b32 s9, s5, 1
	s_lshl_b32 s7, s3, 1
	v_or_b32_e32 v17, s9, v2
	v_or_b32_e32 v0, s7, v3
	v_add_u32_e32 v20, s0, v17
	v_add_u32_e32 v22, s2, v0
	v_mad_u64_u32 v[20:21], s[10:11], v20, s61, v[18:19]
	v_mad_u64_u32 v[22:23], s[10:11], v22, s61, v[18:19]
	global_load_dword v100, v[20:21], off
	global_load_dword v101, v[22:23], off
	v_mad_u64_u32 v[116:117], s[10:11], v17, s77, v[6:7]
	v_mad_u64_u32 v[118:119], s[10:11], v0, s77, v[6:7]
	s_add_i32 s11, s9, 4
	s_add_i32 s10, s7, 4
	v_or_b32_e32 v17, s11, v2
	v_or_b32_e32 v0, s10, v3
	s_add_i32 s5, s5, 16
	s_add_i32 s3, s3, 16
	s_add_i32 s6, s6, -16
	v_add_u32_e32 v20, s0, v17
	v_add_u32_e32 v22, s2, v0
	v_mad_u64_u32 v[20:21], s[10:11], v20, s61, v[18:19]
	v_mad_u64_u32 v[22:23], s[10:11], v22, s61, v[18:19]
	global_load_dword v102, v[20:21], off
	global_load_dword v103, v[22:23], off
	v_mad_u64_u32 v[120:121], s[10:11], v17, s77, v[6:7]
	v_mad_u64_u32 v[122:123], s[10:11], v0, s77, v[6:7]
	s_add_i32 s11, s9, 8
	s_add_i32 s10, s7, 8
	v_or_b32_e32 v17, s11, v2
	v_or_b32_e32 v0, s10, v3
	v_add_u32_e32 v20, s0, v17
	v_add_u32_e32 v22, s2, v0
	v_mad_u64_u32 v[20:21], s[10:11], v20, s61, v[18:19]
	v_mad_u64_u32 v[22:23], s[10:11], v22, s61, v[18:19]
	global_load_dword v104, v[20:21], off
	global_load_dword v105, v[22:23], off
	v_mad_u64_u32 v[124:125], s[10:11], v17, s77, v[6:7]
	v_mad_u64_u32 v[126:127], s[10:11], v0, s77, v[6:7]
	s_add_i32 s11, s9, 12
	s_add_i32 s10, s7, 12
	v_or_b32_e32 v17, s11, v2
	v_or_b32_e32 v0, s10, v3
	v_add_u32_e32 v20, s0, v17
	v_add_u32_e32 v22, s2, v0
	v_mad_u64_u32 v[20:21], s[10:11], v20, s61, v[18:19]
	v_mad_u64_u32 v[22:23], s[10:11], v22, s61, v[18:19]
	global_load_dword v106, v[20:21], off
	global_load_dword v107, v[22:23], off
	v_mad_u64_u32 v[128:129], s[10:11], v17, s77, v[6:7]
	v_mad_u64_u32 v[130:131], s[10:11], v0, s77, v[6:7]
	s_add_i32 s11, s9, 16
	s_add_i32 s10, s7, 16
	v_or_b32_e32 v17, s11, v2
	v_or_b32_e32 v0, s10, v3
	v_add_u32_e32 v20, s0, v17
	v_add_u32_e32 v22, s2, v0
	v_mad_u64_u32 v[20:21], s[10:11], v20, s61, v[18:19]
	v_mad_u64_u32 v[22:23], s[10:11], v22, s61, v[18:19]
	global_load_dword v108, v[20:21], off
	global_load_dword v109, v[22:23], off
	v_mad_u64_u32 v[132:133], s[10:11], v17, s77, v[6:7]
	v_mad_u64_u32 v[134:135], s[10:11], v0, s77, v[6:7]
	s_add_i32 s11, s9, 20
	s_add_i32 s10, s7, 20
	v_or_b32_e32 v17, s11, v2
	v_or_b32_e32 v0, s10, v3
	v_add_u32_e32 v20, s0, v17
	v_add_u32_e32 v22, s2, v0
	v_mad_u64_u32 v[20:21], s[10:11], v20, s61, v[18:19]
	v_mad_u64_u32 v[22:23], s[10:11], v22, s61, v[18:19]
	global_load_dword v110, v[20:21], off
	global_load_dword v111, v[22:23], off
	v_mad_u64_u32 v[136:137], s[10:11], v17, s77, v[6:7]
	v_mad_u64_u32 v[138:139], s[10:11], v0, s77, v[6:7]
	s_add_i32 s11, s9, 24
	s_add_i32 s10, s7, 24
	v_or_b32_e32 v17, s11, v2
	v_or_b32_e32 v0, s10, v3
	s_add_i32 s9, s9, 28
	s_add_i32 s7, s7, 28
	s_cmp_lg_u32 s6, 0
	v_add_u32_e32 v20, s0, v17
	v_add_u32_e32 v22, s2, v0
	v_mad_u64_u32 v[20:21], s[10:11], v20, s61, v[18:19]
	v_mad_u64_u32 v[22:23], s[10:11], v22, s61, v[18:19]
	global_load_dword v112, v[20:21], off
	global_load_dword v113, v[22:23], off
	v_mad_u64_u32 v[140:141], s[10:11], v17, s77, v[6:7]
	v_or_b32_e32 v17, s9, v2
	v_mad_u64_u32 v[142:143], s[10:11], v0, s77, v[6:7]
	v_or_b32_e32 v0, s7, v3
	v_add_u32_e32 v20, s0, v17
	v_add_u32_e32 v22, s2, v0
	v_mad_u64_u32 v[20:21], s[10:11], v20, s61, v[18:19]
	v_mad_u64_u32 v[22:23], s[10:11], v22, s61, v[18:19]
	global_load_dword v114, v[20:21], off
	global_load_dword v115, v[22:23], off
	v_mad_u64_u32 v[144:145], s[10:11], v17, s77, v[6:7]
	v_mad_u64_u32 v[146:147], s[10:11], v0, s77, v[6:7]
	s_lshl_b32 s9, s5, 1
	s_lshl_b32 s7, s3, 1
	v_or_b32_e32 v17, s9, v2
	v_or_b32_e32 v0, s7, v3
	v_add_u32_e32 v20, s0, v17
	v_add_u32_e32 v22, s2, v0
	v_mad_u64_u32 v[20:21], s[10:11], v20, s61, v[18:19]
	v_mad_u64_u32 v[22:23], s[10:11], v22, s61, v[18:19]
	global_load_dword v148, v[20:21], off
	global_load_dword v149, v[22:23], off
	v_mad_u64_u32 v[164:165], s[10:11], v17, s77, v[6:7]
	v_mad_u64_u32 v[166:167], s[10:11], v0, s77, v[6:7]
	s_add_i32 s11, s9, 4
	s_add_i32 s10, s7, 4
	v_or_b32_e32 v17, s11, v2
	v_or_b32_e32 v0, s10, v3
	s_add_i32 s5, s5, 16
	s_add_i32 s3, s3, 16
	s_add_i32 s6, s6, -16
	v_add_u32_e32 v20, s0, v17
	v_add_u32_e32 v22, s2, v0
	v_mad_u64_u32 v[20:21], s[10:11], v20, s61, v[18:19]
	v_mad_u64_u32 v[22:23], s[10:11], v22, s61, v[18:19]
	global_load_dword v150, v[20:21], off
	global_load_dword v151, v[22:23], off
	v_mad_u64_u32 v[168:169], s[10:11], v17, s77, v[6:7]
	v_mad_u64_u32 v[170:171], s[10:11], v0, s77, v[6:7]
	s_add_i32 s11, s9, 8
	s_add_i32 s10, s7, 8
	v_or_b32_e32 v17, s11, v2
	v_or_b32_e32 v0, s10, v3
	v_add_u32_e32 v20, s0, v17
	v_add_u32_e32 v22, s2, v0
	v_mad_u64_u32 v[20:21], s[10:11], v20, s61, v[18:19]
	v_mad_u64_u32 v[22:23], s[10:11], v22, s61, v[18:19]
	global_load_dword v152, v[20:21], off
	global_load_dword v153, v[22:23], off
	v_mad_u64_u32 v[172:173], s[10:11], v17, s77, v[6:7]
	v_mad_u64_u32 v[174:175], s[10:11], v0, s77, v[6:7]
	s_add_i32 s11, s9, 12
	s_add_i32 s10, s7, 12
	v_or_b32_e32 v17, s11, v2
	v_or_b32_e32 v0, s10, v3
	v_add_u32_e32 v20, s0, v17
	v_add_u32_e32 v22, s2, v0
	v_mad_u64_u32 v[20:21], s[10:11], v20, s61, v[18:19]
	v_mad_u64_u32 v[22:23], s[10:11], v22, s61, v[18:19]
	global_load_dword v154, v[20:21], off
	global_load_dword v155, v[22:23], off
	v_mad_u64_u32 v[176:177], s[10:11], v17, s77, v[6:7]
	v_mad_u64_u32 v[178:179], s[10:11], v0, s77, v[6:7]
	s_add_i32 s11, s9, 16
	s_add_i32 s10, s7, 16
	v_or_b32_e32 v17, s11, v2
	v_or_b32_e32 v0, s10, v3
	v_add_u32_e32 v20, s0, v17
	v_add_u32_e32 v22, s2, v0
	v_mad_u64_u32 v[20:21], s[10:11], v20, s61, v[18:19]
	v_mad_u64_u32 v[22:23], s[10:11], v22, s61, v[18:19]
	global_load_dword v156, v[20:21], off
	global_load_dword v157, v[22:23], off
	v_mad_u64_u32 v[180:181], s[10:11], v17, s77, v[6:7]
	v_mad_u64_u32 v[182:183], s[10:11], v0, s77, v[6:7]
	s_add_i32 s11, s9, 20
	s_add_i32 s10, s7, 20
	v_or_b32_e32 v17, s11, v2
	v_or_b32_e32 v0, s10, v3
	v_add_u32_e32 v20, s0, v17
	v_add_u32_e32 v22, s2, v0
	v_mad_u64_u32 v[20:21], s[10:11], v20, s61, v[18:19]
	v_mad_u64_u32 v[22:23], s[10:11], v22, s61, v[18:19]
	global_load_dword v158, v[20:21], off
	global_load_dword v159, v[22:23], off
	v_mad_u64_u32 v[184:185], s[10:11], v17, s77, v[6:7]
	v_mad_u64_u32 v[186:187], s[10:11], v0, s77, v[6:7]
	s_add_i32 s11, s9, 24
	s_add_i32 s10, s7, 24
	v_or_b32_e32 v17, s11, v2
	v_or_b32_e32 v0, s10, v3
	s_add_i32 s9, s9, 28
	s_add_i32 s7, s7, 28
	s_cmp_lg_u32 s6, 0
	v_add_u32_e32 v20, s0, v17
	v_add_u32_e32 v22, s2, v0
	v_mad_u64_u32 v[20:21], s[10:11], v20, s61, v[18:19]
	v_mad_u64_u32 v[22:23], s[10:11], v22, s61, v[18:19]
	global_load_dword v160, v[20:21], off
	global_load_dword v161, v[22:23], off
	v_mad_u64_u32 v[188:189], s[10:11], v17, s77, v[6:7]
	v_or_b32_e32 v17, s9, v2
	v_mad_u64_u32 v[190:191], s[10:11], v0, s77, v[6:7]
	v_or_b32_e32 v0, s7, v3
	v_add_u32_e32 v20, s0, v17
	v_add_u32_e32 v22, s2, v0
	v_mad_u64_u32 v[20:21], s[10:11], v20, s61, v[18:19]
	v_mad_u64_u32 v[22:23], s[10:11], v22, s61, v[18:19]
	global_load_dword v162, v[20:21], off
	global_load_dword v163, v[22:23], off
	v_mad_u64_u32 v[192:193], s[10:11], v17, s77, v[6:7]
	v_mad_u64_u32 v[196:197], s[10:11], v0, s77, v[6:7]
	s_waitcnt vmcnt(0)
	ds_write_b32 v116, v100
	ds_write_b32 v118, v101
	ds_write_b32 v120, v102
	ds_write_b32 v122, v103
	ds_write_b32 v124, v104
	ds_write_b32 v126, v105
	ds_write_b32 v128, v106
	ds_write_b32 v130, v107
	ds_write_b32 v132, v108
	ds_write_b32 v134, v109
	ds_write_b32 v136, v110
	ds_write_b32 v138, v111
	ds_write_b32 v140, v112
	ds_write_b32 v142, v113
	ds_write_b32 v144, v114
	ds_write_b32 v146, v115
	ds_write_b32 v164, v148
	ds_write_b32 v166, v149
	ds_write_b32 v168, v150
	ds_write_b32 v170, v151
	ds_write_b32 v172, v152
	ds_write_b32 v174, v153
	ds_write_b32 v176, v154
	ds_write_b32 v178, v155
	ds_write_b32 v180, v156
	ds_write_b32 v182, v157
	ds_write_b32 v184, v158
	ds_write_b32 v186, v159
	ds_write_b32 v188, v160
	ds_write_b32 v190, v161
	ds_write_b32 v192, v162
	ds_write_b32 v196, v163
	s_cbranch_scc1 .LBB0_350
	s_mulk_i32 s1, 0x6000
	s_add_u32 s1, s50, s1
	s_addc_u32 s2, s51, 0
	s_lshl_b32 s0, s0, 1
	s_add_u32 s0, s1, s0
	s_addc_u32 s1, s2, 0
	v_mov_b32_e32 v0, v35
	v_mov_b32_e32 v18, v34
	v_mov_b32_e32 v20, v33
	v_mov_b32_e32 v22, v32

.LBB0_355:
	s_lshl_b32 s9, s5, 1
	s_lshl_b32 s7, s2, 1
	v_or_b32_e32 v40, s9, v2
	v_or_b32_e32 v17, s7, v3
	v_add_u32_e32 v0, s1, v40
	v_add_u32_e32 v20, s3, v17
	v_mov_b32_e32 v21, v1
	v_lshlrev_b64 v[22:23], 14, v[0:1]
	v_lshlrev_b64 v[20:21], 14, v[20:21]
	v_lshl_add_u64 v[22:23], v[18:19], 0, v[22:23]
	v_lshl_add_u64 v[20:21], v[18:19], 0, v[20:21]
	global_load_dword v100, v[22:23], off
	global_load_dword v101, v[20:21], off
	v_mad_u64_u32 v[116:117], s[10:11], v40, s77, v[6:7]
	v_mad_u64_u32 v[118:119], s[10:11], v17, s77, v[6:7]
	s_add_i32 s11, s9, 4
	s_add_i32 s10, s7, 4
	v_or_b32_e32 v40, s11, v2
	v_or_b32_e32 v17, s10, v3
	v_mov_b32_e32 v21, v1
	s_add_i32 s5, s5, 16
	s_add_i32 s2, s2, 16
	s_add_i32 s6, s6, -16
	v_add_u32_e32 v0, s1, v40
	v_add_u32_e32 v20, s3, v17
	v_lshlrev_b64 v[22:23], 14, v[0:1]
	v_lshlrev_b64 v[20:21], 14, v[20:21]
	v_lshl_add_u64 v[22:23], v[18:19], 0, v[22:23]
	v_lshl_add_u64 v[20:21], v[18:19], 0, v[20:21]
	global_load_dword v102, v[22:23], off
	global_load_dword v103, v[20:21], off
	v_mad_u64_u32 v[120:121], s[10:11], v40, s77, v[6:7]
	v_mad_u64_u32 v[122:123], s[10:11], v17, s77, v[6:7]
	s_add_i32 s11, s9, 8
	s_add_i32 s10, s7, 8
	v_or_b32_e32 v40, s11, v2
	v_or_b32_e32 v17, s10, v3
	v_mov_b32_e32 v21, v1
	v_add_u32_e32 v0, s1, v40
	v_add_u32_e32 v20, s3, v17
	v_lshlrev_b64 v[22:23], 14, v[0:1]
	v_lshlrev_b64 v[20:21], 14, v[20:21]
	v_lshl_add_u64 v[22:23], v[18:19], 0, v[22:23]
	v_lshl_add_u64 v[20:21], v[18:19], 0, v[20:21]
	global_load_dword v104, v[22:23], off
	global_load_dword v105, v[20:21], off
	v_mad_u64_u32 v[124:125], s[10:11], v40, s77, v[6:7]
	v_mad_u64_u32 v[126:127], s[10:11], v17, s77, v[6:7]
	s_add_i32 s11, s9, 12
	s_add_i32 s10, s7, 12
	v_or_b32_e32 v40, s11, v2
	v_or_b32_e32 v17, s10, v3
	v_mov_b32_e32 v21, v1
	v_add_u32_e32 v0, s1, v40
	v_add_u32_e32 v20, s3, v17
	v_lshlrev_b64 v[22:23], 14, v[0:1]
	v_lshlrev_b64 v[20:21], 14, v[20:21]
	v_lshl_add_u64 v[22:23], v[18:19], 0, v[22:23]
	v_lshl_add_u64 v[20:21], v[18:19], 0, v[20:21]
	global_load_dword v106, v[22:23], off
	global_load_dword v107, v[20:21], off
	v_mad_u64_u32 v[128:129], s[10:11], v40, s77, v[6:7]
	v_mad_u64_u32 v[130:131], s[10:11], v17, s77, v[6:7]
	s_add_i32 s11, s9, 16
	s_add_i32 s10, s7, 16
	v_or_b32_e32 v40, s11, v2
	v_or_b32_e32 v17, s10, v3
	v_mov_b32_e32 v21, v1
	v_add_u32_e32 v0, s1, v40
	v_add_u32_e32 v20, s3, v17
	v_lshlrev_b64 v[22:23], 14, v[0:1]
	v_lshlrev_b64 v[20:21], 14, v[20:21]
	v_lshl_add_u64 v[22:23], v[18:19], 0, v[22:23]
	v_lshl_add_u64 v[20:21], v[18:19], 0, v[20:21]
	global_load_dword v108, v[22:23], off
	global_load_dword v109, v[20:21], off
	v_mad_u64_u32 v[132:133], s[10:11], v40, s77, v[6:7]
	v_mad_u64_u32 v[134:135], s[10:11], v17, s77, v[6:7]
	s_add_i32 s11, s9, 20
	s_add_i32 s10, s7, 20
	v_or_b32_e32 v40, s11, v2
	v_or_b32_e32 v17, s10, v3
	v_mov_b32_e32 v21, v1
	v_add_u32_e32 v0, s1, v40
	v_add_u32_e32 v20, s3, v17
	v_lshlrev_b64 v[22:23], 14, v[0:1]
	v_lshlrev_b64 v[20:21], 14, v[20:21]
	v_lshl_add_u64 v[22:23], v[18:19], 0, v[22:23]
	v_lshl_add_u64 v[20:21], v[18:19], 0, v[20:21]
	global_load_dword v110, v[22:23], off
	global_load_dword v111, v[20:21], off
	v_mad_u64_u32 v[136:137], s[10:11], v40, s77, v[6:7]
	v_mad_u64_u32 v[138:139], s[10:11], v17, s77, v[6:7]
	s_add_i32 s11, s9, 24
	s_add_i32 s10, s7, 24
	v_or_b32_e32 v40, s11, v2
	v_or_b32_e32 v17, s10, v3
	v_mov_b32_e32 v21, v1
	s_add_i32 s9, s9, 28
	s_add_i32 s7, s7, 28
	s_cmp_lg_u32 s6, 0
	v_add_u32_e32 v0, s1, v40
	v_add_u32_e32 v20, s3, v17
	v_lshlrev_b64 v[22:23], 14, v[0:1]
	v_lshlrev_b64 v[20:21], 14, v[20:21]
	v_lshl_add_u64 v[22:23], v[18:19], 0, v[22:23]
	v_lshl_add_u64 v[20:21], v[18:19], 0, v[20:21]
	global_load_dword v112, v[22:23], off
	global_load_dword v113, v[20:21], off
	v_mad_u64_u32 v[140:141], s[10:11], v40, s77, v[6:7]
	v_or_b32_e32 v40, s9, v2
	v_mad_u64_u32 v[142:143], s[10:11], v17, s77, v[6:7]
	v_or_b32_e32 v17, s7, v3
	v_mov_b32_e32 v21, v1
	v_add_u32_e32 v0, s1, v40
	v_add_u32_e32 v20, s3, v17
	v_lshlrev_b64 v[22:23], 14, v[0:1]
	v_lshlrev_b64 v[20:21], 14, v[20:21]
	v_lshl_add_u64 v[22:23], v[18:19], 0, v[22:23]
	v_lshl_add_u64 v[20:21], v[18:19], 0, v[20:21]
	global_load_dword v114, v[22:23], off
	global_load_dword v115, v[20:21], off
	v_mad_u64_u32 v[144:145], s[10:11], v40, s77, v[6:7]
	v_mad_u64_u32 v[146:147], s[10:11], v17, s77, v[6:7]
	s_lshl_b32 s9, s5, 1
	s_lshl_b32 s7, s2, 1
	v_or_b32_e32 v40, s9, v2
	v_or_b32_e32 v17, s7, v3
	v_add_u32_e32 v0, s1, v40
	v_add_u32_e32 v20, s3, v17
	v_mov_b32_e32 v21, v1
	v_lshlrev_b64 v[22:23], 14, v[0:1]
	v_lshlrev_b64 v[20:21], 14, v[20:21]
	v_lshl_add_u64 v[22:23], v[18:19], 0, v[22:23]
	v_lshl_add_u64 v[20:21], v[18:19], 0, v[20:21]
	global_load_dword v148, v[22:23], off
	global_load_dword v149, v[20:21], off
	v_mad_u64_u32 v[164:165], s[10:11], v40, s77, v[6:7]
	v_mad_u64_u32 v[166:167], s[10:11], v17, s77, v[6:7]
	s_add_i32 s11, s9, 4
	s_add_i32 s10, s7, 4
	v_or_b32_e32 v40, s11, v2
	v_or_b32_e32 v17, s10, v3
	v_mov_b32_e32 v21, v1
	s_add_i32 s5, s5, 16
	s_add_i32 s2, s2, 16
	s_add_i32 s6, s6, -16
	v_add_u32_e32 v0, s1, v40
	v_add_u32_e32 v20, s3, v17
	v_lshlrev_b64 v[22:23], 14, v[0:1]
	v_lshlrev_b64 v[20:21], 14, v[20:21]
	v_lshl_add_u64 v[22:23], v[18:19], 0, v[22:23]
	v_lshl_add_u64 v[20:21], v[18:19], 0, v[20:21]
	global_load_dword v150, v[22:23], off
	global_load_dword v151, v[20:21], off
	v_mad_u64_u32 v[168:169], s[10:11], v40, s77, v[6:7]
	v_mad_u64_u32 v[170:171], s[10:11], v17, s77, v[6:7]
	s_add_i32 s11, s9, 8
	s_add_i32 s10, s7, 8
	v_or_b32_e32 v40, s11, v2
	v_or_b32_e32 v17, s10, v3
	v_mov_b32_e32 v21, v1
	v_add_u32_e32 v0, s1, v40
	v_add_u32_e32 v20, s3, v17
	v_lshlrev_b64 v[22:23], 14, v[0:1]
	v_lshlrev_b64 v[20:21], 14, v[20:21]
	v_lshl_add_u64 v[22:23], v[18:19], 0, v[22:23]
	v_lshl_add_u64 v[20:21], v[18:19], 0, v[20:21]
	global_load_dword v152, v[22:23], off
	global_load_dword v153, v[20:21], off
	v_mad_u64_u32 v[172:173], s[10:11], v40, s77, v[6:7]
	v_mad_u64_u32 v[174:175], s[10:11], v17, s77, v[6:7]
	s_add_i32 s11, s9, 12
	s_add_i32 s10, s7, 12
	v_or_b32_e32 v40, s11, v2
	v_or_b32_e32 v17, s10, v3
	v_mov_b32_e32 v21, v1
	v_add_u32_e32 v0, s1, v40
	v_add_u32_e32 v20, s3, v17
	v_lshlrev_b64 v[22:23], 14, v[0:1]
	v_lshlrev_b64 v[20:21], 14, v[20:21]
	v_lshl_add_u64 v[22:23], v[18:19], 0, v[22:23]
	v_lshl_add_u64 v[20:21], v[18:19], 0, v[20:21]
	global_load_dword v154, v[22:23], off
	global_load_dword v155, v[20:21], off
	v_mad_u64_u32 v[176:177], s[10:11], v40, s77, v[6:7]
	v_mad_u64_u32 v[178:179], s[10:11], v17, s77, v[6:7]
	s_add_i32 s11, s9, 16
	s_add_i32 s10, s7, 16
	v_or_b32_e32 v40, s11, v2
	v_or_b32_e32 v17, s10, v3
	v_mov_b32_e32 v21, v1
	v_add_u32_e32 v0, s1, v40
	v_add_u32_e32 v20, s3, v17
	v_lshlrev_b64 v[22:23], 14, v[0:1]
	v_lshlrev_b64 v[20:21], 14, v[20:21]
	v_lshl_add_u64 v[22:23], v[18:19], 0, v[22:23]
	v_lshl_add_u64 v[20:21], v[18:19], 0, v[20:21]
	global_load_dword v156, v[22:23], off
	global_load_dword v157, v[20:21], off
	v_mad_u64_u32 v[180:181], s[10:11], v40, s77, v[6:7]
	v_mad_u64_u32 v[182:183], s[10:11], v17, s77, v[6:7]
	s_add_i32 s11, s9, 20
	s_add_i32 s10, s7, 20
	v_or_b32_e32 v40, s11, v2
	v_or_b32_e32 v17, s10, v3
	v_mov_b32_e32 v21, v1
	v_add_u32_e32 v0, s1, v40
	v_add_u32_e32 v20, s3, v17
	v_lshlrev_b64 v[22:23], 14, v[0:1]
	v_lshlrev_b64 v[20:21], 14, v[20:21]
	v_lshl_add_u64 v[22:23], v[18:19], 0, v[22:23]
	v_lshl_add_u64 v[20:21], v[18:19], 0, v[20:21]
	global_load_dword v158, v[22:23], off
	global_load_dword v159, v[20:21], off
	v_mad_u64_u32 v[184:185], s[10:11], v40, s77, v[6:7]
	v_mad_u64_u32 v[186:187], s[10:11], v17, s77, v[6:7]
	s_add_i32 s11, s9, 24
	s_add_i32 s10, s7, 24
	v_or_b32_e32 v40, s11, v2
	v_or_b32_e32 v17, s10, v3
	v_mov_b32_e32 v21, v1
	s_add_i32 s9, s9, 28
	s_add_i32 s7, s7, 28
	s_cmp_lg_u32 s6, 0
	v_add_u32_e32 v0, s1, v40
	v_add_u32_e32 v20, s3, v17
	v_lshlrev_b64 v[22:23], 14, v[0:1]
	v_lshlrev_b64 v[20:21], 14, v[20:21]
	v_lshl_add_u64 v[22:23], v[18:19], 0, v[22:23]
	v_lshl_add_u64 v[20:21], v[18:19], 0, v[20:21]
	global_load_dword v160, v[22:23], off
	global_load_dword v161, v[20:21], off
	v_mad_u64_u32 v[188:189], s[10:11], v40, s77, v[6:7]
	v_or_b32_e32 v40, s9, v2
	v_mad_u64_u32 v[190:191], s[10:11], v17, s77, v[6:7]
	v_or_b32_e32 v17, s7, v3
	v_mov_b32_e32 v21, v1
	v_add_u32_e32 v0, s1, v40
	v_add_u32_e32 v20, s3, v17
	v_lshlrev_b64 v[22:23], 14, v[0:1]
	v_lshlrev_b64 v[20:21], 14, v[20:21]
	v_lshl_add_u64 v[22:23], v[18:19], 0, v[22:23]
	v_lshl_add_u64 v[20:21], v[18:19], 0, v[20:21]
	global_load_dword v162, v[22:23], off
	global_load_dword v163, v[20:21], off
	v_mad_u64_u32 v[192:193], s[10:11], v40, s77, v[6:7]
	v_mad_u64_u32 v[196:197], s[10:11], v17, s77, v[6:7]
	s_waitcnt vmcnt(0)
	ds_write_b32 v116, v100
	ds_write_b32 v118, v101
	ds_write_b32 v120, v102
	ds_write_b32 v122, v103
	ds_write_b32 v124, v104
	ds_write_b32 v126, v105
	ds_write_b32 v128, v106
	ds_write_b32 v130, v107
	ds_write_b32 v132, v108
	ds_write_b32 v134, v109
	ds_write_b32 v136, v110
	ds_write_b32 v138, v111
	ds_write_b32 v140, v112
	ds_write_b32 v142, v113
	ds_write_b32 v144, v114
	ds_write_b32 v146, v115
	ds_write_b32 v164, v148
	ds_write_b32 v166, v149
	ds_write_b32 v168, v150
	ds_write_b32 v170, v151
	ds_write_b32 v172, v152
	ds_write_b32 v174, v153
	ds_write_b32 v176, v154
	ds_write_b32 v178, v155
	ds_write_b32 v180, v156
	ds_write_b32 v182, v157
	ds_write_b32 v184, v158
	ds_write_b32 v186, v159
	ds_write_b32 v188, v160
	ds_write_b32 v190, v161
	ds_write_b32 v192, v162
	ds_write_b32 v196, v163
	s_cbranch_scc1 .LBB0_355
	v_readlane_b32 s12, v249, 0
	s_lshl_b32 s0, s0, 11
	v_readlane_b32 s18, v249, 6
	v_readlane_b32 s19, v249, 7
	s_add_u32 s0, s18, s0
	s_addc_u32 s2, s19, 0
	s_lshl_b32 s1, s1, 1
	s_add_u32 s0, s0, s1
	s_addc_u32 s1, s2, 0
	s_add_u32 s0, s0, 0x680000
	s_addc_u32 s1, s1, 0
	v_mov_b32_e32 v0, v39
	v_mov_b32_e32 v18, v38
	v_mov_b32_e32 v20, v37
	v_mov_b32_e32 v22, v36
	v_readlane_b32 s13, v249, 1
	v_readlane_b32 s14, v249, 2
	v_readlane_b32 s15, v249, 3
	v_readlane_b32 s16, v249, 4
	v_readlane_b32 s17, v249, 5

.LBB0_360:
	s_lshl_b32 s10, s3, 1
	s_lshl_b32 s9, s2, 1
	v_or_b32_e32 v17, s10, v2
	v_or_b32_e32 v0, s9, v3
	v_add_u32_e32 v20, s0, v17
	v_add_u32_e32 v22, s1, v0
	v_mad_i64_i32 v[20:21], s[12:13], v20, s62, v[18:19]
	v_mad_i64_i32 v[22:23], s[12:13], v22, s62, v[18:19]
	global_load_dword v100, v[20:21], off
	global_load_dword v101, v[22:23], off
	v_mad_u64_u32 v[116:117], s[12:13], v17, s77, v[6:7]
	v_mad_u64_u32 v[118:119], s[12:13], v0, s77, v[6:7]
	s_add_i32 s12, s10, 4
	s_add_i32 s11, s9, 4
	v_or_b32_e32 v17, s12, v2
	v_or_b32_e32 v0, s11, v3
	s_add_i32 s11, s9, 8
	s_add_i32 s3, s3, 16
	s_add_i32 s2, s2, 16
	s_add_i32 s5, s5, -16
	v_add_u32_e32 v20, s0, v17
	v_add_u32_e32 v22, s1, v0
	v_mad_i64_i32 v[20:21], s[12:13], v20, s62, v[18:19]
	v_mad_i64_i32 v[22:23], s[12:13], v22, s62, v[18:19]
	global_load_dword v102, v[20:21], off
	global_load_dword v103, v[22:23], off
	v_mad_u64_u32 v[120:121], s[12:13], v17, s77, v[6:7]
	v_mad_u64_u32 v[122:123], s[12:13], v0, s77, v[6:7]
	s_add_i32 s12, s10, 8
	s_nop 0
	v_or_b32_e32 v17, s12, v2
	v_or_b32_e32 v0, s11, v3
	s_add_i32 s11, s9, 12
	v_add_u32_e32 v20, s0, v17
	v_add_u32_e32 v22, s1, v0
	v_mad_i64_i32 v[20:21], s[12:13], v20, s62, v[18:19]
	v_mad_i64_i32 v[22:23], s[12:13], v22, s62, v[18:19]
	global_load_dword v104, v[20:21], off
	global_load_dword v105, v[22:23], off
	v_mad_u64_u32 v[124:125], s[12:13], v17, s77, v[6:7]
	v_mad_u64_u32 v[126:127], s[12:13], v0, s77, v[6:7]
	s_add_i32 s12, s10, 12
	s_nop 0
	v_or_b32_e32 v17, s12, v2
	v_or_b32_e32 v0, s11, v3
	s_add_i32 s11, s9, 16
	v_add_u32_e32 v20, s0, v17
	v_add_u32_e32 v22, s1, v0
	v_mad_i64_i32 v[20:21], s[12:13], v20, s62, v[18:19]
	v_mad_i64_i32 v[22:23], s[12:13], v22, s62, v[18:19]
	global_load_dword v106, v[20:21], off
	global_load_dword v107, v[22:23], off
	v_mad_u64_u32 v[128:129], s[12:13], v17, s77, v[6:7]
	v_mad_u64_u32 v[130:131], s[12:13], v0, s77, v[6:7]
	s_add_i32 s12, s10, 16
	s_nop 0
	v_or_b32_e32 v17, s12, v2
	v_or_b32_e32 v0, s11, v3
	s_add_i32 s11, s9, 20
	v_add_u32_e32 v20, s0, v17
	v_add_u32_e32 v22, s1, v0
	v_mad_i64_i32 v[20:21], s[12:13], v20, s62, v[18:19]
	v_mad_i64_i32 v[22:23], s[12:13], v22, s62, v[18:19]
	global_load_dword v108, v[20:21], off
	global_load_dword v109, v[22:23], off
	v_mad_u64_u32 v[132:133], s[12:13], v17, s77, v[6:7]
	v_mad_u64_u32 v[134:135], s[12:13], v0, s77, v[6:7]
	s_add_i32 s12, s10, 20
	s_nop 0
	v_or_b32_e32 v17, s12, v2
	v_or_b32_e32 v0, s11, v3
	s_add_i32 s11, s9, 24
	s_add_i32 s9, s9, 28
	v_add_u32_e32 v20, s0, v17
	v_add_u32_e32 v22, s1, v0
	v_mad_i64_i32 v[20:21], s[12:13], v20, s62, v[18:19]
	v_mad_i64_i32 v[22:23], s[12:13], v22, s62, v[18:19]
	global_load_dword v110, v[20:21], off
	global_load_dword v111, v[22:23], off
	v_mad_u64_u32 v[136:137], s[12:13], v17, s77, v[6:7]
	v_mad_u64_u32 v[138:139], s[12:13], v0, s77, v[6:7]
	s_add_i32 s12, s10, 24
	s_nop 0
	v_or_b32_e32 v17, s12, v2
	v_or_b32_e32 v0, s11, v3
	s_add_i32 s10, s10, 28
	s_cmp_lg_u32 s5, 0
	v_add_u32_e32 v20, s0, v17
	v_add_u32_e32 v22, s1, v0
	v_mad_i64_i32 v[20:21], s[12:13], v20, s62, v[18:19]
	v_mad_i64_i32 v[22:23], s[12:13], v22, s62, v[18:19]
	global_load_dword v112, v[20:21], off
	global_load_dword v113, v[22:23], off
	v_mad_u64_u32 v[140:141], s[12:13], v17, s77, v[6:7]
	v_or_b32_e32 v17, s10, v2
	v_mad_u64_u32 v[142:143], s[12:13], v0, s77, v[6:7]
	v_or_b32_e32 v0, s9, v3
	v_add_u32_e32 v20, s0, v17
	v_add_u32_e32 v22, s1, v0
	v_mad_i64_i32 v[20:21], s[10:11], v20, s62, v[18:19]
	v_mad_i64_i32 v[22:23], s[10:11], v22, s62, v[18:19]
	global_load_dword v114, v[20:21], off
	global_load_dword v115, v[22:23], off
	v_mad_u64_u32 v[144:145], s[10:11], v17, s77, v[6:7]
	v_mad_u64_u32 v[146:147], s[10:11], v0, s77, v[6:7]
	s_lshl_b32 s10, s3, 1
	s_lshl_b32 s9, s2, 1
	v_or_b32_e32 v17, s10, v2
	v_or_b32_e32 v0, s9, v3
	v_add_u32_e32 v20, s0, v17
	v_add_u32_e32 v22, s1, v0
	v_mad_i64_i32 v[20:21], s[12:13], v20, s62, v[18:19]
	v_mad_i64_i32 v[22:23], s[12:13], v22, s62, v[18:19]
	global_load_dword v148, v[20:21], off
	global_load_dword v149, v[22:23], off
	v_mad_u64_u32 v[164:165], s[12:13], v17, s77, v[6:7]
	v_mad_u64_u32 v[166:167], s[12:13], v0, s77, v[6:7]
	s_add_i32 s12, s10, 4
	s_add_i32 s11, s9, 4
	v_or_b32_e32 v17, s12, v2
	v_or_b32_e32 v0, s11, v3
	s_add_i32 s11, s9, 8
	s_add_i32 s3, s3, 16
	s_add_i32 s2, s2, 16
	s_add_i32 s5, s5, -16
	v_add_u32_e32 v20, s0, v17
	v_add_u32_e32 v22, s1, v0
	v_mad_i64_i32 v[20:21], s[12:13], v20, s62, v[18:19]
	v_mad_i64_i32 v[22:23], s[12:13], v22, s62, v[18:19]
	global_load_dword v150, v[20:21], off
	global_load_dword v151, v[22:23], off
	v_mad_u64_u32 v[168:169], s[12:13], v17, s77, v[6:7]
	v_mad_u64_u32 v[170:171], s[12:13], v0, s77, v[6:7]
	s_add_i32 s12, s10, 8
	s_nop 0
	v_or_b32_e32 v17, s12, v2
	v_or_b32_e32 v0, s11, v3
	s_add_i32 s11, s9, 12
	v_add_u32_e32 v20, s0, v17
	v_add_u32_e32 v22, s1, v0
	v_mad_i64_i32 v[20:21], s[12:13], v20, s62, v[18:19]
	v_mad_i64_i32 v[22:23], s[12:13], v22, s62, v[18:19]
	global_load_dword v152, v[20:21], off
	global_load_dword v153, v[22:23], off
	v_mad_u64_u32 v[172:173], s[12:13], v17, s77, v[6:7]
	v_mad_u64_u32 v[174:175], s[12:13], v0, s77, v[6:7]
	s_add_i32 s12, s10, 12
	s_nop 0
	v_or_b32_e32 v17, s12, v2
	v_or_b32_e32 v0, s11, v3
	s_add_i32 s11, s9, 16
	v_add_u32_e32 v20, s0, v17
	v_add_u32_e32 v22, s1, v0
	v_mad_i64_i32 v[20:21], s[12:13], v20, s62, v[18:19]
	v_mad_i64_i32 v[22:23], s[12:13], v22, s62, v[18:19]
	global_load_dword v154, v[20:21], off
	global_load_dword v155, v[22:23], off
	v_mad_u64_u32 v[176:177], s[12:13], v17, s77, v[6:7]
	v_mad_u64_u32 v[178:179], s[12:13], v0, s77, v[6:7]
	s_add_i32 s12, s10, 16
	s_nop 0
	v_or_b32_e32 v17, s12, v2
	v_or_b32_e32 v0, s11, v3
	s_add_i32 s11, s9, 20
	v_add_u32_e32 v20, s0, v17
	v_add_u32_e32 v22, s1, v0
	v_mad_i64_i32 v[20:21], s[12:13], v20, s62, v[18:19]
	v_mad_i64_i32 v[22:23], s[12:13], v22, s62, v[18:19]
	global_load_dword v156, v[20:21], off
	global_load_dword v157, v[22:23], off
	v_mad_u64_u32 v[180:181], s[12:13], v17, s77, v[6:7]
	v_mad_u64_u32 v[182:183], s[12:13], v0, s77, v[6:7]
	s_add_i32 s12, s10, 20
	s_nop 0
	v_or_b32_e32 v17, s12, v2
	v_or_b32_e32 v0, s11, v3
	s_add_i32 s11, s9, 24
	s_add_i32 s9, s9, 28
	v_add_u32_e32 v20, s0, v17
	v_add_u32_e32 v22, s1, v0
	v_mad_i64_i32 v[20:21], s[12:13], v20, s62, v[18:19]
	v_mad_i64_i32 v[22:23], s[12:13], v22, s62, v[18:19]
	global_load_dword v158, v[20:21], off
	global_load_dword v159, v[22:23], off
	v_mad_u64_u32 v[184:185], s[12:13], v17, s77, v[6:7]
	v_mad_u64_u32 v[186:187], s[12:13], v0, s77, v[6:7]
	s_add_i32 s12, s10, 24
	s_nop 0
	v_or_b32_e32 v17, s12, v2
	v_or_b32_e32 v0, s11, v3
	s_add_i32 s10, s10, 28
	s_cmp_lg_u32 s5, 0
	v_add_u32_e32 v20, s0, v17
	v_add_u32_e32 v22, s1, v0
	v_mad_i64_i32 v[20:21], s[12:13], v20, s62, v[18:19]
	v_mad_i64_i32 v[22:23], s[12:13], v22, s62, v[18:19]
	global_load_dword v160, v[20:21], off
	global_load_dword v161, v[22:23], off
	v_mad_u64_u32 v[188:189], s[12:13], v17, s77, v[6:7]
	v_or_b32_e32 v17, s10, v2
	v_mad_u64_u32 v[190:191], s[12:13], v0, s77, v[6:7]
	v_or_b32_e32 v0, s9, v3
	v_add_u32_e32 v20, s0, v17
	v_add_u32_e32 v22, s1, v0
	v_mad_i64_i32 v[20:21], s[10:11], v20, s62, v[18:19]
	v_mad_i64_i32 v[22:23], s[10:11], v22, s62, v[18:19]
	global_load_dword v162, v[20:21], off
	global_load_dword v163, v[22:23], off
	v_mad_u64_u32 v[192:193], s[10:11], v17, s77, v[6:7]
	v_mad_u64_u32 v[196:197], s[10:11], v0, s77, v[6:7]
	s_waitcnt vmcnt(0)
	ds_write_b32 v116, v100
	ds_write_b32 v118, v101
	ds_write_b32 v120, v102
	ds_write_b32 v122, v103
	ds_write_b32 v124, v104
	ds_write_b32 v126, v105
	ds_write_b32 v128, v106
	ds_write_b32 v130, v107
	ds_write_b32 v132, v108
	ds_write_b32 v134, v109
	ds_write_b32 v136, v110
	ds_write_b32 v138, v111
	ds_write_b32 v140, v112
	ds_write_b32 v142, v113
	ds_write_b32 v144, v114
	ds_write_b32 v146, v115
	ds_write_b32 v164, v148
	ds_write_b32 v166, v149
	ds_write_b32 v168, v150
	ds_write_b32 v170, v151
	ds_write_b32 v172, v152
	ds_write_b32 v174, v153
	ds_write_b32 v176, v154
	ds_write_b32 v178, v155
	ds_write_b32 v180, v156
	ds_write_b32 v182, v157
	ds_write_b32 v184, v158
	ds_write_b32 v186, v159
	ds_write_b32 v188, v160
	ds_write_b32 v190, v161
	ds_write_b32 v192, v162
	ds_write_b32 v196, v163
	s_cbranch_scc1 .LBB0_360
	v_readlane_b32 s12, v249, 0
	s_lshl_b64 s[2:3], s[6:7], 11
	v_readlane_b32 s18, v249, 6
	v_readlane_b32 s19, v249, 7
	s_add_u32 s2, s18, s2
	s_addc_u32 s3, s19, s3
	s_ashr_i32 s1, s0, 31
	s_lshl_b64 s[0:1], s[0:1], 1
	s_add_u32 s0, s2, s0
	s_addc_u32 s1, s3, s1
	v_mov_b32_e32 v0, v39
	v_mov_b32_e32 v18, v38
	v_mov_b32_e32 v20, v37
	v_mov_b32_e32 v22, v36
	v_readlane_b32 s13, v249, 1
	v_readlane_b32 s14, v249, 2
	v_readlane_b32 s15, v249, 3
	v_readlane_b32 s16, v249, 4
	v_readlane_b32 s17, v249, 5
	s_branch .LBB0_332

.LBB0_668:
	s_lshl_b32 s11, s6, 1
	s_lshl_b32 s10, s2, 1
	v_or_b32_e32 v23, s11, v2
	v_or_b32_e32 v0, s10, v3
	v_add_u32_e32 v30, s0, v23
	v_add_u32_e32 v28, s3, v0
	v_ashrrev_i32_e32 v31, 31, v30
	v_ashrrev_i32_e32 v29, 31, v28
	v_lshlrev_b64 v[30:31], 12, v[30:31]
	v_lshlrev_b64 v[28:29], 12, v[28:29]
	v_lshl_add_u64 v[30:31], v[26:27], 0, v[30:31]
	v_lshl_add_u64 v[28:29], v[26:27], 0, v[28:29]
	global_load_dword v100, v[30:31], off
	global_load_dword v101, v[28:29], off
	v_mad_u64_u32 v[116:117], s[12:13], v23, s77, v[6:7]
	v_mad_u64_u32 v[118:119], s[12:13], v0, s77, v[6:7]
	s_add_i32 s13, s11, 4
	s_add_i32 s12, s10, 4
	v_or_b32_e32 v23, s13, v2
	v_or_b32_e32 v0, s12, v3
	s_add_i32 s6, s6, 16
	s_add_i32 s2, s2, 16
	s_add_i32 s7, s7, -16
	v_add_u32_e32 v30, s0, v23
	v_add_u32_e32 v28, s3, v0
	v_ashrrev_i32_e32 v31, 31, v30
	v_ashrrev_i32_e32 v29, 31, v28
	v_lshlrev_b64 v[30:31], 12, v[30:31]
	v_lshlrev_b64 v[28:29], 12, v[28:29]
	v_lshl_add_u64 v[30:31], v[26:27], 0, v[30:31]
	v_lshl_add_u64 v[28:29], v[26:27], 0, v[28:29]
	global_load_dword v102, v[30:31], off
	global_load_dword v103, v[28:29], off
	v_mad_u64_u32 v[120:121], s[12:13], v23, s77, v[6:7]
	v_mad_u64_u32 v[122:123], s[12:13], v0, s77, v[6:7]
	s_add_i32 s13, s11, 8
	s_add_i32 s12, s10, 8
	v_or_b32_e32 v23, s13, v2
	v_or_b32_e32 v0, s12, v3
	v_add_u32_e32 v30, s0, v23
	v_add_u32_e32 v28, s3, v0
	v_ashrrev_i32_e32 v31, 31, v30
	v_ashrrev_i32_e32 v29, 31, v28
	v_lshlrev_b64 v[30:31], 12, v[30:31]
	v_lshlrev_b64 v[28:29], 12, v[28:29]
	v_lshl_add_u64 v[30:31], v[26:27], 0, v[30:31]
	v_lshl_add_u64 v[28:29], v[26:27], 0, v[28:29]
	global_load_dword v104, v[30:31], off
	global_load_dword v105, v[28:29], off
	v_mad_u64_u32 v[124:125], s[12:13], v23, s77, v[6:7]
	v_mad_u64_u32 v[126:127], s[12:13], v0, s77, v[6:7]
	s_add_i32 s13, s11, 12
	s_add_i32 s12, s10, 12
	v_or_b32_e32 v23, s13, v2
	v_or_b32_e32 v0, s12, v3
	v_add_u32_e32 v30, s0, v23
	v_add_u32_e32 v28, s3, v0
	v_ashrrev_i32_e32 v31, 31, v30
	v_ashrrev_i32_e32 v29, 31, v28
	v_lshlrev_b64 v[30:31], 12, v[30:31]
	v_lshlrev_b64 v[28:29], 12, v[28:29]
	v_lshl_add_u64 v[30:31], v[26:27], 0, v[30:31]
	v_lshl_add_u64 v[28:29], v[26:27], 0, v[28:29]
	global_load_dword v106, v[30:31], off
	global_load_dword v107, v[28:29], off
	v_mad_u64_u32 v[128:129], s[12:13], v23, s77, v[6:7]
	v_mad_u64_u32 v[130:131], s[12:13], v0, s77, v[6:7]
	s_add_i32 s13, s11, 16
	s_add_i32 s12, s10, 16
	v_or_b32_e32 v23, s13, v2
	v_or_b32_e32 v0, s12, v3
	v_add_u32_e32 v30, s0, v23
	v_add_u32_e32 v28, s3, v0
	v_ashrrev_i32_e32 v31, 31, v30
	v_ashrrev_i32_e32 v29, 31, v28
	v_lshlrev_b64 v[30:31], 12, v[30:31]
	v_lshlrev_b64 v[28:29], 12, v[28:29]
	v_lshl_add_u64 v[30:31], v[26:27], 0, v[30:31]
	v_lshl_add_u64 v[28:29], v[26:27], 0, v[28:29]
	global_load_dword v108, v[30:31], off
	global_load_dword v109, v[28:29], off
	v_mad_u64_u32 v[132:133], s[12:13], v23, s77, v[6:7]
	v_mad_u64_u32 v[134:135], s[12:13], v0, s77, v[6:7]
	s_add_i32 s13, s11, 20
	s_add_i32 s12, s10, 20
	v_or_b32_e32 v23, s13, v2
	v_or_b32_e32 v0, s12, v3
	v_add_u32_e32 v30, s0, v23
	v_add_u32_e32 v28, s3, v0
	v_ashrrev_i32_e32 v31, 31, v30
	v_ashrrev_i32_e32 v29, 31, v28
	v_lshlrev_b64 v[30:31], 12, v[30:31]
	v_lshlrev_b64 v[28:29], 12, v[28:29]
	v_lshl_add_u64 v[30:31], v[26:27], 0, v[30:31]
	v_lshl_add_u64 v[28:29], v[26:27], 0, v[28:29]
	global_load_dword v110, v[30:31], off
	global_load_dword v111, v[28:29], off
	v_mad_u64_u32 v[136:137], s[12:13], v23, s77, v[6:7]
	v_mad_u64_u32 v[138:139], s[12:13], v0, s77, v[6:7]
	s_add_i32 s13, s11, 24
	s_add_i32 s12, s10, 24
	v_or_b32_e32 v23, s13, v2
	v_or_b32_e32 v0, s12, v3
	s_add_i32 s11, s11, 28
	s_add_i32 s10, s10, 28
	s_cmp_lg_u32 s7, 0
	v_add_u32_e32 v30, s0, v23
	v_add_u32_e32 v28, s3, v0
	v_ashrrev_i32_e32 v31, 31, v30
	v_ashrrev_i32_e32 v29, 31, v28
	v_lshlrev_b64 v[30:31], 12, v[30:31]
	v_lshlrev_b64 v[28:29], 12, v[28:29]
	v_lshl_add_u64 v[30:31], v[26:27], 0, v[30:31]
	v_lshl_add_u64 v[28:29], v[26:27], 0, v[28:29]
	global_load_dword v112, v[30:31], off
	global_load_dword v113, v[28:29], off
	v_mad_u64_u32 v[140:141], s[12:13], v23, s77, v[6:7]
	v_mad_u64_u32 v[142:143], s[12:13], v0, s77, v[6:7]
	v_or_b32_e32 v23, s11, v2
	v_or_b32_e32 v0, s10, v3
	v_add_u32_e32 v30, s0, v23
	v_add_u32_e32 v28, s3, v0
	v_ashrrev_i32_e32 v31, 31, v30
	v_ashrrev_i32_e32 v29, 31, v28
	v_lshlrev_b64 v[30:31], 12, v[30:31]
	v_lshlrev_b64 v[28:29], 12, v[28:29]
	v_lshl_add_u64 v[30:31], v[26:27], 0, v[30:31]
	v_lshl_add_u64 v[28:29], v[26:27], 0, v[28:29]
	global_load_dword v114, v[30:31], off
	global_load_dword v115, v[28:29], off
	v_mad_u64_u32 v[144:145], s[10:11], v23, s77, v[6:7]
	v_mad_u64_u32 v[146:147], s[10:11], v0, s77, v[6:7]
	s_lshl_b32 s11, s6, 1
	s_lshl_b32 s10, s2, 1
	v_or_b32_e32 v23, s11, v2
	v_or_b32_e32 v0, s10, v3
	v_add_u32_e32 v30, s0, v23
	v_add_u32_e32 v28, s3, v0
	v_ashrrev_i32_e32 v31, 31, v30
	v_ashrrev_i32_e32 v29, 31, v28
	v_lshlrev_b64 v[30:31], 12, v[30:31]
	v_lshlrev_b64 v[28:29], 12, v[28:29]
	v_lshl_add_u64 v[30:31], v[26:27], 0, v[30:31]
	v_lshl_add_u64 v[28:29], v[26:27], 0, v[28:29]
	global_load_dword v148, v[30:31], off
	global_load_dword v149, v[28:29], off
	v_mad_u64_u32 v[164:165], s[12:13], v23, s77, v[6:7]
	v_mad_u64_u32 v[166:167], s[12:13], v0, s77, v[6:7]
	s_add_i32 s13, s11, 4
	s_add_i32 s12, s10, 4
	v_or_b32_e32 v23, s13, v2
	v_or_b32_e32 v0, s12, v3
	s_add_i32 s6, s6, 16
	s_add_i32 s2, s2, 16
	s_add_i32 s7, s7, -16
	v_add_u32_e32 v30, s0, v23
	v_add_u32_e32 v28, s3, v0
	v_ashrrev_i32_e32 v31, 31, v30
	v_ashrrev_i32_e32 v29, 31, v28
	v_lshlrev_b64 v[30:31], 12, v[30:31]
	v_lshlrev_b64 v[28:29], 12, v[28:29]
	v_lshl_add_u64 v[30:31], v[26:27], 0, v[30:31]
	v_lshl_add_u64 v[28:29], v[26:27], 0, v[28:29]
	global_load_dword v150, v[30:31], off
	global_load_dword v151, v[28:29], off
	v_mad_u64_u32 v[168:169], s[12:13], v23, s77, v[6:7]
	v_mad_u64_u32 v[170:171], s[12:13], v0, s77, v[6:7]
	s_add_i32 s13, s11, 8
	s_add_i32 s12, s10, 8
	v_or_b32_e32 v23, s13, v2
	v_or_b32_e32 v0, s12, v3
	v_add_u32_e32 v30, s0, v23
	v_add_u32_e32 v28, s3, v0
	v_ashrrev_i32_e32 v31, 31, v30
	v_ashrrev_i32_e32 v29, 31, v28
	v_lshlrev_b64 v[30:31], 12, v[30:31]
	v_lshlrev_b64 v[28:29], 12, v[28:29]
	v_lshl_add_u64 v[30:31], v[26:27], 0, v[30:31]
	v_lshl_add_u64 v[28:29], v[26:27], 0, v[28:29]
	global_load_dword v152, v[30:31], off
	global_load_dword v153, v[28:29], off
	v_mad_u64_u32 v[172:173], s[12:13], v23, s77, v[6:7]
	v_mad_u64_u32 v[174:175], s[12:13], v0, s77, v[6:7]
	s_add_i32 s13, s11, 12
	s_add_i32 s12, s10, 12
	v_or_b32_e32 v23, s13, v2
	v_or_b32_e32 v0, s12, v3
	v_add_u32_e32 v30, s0, v23
	v_add_u32_e32 v28, s3, v0
	v_ashrrev_i32_e32 v31, 31, v30
	v_ashrrev_i32_e32 v29, 31, v28
	v_lshlrev_b64 v[30:31], 12, v[30:31]
	v_lshlrev_b64 v[28:29], 12, v[28:29]
	v_lshl_add_u64 v[30:31], v[26:27], 0, v[30:31]
	v_lshl_add_u64 v[28:29], v[26:27], 0, v[28:29]
	global_load_dword v154, v[30:31], off
	global_load_dword v155, v[28:29], off
	v_mad_u64_u32 v[176:177], s[12:13], v23, s77, v[6:7]
	v_mad_u64_u32 v[178:179], s[12:13], v0, s77, v[6:7]
	s_add_i32 s13, s11, 16
	s_add_i32 s12, s10, 16
	v_or_b32_e32 v23, s13, v2
	v_or_b32_e32 v0, s12, v3
	v_add_u32_e32 v30, s0, v23
	v_add_u32_e32 v28, s3, v0
	v_ashrrev_i32_e32 v31, 31, v30
	v_ashrrev_i32_e32 v29, 31, v28
	v_lshlrev_b64 v[30:31], 12, v[30:31]
	v_lshlrev_b64 v[28:29], 12, v[28:29]
	v_lshl_add_u64 v[30:31], v[26:27], 0, v[30:31]
	v_lshl_add_u64 v[28:29], v[26:27], 0, v[28:29]
	global_load_dword v156, v[30:31], off
	global_load_dword v157, v[28:29], off
	v_mad_u64_u32 v[180:181], s[12:13], v23, s77, v[6:7]
	v_mad_u64_u32 v[182:183], s[12:13], v0, s77, v[6:7]
	s_add_i32 s13, s11, 20
	s_add_i32 s12, s10, 20
	v_or_b32_e32 v23, s13, v2
	v_or_b32_e32 v0, s12, v3
	v_add_u32_e32 v30, s0, v23
	v_add_u32_e32 v28, s3, v0
	v_ashrrev_i32_e32 v31, 31, v30
	v_ashrrev_i32_e32 v29, 31, v28
	v_lshlrev_b64 v[30:31], 12, v[30:31]
	v_lshlrev_b64 v[28:29], 12, v[28:29]
	v_lshl_add_u64 v[30:31], v[26:27], 0, v[30:31]
	v_lshl_add_u64 v[28:29], v[26:27], 0, v[28:29]
	global_load_dword v158, v[30:31], off
	global_load_dword v159, v[28:29], off
	v_mad_u64_u32 v[184:185], s[12:13], v23, s77, v[6:7]
	v_mad_u64_u32 v[186:187], s[12:13], v0, s77, v[6:7]
	s_add_i32 s13, s11, 24
	s_add_i32 s12, s10, 24
	v_or_b32_e32 v23, s13, v2
	v_or_b32_e32 v0, s12, v3
	s_add_i32 s11, s11, 28
	s_add_i32 s10, s10, 28
	s_cmp_lg_u32 s7, 0
	v_add_u32_e32 v30, s0, v23
	v_add_u32_e32 v28, s3, v0
	v_ashrrev_i32_e32 v31, 31, v30
	v_ashrrev_i32_e32 v29, 31, v28
	v_lshlrev_b64 v[30:31], 12, v[30:31]
	v_lshlrev_b64 v[28:29], 12, v[28:29]
	v_lshl_add_u64 v[30:31], v[26:27], 0, v[30:31]
	v_lshl_add_u64 v[28:29], v[26:27], 0, v[28:29]
	global_load_dword v160, v[30:31], off
	global_load_dword v161, v[28:29], off
	v_mad_u64_u32 v[188:189], s[12:13], v23, s77, v[6:7]
	v_mad_u64_u32 v[190:191], s[12:13], v0, s77, v[6:7]
	v_or_b32_e32 v23, s11, v2
	v_or_b32_e32 v0, s10, v3
	v_add_u32_e32 v30, s0, v23
	v_add_u32_e32 v28, s3, v0
	v_ashrrev_i32_e32 v31, 31, v30
	v_ashrrev_i32_e32 v29, 31, v28
	v_lshlrev_b64 v[30:31], 12, v[30:31]
	v_lshlrev_b64 v[28:29], 12, v[28:29]
	v_lshl_add_u64 v[30:31], v[26:27], 0, v[30:31]
	v_lshl_add_u64 v[28:29], v[26:27], 0, v[28:29]
	global_load_dword v162, v[30:31], off
	global_load_dword v163, v[28:29], off
	v_mad_u64_u32 v[192:193], s[10:11], v23, s77, v[6:7]
	v_mad_u64_u32 v[196:197], s[10:11], v0, s77, v[6:7]
	s_waitcnt vmcnt(0)
	ds_write_b32 v116, v100
	ds_write_b32 v118, v101
	ds_write_b32 v120, v102
	ds_write_b32 v122, v103
	ds_write_b32 v124, v104
	ds_write_b32 v126, v105
	ds_write_b32 v128, v106
	ds_write_b32 v130, v107
	ds_write_b32 v132, v108
	ds_write_b32 v134, v109
	ds_write_b32 v136, v110
	ds_write_b32 v138, v111
	ds_write_b32 v140, v112
	ds_write_b32 v142, v113
	ds_write_b32 v144, v114
	ds_write_b32 v146, v115
	ds_write_b32 v164, v148
	ds_write_b32 v166, v149
	ds_write_b32 v168, v150
	ds_write_b32 v170, v151
	ds_write_b32 v172, v152
	ds_write_b32 v174, v153
	ds_write_b32 v176, v154
	ds_write_b32 v178, v155
	ds_write_b32 v180, v156
	ds_write_b32 v182, v157
	ds_write_b32 v184, v158
	ds_write_b32 v186, v159
	ds_write_b32 v188, v160
	ds_write_b32 v190, v161
	ds_write_b32 v192, v162
	ds_write_b32 v196, v163
	s_cbranch_scc1 .LBB0_668
	s_mulk_i32 s1, 0x1600
	v_readlane_b32 s2, v249, 13
	s_add_u32 s2, s2, s1
	v_readlane_b32 s1, v249, 14
	s_addc_u32 s3, s1, 0
	s_mov_b32 s1, s4
	s_lshl_b64 s[0:1], s[0:1], 1
	s_add_u32 s0, s2, s0
	s_addc_u32 s1, s3, s1
	s_mov_b64 s[2:3], 0

.LBB0_676:
	s_lshl_b32 s12, s7, 1
	s_lshl_b32 s11, s6, 1
	v_or_b32_e32 v23, s12, v2
	v_or_b32_e32 v0, s11, v3
	v_add_u32_e32 v28, s1, v23
	v_add_u32_e32 v25, s3, v0
	v_mad_u64_u32 v[28:29], s[14:15], v28, s16, v[26:27]
	v_mad_u64_u32 v[30:31], s[14:15], v25, s16, v[26:27]
	global_load_dword v100, v[28:29], off
	global_load_dword v101, v[30:31], off
	v_mad_u64_u32 v[116:117], s[14:15], v23, s77, v[6:7]
	v_mad_u64_u32 v[118:119], s[14:15], v0, s77, v[6:7]
	s_add_i32 s14, s12, 4
	s_add_i32 s13, s11, 4
	v_or_b32_e32 v23, s14, v2
	v_or_b32_e32 v0, s13, v3
	s_add_i32 s13, s11, 8
	s_add_i32 s7, s7, 16
	s_add_i32 s6, s6, 16
	s_add_i32 s10, s10, -16
	v_add_u32_e32 v28, s1, v23
	v_add_u32_e32 v25, s3, v0
	v_mad_u64_u32 v[28:29], s[14:15], v28, s16, v[26:27]
	v_mad_u64_u32 v[30:31], s[14:15], v25, s16, v[26:27]
	global_load_dword v102, v[28:29], off
	global_load_dword v103, v[30:31], off
	v_mad_u64_u32 v[120:121], s[14:15], v23, s77, v[6:7]
	v_mad_u64_u32 v[122:123], s[14:15], v0, s77, v[6:7]
	s_add_i32 s14, s12, 8
	s_nop 0
	v_or_b32_e32 v23, s14, v2
	v_or_b32_e32 v0, s13, v3
	s_add_i32 s13, s11, 12
	v_add_u32_e32 v28, s1, v23
	v_add_u32_e32 v25, s3, v0
	v_mad_u64_u32 v[28:29], s[14:15], v28, s16, v[26:27]
	v_mad_u64_u32 v[30:31], s[14:15], v25, s16, v[26:27]
	global_load_dword v104, v[28:29], off
	global_load_dword v105, v[30:31], off
	v_mad_u64_u32 v[124:125], s[14:15], v23, s77, v[6:7]
	v_mad_u64_u32 v[126:127], s[14:15], v0, s77, v[6:7]
	s_add_i32 s14, s12, 12
	s_nop 0
	v_or_b32_e32 v23, s14, v2
	v_or_b32_e32 v0, s13, v3
	s_add_i32 s13, s11, 16
	v_add_u32_e32 v28, s1, v23
	v_add_u32_e32 v25, s3, v0
	v_mad_u64_u32 v[28:29], s[14:15], v28, s16, v[26:27]
	v_mad_u64_u32 v[30:31], s[14:15], v25, s16, v[26:27]
	global_load_dword v106, v[28:29], off
	global_load_dword v107, v[30:31], off
	v_mad_u64_u32 v[128:129], s[14:15], v23, s77, v[6:7]
	v_mad_u64_u32 v[130:131], s[14:15], v0, s77, v[6:7]
	s_add_i32 s14, s12, 16
	s_nop 0
	v_or_b32_e32 v23, s14, v2
	v_or_b32_e32 v0, s13, v3
	s_add_i32 s13, s11, 20
	v_add_u32_e32 v28, s1, v23
	v_add_u32_e32 v25, s3, v0
	v_mad_u64_u32 v[28:29], s[14:15], v28, s16, v[26:27]
	v_mad_u64_u32 v[30:31], s[14:15], v25, s16, v[26:27]
	global_load_dword v108, v[28:29], off
	global_load_dword v109, v[30:31], off
	v_mad_u64_u32 v[132:133], s[14:15], v23, s77, v[6:7]
	v_mad_u64_u32 v[134:135], s[14:15], v0, s77, v[6:7]
	s_add_i32 s14, s12, 20
	s_nop 0
	v_or_b32_e32 v23, s14, v2
	v_or_b32_e32 v0, s13, v3
	s_add_i32 s13, s11, 24
	s_add_i32 s11, s11, 28
	v_add_u32_e32 v28, s1, v23
	v_add_u32_e32 v25, s3, v0
	v_mad_u64_u32 v[28:29], s[14:15], v28, s16, v[26:27]
	v_mad_u64_u32 v[30:31], s[14:15], v25, s16, v[26:27]
	global_load_dword v110, v[28:29], off
	global_load_dword v111, v[30:31], off
	v_mad_u64_u32 v[136:137], s[14:15], v23, s77, v[6:7]
	v_mad_u64_u32 v[138:139], s[14:15], v0, s77, v[6:7]
	s_add_i32 s14, s12, 24
	s_nop 0
	v_or_b32_e32 v23, s14, v2
	v_or_b32_e32 v0, s13, v3
	s_add_i32 s12, s12, 28
	s_cmp_lg_u32 s10, 0
	v_add_u32_e32 v28, s1, v23
	v_add_u32_e32 v25, s3, v0
	v_mad_u64_u32 v[28:29], s[14:15], v28, s16, v[26:27]
	v_mad_u64_u32 v[30:31], s[14:15], v25, s16, v[26:27]
	global_load_dword v112, v[28:29], off
	global_load_dword v113, v[30:31], off
	v_mad_u64_u32 v[140:141], s[14:15], v23, s77, v[6:7]
	v_or_b32_e32 v23, s12, v2
	v_mad_u64_u32 v[142:143], s[14:15], v0, s77, v[6:7]
	v_or_b32_e32 v0, s11, v3
	v_add_u32_e32 v28, s1, v23
	v_add_u32_e32 v25, s3, v0
	v_mad_u64_u32 v[28:29], s[12:13], v28, s16, v[26:27]
	v_mad_u64_u32 v[30:31], s[12:13], v25, s16, v[26:27]
	global_load_dword v114, v[28:29], off
	global_load_dword v115, v[30:31], off
	v_mad_u64_u32 v[144:145], s[12:13], v23, s77, v[6:7]
	v_mad_u64_u32 v[146:147], s[12:13], v0, s77, v[6:7]
	s_lshl_b32 s12, s7, 1
	s_lshl_b32 s11, s6, 1
	v_or_b32_e32 v23, s12, v2
	v_or_b32_e32 v0, s11, v3
	v_add_u32_e32 v28, s1, v23
	v_add_u32_e32 v25, s3, v0
	v_mad_u64_u32 v[28:29], s[14:15], v28, s16, v[26:27]
	v_mad_u64_u32 v[30:31], s[14:15], v25, s16, v[26:27]
	global_load_dword v148, v[28:29], off
	global_load_dword v149, v[30:31], off
	v_mad_u64_u32 v[164:165], s[14:15], v23, s77, v[6:7]
	v_mad_u64_u32 v[166:167], s[14:15], v0, s77, v[6:7]
	s_add_i32 s14, s12, 4
	s_add_i32 s13, s11, 4
	v_or_b32_e32 v23, s14, v2
	v_or_b32_e32 v0, s13, v3
	s_add_i32 s13, s11, 8
	s_add_i32 s7, s7, 16
	s_add_i32 s6, s6, 16
	s_add_i32 s10, s10, -16
	v_add_u32_e32 v28, s1, v23
	v_add_u32_e32 v25, s3, v0
	v_mad_u64_u32 v[28:29], s[14:15], v28, s16, v[26:27]
	v_mad_u64_u32 v[30:31], s[14:15], v25, s16, v[26:27]
	global_load_dword v150, v[28:29], off
	global_load_dword v151, v[30:31], off
	v_mad_u64_u32 v[168:169], s[14:15], v23, s77, v[6:7]
	v_mad_u64_u32 v[170:171], s[14:15], v0, s77, v[6:7]
	s_add_i32 s14, s12, 8
	s_nop 0
	v_or_b32_e32 v23, s14, v2
	v_or_b32_e32 v0, s13, v3
	s_add_i32 s13, s11, 12
	v_add_u32_e32 v28, s1, v23
	v_add_u32_e32 v25, s3, v0
	v_mad_u64_u32 v[28:29], s[14:15], v28, s16, v[26:27]
	v_mad_u64_u32 v[30:31], s[14:15], v25, s16, v[26:27]
	global_load_dword v152, v[28:29], off
	global_load_dword v153, v[30:31], off
	v_mad_u64_u32 v[172:173], s[14:15], v23, s77, v[6:7]
	v_mad_u64_u32 v[174:175], s[14:15], v0, s77, v[6:7]
	s_add_i32 s14, s12, 12
	s_nop 0
	v_or_b32_e32 v23, s14, v2
	v_or_b32_e32 v0, s13, v3
	s_add_i32 s13, s11, 16
	v_add_u32_e32 v28, s1, v23
	v_add_u32_e32 v25, s3, v0
	v_mad_u64_u32 v[28:29], s[14:15], v28, s16, v[26:27]
	v_mad_u64_u32 v[30:31], s[14:15], v25, s16, v[26:27]
	global_load_dword v154, v[28:29], off
	global_load_dword v155, v[30:31], off
	v_mad_u64_u32 v[176:177], s[14:15], v23, s77, v[6:7]
	v_mad_u64_u32 v[178:179], s[14:15], v0, s77, v[6:7]
	s_add_i32 s14, s12, 16
	s_nop 0
	v_or_b32_e32 v23, s14, v2
	v_or_b32_e32 v0, s13, v3
	s_add_i32 s13, s11, 20
	v_add_u32_e32 v28, s1, v23
	v_add_u32_e32 v25, s3, v0
	v_mad_u64_u32 v[28:29], s[14:15], v28, s16, v[26:27]
	v_mad_u64_u32 v[30:31], s[14:15], v25, s16, v[26:27]
	global_load_dword v156, v[28:29], off
	global_load_dword v157, v[30:31], off
	v_mad_u64_u32 v[180:181], s[14:15], v23, s77, v[6:7]
	v_mad_u64_u32 v[182:183], s[14:15], v0, s77, v[6:7]
	s_add_i32 s14, s12, 20
	s_nop 0
	v_or_b32_e32 v23, s14, v2
	v_or_b32_e32 v0, s13, v3
	s_add_i32 s13, s11, 24
	s_add_i32 s11, s11, 28
	v_add_u32_e32 v28, s1, v23
	v_add_u32_e32 v25, s3, v0
	v_mad_u64_u32 v[28:29], s[14:15], v28, s16, v[26:27]
	v_mad_u64_u32 v[30:31], s[14:15], v25, s16, v[26:27]
	global_load_dword v158, v[28:29], off
	global_load_dword v159, v[30:31], off
	v_mad_u64_u32 v[184:185], s[14:15], v23, s77, v[6:7]
	v_mad_u64_u32 v[186:187], s[14:15], v0, s77, v[6:7]
	s_add_i32 s14, s12, 24
	s_nop 0
	v_or_b32_e32 v23, s14, v2
	v_or_b32_e32 v0, s13, v3
	s_add_i32 s12, s12, 28
	s_cmp_lg_u32 s10, 0
	v_add_u32_e32 v28, s1, v23
	v_add_u32_e32 v25, s3, v0
	v_mad_u64_u32 v[28:29], s[14:15], v28, s16, v[26:27]
	v_mad_u64_u32 v[30:31], s[14:15], v25, s16, v[26:27]
	global_load_dword v160, v[28:29], off
	global_load_dword v161, v[30:31], off
	v_mad_u64_u32 v[188:189], s[14:15], v23, s77, v[6:7]
	v_or_b32_e32 v23, s12, v2
	v_mad_u64_u32 v[190:191], s[14:15], v0, s77, v[6:7]
	v_or_b32_e32 v0, s11, v3
	v_add_u32_e32 v28, s1, v23
	v_add_u32_e32 v25, s3, v0
	v_mad_u64_u32 v[28:29], s[12:13], v28, s16, v[26:27]
	v_mad_u64_u32 v[30:31], s[12:13], v25, s16, v[26:27]
	global_load_dword v162, v[28:29], off
	global_load_dword v163, v[30:31], off
	v_mad_u64_u32 v[192:193], s[12:13], v23, s77, v[6:7]
	v_mad_u64_u32 v[196:197], s[12:13], v0, s77, v[6:7]
	s_waitcnt vmcnt(0)
	ds_write_b32 v116, v100
	ds_write_b32 v118, v101
	ds_write_b32 v120, v102
	ds_write_b32 v122, v103
	ds_write_b32 v124, v104
	ds_write_b32 v126, v105
	ds_write_b32 v128, v106
	ds_write_b32 v130, v107
	ds_write_b32 v132, v108
	ds_write_b32 v134, v109
	ds_write_b32 v136, v110
	ds_write_b32 v138, v111
	ds_write_b32 v140, v112
	ds_write_b32 v142, v113
	ds_write_b32 v144, v114
	ds_write_b32 v146, v115
	ds_write_b32 v164, v148
	ds_write_b32 v166, v149
	ds_write_b32 v168, v150
	ds_write_b32 v170, v151
	ds_write_b32 v172, v152
	ds_write_b32 v174, v153
	ds_write_b32 v176, v154
	ds_write_b32 v178, v155
	ds_write_b32 v180, v156
	ds_write_b32 v182, v157
	ds_write_b32 v184, v158
	ds_write_b32 v186, v159
	ds_write_b32 v188, v160
	ds_write_b32 v190, v161
	ds_write_b32 v192, v162
	ds_write_b32 v196, v163
	s_cbranch_scc1 .LBB0_676
	s_mov_b32 s1, s4
	s_lshl_b64 s[0:1], s[0:1], 11
	s_add_u32 s0, s72, s0
	v_readlane_b32 s3, v249, 35
	s_addc_u32 s1, s3, s1
	s_and_b32 s2, 0xffff, s2
	s_lshl_b32 s2, s2, 1
	s_add_u32 s0, s0, s2
	s_addc_u32 s1, s1, 0
	v_mov_b32_e32 v0, v39
	v_mov_b32_e32 v26, v38
	v_mov_b32_e32 v28, v37
	v_mov_b32_e32 v30, v36

.LBB0_681:
	s_lshl_b32 s11, s6, 1
	s_lshl_b32 s10, s2, 1
	v_or_b32_e32 v23, s11, v2
	v_or_b32_e32 v0, s10, v3
	v_add_u32_e32 v30, s0, v23
	v_add_u32_e32 v28, s3, v0
	v_ashrrev_i32_e32 v31, 31, v30
	v_ashrrev_i32_e32 v29, 31, v28
	v_lshlrev_b64 v[30:31], 12, v[30:31]
	v_lshlrev_b64 v[28:29], 12, v[28:29]
	v_lshl_add_u64 v[30:31], v[26:27], 0, v[30:31]
	v_lshl_add_u64 v[28:29], v[26:27], 0, v[28:29]
	global_load_dword v100, v[30:31], off
	global_load_dword v101, v[28:29], off
	v_mad_u64_u32 v[116:117], s[12:13], v23, s77, v[6:7]
	v_mad_u64_u32 v[118:119], s[12:13], v0, s77, v[6:7]
	s_add_i32 s13, s11, 4
	s_add_i32 s12, s10, 4
	v_or_b32_e32 v23, s13, v2
	v_or_b32_e32 v0, s12, v3
	s_add_i32 s6, s6, 16
	s_add_i32 s2, s2, 16
	s_add_i32 s7, s7, -16
	v_add_u32_e32 v30, s0, v23
	v_add_u32_e32 v28, s3, v0
	v_ashrrev_i32_e32 v31, 31, v30
	v_ashrrev_i32_e32 v29, 31, v28
	v_lshlrev_b64 v[30:31], 12, v[30:31]
	v_lshlrev_b64 v[28:29], 12, v[28:29]
	v_lshl_add_u64 v[30:31], v[26:27], 0, v[30:31]
	v_lshl_add_u64 v[28:29], v[26:27], 0, v[28:29]
	global_load_dword v102, v[30:31], off
	global_load_dword v103, v[28:29], off
	v_mad_u64_u32 v[120:121], s[12:13], v23, s77, v[6:7]
	v_mad_u64_u32 v[122:123], s[12:13], v0, s77, v[6:7]
	s_add_i32 s13, s11, 8
	s_add_i32 s12, s10, 8
	v_or_b32_e32 v23, s13, v2
	v_or_b32_e32 v0, s12, v3
	v_add_u32_e32 v30, s0, v23
	v_add_u32_e32 v28, s3, v0
	v_ashrrev_i32_e32 v31, 31, v30
	v_ashrrev_i32_e32 v29, 31, v28
	v_lshlrev_b64 v[30:31], 12, v[30:31]
	v_lshlrev_b64 v[28:29], 12, v[28:29]
	v_lshl_add_u64 v[30:31], v[26:27], 0, v[30:31]
	v_lshl_add_u64 v[28:29], v[26:27], 0, v[28:29]
	global_load_dword v104, v[30:31], off
	global_load_dword v105, v[28:29], off
	v_mad_u64_u32 v[124:125], s[12:13], v23, s77, v[6:7]
	v_mad_u64_u32 v[126:127], s[12:13], v0, s77, v[6:7]
	s_add_i32 s13, s11, 12
	s_add_i32 s12, s10, 12
	v_or_b32_e32 v23, s13, v2
	v_or_b32_e32 v0, s12, v3
	v_add_u32_e32 v30, s0, v23
	v_add_u32_e32 v28, s3, v0
	v_ashrrev_i32_e32 v31, 31, v30
	v_ashrrev_i32_e32 v29, 31, v28
	v_lshlrev_b64 v[30:31], 12, v[30:31]
	v_lshlrev_b64 v[28:29], 12, v[28:29]
	v_lshl_add_u64 v[30:31], v[26:27], 0, v[30:31]
	v_lshl_add_u64 v[28:29], v[26:27], 0, v[28:29]
	global_load_dword v106, v[30:31], off
	global_load_dword v107, v[28:29], off
	v_mad_u64_u32 v[128:129], s[12:13], v23, s77, v[6:7]
	v_mad_u64_u32 v[130:131], s[12:13], v0, s77, v[6:7]
	s_add_i32 s13, s11, 16
	s_add_i32 s12, s10, 16
	v_or_b32_e32 v23, s13, v2
	v_or_b32_e32 v0, s12, v3
	v_add_u32_e32 v30, s0, v23
	v_add_u32_e32 v28, s3, v0
	v_ashrrev_i32_e32 v31, 31, v30
	v_ashrrev_i32_e32 v29, 31, v28
	v_lshlrev_b64 v[30:31], 12, v[30:31]
	v_lshlrev_b64 v[28:29], 12, v[28:29]
	v_lshl_add_u64 v[30:31], v[26:27], 0, v[30:31]
	v_lshl_add_u64 v[28:29], v[26:27], 0, v[28:29]
	global_load_dword v108, v[30:31], off
	global_load_dword v109, v[28:29], off
	v_mad_u64_u32 v[132:133], s[12:13], v23, s77, v[6:7]
	v_mad_u64_u32 v[134:135], s[12:13], v0, s77, v[6:7]
	s_add_i32 s13, s11, 20
	s_add_i32 s12, s10, 20
	v_or_b32_e32 v23, s13, v2
	v_or_b32_e32 v0, s12, v3
	v_add_u32_e32 v30, s0, v23
	v_add_u32_e32 v28, s3, v0
	v_ashrrev_i32_e32 v31, 31, v30
	v_ashrrev_i32_e32 v29, 31, v28
	v_lshlrev_b64 v[30:31], 12, v[30:31]
	v_lshlrev_b64 v[28:29], 12, v[28:29]
	v_lshl_add_u64 v[30:31], v[26:27], 0, v[30:31]
	v_lshl_add_u64 v[28:29], v[26:27], 0, v[28:29]
	global_load_dword v110, v[30:31], off
	global_load_dword v111, v[28:29], off
	v_mad_u64_u32 v[136:137], s[12:13], v23, s77, v[6:7]
	v_mad_u64_u32 v[138:139], s[12:13], v0, s77, v[6:7]
	s_add_i32 s13, s11, 24
	s_add_i32 s12, s10, 24
	v_or_b32_e32 v23, s13, v2
	v_or_b32_e32 v0, s12, v3
	s_add_i32 s11, s11, 28
	s_add_i32 s10, s10, 28
	s_cmp_lg_u32 s7, 0
	v_add_u32_e32 v30, s0, v23
	v_add_u32_e32 v28, s3, v0
	v_ashrrev_i32_e32 v31, 31, v30
	v_ashrrev_i32_e32 v29, 31, v28
	v_lshlrev_b64 v[30:31], 12, v[30:31]
	v_lshlrev_b64 v[28:29], 12, v[28:29]
	v_lshl_add_u64 v[30:31], v[26:27], 0, v[30:31]
	v_lshl_add_u64 v[28:29], v[26:27], 0, v[28:29]
	global_load_dword v112, v[30:31], off
	global_load_dword v113, v[28:29], off
	v_mad_u64_u32 v[140:141], s[12:13], v23, s77, v[6:7]
	v_mad_u64_u32 v[142:143], s[12:13], v0, s77, v[6:7]
	v_or_b32_e32 v23, s11, v2
	v_or_b32_e32 v0, s10, v3
	v_add_u32_e32 v30, s0, v23
	v_add_u32_e32 v28, s3, v0
	v_ashrrev_i32_e32 v31, 31, v30
	v_ashrrev_i32_e32 v29, 31, v28
	v_lshlrev_b64 v[30:31], 12, v[30:31]
	v_lshlrev_b64 v[28:29], 12, v[28:29]
	v_lshl_add_u64 v[30:31], v[26:27], 0, v[30:31]
	v_lshl_add_u64 v[28:29], v[26:27], 0, v[28:29]
	global_load_dword v114, v[30:31], off
	global_load_dword v115, v[28:29], off
	v_mad_u64_u32 v[144:145], s[10:11], v23, s77, v[6:7]
	v_mad_u64_u32 v[146:147], s[10:11], v0, s77, v[6:7]
	s_lshl_b32 s11, s6, 1
	s_lshl_b32 s10, s2, 1
	v_or_b32_e32 v23, s11, v2
	v_or_b32_e32 v0, s10, v3
	v_add_u32_e32 v30, s0, v23
	v_add_u32_e32 v28, s3, v0
	v_ashrrev_i32_e32 v31, 31, v30
	v_ashrrev_i32_e32 v29, 31, v28
	v_lshlrev_b64 v[30:31], 12, v[30:31]
	v_lshlrev_b64 v[28:29], 12, v[28:29]
	v_lshl_add_u64 v[30:31], v[26:27], 0, v[30:31]
	v_lshl_add_u64 v[28:29], v[26:27], 0, v[28:29]
	global_load_dword v148, v[30:31], off
	global_load_dword v149, v[28:29], off
	v_mad_u64_u32 v[164:165], s[12:13], v23, s77, v[6:7]
	v_mad_u64_u32 v[166:167], s[12:13], v0, s77, v[6:7]
	s_add_i32 s13, s11, 4
	s_add_i32 s12, s10, 4
	v_or_b32_e32 v23, s13, v2
	v_or_b32_e32 v0, s12, v3
	s_add_i32 s6, s6, 16
	s_add_i32 s2, s2, 16
	s_add_i32 s7, s7, -16
	v_add_u32_e32 v30, s0, v23
	v_add_u32_e32 v28, s3, v0
	v_ashrrev_i32_e32 v31, 31, v30
	v_ashrrev_i32_e32 v29, 31, v28
	v_lshlrev_b64 v[30:31], 12, v[30:31]
	v_lshlrev_b64 v[28:29], 12, v[28:29]
	v_lshl_add_u64 v[30:31], v[26:27], 0, v[30:31]
	v_lshl_add_u64 v[28:29], v[26:27], 0, v[28:29]
	global_load_dword v150, v[30:31], off
	global_load_dword v151, v[28:29], off
	v_mad_u64_u32 v[168:169], s[12:13], v23, s77, v[6:7]
	v_mad_u64_u32 v[170:171], s[12:13], v0, s77, v[6:7]
	s_add_i32 s13, s11, 8
	s_add_i32 s12, s10, 8
	v_or_b32_e32 v23, s13, v2
	v_or_b32_e32 v0, s12, v3
	v_add_u32_e32 v30, s0, v23
	v_add_u32_e32 v28, s3, v0
	v_ashrrev_i32_e32 v31, 31, v30
	v_ashrrev_i32_e32 v29, 31, v28
	v_lshlrev_b64 v[30:31], 12, v[30:31]
	v_lshlrev_b64 v[28:29], 12, v[28:29]
	v_lshl_add_u64 v[30:31], v[26:27], 0, v[30:31]
	v_lshl_add_u64 v[28:29], v[26:27], 0, v[28:29]
	global_load_dword v152, v[30:31], off
	global_load_dword v153, v[28:29], off
	v_mad_u64_u32 v[172:173], s[12:13], v23, s77, v[6:7]
	v_mad_u64_u32 v[174:175], s[12:13], v0, s77, v[6:7]
	s_add_i32 s13, s11, 12
	s_add_i32 s12, s10, 12
	v_or_b32_e32 v23, s13, v2
	v_or_b32_e32 v0, s12, v3
	v_add_u32_e32 v30, s0, v23
	v_add_u32_e32 v28, s3, v0
	v_ashrrev_i32_e32 v31, 31, v30
	v_ashrrev_i32_e32 v29, 31, v28
	v_lshlrev_b64 v[30:31], 12, v[30:31]
	v_lshlrev_b64 v[28:29], 12, v[28:29]
	v_lshl_add_u64 v[30:31], v[26:27], 0, v[30:31]
	v_lshl_add_u64 v[28:29], v[26:27], 0, v[28:29]
	global_load_dword v154, v[30:31], off
	global_load_dword v155, v[28:29], off
	v_mad_u64_u32 v[176:177], s[12:13], v23, s77, v[6:7]
	v_mad_u64_u32 v[178:179], s[12:13], v0, s77, v[6:7]
	s_add_i32 s13, s11, 16
	s_add_i32 s12, s10, 16
	v_or_b32_e32 v23, s13, v2
	v_or_b32_e32 v0, s12, v3
	v_add_u32_e32 v30, s0, v23
	v_add_u32_e32 v28, s3, v0
	v_ashrrev_i32_e32 v31, 31, v30
	v_ashrrev_i32_e32 v29, 31, v28
	v_lshlrev_b64 v[30:31], 12, v[30:31]
	v_lshlrev_b64 v[28:29], 12, v[28:29]
	v_lshl_add_u64 v[30:31], v[26:27], 0, v[30:31]
	v_lshl_add_u64 v[28:29], v[26:27], 0, v[28:29]
	global_load_dword v156, v[30:31], off
	global_load_dword v157, v[28:29], off
	v_mad_u64_u32 v[180:181], s[12:13], v23, s77, v[6:7]
	v_mad_u64_u32 v[182:183], s[12:13], v0, s77, v[6:7]
	s_add_i32 s13, s11, 20
	s_add_i32 s12, s10, 20
	v_or_b32_e32 v23, s13, v2
	v_or_b32_e32 v0, s12, v3
	v_add_u32_e32 v30, s0, v23
	v_add_u32_e32 v28, s3, v0
	v_ashrrev_i32_e32 v31, 31, v30
	v_ashrrev_i32_e32 v29, 31, v28
	v_lshlrev_b64 v[30:31], 12, v[30:31]
	v_lshlrev_b64 v[28:29], 12, v[28:29]
	v_lshl_add_u64 v[30:31], v[26:27], 0, v[30:31]
	v_lshl_add_u64 v[28:29], v[26:27], 0, v[28:29]
	global_load_dword v158, v[30:31], off
	global_load_dword v159, v[28:29], off
	v_mad_u64_u32 v[184:185], s[12:13], v23, s77, v[6:7]
	v_mad_u64_u32 v[186:187], s[12:13], v0, s77, v[6:7]
	s_add_i32 s13, s11, 24
	s_add_i32 s12, s10, 24
	v_or_b32_e32 v23, s13, v2
	v_or_b32_e32 v0, s12, v3
	s_add_i32 s11, s11, 28
	s_add_i32 s10, s10, 28
	s_cmp_lg_u32 s7, 0
	v_add_u32_e32 v30, s0, v23
	v_add_u32_e32 v28, s3, v0
	v_ashrrev_i32_e32 v31, 31, v30
	v_ashrrev_i32_e32 v29, 31, v28
	v_lshlrev_b64 v[30:31], 12, v[30:31]
	v_lshlrev_b64 v[28:29], 12, v[28:29]
	v_lshl_add_u64 v[30:31], v[26:27], 0, v[30:31]
	v_lshl_add_u64 v[28:29], v[26:27], 0, v[28:29]
	global_load_dword v160, v[30:31], off
	global_load_dword v161, v[28:29], off
	v_mad_u64_u32 v[188:189], s[12:13], v23, s77, v[6:7]
	v_mad_u64_u32 v[190:191], s[12:13], v0, s77, v[6:7]
	v_or_b32_e32 v23, s11, v2
	v_or_b32_e32 v0, s10, v3
	v_add_u32_e32 v30, s0, v23
	v_add_u32_e32 v28, s3, v0
	v_ashrrev_i32_e32 v31, 31, v30
	v_ashrrev_i32_e32 v29, 31, v28
	v_lshlrev_b64 v[30:31], 12, v[30:31]
	v_lshlrev_b64 v[28:29], 12, v[28:29]
	v_lshl_add_u64 v[30:31], v[26:27], 0, v[30:31]
	v_lshl_add_u64 v[28:29], v[26:27], 0, v[28:29]
	global_load_dword v162, v[30:31], off
	global_load_dword v163, v[28:29], off
	v_mad_u64_u32 v[192:193], s[10:11], v23, s77, v[6:7]
	v_mad_u64_u32 v[196:197], s[10:11], v0, s77, v[6:7]
	s_waitcnt vmcnt(0)
	ds_write_b32 v116, v100
	ds_write_b32 v118, v101
	ds_write_b32 v120, v102
	ds_write_b32 v122, v103
	ds_write_b32 v124, v104
	ds_write_b32 v126, v105
	ds_write_b32 v128, v106
	ds_write_b32 v130, v107
	ds_write_b32 v132, v108
	ds_write_b32 v134, v109
	ds_write_b32 v136, v110
	ds_write_b32 v138, v111
	ds_write_b32 v140, v112
	ds_write_b32 v142, v113
	ds_write_b32 v144, v114
	ds_write_b32 v146, v115
	ds_write_b32 v164, v148
	ds_write_b32 v166, v149
	ds_write_b32 v168, v150
	ds_write_b32 v170, v151
	ds_write_b32 v172, v152
	ds_write_b32 v174, v153
	ds_write_b32 v176, v154
	ds_write_b32 v178, v155
	ds_write_b32 v180, v156
	ds_write_b32 v182, v157
	ds_write_b32 v184, v158
	ds_write_b32 v186, v159
	ds_write_b32 v188, v160
	ds_write_b32 v190, v161
	ds_write_b32 v192, v162
	ds_write_b32 v196, v163
	s_cbranch_scc1 .LBB0_681
	s_lshl_b32 s1, s1, 11
	v_readlane_b32 s2, v249, 48
	s_add_u32 s2, s2, s1
	v_readlane_b32 s1, v249, 49
	s_addc_u32 s3, s1, 0
	s_mov_b32 s1, s4
	s_lshl_b64 s[0:1], s[0:1], 1
	s_add_u32 s0, s2, s0
	s_addc_u32 s1, s3, s1
	v_mov_b32_e32 v0, v39
	v_mov_b32_e32 v26, v38
	v_mov_b32_e32 v28, v37
	v_mov_b32_e32 v30, v36

.LBB0_686:
	s_lshl_b32 s13, s10, 1
	s_lshl_b32 s12, s6, 1
	v_or_b32_e32 v25, s13, v2
	v_or_b32_e32 v23, s12, v3
	v_add_u32_e32 v0, s3, v25
	v_add_u32_e32 v28, s7, v23
	v_mov_b32_e32 v29, v1
	v_lshlrev_b64 v[30:31], 12, v[0:1]
	v_lshlrev_b64 v[28:29], 12, v[28:29]
	v_lshl_add_u64 v[30:31], v[26:27], 0, v[30:31]
	v_lshl_add_u64 v[28:29], v[26:27], 0, v[28:29]
	global_load_dword v100, v[30:31], off
	global_load_dword v101, v[28:29], off
	v_mad_u64_u32 v[116:117], s[14:15], v25, s77, v[6:7]
	v_mad_u64_u32 v[118:119], s[14:15], v23, s77, v[6:7]
	s_add_i32 s15, s13, 4
	s_add_i32 s14, s12, 4
	v_or_b32_e32 v25, s15, v2
	v_or_b32_e32 v23, s14, v3
	v_mov_b32_e32 v29, v1
	s_add_i32 s10, s10, 16
	s_add_i32 s6, s6, 16
	s_add_i32 s11, s11, -16
	v_add_u32_e32 v0, s3, v25
	v_add_u32_e32 v28, s7, v23
	v_lshlrev_b64 v[30:31], 12, v[0:1]
	v_lshlrev_b64 v[28:29], 12, v[28:29]
	v_lshl_add_u64 v[30:31], v[26:27], 0, v[30:31]
	v_lshl_add_u64 v[28:29], v[26:27], 0, v[28:29]
	global_load_dword v102, v[30:31], off
	global_load_dword v103, v[28:29], off
	v_mad_u64_u32 v[120:121], s[14:15], v25, s77, v[6:7]
	v_mad_u64_u32 v[122:123], s[14:15], v23, s77, v[6:7]
	s_add_i32 s15, s13, 8
	s_add_i32 s14, s12, 8
	v_or_b32_e32 v25, s15, v2
	v_or_b32_e32 v23, s14, v3
	v_mov_b32_e32 v29, v1
	v_add_u32_e32 v0, s3, v25
	v_add_u32_e32 v28, s7, v23
	v_lshlrev_b64 v[30:31], 12, v[0:1]
	v_lshlrev_b64 v[28:29], 12, v[28:29]
	v_lshl_add_u64 v[30:31], v[26:27], 0, v[30:31]
	v_lshl_add_u64 v[28:29], v[26:27], 0, v[28:29]
	global_load_dword v104, v[30:31], off
	global_load_dword v105, v[28:29], off
	v_mad_u64_u32 v[124:125], s[14:15], v25, s77, v[6:7]
	v_mad_u64_u32 v[126:127], s[14:15], v23, s77, v[6:7]
	s_add_i32 s15, s13, 12
	s_add_i32 s14, s12, 12
	v_or_b32_e32 v25, s15, v2
	v_or_b32_e32 v23, s14, v3
	v_mov_b32_e32 v29, v1
	v_add_u32_e32 v0, s3, v25
	v_add_u32_e32 v28, s7, v23
	v_lshlrev_b64 v[30:31], 12, v[0:1]
	v_lshlrev_b64 v[28:29], 12, v[28:29]
	v_lshl_add_u64 v[30:31], v[26:27], 0, v[30:31]
	v_lshl_add_u64 v[28:29], v[26:27], 0, v[28:29]
	global_load_dword v106, v[30:31], off
	global_load_dword v107, v[28:29], off
	v_mad_u64_u32 v[128:129], s[14:15], v25, s77, v[6:7]
	v_mad_u64_u32 v[130:131], s[14:15], v23, s77, v[6:7]
	s_add_i32 s15, s13, 16
	s_add_i32 s14, s12, 16
	v_or_b32_e32 v25, s15, v2
	v_or_b32_e32 v23, s14, v3
	v_mov_b32_e32 v29, v1
	v_add_u32_e32 v0, s3, v25
	v_add_u32_e32 v28, s7, v23
	v_lshlrev_b64 v[30:31], 12, v[0:1]
	v_lshlrev_b64 v[28:29], 12, v[28:29]
	v_lshl_add_u64 v[30:31], v[26:27], 0, v[30:31]
	v_lshl_add_u64 v[28:29], v[26:27], 0, v[28:29]
	global_load_dword v108, v[30:31], off
	global_load_dword v109, v[28:29], off
	v_mad_u64_u32 v[132:133], s[14:15], v25, s77, v[6:7]
	v_mad_u64_u32 v[134:135], s[14:15], v23, s77, v[6:7]
	s_add_i32 s15, s13, 20
	s_add_i32 s14, s12, 20
	v_or_b32_e32 v25, s15, v2
	v_or_b32_e32 v23, s14, v3
	v_mov_b32_e32 v29, v1
	v_add_u32_e32 v0, s3, v25
	v_add_u32_e32 v28, s7, v23
	v_lshlrev_b64 v[30:31], 12, v[0:1]
	v_lshlrev_b64 v[28:29], 12, v[28:29]
	v_lshl_add_u64 v[30:31], v[26:27], 0, v[30:31]
	v_lshl_add_u64 v[28:29], v[26:27], 0, v[28:29]
	global_load_dword v110, v[30:31], off
	global_load_dword v111, v[28:29], off
	v_mad_u64_u32 v[136:137], s[14:15], v25, s77, v[6:7]
	v_mad_u64_u32 v[138:139], s[14:15], v23, s77, v[6:7]
	s_add_i32 s15, s13, 24
	s_add_i32 s14, s12, 24
	v_or_b32_e32 v25, s15, v2
	v_or_b32_e32 v23, s14, v3
	v_mov_b32_e32 v29, v1
	s_add_i32 s13, s13, 28
	s_add_i32 s12, s12, 28
	s_cmp_lg_u32 s11, 0
	v_add_u32_e32 v0, s3, v25
	v_add_u32_e32 v28, s7, v23
	v_lshlrev_b64 v[30:31], 12, v[0:1]
	v_lshlrev_b64 v[28:29], 12, v[28:29]
	v_lshl_add_u64 v[30:31], v[26:27], 0, v[30:31]
	v_lshl_add_u64 v[28:29], v[26:27], 0, v[28:29]
	global_load_dword v112, v[30:31], off
	global_load_dword v113, v[28:29], off
	v_mad_u64_u32 v[140:141], s[14:15], v25, s77, v[6:7]
	v_or_b32_e32 v25, s13, v2
	v_mad_u64_u32 v[142:143], s[14:15], v23, s77, v[6:7]
	v_or_b32_e32 v23, s12, v3
	v_mov_b32_e32 v29, v1
	v_add_u32_e32 v0, s3, v25
	v_add_u32_e32 v28, s7, v23
	v_lshlrev_b64 v[30:31], 12, v[0:1]
	v_lshlrev_b64 v[28:29], 12, v[28:29]
	v_lshl_add_u64 v[30:31], v[26:27], 0, v[30:31]
	v_lshl_add_u64 v[28:29], v[26:27], 0, v[28:29]
	global_load_dword v114, v[30:31], off
	global_load_dword v115, v[28:29], off
	v_mad_u64_u32 v[144:145], s[12:13], v25, s77, v[6:7]
	v_mad_u64_u32 v[146:147], s[12:13], v23, s77, v[6:7]
	s_lshl_b32 s13, s10, 1
	s_lshl_b32 s12, s6, 1
	v_or_b32_e32 v25, s13, v2
	v_or_b32_e32 v23, s12, v3
	v_add_u32_e32 v0, s3, v25
	v_add_u32_e32 v28, s7, v23
	v_mov_b32_e32 v29, v1
	v_lshlrev_b64 v[30:31], 12, v[0:1]
	v_lshlrev_b64 v[28:29], 12, v[28:29]
	v_lshl_add_u64 v[30:31], v[26:27], 0, v[30:31]
	v_lshl_add_u64 v[28:29], v[26:27], 0, v[28:29]
	global_load_dword v148, v[30:31], off
	global_load_dword v149, v[28:29], off
	v_mad_u64_u32 v[164:165], s[14:15], v25, s77, v[6:7]
	v_mad_u64_u32 v[166:167], s[14:15], v23, s77, v[6:7]
	s_add_i32 s15, s13, 4
	s_add_i32 s14, s12, 4
	v_or_b32_e32 v25, s15, v2
	v_or_b32_e32 v23, s14, v3
	v_mov_b32_e32 v29, v1
	s_add_i32 s10, s10, 16
	s_add_i32 s6, s6, 16
	s_add_i32 s11, s11, -16
	v_add_u32_e32 v0, s3, v25
	v_add_u32_e32 v28, s7, v23
	v_lshlrev_b64 v[30:31], 12, v[0:1]
	v_lshlrev_b64 v[28:29], 12, v[28:29]
	v_lshl_add_u64 v[30:31], v[26:27], 0, v[30:31]
	v_lshl_add_u64 v[28:29], v[26:27], 0, v[28:29]
	global_load_dword v150, v[30:31], off
	global_load_dword v151, v[28:29], off
	v_mad_u64_u32 v[168:169], s[14:15], v25, s77, v[6:7]
	v_mad_u64_u32 v[170:171], s[14:15], v23, s77, v[6:7]
	s_add_i32 s15, s13, 8
	s_add_i32 s14, s12, 8
	v_or_b32_e32 v25, s15, v2
	v_or_b32_e32 v23, s14, v3
	v_mov_b32_e32 v29, v1
	v_add_u32_e32 v0, s3, v25
	v_add_u32_e32 v28, s7, v23
	v_lshlrev_b64 v[30:31], 12, v[0:1]
	v_lshlrev_b64 v[28:29], 12, v[28:29]
	v_lshl_add_u64 v[30:31], v[26:27], 0, v[30:31]
	v_lshl_add_u64 v[28:29], v[26:27], 0, v[28:29]
	global_load_dword v152, v[30:31], off
	global_load_dword v153, v[28:29], off
	v_mad_u64_u32 v[172:173], s[14:15], v25, s77, v[6:7]
	v_mad_u64_u32 v[174:175], s[14:15], v23, s77, v[6:7]
	s_add_i32 s15, s13, 12
	s_add_i32 s14, s12, 12
	v_or_b32_e32 v25, s15, v2
	v_or_b32_e32 v23, s14, v3
	v_mov_b32_e32 v29, v1
	v_add_u32_e32 v0, s3, v25
	v_add_u32_e32 v28, s7, v23
	v_lshlrev_b64 v[30:31], 12, v[0:1]
	v_lshlrev_b64 v[28:29], 12, v[28:29]
	v_lshl_add_u64 v[30:31], v[26:27], 0, v[30:31]
	v_lshl_add_u64 v[28:29], v[26:27], 0, v[28:29]
	global_load_dword v154, v[30:31], off
	global_load_dword v155, v[28:29], off
	v_mad_u64_u32 v[176:177], s[14:15], v25, s77, v[6:7]
	v_mad_u64_u32 v[178:179], s[14:15], v23, s77, v[6:7]
	s_add_i32 s15, s13, 16
	s_add_i32 s14, s12, 16
	v_or_b32_e32 v25, s15, v2
	v_or_b32_e32 v23, s14, v3
	v_mov_b32_e32 v29, v1
	v_add_u32_e32 v0, s3, v25
	v_add_u32_e32 v28, s7, v23
	v_lshlrev_b64 v[30:31], 12, v[0:1]
	v_lshlrev_b64 v[28:29], 12, v[28:29]
	v_lshl_add_u64 v[30:31], v[26:27], 0, v[30:31]
	v_lshl_add_u64 v[28:29], v[26:27], 0, v[28:29]
	global_load_dword v156, v[30:31], off
	global_load_dword v157, v[28:29], off
	v_mad_u64_u32 v[180:181], s[14:15], v25, s77, v[6:7]
	v_mad_u64_u32 v[182:183], s[14:15], v23, s77, v[6:7]
	s_add_i32 s15, s13, 20
	s_add_i32 s14, s12, 20
	v_or_b32_e32 v25, s15, v2
	v_or_b32_e32 v23, s14, v3
	v_mov_b32_e32 v29, v1
	v_add_u32_e32 v0, s3, v25
	v_add_u32_e32 v28, s7, v23
	v_lshlrev_b64 v[30:31], 12, v[0:1]
	v_lshlrev_b64 v[28:29], 12, v[28:29]
	v_lshl_add_u64 v[30:31], v[26:27], 0, v[30:31]
	v_lshl_add_u64 v[28:29], v[26:27], 0, v[28:29]
	global_load_dword v158, v[30:31], off
	global_load_dword v159, v[28:29], off
	v_mad_u64_u32 v[184:185], s[14:15], v25, s77, v[6:7]
	v_mad_u64_u32 v[186:187], s[14:15], v23, s77, v[6:7]
	s_add_i32 s15, s13, 24
	s_add_i32 s14, s12, 24
	v_or_b32_e32 v25, s15, v2
	v_or_b32_e32 v23, s14, v3
	v_mov_b32_e32 v29, v1
	s_add_i32 s13, s13, 28
	s_add_i32 s12, s12, 28
	s_cmp_lg_u32 s11, 0
	v_add_u32_e32 v0, s3, v25
	v_add_u32_e32 v28, s7, v23
	v_lshlrev_b64 v[30:31], 12, v[0:1]
	v_lshlrev_b64 v[28:29], 12, v[28:29]
	v_lshl_add_u64 v[30:31], v[26:27], 0, v[30:31]
	v_lshl_add_u64 v[28:29], v[26:27], 0, v[28:29]
	global_load_dword v160, v[30:31], off
	global_load_dword v161, v[28:29], off
	v_mad_u64_u32 v[188:189], s[14:15], v25, s77, v[6:7]
	v_or_b32_e32 v25, s13, v2
	v_mad_u64_u32 v[190:191], s[14:15], v23, s77, v[6:7]
	v_or_b32_e32 v23, s12, v3
	v_mov_b32_e32 v29, v1
	v_add_u32_e32 v0, s3, v25
	v_add_u32_e32 v28, s7, v23
	v_lshlrev_b64 v[30:31], 12, v[0:1]
	v_lshlrev_b64 v[28:29], 12, v[28:29]
	v_lshl_add_u64 v[30:31], v[26:27], 0, v[30:31]
	v_lshl_add_u64 v[28:29], v[26:27], 0, v[28:29]
	global_load_dword v162, v[30:31], off
	global_load_dword v163, v[28:29], off
	v_mad_u64_u32 v[192:193], s[12:13], v25, s77, v[6:7]
	v_mad_u64_u32 v[196:197], s[12:13], v23, s77, v[6:7]
	s_waitcnt vmcnt(0)
	ds_write_b32 v116, v100
	ds_write_b32 v118, v101
	ds_write_b32 v120, v102
	ds_write_b32 v122, v103
	ds_write_b32 v124, v104
	ds_write_b32 v126, v105
	ds_write_b32 v128, v106
	ds_write_b32 v130, v107
	ds_write_b32 v132, v108
	ds_write_b32 v134, v109
	ds_write_b32 v136, v110
	ds_write_b32 v138, v111
	ds_write_b32 v140, v112
	ds_write_b32 v142, v113
	ds_write_b32 v144, v114
	ds_write_b32 v146, v115
	ds_write_b32 v164, v148
	ds_write_b32 v166, v149
	ds_write_b32 v168, v150
	ds_write_b32 v170, v151
	ds_write_b32 v172, v152
	ds_write_b32 v174, v153
	ds_write_b32 v176, v154
	ds_write_b32 v178, v155
	ds_write_b32 v180, v156
	ds_write_b32 v182, v157
	ds_write_b32 v184, v158
	ds_write_b32 v186, v159
	ds_write_b32 v188, v160
	ds_write_b32 v190, v161
	ds_write_b32 v192, v162
	ds_write_b32 v196, v163
	s_cbranch_scc1 .LBB0_686
	s_lshl_b64 s[0:1], s[0:1], 20
	v_readlane_b32 s6, v253, 4
	s_add_u32 s0, s6, s0
	v_readlane_b32 s6, v253, 5
	s_addc_u32 s1, s6, s1
	s_lshl_b32 s2, s2, 10
	s_add_u32 s0, s0, s2
	s_addc_u32 s1, s1, 0
	s_lshl_b32 s2, s3, 1
	s_add_u32 s0, s0, s2
	s_addc_u32 s1, s1, 0
	v_mov_b32_e32 v0, v43
	v_mov_b32_e32 v26, v42
	v_mov_b32_e32 v28, v41
	v_mov_b32_e32 v30, v40

.LBB0_691:
	s_lshl_b32 s11, s6, 1
	s_lshl_b32 s10, s3, 1
	v_or_b32_e32 v23, s11, v2
	v_or_b32_e32 v0, s10, v3
	v_add_u32_e32 v30, s0, v23
	v_add_u32_e32 v28, s2, v0
	v_ashrrev_i32_e32 v31, 31, v30
	v_ashrrev_i32_e32 v29, 31, v28
	v_lshlrev_b64 v[30:31], 11, v[30:31]
	v_lshlrev_b64 v[28:29], 11, v[28:29]
	v_lshl_add_u64 v[30:31], v[26:27], 0, v[30:31]
	v_lshl_add_u64 v[28:29], v[26:27], 0, v[28:29]
	global_load_dword v100, v[30:31], off
	global_load_dword v101, v[28:29], off
	v_mad_u64_u32 v[116:117], s[12:13], v23, s77, v[6:7]
	v_mad_u64_u32 v[118:119], s[12:13], v0, s77, v[6:7]
	s_add_i32 s13, s11, 4
	s_add_i32 s12, s10, 4
	v_or_b32_e32 v23, s13, v2
	v_or_b32_e32 v0, s12, v3
	s_add_i32 s6, s6, 16
	s_add_i32 s3, s3, 16
	s_add_i32 s7, s7, -16
	v_add_u32_e32 v30, s0, v23
	v_add_u32_e32 v28, s2, v0
	v_ashrrev_i32_e32 v31, 31, v30
	v_ashrrev_i32_e32 v29, 31, v28
	v_lshlrev_b64 v[30:31], 11, v[30:31]
	v_lshlrev_b64 v[28:29], 11, v[28:29]
	v_lshl_add_u64 v[30:31], v[26:27], 0, v[30:31]
	v_lshl_add_u64 v[28:29], v[26:27], 0, v[28:29]
	global_load_dword v102, v[30:31], off
	global_load_dword v103, v[28:29], off
	v_mad_u64_u32 v[120:121], s[12:13], v23, s77, v[6:7]
	v_mad_u64_u32 v[122:123], s[12:13], v0, s77, v[6:7]
	s_add_i32 s13, s11, 8
	s_add_i32 s12, s10, 8
	v_or_b32_e32 v23, s13, v2
	v_or_b32_e32 v0, s12, v3
	v_add_u32_e32 v30, s0, v23
	v_add_u32_e32 v28, s2, v0
	v_ashrrev_i32_e32 v31, 31, v30
	v_ashrrev_i32_e32 v29, 31, v28
	v_lshlrev_b64 v[30:31], 11, v[30:31]
	v_lshlrev_b64 v[28:29], 11, v[28:29]
	v_lshl_add_u64 v[30:31], v[26:27], 0, v[30:31]
	v_lshl_add_u64 v[28:29], v[26:27], 0, v[28:29]
	global_load_dword v104, v[30:31], off
	global_load_dword v105, v[28:29], off
	v_mad_u64_u32 v[124:125], s[12:13], v23, s77, v[6:7]
	v_mad_u64_u32 v[126:127], s[12:13], v0, s77, v[6:7]
	s_add_i32 s13, s11, 12
	s_add_i32 s12, s10, 12
	v_or_b32_e32 v23, s13, v2
	v_or_b32_e32 v0, s12, v3
	v_add_u32_e32 v30, s0, v23
	v_add_u32_e32 v28, s2, v0
	v_ashrrev_i32_e32 v31, 31, v30
	v_ashrrev_i32_e32 v29, 31, v28
	v_lshlrev_b64 v[30:31], 11, v[30:31]
	v_lshlrev_b64 v[28:29], 11, v[28:29]
	v_lshl_add_u64 v[30:31], v[26:27], 0, v[30:31]
	v_lshl_add_u64 v[28:29], v[26:27], 0, v[28:29]
	global_load_dword v106, v[30:31], off
	global_load_dword v107, v[28:29], off
	v_mad_u64_u32 v[128:129], s[12:13], v23, s77, v[6:7]
	v_mad_u64_u32 v[130:131], s[12:13], v0, s77, v[6:7]
	s_add_i32 s13, s11, 16
	s_add_i32 s12, s10, 16
	v_or_b32_e32 v23, s13, v2
	v_or_b32_e32 v0, s12, v3
	v_add_u32_e32 v30, s0, v23
	v_add_u32_e32 v28, s2, v0
	v_ashrrev_i32_e32 v31, 31, v30
	v_ashrrev_i32_e32 v29, 31, v28
	v_lshlrev_b64 v[30:31], 11, v[30:31]
	v_lshlrev_b64 v[28:29], 11, v[28:29]
	v_lshl_add_u64 v[30:31], v[26:27], 0, v[30:31]
	v_lshl_add_u64 v[28:29], v[26:27], 0, v[28:29]
	global_load_dword v108, v[30:31], off
	global_load_dword v109, v[28:29], off
	v_mad_u64_u32 v[132:133], s[12:13], v23, s77, v[6:7]
	v_mad_u64_u32 v[134:135], s[12:13], v0, s77, v[6:7]
	s_add_i32 s13, s11, 20
	s_add_i32 s12, s10, 20
	v_or_b32_e32 v23, s13, v2
	v_or_b32_e32 v0, s12, v3
	v_add_u32_e32 v30, s0, v23
	v_add_u32_e32 v28, s2, v0
	v_ashrrev_i32_e32 v31, 31, v30
	v_ashrrev_i32_e32 v29, 31, v28
	v_lshlrev_b64 v[30:31], 11, v[30:31]
	v_lshlrev_b64 v[28:29], 11, v[28:29]
	v_lshl_add_u64 v[30:31], v[26:27], 0, v[30:31]
	v_lshl_add_u64 v[28:29], v[26:27], 0, v[28:29]
	global_load_dword v110, v[30:31], off
	global_load_dword v111, v[28:29], off
	v_mad_u64_u32 v[136:137], s[12:13], v23, s77, v[6:7]
	v_mad_u64_u32 v[138:139], s[12:13], v0, s77, v[6:7]
	s_add_i32 s13, s11, 24
	s_add_i32 s12, s10, 24
	v_or_b32_e32 v23, s13, v2
	v_or_b32_e32 v0, s12, v3
	s_add_i32 s11, s11, 28
	s_add_i32 s10, s10, 28
	s_cmp_lg_u32 s7, 0
	v_add_u32_e32 v30, s0, v23
	v_add_u32_e32 v28, s2, v0
	v_ashrrev_i32_e32 v31, 31, v30
	v_ashrrev_i32_e32 v29, 31, v28
	v_lshlrev_b64 v[30:31], 11, v[30:31]
	v_lshlrev_b64 v[28:29], 11, v[28:29]
	v_lshl_add_u64 v[30:31], v[26:27], 0, v[30:31]
	v_lshl_add_u64 v[28:29], v[26:27], 0, v[28:29]
	global_load_dword v112, v[30:31], off
	global_load_dword v113, v[28:29], off
	v_mad_u64_u32 v[140:141], s[12:13], v23, s77, v[6:7]
	v_mad_u64_u32 v[142:143], s[12:13], v0, s77, v[6:7]
	v_or_b32_e32 v23, s11, v2
	v_or_b32_e32 v0, s10, v3
	v_add_u32_e32 v30, s0, v23
	v_add_u32_e32 v28, s2, v0
	v_ashrrev_i32_e32 v31, 31, v30
	v_ashrrev_i32_e32 v29, 31, v28
	v_lshlrev_b64 v[30:31], 11, v[30:31]
	v_lshlrev_b64 v[28:29], 11, v[28:29]
	v_lshl_add_u64 v[30:31], v[26:27], 0, v[30:31]
	v_lshl_add_u64 v[28:29], v[26:27], 0, v[28:29]
	global_load_dword v114, v[30:31], off
	global_load_dword v115, v[28:29], off
	v_mad_u64_u32 v[144:145], s[10:11], v23, s77, v[6:7]
	v_mad_u64_u32 v[146:147], s[10:11], v0, s77, v[6:7]
	s_lshl_b32 s11, s6, 1
	s_lshl_b32 s10, s3, 1
	v_or_b32_e32 v23, s11, v2
	v_or_b32_e32 v0, s10, v3
	v_add_u32_e32 v30, s0, v23
	v_add_u32_e32 v28, s2, v0
	v_ashrrev_i32_e32 v31, 31, v30
	v_ashrrev_i32_e32 v29, 31, v28
	v_lshlrev_b64 v[30:31], 11, v[30:31]
	v_lshlrev_b64 v[28:29], 11, v[28:29]
	v_lshl_add_u64 v[30:31], v[26:27], 0, v[30:31]
	v_lshl_add_u64 v[28:29], v[26:27], 0, v[28:29]
	global_load_dword v148, v[30:31], off
	global_load_dword v149, v[28:29], off
	v_mad_u64_u32 v[164:165], s[12:13], v23, s77, v[6:7]
	v_mad_u64_u32 v[166:167], s[12:13], v0, s77, v[6:7]
	s_add_i32 s13, s11, 4
	s_add_i32 s12, s10, 4
	v_or_b32_e32 v23, s13, v2
	v_or_b32_e32 v0, s12, v3
	s_add_i32 s6, s6, 16
	s_add_i32 s3, s3, 16
	s_add_i32 s7, s7, -16
	v_add_u32_e32 v30, s0, v23
	v_add_u32_e32 v28, s2, v0
	v_ashrrev_i32_e32 v31, 31, v30
	v_ashrrev_i32_e32 v29, 31, v28
	v_lshlrev_b64 v[30:31], 11, v[30:31]
	v_lshlrev_b64 v[28:29], 11, v[28:29]
	v_lshl_add_u64 v[30:31], v[26:27], 0, v[30:31]
	v_lshl_add_u64 v[28:29], v[26:27], 0, v[28:29]
	global_load_dword v150, v[30:31], off
	global_load_dword v151, v[28:29], off
	v_mad_u64_u32 v[168:169], s[12:13], v23, s77, v[6:7]
	v_mad_u64_u32 v[170:171], s[12:13], v0, s77, v[6:7]
	s_add_i32 s13, s11, 8
	s_add_i32 s12, s10, 8
	v_or_b32_e32 v23, s13, v2
	v_or_b32_e32 v0, s12, v3
	v_add_u32_e32 v30, s0, v23
	v_add_u32_e32 v28, s2, v0
	v_ashrrev_i32_e32 v31, 31, v30
	v_ashrrev_i32_e32 v29, 31, v28
	v_lshlrev_b64 v[30:31], 11, v[30:31]
	v_lshlrev_b64 v[28:29], 11, v[28:29]
	v_lshl_add_u64 v[30:31], v[26:27], 0, v[30:31]
	v_lshl_add_u64 v[28:29], v[26:27], 0, v[28:29]
	global_load_dword v152, v[30:31], off
	global_load_dword v153, v[28:29], off
	v_mad_u64_u32 v[172:173], s[12:13], v23, s77, v[6:7]
	v_mad_u64_u32 v[174:175], s[12:13], v0, s77, v[6:7]
	s_add_i32 s13, s11, 12
	s_add_i32 s12, s10, 12
	v_or_b32_e32 v23, s13, v2
	v_or_b32_e32 v0, s12, v3
	v_add_u32_e32 v30, s0, v23
	v_add_u32_e32 v28, s2, v0
	v_ashrrev_i32_e32 v31, 31, v30
	v_ashrrev_i32_e32 v29, 31, v28
	v_lshlrev_b64 v[30:31], 11, v[30:31]
	v_lshlrev_b64 v[28:29], 11, v[28:29]
	v_lshl_add_u64 v[30:31], v[26:27], 0, v[30:31]
	v_lshl_add_u64 v[28:29], v[26:27], 0, v[28:29]
	global_load_dword v154, v[30:31], off
	global_load_dword v155, v[28:29], off
	v_mad_u64_u32 v[176:177], s[12:13], v23, s77, v[6:7]
	v_mad_u64_u32 v[178:179], s[12:13], v0, s77, v[6:7]
	s_add_i32 s13, s11, 16
	s_add_i32 s12, s10, 16
	v_or_b32_e32 v23, s13, v2
	v_or_b32_e32 v0, s12, v3
	v_add_u32_e32 v30, s0, v23
	v_add_u32_e32 v28, s2, v0
	v_ashrrev_i32_e32 v31, 31, v30
	v_ashrrev_i32_e32 v29, 31, v28
	v_lshlrev_b64 v[30:31], 11, v[30:31]
	v_lshlrev_b64 v[28:29], 11, v[28:29]
	v_lshl_add_u64 v[30:31], v[26:27], 0, v[30:31]
	v_lshl_add_u64 v[28:29], v[26:27], 0, v[28:29]
	global_load_dword v156, v[30:31], off
	global_load_dword v157, v[28:29], off
	v_mad_u64_u32 v[180:181], s[12:13], v23, s77, v[6:7]
	v_mad_u64_u32 v[182:183], s[12:13], v0, s77, v[6:7]
	s_add_i32 s13, s11, 20
	s_add_i32 s12, s10, 20
	v_or_b32_e32 v23, s13, v2
	v_or_b32_e32 v0, s12, v3
	v_add_u32_e32 v30, s0, v23
	v_add_u32_e32 v28, s2, v0
	v_ashrrev_i32_e32 v31, 31, v30
	v_ashrrev_i32_e32 v29, 31, v28
	v_lshlrev_b64 v[30:31], 11, v[30:31]
	v_lshlrev_b64 v[28:29], 11, v[28:29]
	v_lshl_add_u64 v[30:31], v[26:27], 0, v[30:31]
	v_lshl_add_u64 v[28:29], v[26:27], 0, v[28:29]
	global_load_dword v158, v[30:31], off
	global_load_dword v159, v[28:29], off
	v_mad_u64_u32 v[184:185], s[12:13], v23, s77, v[6:7]
	v_mad_u64_u32 v[186:187], s[12:13], v0, s77, v[6:7]
	s_add_i32 s13, s11, 24
	s_add_i32 s12, s10, 24
	v_or_b32_e32 v23, s13, v2
	v_or_b32_e32 v0, s12, v3
	s_add_i32 s11, s11, 28
	s_add_i32 s10, s10, 28
	s_cmp_lg_u32 s7, 0
	v_add_u32_e32 v30, s0, v23
	v_add_u32_e32 v28, s2, v0
	v_ashrrev_i32_e32 v31, 31, v30
	v_ashrrev_i32_e32 v29, 31, v28
	v_lshlrev_b64 v[30:31], 11, v[30:31]
	v_lshlrev_b64 v[28:29], 11, v[28:29]
	v_lshl_add_u64 v[30:31], v[26:27], 0, v[30:31]
	v_lshl_add_u64 v[28:29], v[26:27], 0, v[28:29]
	global_load_dword v160, v[30:31], off
	global_load_dword v161, v[28:29], off
	v_mad_u64_u32 v[188:189], s[12:13], v23, s77, v[6:7]
	v_mad_u64_u32 v[190:191], s[12:13], v0, s77, v[6:7]
	v_or_b32_e32 v23, s11, v2
	v_or_b32_e32 v0, s10, v3
	v_add_u32_e32 v30, s0, v23
	v_add_u32_e32 v28, s2, v0
	v_ashrrev_i32_e32 v31, 31, v30
	v_ashrrev_i32_e32 v29, 31, v28
	v_lshlrev_b64 v[30:31], 11, v[30:31]
	v_lshlrev_b64 v[28:29], 11, v[28:29]
	v_lshl_add_u64 v[30:31], v[26:27], 0, v[30:31]
	v_lshl_add_u64 v[28:29], v[26:27], 0, v[28:29]
	global_load_dword v162, v[30:31], off
	global_load_dword v163, v[28:29], off
	v_mad_u64_u32 v[192:193], s[10:11], v23, s77, v[6:7]
	v_mad_u64_u32 v[196:197], s[10:11], v0, s77, v[6:7]
	s_waitcnt vmcnt(0)
	ds_write_b32 v116, v100
	ds_write_b32 v118, v101
	ds_write_b32 v120, v102
	ds_write_b32 v122, v103
	ds_write_b32 v124, v104
	ds_write_b32 v126, v105
	ds_write_b32 v128, v106
	ds_write_b32 v130, v107
	ds_write_b32 v132, v108
	ds_write_b32 v134, v109
	ds_write_b32 v136, v110
	ds_write_b32 v138, v111
	ds_write_b32 v140, v112
	ds_write_b32 v142, v113
	ds_write_b32 v144, v114
	ds_write_b32 v146, v115
	ds_write_b32 v164, v148
	ds_write_b32 v166, v149
	ds_write_b32 v168, v150
	ds_write_b32 v170, v151
	ds_write_b32 v172, v152
	ds_write_b32 v174, v153
	ds_write_b32 v176, v154
	ds_write_b32 v178, v155
	ds_write_b32 v180, v156
	ds_write_b32 v182, v157
	ds_write_b32 v184, v158
	ds_write_b32 v186, v159
	ds_write_b32 v188, v160
	ds_write_b32 v190, v161
	ds_write_b32 v192, v162
	ds_write_b32 v196, v163
	s_cbranch_scc1 .LBB0_691
	s_lshl_b32 s1, s1, 10
	s_add_u32 s2, s73, s1
	v_readlane_b32 s1, v250, 13
	s_addc_u32 s3, s1, 0
	s_mov_b32 s1, s4
	s_lshl_b64 s[0:1], s[0:1], 1
	s_add_u32 s0, s2, s0
	s_addc_u32 s1, s3, s1
	v_mov_b32_e32 v0, v43
	v_mov_b32_e32 v26, v42
	v_mov_b32_e32 v28, v41
	v_mov_b32_e32 v30, v40

.LBB0_700:
	s_lshl_b32 s12, s7, 1
	s_lshl_b32 s11, s2, 1
	v_or_b32_e32 v23, s12, v2
	v_or_b32_e32 v0, s11, v3
	v_add_u32_e32 v30, s6, v23
	v_add_u32_e32 v28, s3, v0
	v_ashrrev_i32_e32 v31, 31, v30
	v_ashrrev_i32_e32 v29, 31, v28
	v_lshlrev_b64 v[30:31], 12, v[30:31]
	v_lshlrev_b64 v[28:29], 12, v[28:29]
	v_lshl_add_u64 v[30:31], v[26:27], 0, v[30:31]
	v_lshl_add_u64 v[28:29], v[26:27], 0, v[28:29]
	global_load_dword v100, v[30:31], off
	global_load_dword v101, v[28:29], off
	v_mad_u64_u32 v[116:117], s[14:15], v23, s77, v[6:7]
	v_mad_u64_u32 v[118:119], s[14:15], v0, s77, v[6:7]
	s_add_i32 s14, s12, 4
	s_add_i32 s13, s11, 4
	v_or_b32_e32 v23, s14, v2
	v_or_b32_e32 v0, s13, v3
	s_add_i32 s13, s11, 8
	s_add_i32 s7, s7, 16
	s_add_i32 s2, s2, 16
	s_add_i32 s10, s10, -16
	v_add_u32_e32 v30, s6, v23
	v_add_u32_e32 v28, s3, v0
	v_ashrrev_i32_e32 v31, 31, v30
	v_ashrrev_i32_e32 v29, 31, v28
	v_lshlrev_b64 v[30:31], 12, v[30:31]
	v_lshlrev_b64 v[28:29], 12, v[28:29]
	v_lshl_add_u64 v[30:31], v[26:27], 0, v[30:31]
	v_lshl_add_u64 v[28:29], v[26:27], 0, v[28:29]
	global_load_dword v102, v[30:31], off
	global_load_dword v103, v[28:29], off
	v_mad_u64_u32 v[120:121], s[14:15], v23, s77, v[6:7]
	v_mad_u64_u32 v[122:123], s[14:15], v0, s77, v[6:7]
	s_add_i32 s14, s12, 8
	s_nop 0
	v_or_b32_e32 v23, s14, v2
	v_or_b32_e32 v0, s13, v3
	s_add_i32 s13, s11, 12
	v_add_u32_e32 v30, s6, v23
	v_add_u32_e32 v28, s3, v0
	v_ashrrev_i32_e32 v31, 31, v30
	v_ashrrev_i32_e32 v29, 31, v28
	v_lshlrev_b64 v[30:31], 12, v[30:31]
	v_lshlrev_b64 v[28:29], 12, v[28:29]
	v_lshl_add_u64 v[30:31], v[26:27], 0, v[30:31]
	v_lshl_add_u64 v[28:29], v[26:27], 0, v[28:29]
	global_load_dword v104, v[30:31], off
	global_load_dword v105, v[28:29], off
	v_mad_u64_u32 v[124:125], s[14:15], v23, s77, v[6:7]
	v_mad_u64_u32 v[126:127], s[14:15], v0, s77, v[6:7]
	s_add_i32 s14, s12, 12
	s_nop 0
	v_or_b32_e32 v23, s14, v2
	v_or_b32_e32 v0, s13, v3
	s_add_i32 s13, s11, 16
	v_add_u32_e32 v30, s6, v23
	v_add_u32_e32 v28, s3, v0
	v_ashrrev_i32_e32 v31, 31, v30
	v_ashrrev_i32_e32 v29, 31, v28
	v_lshlrev_b64 v[30:31], 12, v[30:31]
	v_lshlrev_b64 v[28:29], 12, v[28:29]
	v_lshl_add_u64 v[30:31], v[26:27], 0, v[30:31]
	v_lshl_add_u64 v[28:29], v[26:27], 0, v[28:29]
	global_load_dword v106, v[30:31], off
	global_load_dword v107, v[28:29], off
	v_mad_u64_u32 v[128:129], s[14:15], v23, s77, v[6:7]
	v_mad_u64_u32 v[130:131], s[14:15], v0, s77, v[6:7]
	s_add_i32 s14, s12, 16
	s_nop 0
	v_or_b32_e32 v23, s14, v2
	v_or_b32_e32 v0, s13, v3
	s_add_i32 s13, s11, 20
	v_add_u32_e32 v30, s6, v23
	v_add_u32_e32 v28, s3, v0
	v_ashrrev_i32_e32 v31, 31, v30
	v_ashrrev_i32_e32 v29, 31, v28
	v_lshlrev_b64 v[30:31], 12, v[30:31]
	v_lshlrev_b64 v[28:29], 12, v[28:29]
	v_lshl_add_u64 v[30:31], v[26:27], 0, v[30:31]
	v_lshl_add_u64 v[28:29], v[26:27], 0, v[28:29]
	global_load_dword v108, v[30:31], off
	global_load_dword v109, v[28:29], off
	v_mad_u64_u32 v[132:133], s[14:15], v23, s77, v[6:7]
	v_mad_u64_u32 v[134:135], s[14:15], v0, s77, v[6:7]
	s_add_i32 s14, s12, 20
	s_nop 0
	v_or_b32_e32 v23, s14, v2
	v_or_b32_e32 v0, s13, v3
	s_add_i32 s13, s11, 24
	s_add_i32 s11, s11, 28
	v_add_u32_e32 v30, s6, v23
	v_add_u32_e32 v28, s3, v0
	v_ashrrev_i32_e32 v31, 31, v30
	v_ashrrev_i32_e32 v29, 31, v28
	v_lshlrev_b64 v[30:31], 12, v[30:31]
	v_lshlrev_b64 v[28:29], 12, v[28:29]
	v_lshl_add_u64 v[30:31], v[26:27], 0, v[30:31]
	v_lshl_add_u64 v[28:29], v[26:27], 0, v[28:29]
	global_load_dword v110, v[30:31], off
	global_load_dword v111, v[28:29], off
	v_mad_u64_u32 v[136:137], s[14:15], v23, s77, v[6:7]
	v_mad_u64_u32 v[138:139], s[14:15], v0, s77, v[6:7]
	s_add_i32 s14, s12, 24
	s_nop 0
	v_or_b32_e32 v23, s14, v2
	v_or_b32_e32 v0, s13, v3
	s_add_i32 s12, s12, 28
	s_cmp_lg_u32 s10, 0
	v_add_u32_e32 v30, s6, v23
	v_add_u32_e32 v28, s3, v0
	v_ashrrev_i32_e32 v31, 31, v30
	v_ashrrev_i32_e32 v29, 31, v28
	v_lshlrev_b64 v[30:31], 12, v[30:31]
	v_lshlrev_b64 v[28:29], 12, v[28:29]
	v_lshl_add_u64 v[30:31], v[26:27], 0, v[30:31]
	v_lshl_add_u64 v[28:29], v[26:27], 0, v[28:29]
	global_load_dword v112, v[30:31], off
	global_load_dword v113, v[28:29], off
	v_mad_u64_u32 v[140:141], s[14:15], v23, s77, v[6:7]
	v_mad_u64_u32 v[142:143], s[14:15], v0, s77, v[6:7]
	v_or_b32_e32 v23, s12, v2
	v_or_b32_e32 v0, s11, v3
	v_add_u32_e32 v30, s6, v23
	v_add_u32_e32 v28, s3, v0
	v_ashrrev_i32_e32 v31, 31, v30
	v_ashrrev_i32_e32 v29, 31, v28
	v_lshlrev_b64 v[30:31], 12, v[30:31]
	v_lshlrev_b64 v[28:29], 12, v[28:29]
	v_lshl_add_u64 v[30:31], v[26:27], 0, v[30:31]
	v_lshl_add_u64 v[28:29], v[26:27], 0, v[28:29]
	global_load_dword v114, v[30:31], off
	global_load_dword v115, v[28:29], off
	v_mad_u64_u32 v[144:145], s[12:13], v23, s77, v[6:7]
	v_mad_u64_u32 v[146:147], s[12:13], v0, s77, v[6:7]
	s_lshl_b32 s12, s7, 1
	s_lshl_b32 s11, s2, 1
	v_or_b32_e32 v23, s12, v2
	v_or_b32_e32 v0, s11, v3
	v_add_u32_e32 v30, s6, v23
	v_add_u32_e32 v28, s3, v0
	v_ashrrev_i32_e32 v31, 31, v30
	v_ashrrev_i32_e32 v29, 31, v28
	v_lshlrev_b64 v[30:31], 12, v[30:31]
	v_lshlrev_b64 v[28:29], 12, v[28:29]
	v_lshl_add_u64 v[30:31], v[26:27], 0, v[30:31]
	v_lshl_add_u64 v[28:29], v[26:27], 0, v[28:29]
	global_load_dword v148, v[30:31], off
	global_load_dword v149, v[28:29], off
	v_mad_u64_u32 v[164:165], s[14:15], v23, s77, v[6:7]
	v_mad_u64_u32 v[166:167], s[14:15], v0, s77, v[6:7]
	s_add_i32 s14, s12, 4
	s_add_i32 s13, s11, 4
	v_or_b32_e32 v23, s14, v2
	v_or_b32_e32 v0, s13, v3
	s_add_i32 s13, s11, 8
	s_add_i32 s7, s7, 16
	s_add_i32 s2, s2, 16
	s_add_i32 s10, s10, -16
	v_add_u32_e32 v30, s6, v23
	v_add_u32_e32 v28, s3, v0
	v_ashrrev_i32_e32 v31, 31, v30
	v_ashrrev_i32_e32 v29, 31, v28
	v_lshlrev_b64 v[30:31], 12, v[30:31]
	v_lshlrev_b64 v[28:29], 12, v[28:29]
	v_lshl_add_u64 v[30:31], v[26:27], 0, v[30:31]
	v_lshl_add_u64 v[28:29], v[26:27], 0, v[28:29]
	global_load_dword v150, v[30:31], off
	global_load_dword v151, v[28:29], off
	v_mad_u64_u32 v[168:169], s[14:15], v23, s77, v[6:7]
	v_mad_u64_u32 v[170:171], s[14:15], v0, s77, v[6:7]
	s_add_i32 s14, s12, 8
	s_nop 0
	v_or_b32_e32 v23, s14, v2
	v_or_b32_e32 v0, s13, v3
	s_add_i32 s13, s11, 12
	v_add_u32_e32 v30, s6, v23
	v_add_u32_e32 v28, s3, v0
	v_ashrrev_i32_e32 v31, 31, v30
	v_ashrrev_i32_e32 v29, 31, v28
	v_lshlrev_b64 v[30:31], 12, v[30:31]
	v_lshlrev_b64 v[28:29], 12, v[28:29]
	v_lshl_add_u64 v[30:31], v[26:27], 0, v[30:31]
	v_lshl_add_u64 v[28:29], v[26:27], 0, v[28:29]
	global_load_dword v152, v[30:31], off
	global_load_dword v153, v[28:29], off
	v_mad_u64_u32 v[172:173], s[14:15], v23, s77, v[6:7]
	v_mad_u64_u32 v[174:175], s[14:15], v0, s77, v[6:7]
	s_add_i32 s14, s12, 12
	s_nop 0
	v_or_b32_e32 v23, s14, v2
	v_or_b32_e32 v0, s13, v3
	s_add_i32 s13, s11, 16
	v_add_u32_e32 v30, s6, v23
	v_add_u32_e32 v28, s3, v0
	v_ashrrev_i32_e32 v31, 31, v30
	v_ashrrev_i32_e32 v29, 31, v28
	v_lshlrev_b64 v[30:31], 12, v[30:31]
	v_lshlrev_b64 v[28:29], 12, v[28:29]
	v_lshl_add_u64 v[30:31], v[26:27], 0, v[30:31]
	v_lshl_add_u64 v[28:29], v[26:27], 0, v[28:29]
	global_load_dword v154, v[30:31], off
	global_load_dword v155, v[28:29], off
	v_mad_u64_u32 v[176:177], s[14:15], v23, s77, v[6:7]
	v_mad_u64_u32 v[178:179], s[14:15], v0, s77, v[6:7]
	s_add_i32 s14, s12, 16
	s_nop 0
	v_or_b32_e32 v23, s14, v2
	v_or_b32_e32 v0, s13, v3
	s_add_i32 s13, s11, 20
	v_add_u32_e32 v30, s6, v23
	v_add_u32_e32 v28, s3, v0
	v_ashrrev_i32_e32 v31, 31, v30
	v_ashrrev_i32_e32 v29, 31, v28
	v_lshlrev_b64 v[30:31], 12, v[30:31]
	v_lshlrev_b64 v[28:29], 12, v[28:29]
	v_lshl_add_u64 v[30:31], v[26:27], 0, v[30:31]
	v_lshl_add_u64 v[28:29], v[26:27], 0, v[28:29]
	global_load_dword v156, v[30:31], off
	global_load_dword v157, v[28:29], off
	v_mad_u64_u32 v[180:181], s[14:15], v23, s77, v[6:7]
	v_mad_u64_u32 v[182:183], s[14:15], v0, s77, v[6:7]
	s_add_i32 s14, s12, 20
	s_nop 0
	v_or_b32_e32 v23, s14, v2
	v_or_b32_e32 v0, s13, v3
	s_add_i32 s13, s11, 24
	s_add_i32 s11, s11, 28
	v_add_u32_e32 v30, s6, v23
	v_add_u32_e32 v28, s3, v0
	v_ashrrev_i32_e32 v31, 31, v30
	v_ashrrev_i32_e32 v29, 31, v28
	v_lshlrev_b64 v[30:31], 12, v[30:31]
	v_lshlrev_b64 v[28:29], 12, v[28:29]
	v_lshl_add_u64 v[30:31], v[26:27], 0, v[30:31]
	v_lshl_add_u64 v[28:29], v[26:27], 0, v[28:29]
	global_load_dword v158, v[30:31], off
	global_load_dword v159, v[28:29], off
	v_mad_u64_u32 v[184:185], s[14:15], v23, s77, v[6:7]
	v_mad_u64_u32 v[186:187], s[14:15], v0, s77, v[6:7]
	s_add_i32 s14, s12, 24
	s_nop 0
	v_or_b32_e32 v23, s14, v2
	v_or_b32_e32 v0, s13, v3
	s_add_i32 s12, s12, 28
	s_cmp_lg_u32 s10, 0
	v_add_u32_e32 v30, s6, v23
	v_add_u32_e32 v28, s3, v0
	v_ashrrev_i32_e32 v31, 31, v30
	v_ashrrev_i32_e32 v29, 31, v28
	v_lshlrev_b64 v[30:31], 12, v[30:31]
	v_lshlrev_b64 v[28:29], 12, v[28:29]
	v_lshl_add_u64 v[30:31], v[26:27], 0, v[30:31]
	v_lshl_add_u64 v[28:29], v[26:27], 0, v[28:29]
	global_load_dword v160, v[30:31], off
	global_load_dword v161, v[28:29], off
	v_mad_u64_u32 v[188:189], s[14:15], v23, s77, v[6:7]
	v_mad_u64_u32 v[190:191], s[14:15], v0, s77, v[6:7]
	v_or_b32_e32 v23, s12, v2
	v_or_b32_e32 v0, s11, v3
	v_add_u32_e32 v30, s6, v23
	v_add_u32_e32 v28, s3, v0
	v_ashrrev_i32_e32 v31, 31, v30
	v_ashrrev_i32_e32 v29, 31, v28
	v_lshlrev_b64 v[30:31], 12, v[30:31]
	v_lshlrev_b64 v[28:29], 12, v[28:29]
	v_lshl_add_u64 v[30:31], v[26:27], 0, v[30:31]
	v_lshl_add_u64 v[28:29], v[26:27], 0, v[28:29]
	global_load_dword v162, v[30:31], off
	global_load_dword v163, v[28:29], off
	v_mad_u64_u32 v[192:193], s[12:13], v23, s77, v[6:7]
	v_mad_u64_u32 v[196:197], s[12:13], v0, s77, v[6:7]
	s_waitcnt vmcnt(0)
	ds_write_b32 v116, v100
	ds_write_b32 v118, v101
	ds_write_b32 v120, v102
	ds_write_b32 v122, v103
	ds_write_b32 v124, v104
	ds_write_b32 v126, v105
	ds_write_b32 v128, v106
	ds_write_b32 v130, v107
	ds_write_b32 v132, v108
	ds_write_b32 v134, v109
	ds_write_b32 v136, v110
	ds_write_b32 v138, v111
	ds_write_b32 v140, v112
	ds_write_b32 v142, v113
	ds_write_b32 v144, v114
	ds_write_b32 v146, v115
	ds_write_b32 v164, v148
	ds_write_b32 v166, v149
	ds_write_b32 v168, v150
	ds_write_b32 v170, v151
	ds_write_b32 v172, v152
	ds_write_b32 v174, v153
	ds_write_b32 v176, v154
	ds_write_b32 v178, v155
	ds_write_b32 v180, v156
	ds_write_b32 v182, v157
	ds_write_b32 v184, v158
	ds_write_b32 v186, v159
	ds_write_b32 v188, v160
	ds_write_b32 v190, v161
	ds_write_b32 v192, v162
	ds_write_b32 v196, v163
	s_cbranch_scc1 .LBB0_700
	s_mov_b32 s7, s4
	s_lshl_b64 s[2:3], s[6:7], 1
	s_add_u32 s0, s0, s2
	s_addc_u32 s1, s1, s3
	v_mov_b32_e32 v0, v47
	v_mov_b32_e32 v26, v46
	v_mov_b32_e32 v28, v45
	v_mov_b32_e32 v30, v44

.LBB0_705:
	s_lshl_b32 s11, s6, 1
	s_lshl_b32 s10, s3, 1
	v_or_b32_e32 v23, s11, v2
	v_or_b32_e32 v0, s10, v3
	v_add_u32_e32 v28, s0, v23
	v_add_u32_e32 v25, s2, v0
	v_mad_u64_u32 v[28:29], s[12:13], v28, s61, v[26:27]
	v_mad_u64_u32 v[30:31], s[12:13], v25, s61, v[26:27]
	global_load_dword v100, v[28:29], off
	global_load_dword v101, v[30:31], off
	v_mad_u64_u32 v[116:117], s[12:13], v23, s77, v[6:7]
	v_mad_u64_u32 v[118:119], s[12:13], v0, s77, v[6:7]
	s_add_i32 s13, s11, 4
	s_add_i32 s12, s10, 4
	v_or_b32_e32 v23, s13, v2
	v_or_b32_e32 v0, s12, v3
	s_add_i32 s6, s6, 16
	s_add_i32 s3, s3, 16
	s_add_i32 s7, s7, -16
	v_add_u32_e32 v28, s0, v23
	v_add_u32_e32 v25, s2, v0
	v_mad_u64_u32 v[28:29], s[12:13], v28, s61, v[26:27]
	v_mad_u64_u32 v[30:31], s[12:13], v25, s61, v[26:27]
	global_load_dword v102, v[28:29], off
	global_load_dword v103, v[30:31], off
	v_mad_u64_u32 v[120:121], s[12:13], v23, s77, v[6:7]
	v_mad_u64_u32 v[122:123], s[12:13], v0, s77, v[6:7]
	s_add_i32 s13, s11, 8
	s_add_i32 s12, s10, 8
	v_or_b32_e32 v23, s13, v2
	v_or_b32_e32 v0, s12, v3
	v_add_u32_e32 v28, s0, v23
	v_add_u32_e32 v25, s2, v0
	v_mad_u64_u32 v[28:29], s[12:13], v28, s61, v[26:27]
	v_mad_u64_u32 v[30:31], s[12:13], v25, s61, v[26:27]
	global_load_dword v104, v[28:29], off
	global_load_dword v105, v[30:31], off
	v_mad_u64_u32 v[124:125], s[12:13], v23, s77, v[6:7]
	v_mad_u64_u32 v[126:127], s[12:13], v0, s77, v[6:7]
	s_add_i32 s13, s11, 12
	s_add_i32 s12, s10, 12
	v_or_b32_e32 v23, s13, v2
	v_or_b32_e32 v0, s12, v3
	v_add_u32_e32 v28, s0, v23
	v_add_u32_e32 v25, s2, v0
	v_mad_u64_u32 v[28:29], s[12:13], v28, s61, v[26:27]
	v_mad_u64_u32 v[30:31], s[12:13], v25, s61, v[26:27]
	global_load_dword v106, v[28:29], off
	global_load_dword v107, v[30:31], off
	v_mad_u64_u32 v[128:129], s[12:13], v23, s77, v[6:7]
	v_mad_u64_u32 v[130:131], s[12:13], v0, s77, v[6:7]
	s_add_i32 s13, s11, 16
	s_add_i32 s12, s10, 16
	v_or_b32_e32 v23, s13, v2
	v_or_b32_e32 v0, s12, v3
	v_add_u32_e32 v28, s0, v23
	v_add_u32_e32 v25, s2, v0
	v_mad_u64_u32 v[28:29], s[12:13], v28, s61, v[26:27]
	v_mad_u64_u32 v[30:31], s[12:13], v25, s61, v[26:27]
	global_load_dword v108, v[28:29], off
	global_load_dword v109, v[30:31], off
	v_mad_u64_u32 v[132:133], s[12:13], v23, s77, v[6:7]
	v_mad_u64_u32 v[134:135], s[12:13], v0, s77, v[6:7]
	s_add_i32 s13, s11, 20
	s_add_i32 s12, s10, 20
	v_or_b32_e32 v23, s13, v2
	v_or_b32_e32 v0, s12, v3
	v_add_u32_e32 v28, s0, v23
	v_add_u32_e32 v25, s2, v0
	v_mad_u64_u32 v[28:29], s[12:13], v28, s61, v[26:27]
	v_mad_u64_u32 v[30:31], s[12:13], v25, s61, v[26:27]
	global_load_dword v110, v[28:29], off
	global_load_dword v111, v[30:31], off
	v_mad_u64_u32 v[136:137], s[12:13], v23, s77, v[6:7]
	v_mad_u64_u32 v[138:139], s[12:13], v0, s77, v[6:7]
	s_add_i32 s13, s11, 24
	s_add_i32 s12, s10, 24
	v_or_b32_e32 v23, s13, v2
	v_or_b32_e32 v0, s12, v3
	s_add_i32 s11, s11, 28
	s_add_i32 s10, s10, 28
	s_cmp_lg_u32 s7, 0
	v_add_u32_e32 v28, s0, v23
	v_add_u32_e32 v25, s2, v0
	v_mad_u64_u32 v[28:29], s[12:13], v28, s61, v[26:27]
	v_mad_u64_u32 v[30:31], s[12:13], v25, s61, v[26:27]
	global_load_dword v112, v[28:29], off
	global_load_dword v113, v[30:31], off
	v_mad_u64_u32 v[140:141], s[12:13], v23, s77, v[6:7]
	v_or_b32_e32 v23, s11, v2
	v_mad_u64_u32 v[142:143], s[12:13], v0, s77, v[6:7]
	v_or_b32_e32 v0, s10, v3
	v_add_u32_e32 v28, s0, v23
	v_add_u32_e32 v25, s2, v0
	v_mad_u64_u32 v[28:29], s[10:11], v28, s61, v[26:27]
	v_mad_u64_u32 v[30:31], s[10:11], v25, s61, v[26:27]
	global_load_dword v114, v[28:29], off
	global_load_dword v115, v[30:31], off
	v_mad_u64_u32 v[144:145], s[10:11], v23, s77, v[6:7]
	v_mad_u64_u32 v[146:147], s[10:11], v0, s77, v[6:7]
	s_lshl_b32 s11, s6, 1
	s_lshl_b32 s10, s3, 1
	v_or_b32_e32 v23, s11, v2
	v_or_b32_e32 v0, s10, v3
	v_add_u32_e32 v28, s0, v23
	v_add_u32_e32 v25, s2, v0
	v_mad_u64_u32 v[28:29], s[12:13], v28, s61, v[26:27]
	v_mad_u64_u32 v[30:31], s[12:13], v25, s61, v[26:27]
	global_load_dword v148, v[28:29], off
	global_load_dword v149, v[30:31], off
	v_mad_u64_u32 v[164:165], s[12:13], v23, s77, v[6:7]
	v_mad_u64_u32 v[166:167], s[12:13], v0, s77, v[6:7]
	s_add_i32 s13, s11, 4
	s_add_i32 s12, s10, 4
	v_or_b32_e32 v23, s13, v2
	v_or_b32_e32 v0, s12, v3
	s_add_i32 s6, s6, 16
	s_add_i32 s3, s3, 16
	s_add_i32 s7, s7, -16
	v_add_u32_e32 v28, s0, v23
	v_add_u32_e32 v25, s2, v0
	v_mad_u64_u32 v[28:29], s[12:13], v28, s61, v[26:27]
	v_mad_u64_u32 v[30:31], s[12:13], v25, s61, v[26:27]
	global_load_dword v150, v[28:29], off
	global_load_dword v151, v[30:31], off
	v_mad_u64_u32 v[168:169], s[12:13], v23, s77, v[6:7]
	v_mad_u64_u32 v[170:171], s[12:13], v0, s77, v[6:7]
	s_add_i32 s13, s11, 8
	s_add_i32 s12, s10, 8
	v_or_b32_e32 v23, s13, v2
	v_or_b32_e32 v0, s12, v3
	v_add_u32_e32 v28, s0, v23
	v_add_u32_e32 v25, s2, v0
	v_mad_u64_u32 v[28:29], s[12:13], v28, s61, v[26:27]
	v_mad_u64_u32 v[30:31], s[12:13], v25, s61, v[26:27]
	global_load_dword v152, v[28:29], off
	global_load_dword v153, v[30:31], off
	v_mad_u64_u32 v[172:173], s[12:13], v23, s77, v[6:7]
	v_mad_u64_u32 v[174:175], s[12:13], v0, s77, v[6:7]
	s_add_i32 s13, s11, 12
	s_add_i32 s12, s10, 12
	v_or_b32_e32 v23, s13, v2
	v_or_b32_e32 v0, s12, v3
	v_add_u32_e32 v28, s0, v23
	v_add_u32_e32 v25, s2, v0
	v_mad_u64_u32 v[28:29], s[12:13], v28, s61, v[26:27]
	v_mad_u64_u32 v[30:31], s[12:13], v25, s61, v[26:27]
	global_load_dword v154, v[28:29], off
	global_load_dword v155, v[30:31], off
	v_mad_u64_u32 v[176:177], s[12:13], v23, s77, v[6:7]
	v_mad_u64_u32 v[178:179], s[12:13], v0, s77, v[6:7]
	s_add_i32 s13, s11, 16
	s_add_i32 s12, s10, 16
	v_or_b32_e32 v23, s13, v2
	v_or_b32_e32 v0, s12, v3
	v_add_u32_e32 v28, s0, v23
	v_add_u32_e32 v25, s2, v0
	v_mad_u64_u32 v[28:29], s[12:13], v28, s61, v[26:27]
	v_mad_u64_u32 v[30:31], s[12:13], v25, s61, v[26:27]
	global_load_dword v156, v[28:29], off
	global_load_dword v157, v[30:31], off
	v_mad_u64_u32 v[180:181], s[12:13], v23, s77, v[6:7]
	v_mad_u64_u32 v[182:183], s[12:13], v0, s77, v[6:7]
	s_add_i32 s13, s11, 20
	s_add_i32 s12, s10, 20
	v_or_b32_e32 v23, s13, v2
	v_or_b32_e32 v0, s12, v3
	v_add_u32_e32 v28, s0, v23
	v_add_u32_e32 v25, s2, v0
	v_mad_u64_u32 v[28:29], s[12:13], v28, s61, v[26:27]
	v_mad_u64_u32 v[30:31], s[12:13], v25, s61, v[26:27]
	global_load_dword v158, v[28:29], off
	global_load_dword v159, v[30:31], off
	v_mad_u64_u32 v[184:185], s[12:13], v23, s77, v[6:7]
	v_mad_u64_u32 v[186:187], s[12:13], v0, s77, v[6:7]
	s_add_i32 s13, s11, 24
	s_add_i32 s12, s10, 24
	v_or_b32_e32 v23, s13, v2
	v_or_b32_e32 v0, s12, v3
	s_add_i32 s11, s11, 28
	s_add_i32 s10, s10, 28
	s_cmp_lg_u32 s7, 0
	v_add_u32_e32 v28, s0, v23
	v_add_u32_e32 v25, s2, v0
	v_mad_u64_u32 v[28:29], s[12:13], v28, s61, v[26:27]
	v_mad_u64_u32 v[30:31], s[12:13], v25, s61, v[26:27]
	global_load_dword v160, v[28:29], off
	global_load_dword v161, v[30:31], off
	v_mad_u64_u32 v[188:189], s[12:13], v23, s77, v[6:7]
	v_or_b32_e32 v23, s11, v2
	v_mad_u64_u32 v[190:191], s[12:13], v0, s77, v[6:7]
	v_or_b32_e32 v0, s10, v3
	v_add_u32_e32 v28, s0, v23
	v_add_u32_e32 v25, s2, v0
	v_mad_u64_u32 v[28:29], s[10:11], v28, s61, v[26:27]
	v_mad_u64_u32 v[30:31], s[10:11], v25, s61, v[26:27]
	global_load_dword v162, v[28:29], off
	global_load_dword v163, v[30:31], off
	v_mad_u64_u32 v[192:193], s[10:11], v23, s77, v[6:7]
	v_mad_u64_u32 v[196:197], s[10:11], v0, s77, v[6:7]
	s_waitcnt vmcnt(0)
	ds_write_b32 v116, v100
	ds_write_b32 v118, v101
	ds_write_b32 v120, v102
	ds_write_b32 v122, v103
	ds_write_b32 v124, v104
	ds_write_b32 v126, v105
	ds_write_b32 v128, v106
	ds_write_b32 v130, v107
	ds_write_b32 v132, v108
	ds_write_b32 v134, v109
	ds_write_b32 v136, v110
	ds_write_b32 v138, v111
	ds_write_b32 v140, v112
	ds_write_b32 v142, v113
	ds_write_b32 v144, v114
	ds_write_b32 v146, v115
	ds_write_b32 v164, v148
	ds_write_b32 v166, v149
	ds_write_b32 v168, v150
	ds_write_b32 v170, v151
	ds_write_b32 v172, v152
	ds_write_b32 v174, v153
	ds_write_b32 v176, v154
	ds_write_b32 v178, v155
	ds_write_b32 v180, v156
	ds_write_b32 v182, v157
	ds_write_b32 v184, v158
	ds_write_b32 v186, v159
	ds_write_b32 v188, v160
	ds_write_b32 v190, v161
	ds_write_b32 v192, v162
	ds_write_b32 v196, v163
	s_cbranch_scc1 .LBB0_705
	s_mulk_i32 s1, 0x6000
	s_add_u32 s1, s50, s1
	s_addc_u32 s2, s51, 0
	s_lshl_b32 s0, s0, 1
	s_add_u32 s0, s1, s0
	s_addc_u32 s1, s2, 0
	v_mov_b32_e32 v0, v51
	v_mov_b32_e32 v26, v50
	v_mov_b32_e32 v28, v49
	v_mov_b32_e32 v30, v48

.LBB0_710:
	s_lshl_b32 s11, s6, 1
	s_lshl_b32 s10, s2, 1
	v_or_b32_e32 v25, s11, v2
	v_or_b32_e32 v23, s10, v3
	v_add_u32_e32 v0, s1, v25
	v_add_u32_e32 v28, s3, v23
	v_mov_b32_e32 v29, v1
	v_lshlrev_b64 v[30:31], 14, v[0:1]
	v_lshlrev_b64 v[28:29], 14, v[28:29]
	v_lshl_add_u64 v[30:31], v[26:27], 0, v[30:31]
	v_lshl_add_u64 v[28:29], v[26:27], 0, v[28:29]
	global_load_dword v100, v[30:31], off
	global_load_dword v101, v[28:29], off
	v_mad_u64_u32 v[116:117], s[12:13], v25, s77, v[6:7]
	v_mad_u64_u32 v[118:119], s[12:13], v23, s77, v[6:7]
	s_add_i32 s13, s11, 4
	s_add_i32 s12, s10, 4
	v_or_b32_e32 v25, s13, v2
	v_or_b32_e32 v23, s12, v3
	v_mov_b32_e32 v29, v1
	s_add_i32 s6, s6, 16
	s_add_i32 s2, s2, 16
	s_add_i32 s7, s7, -16
	v_add_u32_e32 v0, s1, v25
	v_add_u32_e32 v28, s3, v23
	v_lshlrev_b64 v[30:31], 14, v[0:1]
	v_lshlrev_b64 v[28:29], 14, v[28:29]
	v_lshl_add_u64 v[30:31], v[26:27], 0, v[30:31]
	v_lshl_add_u64 v[28:29], v[26:27], 0, v[28:29]
	global_load_dword v102, v[30:31], off
	global_load_dword v103, v[28:29], off
	v_mad_u64_u32 v[120:121], s[12:13], v25, s77, v[6:7]
	v_mad_u64_u32 v[122:123], s[12:13], v23, s77, v[6:7]
	s_add_i32 s13, s11, 8
	s_add_i32 s12, s10, 8
	v_or_b32_e32 v25, s13, v2
	v_or_b32_e32 v23, s12, v3
	v_mov_b32_e32 v29, v1
	v_add_u32_e32 v0, s1, v25
	v_add_u32_e32 v28, s3, v23
	v_lshlrev_b64 v[30:31], 14, v[0:1]
	v_lshlrev_b64 v[28:29], 14, v[28:29]
	v_lshl_add_u64 v[30:31], v[26:27], 0, v[30:31]
	v_lshl_add_u64 v[28:29], v[26:27], 0, v[28:29]
	global_load_dword v104, v[30:31], off
	global_load_dword v105, v[28:29], off
	v_mad_u64_u32 v[124:125], s[12:13], v25, s77, v[6:7]
	v_mad_u64_u32 v[126:127], s[12:13], v23, s77, v[6:7]
	s_add_i32 s13, s11, 12
	s_add_i32 s12, s10, 12
	v_or_b32_e32 v25, s13, v2
	v_or_b32_e32 v23, s12, v3
	v_mov_b32_e32 v29, v1
	v_add_u32_e32 v0, s1, v25
	v_add_u32_e32 v28, s3, v23
	v_lshlrev_b64 v[30:31], 14, v[0:1]
	v_lshlrev_b64 v[28:29], 14, v[28:29]
	v_lshl_add_u64 v[30:31], v[26:27], 0, v[30:31]
	v_lshl_add_u64 v[28:29], v[26:27], 0, v[28:29]
	global_load_dword v106, v[30:31], off
	global_load_dword v107, v[28:29], off
	v_mad_u64_u32 v[128:129], s[12:13], v25, s77, v[6:7]
	v_mad_u64_u32 v[130:131], s[12:13], v23, s77, v[6:7]
	s_add_i32 s13, s11, 16
	s_add_i32 s12, s10, 16
	v_or_b32_e32 v25, s13, v2
	v_or_b32_e32 v23, s12, v3
	v_mov_b32_e32 v29, v1
	v_add_u32_e32 v0, s1, v25
	v_add_u32_e32 v28, s3, v23
	v_lshlrev_b64 v[30:31], 14, v[0:1]
	v_lshlrev_b64 v[28:29], 14, v[28:29]
	v_lshl_add_u64 v[30:31], v[26:27], 0, v[30:31]
	v_lshl_add_u64 v[28:29], v[26:27], 0, v[28:29]
	global_load_dword v108, v[30:31], off
	global_load_dword v109, v[28:29], off
	v_mad_u64_u32 v[132:133], s[12:13], v25, s77, v[6:7]
	v_mad_u64_u32 v[134:135], s[12:13], v23, s77, v[6:7]
	s_add_i32 s13, s11, 20
	s_add_i32 s12, s10, 20
	v_or_b32_e32 v25, s13, v2
	v_or_b32_e32 v23, s12, v3
	v_mov_b32_e32 v29, v1
	v_add_u32_e32 v0, s1, v25
	v_add_u32_e32 v28, s3, v23
	v_lshlrev_b64 v[30:31], 14, v[0:1]
	v_lshlrev_b64 v[28:29], 14, v[28:29]
	v_lshl_add_u64 v[30:31], v[26:27], 0, v[30:31]
	v_lshl_add_u64 v[28:29], v[26:27], 0, v[28:29]
	global_load_dword v110, v[30:31], off
	global_load_dword v111, v[28:29], off
	v_mad_u64_u32 v[136:137], s[12:13], v25, s77, v[6:7]
	v_mad_u64_u32 v[138:139], s[12:13], v23, s77, v[6:7]
	s_add_i32 s13, s11, 24
	s_add_i32 s12, s10, 24
	v_or_b32_e32 v25, s13, v2
	v_or_b32_e32 v23, s12, v3
	v_mov_b32_e32 v29, v1
	s_add_i32 s11, s11, 28
	s_add_i32 s10, s10, 28
	s_cmp_lg_u32 s7, 0
	v_add_u32_e32 v0, s1, v25
	v_add_u32_e32 v28, s3, v23
	v_lshlrev_b64 v[30:31], 14, v[0:1]
	v_lshlrev_b64 v[28:29], 14, v[28:29]
	v_lshl_add_u64 v[30:31], v[26:27], 0, v[30:31]
	v_lshl_add_u64 v[28:29], v[26:27], 0, v[28:29]
	global_load_dword v112, v[30:31], off
	global_load_dword v113, v[28:29], off
	v_mad_u64_u32 v[140:141], s[12:13], v25, s77, v[6:7]
	v_or_b32_e32 v25, s11, v2
	v_mad_u64_u32 v[142:143], s[12:13], v23, s77, v[6:7]
	v_or_b32_e32 v23, s10, v3
	v_mov_b32_e32 v29, v1
	v_add_u32_e32 v0, s1, v25
	v_add_u32_e32 v28, s3, v23
	v_lshlrev_b64 v[30:31], 14, v[0:1]
	v_lshlrev_b64 v[28:29], 14, v[28:29]
	v_lshl_add_u64 v[30:31], v[26:27], 0, v[30:31]
	v_lshl_add_u64 v[28:29], v[26:27], 0, v[28:29]
	global_load_dword v114, v[30:31], off
	global_load_dword v115, v[28:29], off
	v_mad_u64_u32 v[144:145], s[10:11], v25, s77, v[6:7]
	v_mad_u64_u32 v[146:147], s[10:11], v23, s77, v[6:7]
	s_lshl_b32 s11, s6, 1
	s_lshl_b32 s10, s2, 1
	v_or_b32_e32 v25, s11, v2
	v_or_b32_e32 v23, s10, v3
	v_add_u32_e32 v0, s1, v25
	v_add_u32_e32 v28, s3, v23
	v_mov_b32_e32 v29, v1
	v_lshlrev_b64 v[30:31], 14, v[0:1]
	v_lshlrev_b64 v[28:29], 14, v[28:29]
	v_lshl_add_u64 v[30:31], v[26:27], 0, v[30:31]
	v_lshl_add_u64 v[28:29], v[26:27], 0, v[28:29]
	global_load_dword v148, v[30:31], off
	global_load_dword v149, v[28:29], off
	v_mad_u64_u32 v[164:165], s[12:13], v25, s77, v[6:7]
	v_mad_u64_u32 v[166:167], s[12:13], v23, s77, v[6:7]
	s_add_i32 s13, s11, 4
	s_add_i32 s12, s10, 4
	v_or_b32_e32 v25, s13, v2
	v_or_b32_e32 v23, s12, v3
	v_mov_b32_e32 v29, v1
	s_add_i32 s6, s6, 16
	s_add_i32 s2, s2, 16
	s_add_i32 s7, s7, -16
	v_add_u32_e32 v0, s1, v25
	v_add_u32_e32 v28, s3, v23
	v_lshlrev_b64 v[30:31], 14, v[0:1]
	v_lshlrev_b64 v[28:29], 14, v[28:29]
	v_lshl_add_u64 v[30:31], v[26:27], 0, v[30:31]
	v_lshl_add_u64 v[28:29], v[26:27], 0, v[28:29]
	global_load_dword v150, v[30:31], off
	global_load_dword v151, v[28:29], off
	v_mad_u64_u32 v[168:169], s[12:13], v25, s77, v[6:7]
	v_mad_u64_u32 v[170:171], s[12:13], v23, s77, v[6:7]
	s_add_i32 s13, s11, 8
	s_add_i32 s12, s10, 8
	v_or_b32_e32 v25, s13, v2
	v_or_b32_e32 v23, s12, v3
	v_mov_b32_e32 v29, v1
	v_add_u32_e32 v0, s1, v25
	v_add_u32_e32 v28, s3, v23
	v_lshlrev_b64 v[30:31], 14, v[0:1]
	v_lshlrev_b64 v[28:29], 14, v[28:29]
	v_lshl_add_u64 v[30:31], v[26:27], 0, v[30:31]
	v_lshl_add_u64 v[28:29], v[26:27], 0, v[28:29]
	global_load_dword v152, v[30:31], off
	global_load_dword v153, v[28:29], off
	v_mad_u64_u32 v[172:173], s[12:13], v25, s77, v[6:7]
	v_mad_u64_u32 v[174:175], s[12:13], v23, s77, v[6:7]
	s_add_i32 s13, s11, 12
	s_add_i32 s12, s10, 12
	v_or_b32_e32 v25, s13, v2
	v_or_b32_e32 v23, s12, v3
	v_mov_b32_e32 v29, v1
	v_add_u32_e32 v0, s1, v25
	v_add_u32_e32 v28, s3, v23
	v_lshlrev_b64 v[30:31], 14, v[0:1]
	v_lshlrev_b64 v[28:29], 14, v[28:29]
	v_lshl_add_u64 v[30:31], v[26:27], 0, v[30:31]
	v_lshl_add_u64 v[28:29], v[26:27], 0, v[28:29]
	global_load_dword v154, v[30:31], off
	global_load_dword v155, v[28:29], off
	v_mad_u64_u32 v[176:177], s[12:13], v25, s77, v[6:7]
	v_mad_u64_u32 v[178:179], s[12:13], v23, s77, v[6:7]
	s_add_i32 s13, s11, 16
	s_add_i32 s12, s10, 16
	v_or_b32_e32 v25, s13, v2
	v_or_b32_e32 v23, s12, v3
	v_mov_b32_e32 v29, v1
	v_add_u32_e32 v0, s1, v25
	v_add_u32_e32 v28, s3, v23
	v_lshlrev_b64 v[30:31], 14, v[0:1]
	v_lshlrev_b64 v[28:29], 14, v[28:29]
	v_lshl_add_u64 v[30:31], v[26:27], 0, v[30:31]
	v_lshl_add_u64 v[28:29], v[26:27], 0, v[28:29]
	global_load_dword v156, v[30:31], off
	global_load_dword v157, v[28:29], off
	v_mad_u64_u32 v[180:181], s[12:13], v25, s77, v[6:7]
	v_mad_u64_u32 v[182:183], s[12:13], v23, s77, v[6:7]
	s_add_i32 s13, s11, 20
	s_add_i32 s12, s10, 20
	v_or_b32_e32 v25, s13, v2
	v_or_b32_e32 v23, s12, v3
	v_mov_b32_e32 v29, v1
	v_add_u32_e32 v0, s1, v25
	v_add_u32_e32 v28, s3, v23
	v_lshlrev_b64 v[30:31], 14, v[0:1]
	v_lshlrev_b64 v[28:29], 14, v[28:29]
	v_lshl_add_u64 v[30:31], v[26:27], 0, v[30:31]
	v_lshl_add_u64 v[28:29], v[26:27], 0, v[28:29]
	global_load_dword v158, v[30:31], off
	global_load_dword v159, v[28:29], off
	v_mad_u64_u32 v[184:185], s[12:13], v25, s77, v[6:7]
	v_mad_u64_u32 v[186:187], s[12:13], v23, s77, v[6:7]
	s_add_i32 s13, s11, 24
	s_add_i32 s12, s10, 24
	v_or_b32_e32 v25, s13, v2
	v_or_b32_e32 v23, s12, v3
	v_mov_b32_e32 v29, v1
	s_add_i32 s11, s11, 28
	s_add_i32 s10, s10, 28
	s_cmp_lg_u32 s7, 0
	v_add_u32_e32 v0, s1, v25
	v_add_u32_e32 v28, s3, v23
	v_lshlrev_b64 v[30:31], 14, v[0:1]
	v_lshlrev_b64 v[28:29], 14, v[28:29]
	v_lshl_add_u64 v[30:31], v[26:27], 0, v[30:31]
	v_lshl_add_u64 v[28:29], v[26:27], 0, v[28:29]
	global_load_dword v160, v[30:31], off
	global_load_dword v161, v[28:29], off
	v_mad_u64_u32 v[188:189], s[12:13], v25, s77, v[6:7]
	v_or_b32_e32 v25, s11, v2
	v_mad_u64_u32 v[190:191], s[12:13], v23, s77, v[6:7]
	v_or_b32_e32 v23, s10, v3
	v_mov_b32_e32 v29, v1
	v_add_u32_e32 v0, s1, v25
	v_add_u32_e32 v28, s3, v23
	v_lshlrev_b64 v[30:31], 14, v[0:1]
	v_lshlrev_b64 v[28:29], 14, v[28:29]
	v_lshl_add_u64 v[30:31], v[26:27], 0, v[30:31]
	v_lshl_add_u64 v[28:29], v[26:27], 0, v[28:29]
	global_load_dword v162, v[30:31], off
	global_load_dword v163, v[28:29], off
	v_mad_u64_u32 v[192:193], s[10:11], v25, s77, v[6:7]
	v_mad_u64_u32 v[196:197], s[10:11], v23, s77, v[6:7]
	s_waitcnt vmcnt(0)
	ds_write_b32 v116, v100
	ds_write_b32 v118, v101
	ds_write_b32 v120, v102
	ds_write_b32 v122, v103
	ds_write_b32 v124, v104
	ds_write_b32 v126, v105
	ds_write_b32 v128, v106
	ds_write_b32 v130, v107
	ds_write_b32 v132, v108
	ds_write_b32 v134, v109
	ds_write_b32 v136, v110
	ds_write_b32 v138, v111
	ds_write_b32 v140, v112
	ds_write_b32 v142, v113
	ds_write_b32 v144, v114
	ds_write_b32 v146, v115
	ds_write_b32 v164, v148
	ds_write_b32 v166, v149
	ds_write_b32 v168, v150
	ds_write_b32 v170, v151
	ds_write_b32 v172, v152
	ds_write_b32 v174, v153
	ds_write_b32 v176, v154
	ds_write_b32 v178, v155
	ds_write_b32 v180, v156
	ds_write_b32 v182, v157
	ds_write_b32 v184, v158
	ds_write_b32 v186, v159
	ds_write_b32 v188, v160
	ds_write_b32 v190, v161
	ds_write_b32 v192, v162
	ds_write_b32 v196, v163
	s_cbranch_scc1 .LBB0_710
	v_readlane_b32 s12, v249, 0
	s_lshl_b32 s0, s0, 11
	v_readlane_b32 s18, v249, 6
	v_readlane_b32 s19, v249, 7
	s_add_u32 s0, s18, s0
	s_addc_u32 s2, s19, 0
	s_lshl_b32 s1, s1, 1
	s_add_u32 s0, s0, s1
	s_addc_u32 s1, s2, 0
	s_add_u32 s0, s0, 0x680000
	s_addc_u32 s1, s1, 0
	v_mov_b32_e32 v0, v39
	v_mov_b32_e32 v26, v38
	v_mov_b32_e32 v28, v37
	v_mov_b32_e32 v30, v36
	v_readlane_b32 s13, v249, 1
	v_readlane_b32 s14, v249, 2
	v_readlane_b32 s15, v249, 3
	v_readlane_b32 s16, v249, 4
	v_readlane_b32 s17, v249, 5

.LBB0_715:
	s_lshl_b32 s12, s3, 1
	s_lshl_b32 s11, s2, 1
	v_or_b32_e32 v23, s12, v2
	v_or_b32_e32 v0, s11, v3
	v_add_u32_e32 v28, s0, v23
	v_add_u32_e32 v25, s1, v0
	v_mad_i64_i32 v[28:29], s[14:15], v28, s62, v[26:27]
	v_mad_i64_i32 v[30:31], s[14:15], v25, s62, v[26:27]
	global_load_dword v100, v[28:29], off
	global_load_dword v101, v[30:31], off
	v_mad_u64_u32 v[116:117], s[14:15], v23, s77, v[6:7]
	v_mad_u64_u32 v[118:119], s[14:15], v0, s77, v[6:7]
	s_add_i32 s14, s12, 4
	s_add_i32 s13, s11, 4
	v_or_b32_e32 v23, s14, v2
	v_or_b32_e32 v0, s13, v3
	s_add_i32 s13, s11, 8
	s_add_i32 s3, s3, 16
	s_add_i32 s2, s2, 16
	s_add_i32 s10, s10, -16
	v_add_u32_e32 v28, s0, v23
	v_add_u32_e32 v25, s1, v0
	v_mad_i64_i32 v[28:29], s[14:15], v28, s62, v[26:27]
	v_mad_i64_i32 v[30:31], s[14:15], v25, s62, v[26:27]
	global_load_dword v102, v[28:29], off
	global_load_dword v103, v[30:31], off
	v_mad_u64_u32 v[120:121], s[14:15], v23, s77, v[6:7]
	v_mad_u64_u32 v[122:123], s[14:15], v0, s77, v[6:7]
	s_add_i32 s14, s12, 8
	s_nop 0
	v_or_b32_e32 v23, s14, v2
	v_or_b32_e32 v0, s13, v3
	s_add_i32 s13, s11, 12
	v_add_u32_e32 v28, s0, v23
	v_add_u32_e32 v25, s1, v0
	v_mad_i64_i32 v[28:29], s[14:15], v28, s62, v[26:27]
	v_mad_i64_i32 v[30:31], s[14:15], v25, s62, v[26:27]
	global_load_dword v104, v[28:29], off
	global_load_dword v105, v[30:31], off
	v_mad_u64_u32 v[124:125], s[14:15], v23, s77, v[6:7]
	v_mad_u64_u32 v[126:127], s[14:15], v0, s77, v[6:7]
	s_add_i32 s14, s12, 12
	s_nop 0
	v_or_b32_e32 v23, s14, v2
	v_or_b32_e32 v0, s13, v3
	s_add_i32 s13, s11, 16
	v_add_u32_e32 v28, s0, v23
	v_add_u32_e32 v25, s1, v0
	v_mad_i64_i32 v[28:29], s[14:15], v28, s62, v[26:27]
	v_mad_i64_i32 v[30:31], s[14:15], v25, s62, v[26:27]
	global_load_dword v106, v[28:29], off
	global_load_dword v107, v[30:31], off
	v_mad_u64_u32 v[128:129], s[14:15], v23, s77, v[6:7]
	v_mad_u64_u32 v[130:131], s[14:15], v0, s77, v[6:7]
	s_add_i32 s14, s12, 16
	s_nop 0
	v_or_b32_e32 v23, s14, v2
	v_or_b32_e32 v0, s13, v3
	s_add_i32 s13, s11, 20
	v_add_u32_e32 v28, s0, v23
	v_add_u32_e32 v25, s1, v0
	v_mad_i64_i32 v[28:29], s[14:15], v28, s62, v[26:27]
	v_mad_i64_i32 v[30:31], s[14:15], v25, s62, v[26:27]
	global_load_dword v108, v[28:29], off
	global_load_dword v109, v[30:31], off
	v_mad_u64_u32 v[132:133], s[14:15], v23, s77, v[6:7]
	v_mad_u64_u32 v[134:135], s[14:15], v0, s77, v[6:7]
	s_add_i32 s14, s12, 20
	s_nop 0
	v_or_b32_e32 v23, s14, v2
	v_or_b32_e32 v0, s13, v3
	s_add_i32 s13, s11, 24
	s_add_i32 s11, s11, 28
	v_add_u32_e32 v28, s0, v23
	v_add_u32_e32 v25, s1, v0
	v_mad_i64_i32 v[28:29], s[14:15], v28, s62, v[26:27]
	v_mad_i64_i32 v[30:31], s[14:15], v25, s62, v[26:27]
	global_load_dword v110, v[28:29], off
	global_load_dword v111, v[30:31], off
	v_mad_u64_u32 v[136:137], s[14:15], v23, s77, v[6:7]
	v_mad_u64_u32 v[138:139], s[14:15], v0, s77, v[6:7]
	s_add_i32 s14, s12, 24
	s_nop 0
	v_or_b32_e32 v23, s14, v2
	v_or_b32_e32 v0, s13, v3
	s_add_i32 s12, s12, 28
	s_cmp_lg_u32 s10, 0
	v_add_u32_e32 v28, s0, v23
	v_add_u32_e32 v25, s1, v0
	v_mad_i64_i32 v[28:29], s[14:15], v28, s62, v[26:27]
	v_mad_i64_i32 v[30:31], s[14:15], v25, s62, v[26:27]
	global_load_dword v112, v[28:29], off
	global_load_dword v113, v[30:31], off
	v_mad_u64_u32 v[140:141], s[14:15], v23, s77, v[6:7]
	v_or_b32_e32 v23, s12, v2
	v_mad_u64_u32 v[142:143], s[14:15], v0, s77, v[6:7]
	v_or_b32_e32 v0, s11, v3
	v_add_u32_e32 v28, s0, v23
	v_add_u32_e32 v25, s1, v0
	v_mad_i64_i32 v[28:29], s[12:13], v28, s62, v[26:27]
	v_mad_i64_i32 v[30:31], s[12:13], v25, s62, v[26:27]
	global_load_dword v114, v[28:29], off
	global_load_dword v115, v[30:31], off
	v_mad_u64_u32 v[144:145], s[12:13], v23, s77, v[6:7]
	v_mad_u64_u32 v[146:147], s[12:13], v0, s77, v[6:7]
	s_lshl_b32 s12, s3, 1
	s_lshl_b32 s11, s2, 1
	v_or_b32_e32 v23, s12, v2
	v_or_b32_e32 v0, s11, v3
	v_add_u32_e32 v28, s0, v23
	v_add_u32_e32 v25, s1, v0
	v_mad_i64_i32 v[28:29], s[14:15], v28, s62, v[26:27]
	v_mad_i64_i32 v[30:31], s[14:15], v25, s62, v[26:27]
	global_load_dword v148, v[28:29], off
	global_load_dword v149, v[30:31], off
	v_mad_u64_u32 v[164:165], s[14:15], v23, s77, v[6:7]
	v_mad_u64_u32 v[166:167], s[14:15], v0, s77, v[6:7]
	s_add_i32 s14, s12, 4
	s_add_i32 s13, s11, 4
	v_or_b32_e32 v23, s14, v2
	v_or_b32_e32 v0, s13, v3
	s_add_i32 s13, s11, 8
	s_add_i32 s3, s3, 16
	s_add_i32 s2, s2, 16
	s_add_i32 s10, s10, -16
	v_add_u32_e32 v28, s0, v23
	v_add_u32_e32 v25, s1, v0
	v_mad_i64_i32 v[28:29], s[14:15], v28, s62, v[26:27]
	v_mad_i64_i32 v[30:31], s[14:15], v25, s62, v[26:27]
	global_load_dword v150, v[28:29], off
	global_load_dword v151, v[30:31], off
	v_mad_u64_u32 v[168:169], s[14:15], v23, s77, v[6:7]
	v_mad_u64_u32 v[170:171], s[14:15], v0, s77, v[6:7]
	s_add_i32 s14, s12, 8
	s_nop 0
	v_or_b32_e32 v23, s14, v2
	v_or_b32_e32 v0, s13, v3
	s_add_i32 s13, s11, 12
	v_add_u32_e32 v28, s0, v23
	v_add_u32_e32 v25, s1, v0
	v_mad_i64_i32 v[28:29], s[14:15], v28, s62, v[26:27]
	v_mad_i64_i32 v[30:31], s[14:15], v25, s62, v[26:27]
	global_load_dword v152, v[28:29], off
	global_load_dword v153, v[30:31], off
	v_mad_u64_u32 v[172:173], s[14:15], v23, s77, v[6:7]
	v_mad_u64_u32 v[174:175], s[14:15], v0, s77, v[6:7]
	s_add_i32 s14, s12, 12
	s_nop 0
	v_or_b32_e32 v23, s14, v2
	v_or_b32_e32 v0, s13, v3
	s_add_i32 s13, s11, 16
	v_add_u32_e32 v28, s0, v23
	v_add_u32_e32 v25, s1, v0
	v_mad_i64_i32 v[28:29], s[14:15], v28, s62, v[26:27]
	v_mad_i64_i32 v[30:31], s[14:15], v25, s62, v[26:27]
	global_load_dword v154, v[28:29], off
	global_load_dword v155, v[30:31], off
	v_mad_u64_u32 v[176:177], s[14:15], v23, s77, v[6:7]
	v_mad_u64_u32 v[178:179], s[14:15], v0, s77, v[6:7]
	s_add_i32 s14, s12, 16
	s_nop 0
	v_or_b32_e32 v23, s14, v2
	v_or_b32_e32 v0, s13, v3
	s_add_i32 s13, s11, 20
	v_add_u32_e32 v28, s0, v23
	v_add_u32_e32 v25, s1, v0
	v_mad_i64_i32 v[28:29], s[14:15], v28, s62, v[26:27]
	v_mad_i64_i32 v[30:31], s[14:15], v25, s62, v[26:27]
	global_load_dword v156, v[28:29], off
	global_load_dword v157, v[30:31], off
	v_mad_u64_u32 v[180:181], s[14:15], v23, s77, v[6:7]
	v_mad_u64_u32 v[182:183], s[14:15], v0, s77, v[6:7]
	s_add_i32 s14, s12, 20
	s_nop 0
	v_or_b32_e32 v23, s14, v2
	v_or_b32_e32 v0, s13, v3
	s_add_i32 s13, s11, 24
	s_add_i32 s11, s11, 28
	v_add_u32_e32 v28, s0, v23
	v_add_u32_e32 v25, s1, v0
	v_mad_i64_i32 v[28:29], s[14:15], v28, s62, v[26:27]
	v_mad_i64_i32 v[30:31], s[14:15], v25, s62, v[26:27]
	global_load_dword v158, v[28:29], off
	global_load_dword v159, v[30:31], off
	v_mad_u64_u32 v[184:185], s[14:15], v23, s77, v[6:7]
	v_mad_u64_u32 v[186:187], s[14:15], v0, s77, v[6:7]
	s_add_i32 s14, s12, 24
	s_nop 0
	v_or_b32_e32 v23, s14, v2
	v_or_b32_e32 v0, s13, v3
	s_add_i32 s12, s12, 28
	s_cmp_lg_u32 s10, 0
	v_add_u32_e32 v28, s0, v23
	v_add_u32_e32 v25, s1, v0
	v_mad_i64_i32 v[28:29], s[14:15], v28, s62, v[26:27]
	v_mad_i64_i32 v[30:31], s[14:15], v25, s62, v[26:27]
	global_load_dword v160, v[28:29], off
	global_load_dword v161, v[30:31], off
	v_mad_u64_u32 v[188:189], s[14:15], v23, s77, v[6:7]
	v_or_b32_e32 v23, s12, v2
	v_mad_u64_u32 v[190:191], s[14:15], v0, s77, v[6:7]
	v_or_b32_e32 v0, s11, v3
	v_add_u32_e32 v28, s0, v23
	v_add_u32_e32 v25, s1, v0
	v_mad_i64_i32 v[28:29], s[12:13], v28, s62, v[26:27]
	v_mad_i64_i32 v[30:31], s[12:13], v25, s62, v[26:27]
	global_load_dword v162, v[28:29], off
	global_load_dword v163, v[30:31], off
	v_mad_u64_u32 v[192:193], s[12:13], v23, s77, v[6:7]
	v_mad_u64_u32 v[196:197], s[12:13], v0, s77, v[6:7]
	s_waitcnt vmcnt(0)
	ds_write_b32 v116, v100
	ds_write_b32 v118, v101
	ds_write_b32 v120, v102
	ds_write_b32 v122, v103
	ds_write_b32 v124, v104
	ds_write_b32 v126, v105
	ds_write_b32 v128, v106
	ds_write_b32 v130, v107
	ds_write_b32 v132, v108
	ds_write_b32 v134, v109
	ds_write_b32 v136, v110
	ds_write_b32 v138, v111
	ds_write_b32 v140, v112
	ds_write_b32 v142, v113
	ds_write_b32 v144, v114
	ds_write_b32 v146, v115
	ds_write_b32 v164, v148
	ds_write_b32 v166, v149
	ds_write_b32 v168, v150
	ds_write_b32 v170, v151
	ds_write_b32 v172, v152
	ds_write_b32 v174, v153
	ds_write_b32 v176, v154
	ds_write_b32 v178, v155
	ds_write_b32 v180, v156
	ds_write_b32 v182, v157
	ds_write_b32 v184, v158
	ds_write_b32 v186, v159
	ds_write_b32 v188, v160
	ds_write_b32 v190, v161
	ds_write_b32 v192, v162
	ds_write_b32 v196, v163
	s_cbranch_scc1 .LBB0_715
	v_readlane_b32 s12, v249, 0
	s_lshl_b64 s[2:3], s[6:7], 11
	v_readlane_b32 s18, v249, 6
	v_readlane_b32 s19, v249, 7
	s_add_u32 s2, s18, s2
	s_addc_u32 s3, s19, s3
	s_ashr_i32 s1, s0, 31
	s_lshl_b64 s[0:1], s[0:1], 1
	s_add_u32 s0, s2, s0
	s_addc_u32 s1, s3, s1
	v_mov_b32_e32 v0, v39
	v_mov_b32_e32 v26, v38
	v_mov_b32_e32 v28, v37
	v_mov_b32_e32 v30, v36
	v_readlane_b32 s13, v249, 1
	v_readlane_b32 s14, v249, 2
	v_readlane_b32 s15, v249, 3
	v_readlane_b32 s16, v249, 4
	v_readlane_b32 s17, v249, 5
	s_branch .LBB0_658

.LBB0_788:
	s_lshl_b32 s8, s5, 1
	s_lshl_b32 s7, s2, 1
	v_or_b32_e32 v23, s8, v2
	v_or_b32_e32 v0, s7, v3
	v_add_u32_e32 v30, s0, v23
	v_add_u32_e32 v28, s3, v0
	v_ashrrev_i32_e32 v31, 31, v30
	v_ashrrev_i32_e32 v29, 31, v28
	v_lshlrev_b64 v[30:31], 12, v[30:31]
	v_lshlrev_b64 v[28:29], 12, v[28:29]
	v_lshl_add_u64 v[30:31], v[26:27], 0, v[30:31]
	v_lshl_add_u64 v[28:29], v[26:27], 0, v[28:29]
	global_load_dword v100, v[30:31], off
	global_load_dword v101, v[28:29], off
	v_mad_u64_u32 v[116:117], s[10:11], v23, s77, v[6:7]
	v_mad_u64_u32 v[118:119], s[10:11], v0, s77, v[6:7]
	s_add_i32 s10, s8, 4
	s_add_i32 s9, s7, 4
	v_or_b32_e32 v23, s10, v2
	v_or_b32_e32 v0, s9, v3
	s_add_i32 s9, s7, 8
	s_add_i32 s5, s5, 16
	s_add_i32 s2, s2, 16
	s_add_i32 s6, s6, -16
	s_waitcnt vmcnt(1)
	v_add_u32_e32 v30, s0, v23
	v_add_u32_e32 v28, s3, v0
	v_ashrrev_i32_e32 v31, 31, v30
	v_ashrrev_i32_e32 v29, 31, v28
	v_lshlrev_b64 v[30:31], 12, v[30:31]
	v_lshlrev_b64 v[28:29], 12, v[28:29]
	v_lshl_add_u64 v[30:31], v[26:27], 0, v[30:31]
	v_lshl_add_u64 v[28:29], v[26:27], 0, v[28:29]
	global_load_dword v102, v[30:31], off
	global_load_dword v103, v[28:29], off
	v_mad_u64_u32 v[120:121], s[10:11], v23, s77, v[6:7]
	v_mad_u64_u32 v[122:123], s[10:11], v0, s77, v[6:7]
	s_add_i32 s10, s8, 8
	s_nop 0
	v_or_b32_e32 v23, s10, v2
	v_or_b32_e32 v0, s9, v3
	s_add_i32 s9, s7, 12
	s_waitcnt vmcnt(1)
	v_add_u32_e32 v30, s0, v23
	v_add_u32_e32 v28, s3, v0
	v_ashrrev_i32_e32 v31, 31, v30
	v_ashrrev_i32_e32 v29, 31, v28
	v_lshlrev_b64 v[30:31], 12, v[30:31]
	v_lshlrev_b64 v[28:29], 12, v[28:29]
	v_lshl_add_u64 v[30:31], v[26:27], 0, v[30:31]
	v_lshl_add_u64 v[28:29], v[26:27], 0, v[28:29]
	global_load_dword v104, v[30:31], off
	global_load_dword v105, v[28:29], off
	v_mad_u64_u32 v[124:125], s[10:11], v23, s77, v[6:7]
	v_mad_u64_u32 v[126:127], s[10:11], v0, s77, v[6:7]
	s_add_i32 s10, s8, 12
	s_nop 0
	v_or_b32_e32 v23, s10, v2
	v_or_b32_e32 v0, s9, v3
	s_add_i32 s9, s7, 16
	s_waitcnt vmcnt(1)
	v_add_u32_e32 v30, s0, v23
	v_add_u32_e32 v28, s3, v0
	v_ashrrev_i32_e32 v31, 31, v30
	v_ashrrev_i32_e32 v29, 31, v28
	v_lshlrev_b64 v[30:31], 12, v[30:31]
	v_lshlrev_b64 v[28:29], 12, v[28:29]
	v_lshl_add_u64 v[30:31], v[26:27], 0, v[30:31]
	v_lshl_add_u64 v[28:29], v[26:27], 0, v[28:29]
	global_load_dword v106, v[30:31], off
	global_load_dword v107, v[28:29], off
	v_mad_u64_u32 v[128:129], s[10:11], v23, s77, v[6:7]
	v_mad_u64_u32 v[130:131], s[10:11], v0, s77, v[6:7]
	s_add_i32 s10, s8, 16
	s_nop 0
	v_or_b32_e32 v23, s10, v2
	v_or_b32_e32 v0, s9, v3
	s_add_i32 s9, s7, 20
	s_waitcnt vmcnt(1)
	v_add_u32_e32 v30, s0, v23
	v_add_u32_e32 v28, s3, v0
	v_ashrrev_i32_e32 v31, 31, v30
	v_ashrrev_i32_e32 v29, 31, v28
	v_lshlrev_b64 v[30:31], 12, v[30:31]
	v_lshlrev_b64 v[28:29], 12, v[28:29]
	v_lshl_add_u64 v[30:31], v[26:27], 0, v[30:31]
	v_lshl_add_u64 v[28:29], v[26:27], 0, v[28:29]
	global_load_dword v108, v[30:31], off
	global_load_dword v109, v[28:29], off
	v_mad_u64_u32 v[132:133], s[10:11], v23, s77, v[6:7]
	v_mad_u64_u32 v[134:135], s[10:11], v0, s77, v[6:7]
	s_add_i32 s10, s8, 20
	s_nop 0
	v_or_b32_e32 v23, s10, v2
	v_or_b32_e32 v0, s9, v3
	s_add_i32 s9, s7, 24
	s_add_i32 s7, s7, 28
	s_waitcnt vmcnt(1)
	v_add_u32_e32 v30, s0, v23
	v_add_u32_e32 v28, s3, v0
	v_ashrrev_i32_e32 v31, 31, v30
	v_ashrrev_i32_e32 v29, 31, v28
	v_lshlrev_b64 v[30:31], 12, v[30:31]
	v_lshlrev_b64 v[28:29], 12, v[28:29]
	v_lshl_add_u64 v[30:31], v[26:27], 0, v[30:31]
	v_lshl_add_u64 v[28:29], v[26:27], 0, v[28:29]
	global_load_dword v110, v[30:31], off
	global_load_dword v111, v[28:29], off
	v_mad_u64_u32 v[136:137], s[10:11], v23, s77, v[6:7]
	v_mad_u64_u32 v[138:139], s[10:11], v0, s77, v[6:7]
	s_add_i32 s10, s8, 24
	s_nop 0
	v_or_b32_e32 v23, s10, v2
	v_or_b32_e32 v0, s9, v3
	s_add_i32 s8, s8, 28
	s_cmp_lg_u32 s6, 0
	s_waitcnt vmcnt(1)
	v_add_u32_e32 v30, s0, v23
	v_add_u32_e32 v28, s3, v0
	v_ashrrev_i32_e32 v31, 31, v30
	v_ashrrev_i32_e32 v29, 31, v28
	v_lshlrev_b64 v[30:31], 12, v[30:31]
	v_lshlrev_b64 v[28:29], 12, v[28:29]
	v_lshl_add_u64 v[30:31], v[26:27], 0, v[30:31]
	v_lshl_add_u64 v[28:29], v[26:27], 0, v[28:29]
	global_load_dword v112, v[30:31], off
	global_load_dword v113, v[28:29], off
	v_mad_u64_u32 v[140:141], s[10:11], v23, s77, v[6:7]
	v_mad_u64_u32 v[142:143], s[10:11], v0, s77, v[6:7]
	v_or_b32_e32 v23, s8, v2
	v_or_b32_e32 v0, s7, v3
	s_waitcnt vmcnt(1)
	v_add_u32_e32 v30, s0, v23
	v_add_u32_e32 v28, s3, v0
	v_ashrrev_i32_e32 v31, 31, v30
	v_ashrrev_i32_e32 v29, 31, v28
	v_lshlrev_b64 v[30:31], 12, v[30:31]
	v_lshlrev_b64 v[28:29], 12, v[28:29]
	v_lshl_add_u64 v[30:31], v[26:27], 0, v[30:31]
	v_lshl_add_u64 v[28:29], v[26:27], 0, v[28:29]
	global_load_dword v114, v[30:31], off
	global_load_dword v115, v[28:29], off
	v_mad_u64_u32 v[144:145], s[8:9], v23, s77, v[6:7]
	v_mad_u64_u32 v[146:147], s[8:9], v0, s77, v[6:7]
	s_waitcnt vmcnt(1)
	s_lshl_b32 s8, s5, 1
	s_lshl_b32 s7, s2, 1
	v_or_b32_e32 v23, s8, v2
	v_or_b32_e32 v0, s7, v3
	v_add_u32_e32 v30, s0, v23
	v_add_u32_e32 v28, s3, v0
	v_ashrrev_i32_e32 v31, 31, v30
	v_ashrrev_i32_e32 v29, 31, v28
	v_lshlrev_b64 v[30:31], 12, v[30:31]
	v_lshlrev_b64 v[28:29], 12, v[28:29]
	v_lshl_add_u64 v[30:31], v[26:27], 0, v[30:31]
	v_lshl_add_u64 v[28:29], v[26:27], 0, v[28:29]
	global_load_dword v148, v[30:31], off
	global_load_dword v149, v[28:29], off
	v_mad_u64_u32 v[164:165], s[10:11], v23, s77, v[6:7]
	v_mad_u64_u32 v[166:167], s[10:11], v0, s77, v[6:7]
	s_add_i32 s10, s8, 4
	s_add_i32 s9, s7, 4
	v_or_b32_e32 v23, s10, v2
	v_or_b32_e32 v0, s9, v3
	s_add_i32 s9, s7, 8
	s_add_i32 s5, s5, 16
	s_add_i32 s2, s2, 16
	s_add_i32 s6, s6, -16
	s_waitcnt vmcnt(1)
	v_add_u32_e32 v30, s0, v23
	v_add_u32_e32 v28, s3, v0
	v_ashrrev_i32_e32 v31, 31, v30
	v_ashrrev_i32_e32 v29, 31, v28
	v_lshlrev_b64 v[30:31], 12, v[30:31]
	v_lshlrev_b64 v[28:29], 12, v[28:29]
	v_lshl_add_u64 v[30:31], v[26:27], 0, v[30:31]
	v_lshl_add_u64 v[28:29], v[26:27], 0, v[28:29]
	global_load_dword v150, v[30:31], off
	global_load_dword v151, v[28:29], off
	v_mad_u64_u32 v[168:169], s[10:11], v23, s77, v[6:7]
	v_mad_u64_u32 v[170:171], s[10:11], v0, s77, v[6:7]
	s_add_i32 s10, s8, 8
	s_nop 0
	v_or_b32_e32 v23, s10, v2
	v_or_b32_e32 v0, s9, v3
	s_add_i32 s9, s7, 12
	s_waitcnt vmcnt(1)
	v_add_u32_e32 v30, s0, v23
	v_add_u32_e32 v28, s3, v0
	v_ashrrev_i32_e32 v31, 31, v30
	v_ashrrev_i32_e32 v29, 31, v28
	v_lshlrev_b64 v[30:31], 12, v[30:31]
	v_lshlrev_b64 v[28:29], 12, v[28:29]
	v_lshl_add_u64 v[30:31], v[26:27], 0, v[30:31]
	v_lshl_add_u64 v[28:29], v[26:27], 0, v[28:29]
	global_load_dword v152, v[30:31], off
	global_load_dword v153, v[28:29], off
	v_mad_u64_u32 v[172:173], s[10:11], v23, s77, v[6:7]
	v_mad_u64_u32 v[174:175], s[10:11], v0, s77, v[6:7]
	s_add_i32 s10, s8, 12
	s_nop 0
	v_or_b32_e32 v23, s10, v2
	v_or_b32_e32 v0, s9, v3
	s_add_i32 s9, s7, 16
	s_waitcnt vmcnt(1)
	v_add_u32_e32 v30, s0, v23
	v_add_u32_e32 v28, s3, v0
	v_ashrrev_i32_e32 v31, 31, v30
	v_ashrrev_i32_e32 v29, 31, v28
	v_lshlrev_b64 v[30:31], 12, v[30:31]
	v_lshlrev_b64 v[28:29], 12, v[28:29]
	v_lshl_add_u64 v[30:31], v[26:27], 0, v[30:31]
	v_lshl_add_u64 v[28:29], v[26:27], 0, v[28:29]
	global_load_dword v154, v[30:31], off
	global_load_dword v155, v[28:29], off
	v_mad_u64_u32 v[176:177], s[10:11], v23, s77, v[6:7]
	v_mad_u64_u32 v[178:179], s[10:11], v0, s77, v[6:7]
	s_add_i32 s10, s8, 16
	s_nop 0
	v_or_b32_e32 v23, s10, v2
	v_or_b32_e32 v0, s9, v3
	s_add_i32 s9, s7, 20
	s_waitcnt vmcnt(1)
	v_add_u32_e32 v30, s0, v23
	v_add_u32_e32 v28, s3, v0
	v_ashrrev_i32_e32 v31, 31, v30
	v_ashrrev_i32_e32 v29, 31, v28
	v_lshlrev_b64 v[30:31], 12, v[30:31]
	v_lshlrev_b64 v[28:29], 12, v[28:29]
	v_lshl_add_u64 v[30:31], v[26:27], 0, v[30:31]
	v_lshl_add_u64 v[28:29], v[26:27], 0, v[28:29]
	global_load_dword v156, v[30:31], off
	global_load_dword v157, v[28:29], off
	v_mad_u64_u32 v[180:181], s[10:11], v23, s77, v[6:7]
	v_mad_u64_u32 v[182:183], s[10:11], v0, s77, v[6:7]
	s_add_i32 s10, s8, 20
	s_nop 0
	v_or_b32_e32 v23, s10, v2
	v_or_b32_e32 v0, s9, v3
	s_add_i32 s9, s7, 24
	s_add_i32 s7, s7, 28
	s_waitcnt vmcnt(1)
	v_add_u32_e32 v30, s0, v23
	v_add_u32_e32 v28, s3, v0
	v_ashrrev_i32_e32 v31, 31, v30
	v_ashrrev_i32_e32 v29, 31, v28
	v_lshlrev_b64 v[30:31], 12, v[30:31]
	v_lshlrev_b64 v[28:29], 12, v[28:29]
	v_lshl_add_u64 v[30:31], v[26:27], 0, v[30:31]
	v_lshl_add_u64 v[28:29], v[26:27], 0, v[28:29]
	global_load_dword v158, v[30:31], off
	global_load_dword v159, v[28:29], off
	v_mad_u64_u32 v[184:185], s[10:11], v23, s77, v[6:7]
	v_mad_u64_u32 v[186:187], s[10:11], v0, s77, v[6:7]
	s_add_i32 s10, s8, 24
	s_nop 0
	v_or_b32_e32 v23, s10, v2
	v_or_b32_e32 v0, s9, v3
	s_add_i32 s8, s8, 28
	s_cmp_lg_u32 s6, 0
	s_waitcnt vmcnt(1)
	v_add_u32_e32 v30, s0, v23
	v_add_u32_e32 v28, s3, v0
	v_ashrrev_i32_e32 v31, 31, v30
	v_ashrrev_i32_e32 v29, 31, v28
	v_lshlrev_b64 v[30:31], 12, v[30:31]
	v_lshlrev_b64 v[28:29], 12, v[28:29]
	v_lshl_add_u64 v[30:31], v[26:27], 0, v[30:31]
	v_lshl_add_u64 v[28:29], v[26:27], 0, v[28:29]
	global_load_dword v160, v[30:31], off
	global_load_dword v161, v[28:29], off
	v_mad_u64_u32 v[188:189], s[10:11], v23, s77, v[6:7]
	v_mad_u64_u32 v[190:191], s[10:11], v0, s77, v[6:7]
	v_or_b32_e32 v23, s8, v2
	v_or_b32_e32 v0, s7, v3
	s_waitcnt vmcnt(1)
	v_add_u32_e32 v30, s0, v23
	v_add_u32_e32 v28, s3, v0
	v_ashrrev_i32_e32 v31, 31, v30
	v_ashrrev_i32_e32 v29, 31, v28
	v_lshlrev_b64 v[30:31], 12, v[30:31]
	v_lshlrev_b64 v[28:29], 12, v[28:29]
	v_lshl_add_u64 v[30:31], v[26:27], 0, v[30:31]
	v_lshl_add_u64 v[28:29], v[26:27], 0, v[28:29]
	global_load_dword v162, v[30:31], off
	global_load_dword v163, v[28:29], off
	v_mad_u64_u32 v[192:193], s[8:9], v23, s77, v[6:7]
	v_mad_u64_u32 v[196:197], s[8:9], v0, s77, v[6:7]
	s_waitcnt vmcnt(1)
	s_waitcnt vmcnt(0)
	ds_write_b32 v116, v100
	ds_write_b32 v118, v101
	ds_write_b32 v120, v102
	ds_write_b32 v122, v103
	ds_write_b32 v124, v104
	ds_write_b32 v126, v105
	ds_write_b32 v128, v106
	ds_write_b32 v130, v107
	ds_write_b32 v132, v108
	ds_write_b32 v134, v109
	ds_write_b32 v136, v110
	ds_write_b32 v138, v111
	ds_write_b32 v140, v112
	ds_write_b32 v142, v113
	ds_write_b32 v144, v114
	ds_write_b32 v146, v115
	ds_write_b32 v164, v148
	ds_write_b32 v166, v149
	ds_write_b32 v168, v150
	ds_write_b32 v170, v151
	ds_write_b32 v172, v152
	ds_write_b32 v174, v153
	ds_write_b32 v176, v154
	ds_write_b32 v178, v155
	ds_write_b32 v180, v156
	ds_write_b32 v182, v157
	ds_write_b32 v184, v158
	ds_write_b32 v186, v159
	ds_write_b32 v188, v160
	ds_write_b32 v190, v161
	ds_write_b32 v192, v162
	ds_write_b32 v196, v163
	s_cbranch_scc1 .LBB0_788
	s_mulk_i32 s1, 0x1600
	v_readlane_b32 s2, v249, 13
	s_add_u32 s2, s2, s1
	v_readlane_b32 s1, v249, 14
	s_addc_u32 s3, s1, 0
	s_mov_b32 s1, s4
	s_lshl_b64 s[0:1], s[0:1], 1
	s_add_u32 s0, s2, s0
	s_addc_u32 s1, s3, s1
	s_mov_b64 s[2:3], 0

.LBB0_796:
	s_lshl_b32 s9, s6, 1
	s_lshl_b32 s8, s5, 1
	v_or_b32_e32 v23, s9, v2
	v_or_b32_e32 v0, s8, v3
	v_add_u32_e32 v28, s1, v23
	v_add_u32_e32 v25, s3, v0
	v_mad_u64_u32 v[28:29], s[10:11], v28, s12, v[26:27]
	v_mad_u64_u32 v[30:31], s[10:11], v25, s12, v[26:27]
	global_load_dword v100, v[28:29], off
	global_load_dword v101, v[30:31], off
	v_mad_u64_u32 v[116:117], s[10:11], v23, s77, v[6:7]
	v_mad_u64_u32 v[118:119], s[10:11], v0, s77, v[6:7]
	s_add_i32 s11, s9, 4
	s_add_i32 s10, s8, 4
	v_or_b32_e32 v23, s11, v2
	v_or_b32_e32 v0, s10, v3
	s_add_i32 s6, s6, 16
	s_add_i32 s5, s5, 16
	s_add_i32 s7, s7, -16
	s_waitcnt vmcnt(1)
	v_add_u32_e32 v28, s1, v23
	v_add_u32_e32 v25, s3, v0
	v_mad_u64_u32 v[28:29], s[10:11], v28, s12, v[26:27]
	v_mad_u64_u32 v[30:31], s[10:11], v25, s12, v[26:27]
	global_load_dword v102, v[28:29], off
	global_load_dword v103, v[30:31], off
	v_mad_u64_u32 v[120:121], s[10:11], v23, s77, v[6:7]
	v_mad_u64_u32 v[122:123], s[10:11], v0, s77, v[6:7]
	s_add_i32 s11, s9, 8
	s_add_i32 s10, s8, 8
	v_or_b32_e32 v23, s11, v2
	v_or_b32_e32 v0, s10, v3
	s_waitcnt vmcnt(1)
	v_add_u32_e32 v28, s1, v23
	v_add_u32_e32 v25, s3, v0
	v_mad_u64_u32 v[28:29], s[10:11], v28, s12, v[26:27]
	v_mad_u64_u32 v[30:31], s[10:11], v25, s12, v[26:27]
	global_load_dword v104, v[28:29], off
	global_load_dword v105, v[30:31], off
	v_mad_u64_u32 v[124:125], s[10:11], v23, s77, v[6:7]
	v_mad_u64_u32 v[126:127], s[10:11], v0, s77, v[6:7]
	s_add_i32 s11, s9, 12
	s_add_i32 s10, s8, 12
	v_or_b32_e32 v23, s11, v2
	v_or_b32_e32 v0, s10, v3
	s_waitcnt vmcnt(1)
	v_add_u32_e32 v28, s1, v23
	v_add_u32_e32 v25, s3, v0
	v_mad_u64_u32 v[28:29], s[10:11], v28, s12, v[26:27]
	v_mad_u64_u32 v[30:31], s[10:11], v25, s12, v[26:27]
	global_load_dword v106, v[28:29], off
	global_load_dword v107, v[30:31], off
	v_mad_u64_u32 v[128:129], s[10:11], v23, s77, v[6:7]
	v_mad_u64_u32 v[130:131], s[10:11], v0, s77, v[6:7]
	s_add_i32 s11, s9, 16
	s_add_i32 s10, s8, 16
	v_or_b32_e32 v23, s11, v2
	v_or_b32_e32 v0, s10, v3
	s_waitcnt vmcnt(1)
	v_add_u32_e32 v28, s1, v23
	v_add_u32_e32 v25, s3, v0
	v_mad_u64_u32 v[28:29], s[10:11], v28, s12, v[26:27]
	v_mad_u64_u32 v[30:31], s[10:11], v25, s12, v[26:27]
	global_load_dword v108, v[28:29], off
	global_load_dword v109, v[30:31], off
	v_mad_u64_u32 v[132:133], s[10:11], v23, s77, v[6:7]
	v_mad_u64_u32 v[134:135], s[10:11], v0, s77, v[6:7]
	s_add_i32 s11, s9, 20
	s_add_i32 s10, s8, 20
	v_or_b32_e32 v23, s11, v2
	v_or_b32_e32 v0, s10, v3
	s_waitcnt vmcnt(1)
	v_add_u32_e32 v28, s1, v23
	v_add_u32_e32 v25, s3, v0
	v_mad_u64_u32 v[28:29], s[10:11], v28, s12, v[26:27]
	v_mad_u64_u32 v[30:31], s[10:11], v25, s12, v[26:27]
	global_load_dword v110, v[28:29], off
	global_load_dword v111, v[30:31], off
	v_mad_u64_u32 v[136:137], s[10:11], v23, s77, v[6:7]
	v_mad_u64_u32 v[138:139], s[10:11], v0, s77, v[6:7]
	s_add_i32 s11, s9, 24
	s_add_i32 s10, s8, 24
	v_or_b32_e32 v23, s11, v2
	v_or_b32_e32 v0, s10, v3
	s_add_i32 s9, s9, 28
	s_add_i32 s8, s8, 28
	s_cmp_lg_u32 s7, 0
	s_waitcnt vmcnt(1)
	v_add_u32_e32 v28, s1, v23
	v_add_u32_e32 v25, s3, v0
	v_mad_u64_u32 v[28:29], s[10:11], v28, s12, v[26:27]
	v_mad_u64_u32 v[30:31], s[10:11], v25, s12, v[26:27]
	global_load_dword v112, v[28:29], off
	global_load_dword v113, v[30:31], off
	v_mad_u64_u32 v[140:141], s[10:11], v23, s77, v[6:7]
	v_or_b32_e32 v23, s9, v2
	v_mad_u64_u32 v[142:143], s[10:11], v0, s77, v[6:7]
	v_or_b32_e32 v0, s8, v3
	s_waitcnt vmcnt(1)
	v_add_u32_e32 v28, s1, v23
	v_add_u32_e32 v25, s3, v0
	v_mad_u64_u32 v[28:29], s[8:9], v28, s12, v[26:27]
	v_mad_u64_u32 v[30:31], s[8:9], v25, s12, v[26:27]
	global_load_dword v114, v[28:29], off
	global_load_dword v115, v[30:31], off
	v_mad_u64_u32 v[144:145], s[8:9], v23, s77, v[6:7]
	v_mad_u64_u32 v[146:147], s[8:9], v0, s77, v[6:7]
	s_waitcnt vmcnt(1)
	s_lshl_b32 s9, s6, 1
	s_lshl_b32 s8, s5, 1
	v_or_b32_e32 v23, s9, v2
	v_or_b32_e32 v0, s8, v3
	v_add_u32_e32 v28, s1, v23
	v_add_u32_e32 v25, s3, v0
	v_mad_u64_u32 v[28:29], s[10:11], v28, s12, v[26:27]
	v_mad_u64_u32 v[30:31], s[10:11], v25, s12, v[26:27]
	global_load_dword v148, v[28:29], off
	global_load_dword v149, v[30:31], off
	v_mad_u64_u32 v[164:165], s[10:11], v23, s77, v[6:7]
	v_mad_u64_u32 v[166:167], s[10:11], v0, s77, v[6:7]
	s_add_i32 s11, s9, 4
	s_add_i32 s10, s8, 4
	v_or_b32_e32 v23, s11, v2
	v_or_b32_e32 v0, s10, v3
	s_add_i32 s6, s6, 16
	s_add_i32 s5, s5, 16
	s_add_i32 s7, s7, -16
	s_waitcnt vmcnt(1)
	v_add_u32_e32 v28, s1, v23
	v_add_u32_e32 v25, s3, v0
	v_mad_u64_u32 v[28:29], s[10:11], v28, s12, v[26:27]
	v_mad_u64_u32 v[30:31], s[10:11], v25, s12, v[26:27]
	global_load_dword v150, v[28:29], off
	global_load_dword v151, v[30:31], off
	v_mad_u64_u32 v[168:169], s[10:11], v23, s77, v[6:7]
	v_mad_u64_u32 v[170:171], s[10:11], v0, s77, v[6:7]
	s_add_i32 s11, s9, 8
	s_add_i32 s10, s8, 8
	v_or_b32_e32 v23, s11, v2
	v_or_b32_e32 v0, s10, v3
	s_waitcnt vmcnt(1)
	v_add_u32_e32 v28, s1, v23
	v_add_u32_e32 v25, s3, v0
	v_mad_u64_u32 v[28:29], s[10:11], v28, s12, v[26:27]
	v_mad_u64_u32 v[30:31], s[10:11], v25, s12, v[26:27]
	global_load_dword v152, v[28:29], off
	global_load_dword v153, v[30:31], off
	v_mad_u64_u32 v[172:173], s[10:11], v23, s77, v[6:7]
	v_mad_u64_u32 v[174:175], s[10:11], v0, s77, v[6:7]
	s_add_i32 s11, s9, 12
	s_add_i32 s10, s8, 12
	v_or_b32_e32 v23, s11, v2
	v_or_b32_e32 v0, s10, v3
	s_waitcnt vmcnt(1)
	v_add_u32_e32 v28, s1, v23
	v_add_u32_e32 v25, s3, v0
	v_mad_u64_u32 v[28:29], s[10:11], v28, s12, v[26:27]
	v_mad_u64_u32 v[30:31], s[10:11], v25, s12, v[26:27]
	global_load_dword v154, v[28:29], off
	global_load_dword v155, v[30:31], off
	v_mad_u64_u32 v[176:177], s[10:11], v23, s77, v[6:7]
	v_mad_u64_u32 v[178:179], s[10:11], v0, s77, v[6:7]
	s_add_i32 s11, s9, 16
	s_add_i32 s10, s8, 16
	v_or_b32_e32 v23, s11, v2
	v_or_b32_e32 v0, s10, v3
	s_waitcnt vmcnt(1)
	v_add_u32_e32 v28, s1, v23
	v_add_u32_e32 v25, s3, v0
	v_mad_u64_u32 v[28:29], s[10:11], v28, s12, v[26:27]
	v_mad_u64_u32 v[30:31], s[10:11], v25, s12, v[26:27]
	global_load_dword v156, v[28:29], off
	global_load_dword v157, v[30:31], off
	v_mad_u64_u32 v[180:181], s[10:11], v23, s77, v[6:7]
	v_mad_u64_u32 v[182:183], s[10:11], v0, s77, v[6:7]
	s_add_i32 s11, s9, 20
	s_add_i32 s10, s8, 20
	v_or_b32_e32 v23, s11, v2
	v_or_b32_e32 v0, s10, v3
	s_waitcnt vmcnt(1)
	v_add_u32_e32 v28, s1, v23
	v_add_u32_e32 v25, s3, v0
	v_mad_u64_u32 v[28:29], s[10:11], v28, s12, v[26:27]
	v_mad_u64_u32 v[30:31], s[10:11], v25, s12, v[26:27]
	global_load_dword v158, v[28:29], off
	global_load_dword v159, v[30:31], off
	v_mad_u64_u32 v[184:185], s[10:11], v23, s77, v[6:7]
	v_mad_u64_u32 v[186:187], s[10:11], v0, s77, v[6:7]
	s_add_i32 s11, s9, 24
	s_add_i32 s10, s8, 24
	v_or_b32_e32 v23, s11, v2
	v_or_b32_e32 v0, s10, v3
	s_add_i32 s9, s9, 28
	s_add_i32 s8, s8, 28
	s_cmp_lg_u32 s7, 0
	s_waitcnt vmcnt(1)
	v_add_u32_e32 v28, s1, v23
	v_add_u32_e32 v25, s3, v0
	v_mad_u64_u32 v[28:29], s[10:11], v28, s12, v[26:27]
	v_mad_u64_u32 v[30:31], s[10:11], v25, s12, v[26:27]
	global_load_dword v160, v[28:29], off
	global_load_dword v161, v[30:31], off
	v_mad_u64_u32 v[188:189], s[10:11], v23, s77, v[6:7]
	v_or_b32_e32 v23, s9, v2
	v_mad_u64_u32 v[190:191], s[10:11], v0, s77, v[6:7]
	v_or_b32_e32 v0, s8, v3
	s_waitcnt vmcnt(1)
	v_add_u32_e32 v28, s1, v23
	v_add_u32_e32 v25, s3, v0
	v_mad_u64_u32 v[28:29], s[8:9], v28, s12, v[26:27]
	v_mad_u64_u32 v[30:31], s[8:9], v25, s12, v[26:27]
	global_load_dword v162, v[28:29], off
	global_load_dword v163, v[30:31], off
	v_mad_u64_u32 v[192:193], s[8:9], v23, s77, v[6:7]
	v_mad_u64_u32 v[196:197], s[8:9], v0, s77, v[6:7]
	s_waitcnt vmcnt(1)
	s_waitcnt vmcnt(0)
	ds_write_b32 v116, v100
	ds_write_b32 v118, v101
	ds_write_b32 v120, v102
	ds_write_b32 v122, v103
	ds_write_b32 v124, v104
	ds_write_b32 v126, v105
	ds_write_b32 v128, v106
	ds_write_b32 v130, v107
	ds_write_b32 v132, v108
	ds_write_b32 v134, v109
	ds_write_b32 v136, v110
	ds_write_b32 v138, v111
	ds_write_b32 v140, v112
	ds_write_b32 v142, v113
	ds_write_b32 v144, v114
	ds_write_b32 v146, v115
	ds_write_b32 v164, v148
	ds_write_b32 v166, v149
	ds_write_b32 v168, v150
	ds_write_b32 v170, v151
	ds_write_b32 v172, v152
	ds_write_b32 v174, v153
	ds_write_b32 v176, v154
	ds_write_b32 v178, v155
	ds_write_b32 v180, v156
	ds_write_b32 v182, v157
	ds_write_b32 v184, v158
	ds_write_b32 v186, v159
	ds_write_b32 v188, v160
	ds_write_b32 v190, v161
	ds_write_b32 v192, v162
	ds_write_b32 v196, v163
	s_cbranch_scc1 .LBB0_796
	s_mov_b32 s1, s4
	s_lshl_b64 s[0:1], s[0:1], 11
	s_add_u32 s0, s72, s0
	v_readlane_b32 s3, v249, 35
	s_addc_u32 s1, s3, s1
	s_and_b32 s2, 0xffff, s2
	s_lshl_b32 s2, s2, 1
	s_add_u32 s0, s0, s2
	s_addc_u32 s1, s1, 0
	v_mov_b32_e32 v0, v39
	v_mov_b32_e32 v26, v38
	v_mov_b32_e32 v28, v37
	v_mov_b32_e32 v30, v36
	s_mov_b64 s[2:3], 0

.LBB0_800:
	s_lshl_b32 s8, s5, 1
	s_lshl_b32 s7, s2, 1
	v_or_b32_e32 v23, s8, v2
	v_or_b32_e32 v0, s7, v3
	v_add_u32_e32 v30, s0, v23
	v_add_u32_e32 v28, s3, v0
	v_ashrrev_i32_e32 v31, 31, v30
	v_ashrrev_i32_e32 v29, 31, v28
	v_lshlrev_b64 v[30:31], 12, v[30:31]
	v_lshlrev_b64 v[28:29], 12, v[28:29]
	v_lshl_add_u64 v[30:31], v[26:27], 0, v[30:31]
	v_lshl_add_u64 v[28:29], v[26:27], 0, v[28:29]
	global_load_dword v100, v[30:31], off
	global_load_dword v101, v[28:29], off
	v_mad_u64_u32 v[116:117], s[10:11], v23, s77, v[6:7]
	v_mad_u64_u32 v[118:119], s[10:11], v0, s77, v[6:7]
	s_add_i32 s10, s8, 4
	s_add_i32 s9, s7, 4
	v_or_b32_e32 v23, s10, v2
	v_or_b32_e32 v0, s9, v3
	s_add_i32 s9, s7, 8
	s_add_i32 s5, s5, 16
	s_add_i32 s2, s2, 16
	s_add_i32 s6, s6, -16
	s_waitcnt vmcnt(1)
	v_add_u32_e32 v30, s0, v23
	v_add_u32_e32 v28, s3, v0
	v_ashrrev_i32_e32 v31, 31, v30
	v_ashrrev_i32_e32 v29, 31, v28
	v_lshlrev_b64 v[30:31], 12, v[30:31]
	v_lshlrev_b64 v[28:29], 12, v[28:29]
	v_lshl_add_u64 v[30:31], v[26:27], 0, v[30:31]
	v_lshl_add_u64 v[28:29], v[26:27], 0, v[28:29]
	global_load_dword v102, v[30:31], off
	global_load_dword v103, v[28:29], off
	v_mad_u64_u32 v[120:121], s[10:11], v23, s77, v[6:7]
	v_mad_u64_u32 v[122:123], s[10:11], v0, s77, v[6:7]
	s_add_i32 s10, s8, 8
	s_nop 0
	v_or_b32_e32 v23, s10, v2
	v_or_b32_e32 v0, s9, v3
	s_add_i32 s9, s7, 12
	s_waitcnt vmcnt(1)
	v_add_u32_e32 v30, s0, v23
	v_add_u32_e32 v28, s3, v0
	v_ashrrev_i32_e32 v31, 31, v30
	v_ashrrev_i32_e32 v29, 31, v28
	v_lshlrev_b64 v[30:31], 12, v[30:31]
	v_lshlrev_b64 v[28:29], 12, v[28:29]
	v_lshl_add_u64 v[30:31], v[26:27], 0, v[30:31]
	v_lshl_add_u64 v[28:29], v[26:27], 0, v[28:29]
	global_load_dword v104, v[30:31], off
	global_load_dword v105, v[28:29], off
	v_mad_u64_u32 v[124:125], s[10:11], v23, s77, v[6:7]
	v_mad_u64_u32 v[126:127], s[10:11], v0, s77, v[6:7]
	s_add_i32 s10, s8, 12
	s_nop 0
	v_or_b32_e32 v23, s10, v2
	v_or_b32_e32 v0, s9, v3
	s_add_i32 s9, s7, 16
	s_waitcnt vmcnt(1)
	v_add_u32_e32 v30, s0, v23
	v_add_u32_e32 v28, s3, v0
	v_ashrrev_i32_e32 v31, 31, v30
	v_ashrrev_i32_e32 v29, 31, v28
	v_lshlrev_b64 v[30:31], 12, v[30:31]
	v_lshlrev_b64 v[28:29], 12, v[28:29]
	v_lshl_add_u64 v[30:31], v[26:27], 0, v[30:31]
	v_lshl_add_u64 v[28:29], v[26:27], 0, v[28:29]
	global_load_dword v106, v[30:31], off
	global_load_dword v107, v[28:29], off
	v_mad_u64_u32 v[128:129], s[10:11], v23, s77, v[6:7]
	v_mad_u64_u32 v[130:131], s[10:11], v0, s77, v[6:7]
	s_add_i32 s10, s8, 16
	s_nop 0
	v_or_b32_e32 v23, s10, v2
	v_or_b32_e32 v0, s9, v3
	s_add_i32 s9, s7, 20
	s_waitcnt vmcnt(1)
	v_add_u32_e32 v30, s0, v23
	v_add_u32_e32 v28, s3, v0
	v_ashrrev_i32_e32 v31, 31, v30
	v_ashrrev_i32_e32 v29, 31, v28
	v_lshlrev_b64 v[30:31], 12, v[30:31]
	v_lshlrev_b64 v[28:29], 12, v[28:29]
	v_lshl_add_u64 v[30:31], v[26:27], 0, v[30:31]
	v_lshl_add_u64 v[28:29], v[26:27], 0, v[28:29]
	global_load_dword v108, v[30:31], off
	global_load_dword v109, v[28:29], off
	v_mad_u64_u32 v[132:133], s[10:11], v23, s77, v[6:7]
	v_mad_u64_u32 v[134:135], s[10:11], v0, s77, v[6:7]
	s_add_i32 s10, s8, 20
	s_nop 0
	v_or_b32_e32 v23, s10, v2
	v_or_b32_e32 v0, s9, v3
	s_add_i32 s9, s7, 24
	s_add_i32 s7, s7, 28
	s_waitcnt vmcnt(1)
	v_add_u32_e32 v30, s0, v23
	v_add_u32_e32 v28, s3, v0
	v_ashrrev_i32_e32 v31, 31, v30
	v_ashrrev_i32_e32 v29, 31, v28
	v_lshlrev_b64 v[30:31], 12, v[30:31]
	v_lshlrev_b64 v[28:29], 12, v[28:29]
	v_lshl_add_u64 v[30:31], v[26:27], 0, v[30:31]
	v_lshl_add_u64 v[28:29], v[26:27], 0, v[28:29]
	global_load_dword v110, v[30:31], off
	global_load_dword v111, v[28:29], off
	v_mad_u64_u32 v[136:137], s[10:11], v23, s77, v[6:7]
	v_mad_u64_u32 v[138:139], s[10:11], v0, s77, v[6:7]
	s_add_i32 s10, s8, 24
	s_nop 0
	v_or_b32_e32 v23, s10, v2
	v_or_b32_e32 v0, s9, v3
	s_add_i32 s8, s8, 28
	s_cmp_lg_u32 s6, 0
	s_waitcnt vmcnt(1)
	v_add_u32_e32 v30, s0, v23
	v_add_u32_e32 v28, s3, v0
	v_ashrrev_i32_e32 v31, 31, v30
	v_ashrrev_i32_e32 v29, 31, v28
	v_lshlrev_b64 v[30:31], 12, v[30:31]
	v_lshlrev_b64 v[28:29], 12, v[28:29]
	v_lshl_add_u64 v[30:31], v[26:27], 0, v[30:31]
	v_lshl_add_u64 v[28:29], v[26:27], 0, v[28:29]
	global_load_dword v112, v[30:31], off
	global_load_dword v113, v[28:29], off
	v_mad_u64_u32 v[140:141], s[10:11], v23, s77, v[6:7]
	v_mad_u64_u32 v[142:143], s[10:11], v0, s77, v[6:7]
	v_or_b32_e32 v23, s8, v2
	v_or_b32_e32 v0, s7, v3
	s_waitcnt vmcnt(1)
	v_add_u32_e32 v30, s0, v23
	v_add_u32_e32 v28, s3, v0
	v_ashrrev_i32_e32 v31, 31, v30
	v_ashrrev_i32_e32 v29, 31, v28
	v_lshlrev_b64 v[30:31], 12, v[30:31]
	v_lshlrev_b64 v[28:29], 12, v[28:29]
	v_lshl_add_u64 v[30:31], v[26:27], 0, v[30:31]
	v_lshl_add_u64 v[28:29], v[26:27], 0, v[28:29]
	global_load_dword v114, v[30:31], off
	global_load_dword v115, v[28:29], off
	v_mad_u64_u32 v[144:145], s[8:9], v23, s77, v[6:7]
	v_mad_u64_u32 v[146:147], s[8:9], v0, s77, v[6:7]
	s_waitcnt vmcnt(1)
	s_lshl_b32 s8, s5, 1
	s_lshl_b32 s7, s2, 1
	v_or_b32_e32 v23, s8, v2
	v_or_b32_e32 v0, s7, v3
	v_add_u32_e32 v30, s0, v23
	v_add_u32_e32 v28, s3, v0
	v_ashrrev_i32_e32 v31, 31, v30
	v_ashrrev_i32_e32 v29, 31, v28
	v_lshlrev_b64 v[30:31], 12, v[30:31]
	v_lshlrev_b64 v[28:29], 12, v[28:29]
	v_lshl_add_u64 v[30:31], v[26:27], 0, v[30:31]
	v_lshl_add_u64 v[28:29], v[26:27], 0, v[28:29]
	global_load_dword v148, v[30:31], off
	global_load_dword v149, v[28:29], off
	v_mad_u64_u32 v[164:165], s[10:11], v23, s77, v[6:7]
	v_mad_u64_u32 v[166:167], s[10:11], v0, s77, v[6:7]
	s_add_i32 s10, s8, 4
	s_add_i32 s9, s7, 4
	v_or_b32_e32 v23, s10, v2
	v_or_b32_e32 v0, s9, v3
	s_add_i32 s9, s7, 8
	s_add_i32 s5, s5, 16
	s_add_i32 s2, s2, 16
	s_add_i32 s6, s6, -16
	s_waitcnt vmcnt(1)
	v_add_u32_e32 v30, s0, v23
	v_add_u32_e32 v28, s3, v0
	v_ashrrev_i32_e32 v31, 31, v30
	v_ashrrev_i32_e32 v29, 31, v28
	v_lshlrev_b64 v[30:31], 12, v[30:31]
	v_lshlrev_b64 v[28:29], 12, v[28:29]
	v_lshl_add_u64 v[30:31], v[26:27], 0, v[30:31]
	v_lshl_add_u64 v[28:29], v[26:27], 0, v[28:29]
	global_load_dword v150, v[30:31], off
	global_load_dword v151, v[28:29], off
	v_mad_u64_u32 v[168:169], s[10:11], v23, s77, v[6:7]
	v_mad_u64_u32 v[170:171], s[10:11], v0, s77, v[6:7]
	s_add_i32 s10, s8, 8
	s_nop 0
	v_or_b32_e32 v23, s10, v2
	v_or_b32_e32 v0, s9, v3
	s_add_i32 s9, s7, 12
	s_waitcnt vmcnt(1)
	v_add_u32_e32 v30, s0, v23
	v_add_u32_e32 v28, s3, v0
	v_ashrrev_i32_e32 v31, 31, v30
	v_ashrrev_i32_e32 v29, 31, v28
	v_lshlrev_b64 v[30:31], 12, v[30:31]
	v_lshlrev_b64 v[28:29], 12, v[28:29]
	v_lshl_add_u64 v[30:31], v[26:27], 0, v[30:31]
	v_lshl_add_u64 v[28:29], v[26:27], 0, v[28:29]
	global_load_dword v152, v[30:31], off
	global_load_dword v153, v[28:29], off
	v_mad_u64_u32 v[172:173], s[10:11], v23, s77, v[6:7]
	v_mad_u64_u32 v[174:175], s[10:11], v0, s77, v[6:7]
	s_add_i32 s10, s8, 12
	s_nop 0
	v_or_b32_e32 v23, s10, v2
	v_or_b32_e32 v0, s9, v3
	s_add_i32 s9, s7, 16
	s_waitcnt vmcnt(1)
	v_add_u32_e32 v30, s0, v23
	v_add_u32_e32 v28, s3, v0
	v_ashrrev_i32_e32 v31, 31, v30
	v_ashrrev_i32_e32 v29, 31, v28
	v_lshlrev_b64 v[30:31], 12, v[30:31]
	v_lshlrev_b64 v[28:29], 12, v[28:29]
	v_lshl_add_u64 v[30:31], v[26:27], 0, v[30:31]
	v_lshl_add_u64 v[28:29], v[26:27], 0, v[28:29]
	global_load_dword v154, v[30:31], off
	global_load_dword v155, v[28:29], off
	v_mad_u64_u32 v[176:177], s[10:11], v23, s77, v[6:7]
	v_mad_u64_u32 v[178:179], s[10:11], v0, s77, v[6:7]
	s_add_i32 s10, s8, 16
	s_nop 0
	v_or_b32_e32 v23, s10, v2
	v_or_b32_e32 v0, s9, v3
	s_add_i32 s9, s7, 20
	s_waitcnt vmcnt(1)
	v_add_u32_e32 v30, s0, v23
	v_add_u32_e32 v28, s3, v0
	v_ashrrev_i32_e32 v31, 31, v30
	v_ashrrev_i32_e32 v29, 31, v28
	v_lshlrev_b64 v[30:31], 12, v[30:31]
	v_lshlrev_b64 v[28:29], 12, v[28:29]
	v_lshl_add_u64 v[30:31], v[26:27], 0, v[30:31]
	v_lshl_add_u64 v[28:29], v[26:27], 0, v[28:29]
	global_load_dword v156, v[30:31], off
	global_load_dword v157, v[28:29], off
	v_mad_u64_u32 v[180:181], s[10:11], v23, s77, v[6:7]
	v_mad_u64_u32 v[182:183], s[10:11], v0, s77, v[6:7]
	s_add_i32 s10, s8, 20
	s_nop 0
	v_or_b32_e32 v23, s10, v2
	v_or_b32_e32 v0, s9, v3
	s_add_i32 s9, s7, 24
	s_add_i32 s7, s7, 28
	s_waitcnt vmcnt(1)
	v_add_u32_e32 v30, s0, v23
	v_add_u32_e32 v28, s3, v0
	v_ashrrev_i32_e32 v31, 31, v30
	v_ashrrev_i32_e32 v29, 31, v28
	v_lshlrev_b64 v[30:31], 12, v[30:31]
	v_lshlrev_b64 v[28:29], 12, v[28:29]
	v_lshl_add_u64 v[30:31], v[26:27], 0, v[30:31]
	v_lshl_add_u64 v[28:29], v[26:27], 0, v[28:29]
	global_load_dword v158, v[30:31], off
	global_load_dword v159, v[28:29], off
	v_mad_u64_u32 v[184:185], s[10:11], v23, s77, v[6:7]
	v_mad_u64_u32 v[186:187], s[10:11], v0, s77, v[6:7]
	s_add_i32 s10, s8, 24
	s_nop 0
	v_or_b32_e32 v23, s10, v2
	v_or_b32_e32 v0, s9, v3
	s_add_i32 s8, s8, 28
	s_cmp_lg_u32 s6, 0
	s_waitcnt vmcnt(1)
	v_add_u32_e32 v30, s0, v23
	v_add_u32_e32 v28, s3, v0
	v_ashrrev_i32_e32 v31, 31, v30
	v_ashrrev_i32_e32 v29, 31, v28
	v_lshlrev_b64 v[30:31], 12, v[30:31]
	v_lshlrev_b64 v[28:29], 12, v[28:29]
	v_lshl_add_u64 v[30:31], v[26:27], 0, v[30:31]
	v_lshl_add_u64 v[28:29], v[26:27], 0, v[28:29]
	global_load_dword v160, v[30:31], off
	global_load_dword v161, v[28:29], off
	v_mad_u64_u32 v[188:189], s[10:11], v23, s77, v[6:7]
	v_mad_u64_u32 v[190:191], s[10:11], v0, s77, v[6:7]
	v_or_b32_e32 v23, s8, v2
	v_or_b32_e32 v0, s7, v3
	s_waitcnt vmcnt(1)
	v_add_u32_e32 v30, s0, v23
	v_add_u32_e32 v28, s3, v0
	v_ashrrev_i32_e32 v31, 31, v30
	v_ashrrev_i32_e32 v29, 31, v28
	v_lshlrev_b64 v[30:31], 12, v[30:31]
	v_lshlrev_b64 v[28:29], 12, v[28:29]
	v_lshl_add_u64 v[30:31], v[26:27], 0, v[30:31]
	v_lshl_add_u64 v[28:29], v[26:27], 0, v[28:29]
	global_load_dword v162, v[30:31], off
	global_load_dword v163, v[28:29], off
	v_mad_u64_u32 v[192:193], s[8:9], v23, s77, v[6:7]
	v_mad_u64_u32 v[196:197], s[8:9], v0, s77, v[6:7]
	s_waitcnt vmcnt(1)
	s_waitcnt vmcnt(0)
	ds_write_b32 v116, v100
	ds_write_b32 v118, v101
	ds_write_b32 v120, v102
	ds_write_b32 v122, v103
	ds_write_b32 v124, v104
	ds_write_b32 v126, v105
	ds_write_b32 v128, v106
	ds_write_b32 v130, v107
	ds_write_b32 v132, v108
	ds_write_b32 v134, v109
	ds_write_b32 v136, v110
	ds_write_b32 v138, v111
	ds_write_b32 v140, v112
	ds_write_b32 v142, v113
	ds_write_b32 v144, v114
	ds_write_b32 v146, v115
	ds_write_b32 v164, v148
	ds_write_b32 v166, v149
	ds_write_b32 v168, v150
	ds_write_b32 v170, v151
	ds_write_b32 v172, v152
	ds_write_b32 v174, v153
	ds_write_b32 v176, v154
	ds_write_b32 v178, v155
	ds_write_b32 v180, v156
	ds_write_b32 v182, v157
	ds_write_b32 v184, v158
	ds_write_b32 v186, v159
	ds_write_b32 v188, v160
	ds_write_b32 v190, v161
	ds_write_b32 v192, v162
	ds_write_b32 v196, v163
	s_cbranch_scc1 .LBB0_800
	s_lshl_b32 s1, s1, 11
	v_readlane_b32 s2, v249, 48
	s_add_u32 s2, s2, s1
	v_readlane_b32 s1, v249, 49
	s_addc_u32 s3, s1, 0
	s_mov_b32 s1, s4
	s_lshl_b64 s[0:1], s[0:1], 1
	s_add_u32 s0, s2, s0
	s_addc_u32 s1, s3, s1
	v_mov_b32_e32 v0, v39
	v_mov_b32_e32 v26, v38
	v_mov_b32_e32 v28, v37
	v_mov_b32_e32 v30, v36

.LBB0_805:
	s_lshl_b32 s10, s7, 1
	s_lshl_b32 s9, s5, 1
	v_or_b32_e32 v25, s10, v2
	v_or_b32_e32 v23, s9, v3
	v_add_u32_e32 v0, s3, v25
	v_add_u32_e32 v28, s6, v23
	v_mov_b32_e32 v29, v1
	v_lshlrev_b64 v[30:31], 12, v[0:1]
	v_lshlrev_b64 v[28:29], 12, v[28:29]
	v_lshl_add_u64 v[30:31], v[26:27], 0, v[30:31]
	v_lshl_add_u64 v[28:29], v[26:27], 0, v[28:29]
	global_load_dword v100, v[30:31], off
	global_load_dword v101, v[28:29], off
	v_mad_u64_u32 v[116:117], s[12:13], v25, s77, v[6:7]
	v_mad_u64_u32 v[118:119], s[12:13], v23, s77, v[6:7]
	s_add_i32 s12, s10, 4
	s_add_i32 s11, s9, 4
	v_or_b32_e32 v25, s12, v2
	v_or_b32_e32 v23, s11, v3
	v_mov_b32_e32 v29, v1
	s_add_i32 s11, s9, 8
	s_add_i32 s7, s7, 16
	s_add_i32 s5, s5, 16
	s_add_i32 s8, s8, -16
	s_waitcnt vmcnt(1)
	v_add_u32_e32 v0, s3, v25
	v_add_u32_e32 v28, s6, v23
	v_lshlrev_b64 v[30:31], 12, v[0:1]
	v_lshlrev_b64 v[28:29], 12, v[28:29]
	v_lshl_add_u64 v[30:31], v[26:27], 0, v[30:31]
	v_lshl_add_u64 v[28:29], v[26:27], 0, v[28:29]
	global_load_dword v102, v[30:31], off
	global_load_dword v103, v[28:29], off
	v_mad_u64_u32 v[120:121], s[12:13], v25, s77, v[6:7]
	v_mad_u64_u32 v[122:123], s[12:13], v23, s77, v[6:7]
	s_add_i32 s12, s10, 8
	s_nop 0
	v_or_b32_e32 v25, s12, v2
	v_or_b32_e32 v23, s11, v3
	v_mov_b32_e32 v29, v1
	s_add_i32 s11, s9, 12
	s_waitcnt vmcnt(1)
	v_add_u32_e32 v0, s3, v25
	v_add_u32_e32 v28, s6, v23
	v_lshlrev_b64 v[30:31], 12, v[0:1]
	v_lshlrev_b64 v[28:29], 12, v[28:29]
	v_lshl_add_u64 v[30:31], v[26:27], 0, v[30:31]
	v_lshl_add_u64 v[28:29], v[26:27], 0, v[28:29]
	global_load_dword v104, v[30:31], off
	global_load_dword v105, v[28:29], off
	v_mad_u64_u32 v[124:125], s[12:13], v25, s77, v[6:7]
	v_mad_u64_u32 v[126:127], s[12:13], v23, s77, v[6:7]
	s_add_i32 s12, s10, 12
	s_nop 0
	v_or_b32_e32 v25, s12, v2
	v_or_b32_e32 v23, s11, v3
	v_mov_b32_e32 v29, v1
	s_add_i32 s11, s9, 16
	s_waitcnt vmcnt(1)
	v_add_u32_e32 v0, s3, v25
	v_add_u32_e32 v28, s6, v23
	v_lshlrev_b64 v[30:31], 12, v[0:1]
	v_lshlrev_b64 v[28:29], 12, v[28:29]
	v_lshl_add_u64 v[30:31], v[26:27], 0, v[30:31]
	v_lshl_add_u64 v[28:29], v[26:27], 0, v[28:29]
	global_load_dword v106, v[30:31], off
	global_load_dword v107, v[28:29], off
	v_mad_u64_u32 v[128:129], s[12:13], v25, s77, v[6:7]
	v_mad_u64_u32 v[130:131], s[12:13], v23, s77, v[6:7]
	s_add_i32 s12, s10, 16
	s_nop 0
	v_or_b32_e32 v25, s12, v2
	v_or_b32_e32 v23, s11, v3
	v_mov_b32_e32 v29, v1
	s_add_i32 s11, s9, 20
	s_waitcnt vmcnt(1)
	v_add_u32_e32 v0, s3, v25
	v_add_u32_e32 v28, s6, v23
	v_lshlrev_b64 v[30:31], 12, v[0:1]
	v_lshlrev_b64 v[28:29], 12, v[28:29]
	v_lshl_add_u64 v[30:31], v[26:27], 0, v[30:31]
	v_lshl_add_u64 v[28:29], v[26:27], 0, v[28:29]
	global_load_dword v108, v[30:31], off
	global_load_dword v109, v[28:29], off
	v_mad_u64_u32 v[132:133], s[12:13], v25, s77, v[6:7]
	v_mad_u64_u32 v[134:135], s[12:13], v23, s77, v[6:7]
	s_add_i32 s12, s10, 20
	s_nop 0
	v_or_b32_e32 v25, s12, v2
	v_or_b32_e32 v23, s11, v3
	v_mov_b32_e32 v29, v1
	s_add_i32 s11, s9, 24
	s_add_i32 s9, s9, 28
	s_waitcnt vmcnt(1)
	v_add_u32_e32 v0, s3, v25
	v_add_u32_e32 v28, s6, v23
	v_lshlrev_b64 v[30:31], 12, v[0:1]
	v_lshlrev_b64 v[28:29], 12, v[28:29]
	v_lshl_add_u64 v[30:31], v[26:27], 0, v[30:31]
	v_lshl_add_u64 v[28:29], v[26:27], 0, v[28:29]
	global_load_dword v110, v[30:31], off
	global_load_dword v111, v[28:29], off
	v_mad_u64_u32 v[136:137], s[12:13], v25, s77, v[6:7]
	v_mad_u64_u32 v[138:139], s[12:13], v23, s77, v[6:7]
	s_add_i32 s12, s10, 24
	s_nop 0
	v_or_b32_e32 v25, s12, v2
	v_or_b32_e32 v23, s11, v3
	v_mov_b32_e32 v29, v1
	s_add_i32 s10, s10, 28
	s_cmp_lg_u32 s8, 0
	s_waitcnt vmcnt(1)
	v_add_u32_e32 v0, s3, v25
	v_add_u32_e32 v28, s6, v23
	v_lshlrev_b64 v[30:31], 12, v[0:1]
	v_lshlrev_b64 v[28:29], 12, v[28:29]
	v_lshl_add_u64 v[30:31], v[26:27], 0, v[30:31]
	v_lshl_add_u64 v[28:29], v[26:27], 0, v[28:29]
	global_load_dword v112, v[30:31], off
	global_load_dword v113, v[28:29], off
	v_mad_u64_u32 v[140:141], s[12:13], v25, s77, v[6:7]
	v_or_b32_e32 v25, s10, v2
	v_mad_u64_u32 v[142:143], s[12:13], v23, s77, v[6:7]
	v_or_b32_e32 v23, s9, v3
	v_mov_b32_e32 v29, v1
	s_waitcnt vmcnt(1)
	v_add_u32_e32 v0, s3, v25
	v_add_u32_e32 v28, s6, v23
	v_lshlrev_b64 v[30:31], 12, v[0:1]
	v_lshlrev_b64 v[28:29], 12, v[28:29]
	v_lshl_add_u64 v[30:31], v[26:27], 0, v[30:31]
	v_lshl_add_u64 v[28:29], v[26:27], 0, v[28:29]
	global_load_dword v114, v[30:31], off
	global_load_dword v115, v[28:29], off
	v_mad_u64_u32 v[144:145], s[10:11], v25, s77, v[6:7]
	v_mad_u64_u32 v[146:147], s[10:11], v23, s77, v[6:7]
	s_waitcnt vmcnt(1)
	s_lshl_b32 s10, s7, 1
	s_lshl_b32 s9, s5, 1
	v_or_b32_e32 v25, s10, v2
	v_or_b32_e32 v23, s9, v3
	v_add_u32_e32 v0, s3, v25
	v_add_u32_e32 v28, s6, v23
	v_mov_b32_e32 v29, v1
	v_lshlrev_b64 v[30:31], 12, v[0:1]
	v_lshlrev_b64 v[28:29], 12, v[28:29]
	v_lshl_add_u64 v[30:31], v[26:27], 0, v[30:31]
	v_lshl_add_u64 v[28:29], v[26:27], 0, v[28:29]
	global_load_dword v148, v[30:31], off
	global_load_dword v149, v[28:29], off
	v_mad_u64_u32 v[164:165], s[12:13], v25, s77, v[6:7]
	v_mad_u64_u32 v[166:167], s[12:13], v23, s77, v[6:7]
	s_add_i32 s12, s10, 4
	s_add_i32 s11, s9, 4
	v_or_b32_e32 v25, s12, v2
	v_or_b32_e32 v23, s11, v3
	v_mov_b32_e32 v29, v1
	s_add_i32 s11, s9, 8
	s_add_i32 s7, s7, 16
	s_add_i32 s5, s5, 16
	s_add_i32 s8, s8, -16
	s_waitcnt vmcnt(1)
	v_add_u32_e32 v0, s3, v25
	v_add_u32_e32 v28, s6, v23
	v_lshlrev_b64 v[30:31], 12, v[0:1]
	v_lshlrev_b64 v[28:29], 12, v[28:29]
	v_lshl_add_u64 v[30:31], v[26:27], 0, v[30:31]
	v_lshl_add_u64 v[28:29], v[26:27], 0, v[28:29]
	global_load_dword v150, v[30:31], off
	global_load_dword v151, v[28:29], off
	v_mad_u64_u32 v[168:169], s[12:13], v25, s77, v[6:7]
	v_mad_u64_u32 v[170:171], s[12:13], v23, s77, v[6:7]
	s_add_i32 s12, s10, 8
	s_nop 0
	v_or_b32_e32 v25, s12, v2
	v_or_b32_e32 v23, s11, v3
	v_mov_b32_e32 v29, v1
	s_add_i32 s11, s9, 12
	s_waitcnt vmcnt(1)
	v_add_u32_e32 v0, s3, v25
	v_add_u32_e32 v28, s6, v23
	v_lshlrev_b64 v[30:31], 12, v[0:1]
	v_lshlrev_b64 v[28:29], 12, v[28:29]
	v_lshl_add_u64 v[30:31], v[26:27], 0, v[30:31]
	v_lshl_add_u64 v[28:29], v[26:27], 0, v[28:29]
	global_load_dword v152, v[30:31], off
	global_load_dword v153, v[28:29], off
	v_mad_u64_u32 v[172:173], s[12:13], v25, s77, v[6:7]
	v_mad_u64_u32 v[174:175], s[12:13], v23, s77, v[6:7]
	s_add_i32 s12, s10, 12
	s_nop 0
	v_or_b32_e32 v25, s12, v2
	v_or_b32_e32 v23, s11, v3
	v_mov_b32_e32 v29, v1
	s_add_i32 s11, s9, 16
	s_waitcnt vmcnt(1)
	v_add_u32_e32 v0, s3, v25
	v_add_u32_e32 v28, s6, v23
	v_lshlrev_b64 v[30:31], 12, v[0:1]
	v_lshlrev_b64 v[28:29], 12, v[28:29]
	v_lshl_add_u64 v[30:31], v[26:27], 0, v[30:31]
	v_lshl_add_u64 v[28:29], v[26:27], 0, v[28:29]
	global_load_dword v154, v[30:31], off
	global_load_dword v155, v[28:29], off
	v_mad_u64_u32 v[176:177], s[12:13], v25, s77, v[6:7]
	v_mad_u64_u32 v[178:179], s[12:13], v23, s77, v[6:7]
	s_add_i32 s12, s10, 16
	s_nop 0
	v_or_b32_e32 v25, s12, v2
	v_or_b32_e32 v23, s11, v3
	v_mov_b32_e32 v29, v1
	s_add_i32 s11, s9, 20
	s_waitcnt vmcnt(1)
	v_add_u32_e32 v0, s3, v25
	v_add_u32_e32 v28, s6, v23
	v_lshlrev_b64 v[30:31], 12, v[0:1]
	v_lshlrev_b64 v[28:29], 12, v[28:29]
	v_lshl_add_u64 v[30:31], v[26:27], 0, v[30:31]
	v_lshl_add_u64 v[28:29], v[26:27], 0, v[28:29]
	global_load_dword v156, v[30:31], off
	global_load_dword v157, v[28:29], off
	v_mad_u64_u32 v[180:181], s[12:13], v25, s77, v[6:7]
	v_mad_u64_u32 v[182:183], s[12:13], v23, s77, v[6:7]
	s_add_i32 s12, s10, 20
	s_nop 0
	v_or_b32_e32 v25, s12, v2
	v_or_b32_e32 v23, s11, v3
	v_mov_b32_e32 v29, v1
	s_add_i32 s11, s9, 24
	s_add_i32 s9, s9, 28
	s_waitcnt vmcnt(1)
	v_add_u32_e32 v0, s3, v25
	v_add_u32_e32 v28, s6, v23
	v_lshlrev_b64 v[30:31], 12, v[0:1]
	v_lshlrev_b64 v[28:29], 12, v[28:29]
	v_lshl_add_u64 v[30:31], v[26:27], 0, v[30:31]
	v_lshl_add_u64 v[28:29], v[26:27], 0, v[28:29]
	global_load_dword v158, v[30:31], off
	global_load_dword v159, v[28:29], off
	v_mad_u64_u32 v[184:185], s[12:13], v25, s77, v[6:7]
	v_mad_u64_u32 v[186:187], s[12:13], v23, s77, v[6:7]
	s_add_i32 s12, s10, 24
	s_nop 0
	v_or_b32_e32 v25, s12, v2
	v_or_b32_e32 v23, s11, v3
	v_mov_b32_e32 v29, v1
	s_add_i32 s10, s10, 28
	s_cmp_lg_u32 s8, 0
	s_waitcnt vmcnt(1)
	v_add_u32_e32 v0, s3, v25
	v_add_u32_e32 v28, s6, v23
	v_lshlrev_b64 v[30:31], 12, v[0:1]
	v_lshlrev_b64 v[28:29], 12, v[28:29]
	v_lshl_add_u64 v[30:31], v[26:27], 0, v[30:31]
	v_lshl_add_u64 v[28:29], v[26:27], 0, v[28:29]
	global_load_dword v160, v[30:31], off
	global_load_dword v161, v[28:29], off
	v_mad_u64_u32 v[188:189], s[12:13], v25, s77, v[6:7]
	v_or_b32_e32 v25, s10, v2
	v_mad_u64_u32 v[190:191], s[12:13], v23, s77, v[6:7]
	v_or_b32_e32 v23, s9, v3
	v_mov_b32_e32 v29, v1
	s_waitcnt vmcnt(1)
	v_add_u32_e32 v0, s3, v25
	v_add_u32_e32 v28, s6, v23
	v_lshlrev_b64 v[30:31], 12, v[0:1]
	v_lshlrev_b64 v[28:29], 12, v[28:29]
	v_lshl_add_u64 v[30:31], v[26:27], 0, v[30:31]
	v_lshl_add_u64 v[28:29], v[26:27], 0, v[28:29]
	global_load_dword v162, v[30:31], off
	global_load_dword v163, v[28:29], off
	v_mad_u64_u32 v[192:193], s[10:11], v25, s77, v[6:7]
	v_mad_u64_u32 v[196:197], s[10:11], v23, s77, v[6:7]
	s_waitcnt vmcnt(1)
	s_waitcnt vmcnt(0)
	ds_write_b32 v116, v100
	ds_write_b32 v118, v101
	ds_write_b32 v120, v102
	ds_write_b32 v122, v103
	ds_write_b32 v124, v104
	ds_write_b32 v126, v105
	ds_write_b32 v128, v106
	ds_write_b32 v130, v107
	ds_write_b32 v132, v108
	ds_write_b32 v134, v109
	ds_write_b32 v136, v110
	ds_write_b32 v138, v111
	ds_write_b32 v140, v112
	ds_write_b32 v142, v113
	ds_write_b32 v144, v114
	ds_write_b32 v146, v115
	ds_write_b32 v164, v148
	ds_write_b32 v166, v149
	ds_write_b32 v168, v150
	ds_write_b32 v170, v151
	ds_write_b32 v172, v152
	ds_write_b32 v174, v153
	ds_write_b32 v176, v154
	ds_write_b32 v178, v155
	ds_write_b32 v180, v156
	ds_write_b32 v182, v157
	ds_write_b32 v184, v158
	ds_write_b32 v186, v159
	ds_write_b32 v188, v160
	ds_write_b32 v190, v161
	ds_write_b32 v192, v162
	ds_write_b32 v196, v163
	s_cbranch_scc1 .LBB0_805
	s_lshl_b64 s[0:1], s[0:1], 20
	v_readlane_b32 s5, v253, 4
	s_add_u32 s0, s5, s0
	v_readlane_b32 s5, v253, 5
	s_addc_u32 s1, s5, s1
	s_lshl_b32 s2, s2, 10
	s_add_u32 s0, s0, s2
	s_addc_u32 s1, s1, 0
	s_lshl_b32 s2, s3, 1
	s_add_u32 s0, s0, s2
	s_addc_u32 s1, s1, 0
	v_mov_b32_e32 v0, v43
	v_mov_b32_e32 v26, v42
	v_mov_b32_e32 v28, v41
	v_mov_b32_e32 v30, v40

.LBB0_810:
	s_lshl_b32 s8, s5, 1
	s_lshl_b32 s7, s3, 1
	v_or_b32_e32 v23, s8, v2
	v_or_b32_e32 v0, s7, v3
	v_add_u32_e32 v30, s0, v23
	v_add_u32_e32 v28, s2, v0
	v_ashrrev_i32_e32 v31, 31, v30
	v_ashrrev_i32_e32 v29, 31, v28
	v_lshlrev_b64 v[30:31], 11, v[30:31]
	v_lshlrev_b64 v[28:29], 11, v[28:29]
	v_lshl_add_u64 v[30:31], v[26:27], 0, v[30:31]
	v_lshl_add_u64 v[28:29], v[26:27], 0, v[28:29]
	global_load_dword v100, v[30:31], off
	global_load_dword v101, v[28:29], off
	v_mad_u64_u32 v[116:117], s[10:11], v23, s77, v[6:7]
	v_mad_u64_u32 v[118:119], s[10:11], v0, s77, v[6:7]
	s_add_i32 s10, s8, 4
	s_add_i32 s9, s7, 4
	v_or_b32_e32 v23, s10, v2
	v_or_b32_e32 v0, s9, v3
	s_add_i32 s9, s7, 8
	s_add_i32 s5, s5, 16
	s_add_i32 s3, s3, 16
	s_add_i32 s6, s6, -16
	s_waitcnt vmcnt(1)
	v_add_u32_e32 v30, s0, v23
	v_add_u32_e32 v28, s2, v0
	v_ashrrev_i32_e32 v31, 31, v30
	v_ashrrev_i32_e32 v29, 31, v28
	v_lshlrev_b64 v[30:31], 11, v[30:31]
	v_lshlrev_b64 v[28:29], 11, v[28:29]
	v_lshl_add_u64 v[30:31], v[26:27], 0, v[30:31]
	v_lshl_add_u64 v[28:29], v[26:27], 0, v[28:29]
	global_load_dword v102, v[30:31], off
	global_load_dword v103, v[28:29], off
	v_mad_u64_u32 v[120:121], s[10:11], v23, s77, v[6:7]
	v_mad_u64_u32 v[122:123], s[10:11], v0, s77, v[6:7]
	s_add_i32 s10, s8, 8
	s_nop 0
	v_or_b32_e32 v23, s10, v2
	v_or_b32_e32 v0, s9, v3
	s_add_i32 s9, s7, 12
	s_waitcnt vmcnt(1)
	v_add_u32_e32 v30, s0, v23
	v_add_u32_e32 v28, s2, v0
	v_ashrrev_i32_e32 v31, 31, v30
	v_ashrrev_i32_e32 v29, 31, v28
	v_lshlrev_b64 v[30:31], 11, v[30:31]
	v_lshlrev_b64 v[28:29], 11, v[28:29]
	v_lshl_add_u64 v[30:31], v[26:27], 0, v[30:31]
	v_lshl_add_u64 v[28:29], v[26:27], 0, v[28:29]
	global_load_dword v104, v[30:31], off
	global_load_dword v105, v[28:29], off
	v_mad_u64_u32 v[124:125], s[10:11], v23, s77, v[6:7]
	v_mad_u64_u32 v[126:127], s[10:11], v0, s77, v[6:7]
	s_add_i32 s10, s8, 12
	s_nop 0
	v_or_b32_e32 v23, s10, v2
	v_or_b32_e32 v0, s9, v3
	s_add_i32 s9, s7, 16
	s_waitcnt vmcnt(1)
	v_add_u32_e32 v30, s0, v23
	v_add_u32_e32 v28, s2, v0
	v_ashrrev_i32_e32 v31, 31, v30
	v_ashrrev_i32_e32 v29, 31, v28
	v_lshlrev_b64 v[30:31], 11, v[30:31]
	v_lshlrev_b64 v[28:29], 11, v[28:29]
	v_lshl_add_u64 v[30:31], v[26:27], 0, v[30:31]
	v_lshl_add_u64 v[28:29], v[26:27], 0, v[28:29]
	global_load_dword v106, v[30:31], off
	global_load_dword v107, v[28:29], off
	v_mad_u64_u32 v[128:129], s[10:11], v23, s77, v[6:7]
	v_mad_u64_u32 v[130:131], s[10:11], v0, s77, v[6:7]
	s_add_i32 s10, s8, 16
	s_nop 0
	v_or_b32_e32 v23, s10, v2
	v_or_b32_e32 v0, s9, v3
	s_add_i32 s9, s7, 20
	s_waitcnt vmcnt(1)
	v_add_u32_e32 v30, s0, v23
	v_add_u32_e32 v28, s2, v0
	v_ashrrev_i32_e32 v31, 31, v30
	v_ashrrev_i32_e32 v29, 31, v28
	v_lshlrev_b64 v[30:31], 11, v[30:31]
	v_lshlrev_b64 v[28:29], 11, v[28:29]
	v_lshl_add_u64 v[30:31], v[26:27], 0, v[30:31]
	v_lshl_add_u64 v[28:29], v[26:27], 0, v[28:29]
	global_load_dword v108, v[30:31], off
	global_load_dword v109, v[28:29], off
	v_mad_u64_u32 v[132:133], s[10:11], v23, s77, v[6:7]
	v_mad_u64_u32 v[134:135], s[10:11], v0, s77, v[6:7]
	s_add_i32 s10, s8, 20
	s_nop 0
	v_or_b32_e32 v23, s10, v2
	v_or_b32_e32 v0, s9, v3
	s_add_i32 s9, s7, 24
	s_add_i32 s7, s7, 28
	s_waitcnt vmcnt(1)
	v_add_u32_e32 v30, s0, v23
	v_add_u32_e32 v28, s2, v0
	v_ashrrev_i32_e32 v31, 31, v30
	v_ashrrev_i32_e32 v29, 31, v28
	v_lshlrev_b64 v[30:31], 11, v[30:31]
	v_lshlrev_b64 v[28:29], 11, v[28:29]
	v_lshl_add_u64 v[30:31], v[26:27], 0, v[30:31]
	v_lshl_add_u64 v[28:29], v[26:27], 0, v[28:29]
	global_load_dword v110, v[30:31], off
	global_load_dword v111, v[28:29], off
	v_mad_u64_u32 v[136:137], s[10:11], v23, s77, v[6:7]
	v_mad_u64_u32 v[138:139], s[10:11], v0, s77, v[6:7]
	s_add_i32 s10, s8, 24
	s_nop 0
	v_or_b32_e32 v23, s10, v2
	v_or_b32_e32 v0, s9, v3
	s_add_i32 s8, s8, 28
	s_cmp_lg_u32 s6, 0
	s_waitcnt vmcnt(1)
	v_add_u32_e32 v30, s0, v23
	v_add_u32_e32 v28, s2, v0
	v_ashrrev_i32_e32 v31, 31, v30
	v_ashrrev_i32_e32 v29, 31, v28
	v_lshlrev_b64 v[30:31], 11, v[30:31]
	v_lshlrev_b64 v[28:29], 11, v[28:29]
	v_lshl_add_u64 v[30:31], v[26:27], 0, v[30:31]
	v_lshl_add_u64 v[28:29], v[26:27], 0, v[28:29]
	global_load_dword v112, v[30:31], off
	global_load_dword v113, v[28:29], off
	v_mad_u64_u32 v[140:141], s[10:11], v23, s77, v[6:7]
	v_mad_u64_u32 v[142:143], s[10:11], v0, s77, v[6:7]
	v_or_b32_e32 v23, s8, v2
	v_or_b32_e32 v0, s7, v3
	s_waitcnt vmcnt(1)
	v_add_u32_e32 v30, s0, v23
	v_add_u32_e32 v28, s2, v0
	v_ashrrev_i32_e32 v31, 31, v30
	v_ashrrev_i32_e32 v29, 31, v28
	v_lshlrev_b64 v[30:31], 11, v[30:31]
	v_lshlrev_b64 v[28:29], 11, v[28:29]
	v_lshl_add_u64 v[30:31], v[26:27], 0, v[30:31]
	v_lshl_add_u64 v[28:29], v[26:27], 0, v[28:29]
	global_load_dword v114, v[30:31], off
	global_load_dword v115, v[28:29], off
	v_mad_u64_u32 v[144:145], s[8:9], v23, s77, v[6:7]
	v_mad_u64_u32 v[146:147], s[8:9], v0, s77, v[6:7]
	s_waitcnt vmcnt(1)
	s_lshl_b32 s8, s5, 1
	s_lshl_b32 s7, s3, 1
	v_or_b32_e32 v23, s8, v2
	v_or_b32_e32 v0, s7, v3
	v_add_u32_e32 v30, s0, v23
	v_add_u32_e32 v28, s2, v0
	v_ashrrev_i32_e32 v31, 31, v30
	v_ashrrev_i32_e32 v29, 31, v28
	v_lshlrev_b64 v[30:31], 11, v[30:31]
	v_lshlrev_b64 v[28:29], 11, v[28:29]
	v_lshl_add_u64 v[30:31], v[26:27], 0, v[30:31]
	v_lshl_add_u64 v[28:29], v[26:27], 0, v[28:29]
	global_load_dword v148, v[30:31], off
	global_load_dword v149, v[28:29], off
	v_mad_u64_u32 v[164:165], s[10:11], v23, s77, v[6:7]
	v_mad_u64_u32 v[166:167], s[10:11], v0, s77, v[6:7]
	s_add_i32 s10, s8, 4
	s_add_i32 s9, s7, 4
	v_or_b32_e32 v23, s10, v2
	v_or_b32_e32 v0, s9, v3
	s_add_i32 s9, s7, 8
	s_add_i32 s5, s5, 16
	s_add_i32 s3, s3, 16
	s_add_i32 s6, s6, -16
	s_waitcnt vmcnt(1)
	v_add_u32_e32 v30, s0, v23
	v_add_u32_e32 v28, s2, v0
	v_ashrrev_i32_e32 v31, 31, v30
	v_ashrrev_i32_e32 v29, 31, v28
	v_lshlrev_b64 v[30:31], 11, v[30:31]
	v_lshlrev_b64 v[28:29], 11, v[28:29]
	v_lshl_add_u64 v[30:31], v[26:27], 0, v[30:31]
	v_lshl_add_u64 v[28:29], v[26:27], 0, v[28:29]
	global_load_dword v150, v[30:31], off
	global_load_dword v151, v[28:29], off
	v_mad_u64_u32 v[168:169], s[10:11], v23, s77, v[6:7]
	v_mad_u64_u32 v[170:171], s[10:11], v0, s77, v[6:7]
	s_add_i32 s10, s8, 8
	s_nop 0
	v_or_b32_e32 v23, s10, v2
	v_or_b32_e32 v0, s9, v3
	s_add_i32 s9, s7, 12
	s_waitcnt vmcnt(1)
	v_add_u32_e32 v30, s0, v23
	v_add_u32_e32 v28, s2, v0
	v_ashrrev_i32_e32 v31, 31, v30
	v_ashrrev_i32_e32 v29, 31, v28
	v_lshlrev_b64 v[30:31], 11, v[30:31]
	v_lshlrev_b64 v[28:29], 11, v[28:29]
	v_lshl_add_u64 v[30:31], v[26:27], 0, v[30:31]
	v_lshl_add_u64 v[28:29], v[26:27], 0, v[28:29]
	global_load_dword v152, v[30:31], off
	global_load_dword v153, v[28:29], off
	v_mad_u64_u32 v[172:173], s[10:11], v23, s77, v[6:7]
	v_mad_u64_u32 v[174:175], s[10:11], v0, s77, v[6:7]
	s_add_i32 s10, s8, 12
	s_nop 0
	v_or_b32_e32 v23, s10, v2
	v_or_b32_e32 v0, s9, v3
	s_add_i32 s9, s7, 16
	s_waitcnt vmcnt(1)
	v_add_u32_e32 v30, s0, v23
	v_add_u32_e32 v28, s2, v0
	v_ashrrev_i32_e32 v31, 31, v30
	v_ashrrev_i32_e32 v29, 31, v28
	v_lshlrev_b64 v[30:31], 11, v[30:31]
	v_lshlrev_b64 v[28:29], 11, v[28:29]
	v_lshl_add_u64 v[30:31], v[26:27], 0, v[30:31]
	v_lshl_add_u64 v[28:29], v[26:27], 0, v[28:29]
	global_load_dword v154, v[30:31], off
	global_load_dword v155, v[28:29], off
	v_mad_u64_u32 v[176:177], s[10:11], v23, s77, v[6:7]
	v_mad_u64_u32 v[178:179], s[10:11], v0, s77, v[6:7]
	s_add_i32 s10, s8, 16
	s_nop 0
	v_or_b32_e32 v23, s10, v2
	v_or_b32_e32 v0, s9, v3
	s_add_i32 s9, s7, 20
	s_waitcnt vmcnt(1)
	v_add_u32_e32 v30, s0, v23
	v_add_u32_e32 v28, s2, v0
	v_ashrrev_i32_e32 v31, 31, v30
	v_ashrrev_i32_e32 v29, 31, v28
	v_lshlrev_b64 v[30:31], 11, v[30:31]
	v_lshlrev_b64 v[28:29], 11, v[28:29]
	v_lshl_add_u64 v[30:31], v[26:27], 0, v[30:31]
	v_lshl_add_u64 v[28:29], v[26:27], 0, v[28:29]
	global_load_dword v156, v[30:31], off
	global_load_dword v157, v[28:29], off
	v_mad_u64_u32 v[180:181], s[10:11], v23, s77, v[6:7]
	v_mad_u64_u32 v[182:183], s[10:11], v0, s77, v[6:7]
	s_add_i32 s10, s8, 20
	s_nop 0
	v_or_b32_e32 v23, s10, v2
	v_or_b32_e32 v0, s9, v3
	s_add_i32 s9, s7, 24
	s_add_i32 s7, s7, 28
	s_waitcnt vmcnt(1)
	v_add_u32_e32 v30, s0, v23
	v_add_u32_e32 v28, s2, v0
	v_ashrrev_i32_e32 v31, 31, v30
	v_ashrrev_i32_e32 v29, 31, v28
	v_lshlrev_b64 v[30:31], 11, v[30:31]
	v_lshlrev_b64 v[28:29], 11, v[28:29]
	v_lshl_add_u64 v[30:31], v[26:27], 0, v[30:31]
	v_lshl_add_u64 v[28:29], v[26:27], 0, v[28:29]
	global_load_dword v158, v[30:31], off
	global_load_dword v159, v[28:29], off
	v_mad_u64_u32 v[184:185], s[10:11], v23, s77, v[6:7]
	v_mad_u64_u32 v[186:187], s[10:11], v0, s77, v[6:7]
	s_add_i32 s10, s8, 24
	s_nop 0
	v_or_b32_e32 v23, s10, v2
	v_or_b32_e32 v0, s9, v3
	s_add_i32 s8, s8, 28
	s_cmp_lg_u32 s6, 0
	s_waitcnt vmcnt(1)
	v_add_u32_e32 v30, s0, v23
	v_add_u32_e32 v28, s2, v0
	v_ashrrev_i32_e32 v31, 31, v30
	v_ashrrev_i32_e32 v29, 31, v28
	v_lshlrev_b64 v[30:31], 11, v[30:31]
	v_lshlrev_b64 v[28:29], 11, v[28:29]
	v_lshl_add_u64 v[30:31], v[26:27], 0, v[30:31]
	v_lshl_add_u64 v[28:29], v[26:27], 0, v[28:29]
	global_load_dword v160, v[30:31], off
	global_load_dword v161, v[28:29], off
	v_mad_u64_u32 v[188:189], s[10:11], v23, s77, v[6:7]
	v_mad_u64_u32 v[190:191], s[10:11], v0, s77, v[6:7]
	v_or_b32_e32 v23, s8, v2
	v_or_b32_e32 v0, s7, v3
	s_waitcnt vmcnt(1)
	v_add_u32_e32 v30, s0, v23
	v_add_u32_e32 v28, s2, v0
	v_ashrrev_i32_e32 v31, 31, v30
	v_ashrrev_i32_e32 v29, 31, v28
	v_lshlrev_b64 v[30:31], 11, v[30:31]
	v_lshlrev_b64 v[28:29], 11, v[28:29]
	v_lshl_add_u64 v[30:31], v[26:27], 0, v[30:31]
	v_lshl_add_u64 v[28:29], v[26:27], 0, v[28:29]
	global_load_dword v162, v[30:31], off
	global_load_dword v163, v[28:29], off
	v_mad_u64_u32 v[192:193], s[8:9], v23, s77, v[6:7]
	v_mad_u64_u32 v[196:197], s[8:9], v0, s77, v[6:7]
	s_waitcnt vmcnt(1)
	s_waitcnt vmcnt(0)
	ds_write_b32 v116, v100
	ds_write_b32 v118, v101
	ds_write_b32 v120, v102
	ds_write_b32 v122, v103
	ds_write_b32 v124, v104
	ds_write_b32 v126, v105
	ds_write_b32 v128, v106
	ds_write_b32 v130, v107
	ds_write_b32 v132, v108
	ds_write_b32 v134, v109
	ds_write_b32 v136, v110
	ds_write_b32 v138, v111
	ds_write_b32 v140, v112
	ds_write_b32 v142, v113
	ds_write_b32 v144, v114
	ds_write_b32 v146, v115
	ds_write_b32 v164, v148
	ds_write_b32 v166, v149
	ds_write_b32 v168, v150
	ds_write_b32 v170, v151
	ds_write_b32 v172, v152
	ds_write_b32 v174, v153
	ds_write_b32 v176, v154
	ds_write_b32 v178, v155
	ds_write_b32 v180, v156
	ds_write_b32 v182, v157
	ds_write_b32 v184, v158
	ds_write_b32 v186, v159
	ds_write_b32 v188, v160
	ds_write_b32 v190, v161
	ds_write_b32 v192, v162
	ds_write_b32 v196, v163
	s_cbranch_scc1 .LBB0_810
	s_lshl_b32 s1, s1, 10
	s_add_u32 s2, s73, s1
	v_readlane_b32 s1, v250, 13
	s_addc_u32 s3, s1, 0
	s_mov_b32 s1, s4
	s_lshl_b64 s[0:1], s[0:1], 1
	s_add_u32 s0, s2, s0
	s_addc_u32 s1, s3, s1
	v_mov_b32_e32 v0, v43
	v_mov_b32_e32 v26, v42
	v_mov_b32_e32 v28, v41
	v_mov_b32_e32 v30, v40

.LBB0_819:
	s_lshl_b32 s9, s5, 1
	s_lshl_b32 s8, s2, 1
	v_or_b32_e32 v23, s9, v2
	v_or_b32_e32 v0, s8, v3
	v_add_u32_e32 v30, s6, v23
	v_add_u32_e32 v28, s3, v0
	v_ashrrev_i32_e32 v31, 31, v30
	v_ashrrev_i32_e32 v29, 31, v28
	v_lshlrev_b64 v[30:31], 12, v[30:31]
	v_lshlrev_b64 v[28:29], 12, v[28:29]
	v_lshl_add_u64 v[30:31], v[26:27], 0, v[30:31]
	v_lshl_add_u64 v[28:29], v[26:27], 0, v[28:29]
	global_load_dword v100, v[30:31], off
	global_load_dword v101, v[28:29], off
	v_mad_u64_u32 v[116:117], s[10:11], v23, s77, v[6:7]
	v_mad_u64_u32 v[118:119], s[10:11], v0, s77, v[6:7]
	s_add_i32 s11, s9, 4
	s_add_i32 s10, s8, 4
	v_or_b32_e32 v23, s11, v2
	v_or_b32_e32 v0, s10, v3
	s_add_i32 s5, s5, 16
	s_add_i32 s2, s2, 16
	s_add_i32 s7, s7, -16
	s_waitcnt vmcnt(1)
	v_add_u32_e32 v30, s6, v23
	v_add_u32_e32 v28, s3, v0
	v_ashrrev_i32_e32 v31, 31, v30
	v_ashrrev_i32_e32 v29, 31, v28
	v_lshlrev_b64 v[30:31], 12, v[30:31]
	v_lshlrev_b64 v[28:29], 12, v[28:29]
	v_lshl_add_u64 v[30:31], v[26:27], 0, v[30:31]
	v_lshl_add_u64 v[28:29], v[26:27], 0, v[28:29]
	global_load_dword v102, v[30:31], off
	global_load_dword v103, v[28:29], off
	v_mad_u64_u32 v[120:121], s[10:11], v23, s77, v[6:7]
	v_mad_u64_u32 v[122:123], s[10:11], v0, s77, v[6:7]
	s_add_i32 s11, s9, 8
	s_add_i32 s10, s8, 8
	v_or_b32_e32 v23, s11, v2
	v_or_b32_e32 v0, s10, v3
	s_waitcnt vmcnt(1)
	v_add_u32_e32 v30, s6, v23
	v_add_u32_e32 v28, s3, v0
	v_ashrrev_i32_e32 v31, 31, v30
	v_ashrrev_i32_e32 v29, 31, v28
	v_lshlrev_b64 v[30:31], 12, v[30:31]
	v_lshlrev_b64 v[28:29], 12, v[28:29]
	v_lshl_add_u64 v[30:31], v[26:27], 0, v[30:31]
	v_lshl_add_u64 v[28:29], v[26:27], 0, v[28:29]
	global_load_dword v104, v[30:31], off
	global_load_dword v105, v[28:29], off
	v_mad_u64_u32 v[124:125], s[10:11], v23, s77, v[6:7]
	v_mad_u64_u32 v[126:127], s[10:11], v0, s77, v[6:7]
	s_add_i32 s11, s9, 12
	s_add_i32 s10, s8, 12
	v_or_b32_e32 v23, s11, v2
	v_or_b32_e32 v0, s10, v3
	s_waitcnt vmcnt(1)
	v_add_u32_e32 v30, s6, v23
	v_add_u32_e32 v28, s3, v0
	v_ashrrev_i32_e32 v31, 31, v30
	v_ashrrev_i32_e32 v29, 31, v28
	v_lshlrev_b64 v[30:31], 12, v[30:31]
	v_lshlrev_b64 v[28:29], 12, v[28:29]
	v_lshl_add_u64 v[30:31], v[26:27], 0, v[30:31]
	v_lshl_add_u64 v[28:29], v[26:27], 0, v[28:29]
	global_load_dword v106, v[30:31], off
	global_load_dword v107, v[28:29], off
	v_mad_u64_u32 v[128:129], s[10:11], v23, s77, v[6:7]
	v_mad_u64_u32 v[130:131], s[10:11], v0, s77, v[6:7]
	s_add_i32 s11, s9, 16
	s_add_i32 s10, s8, 16
	v_or_b32_e32 v23, s11, v2
	v_or_b32_e32 v0, s10, v3
	s_waitcnt vmcnt(1)
	v_add_u32_e32 v30, s6, v23
	v_add_u32_e32 v28, s3, v0
	v_ashrrev_i32_e32 v31, 31, v30
	v_ashrrev_i32_e32 v29, 31, v28
	v_lshlrev_b64 v[30:31], 12, v[30:31]
	v_lshlrev_b64 v[28:29], 12, v[28:29]
	v_lshl_add_u64 v[30:31], v[26:27], 0, v[30:31]
	v_lshl_add_u64 v[28:29], v[26:27], 0, v[28:29]
	global_load_dword v108, v[30:31], off
	global_load_dword v109, v[28:29], off
	v_mad_u64_u32 v[132:133], s[10:11], v23, s77, v[6:7]
	v_mad_u64_u32 v[134:135], s[10:11], v0, s77, v[6:7]
	s_add_i32 s11, s9, 20
	s_add_i32 s10, s8, 20
	v_or_b32_e32 v23, s11, v2
	v_or_b32_e32 v0, s10, v3
	s_waitcnt vmcnt(1)
	v_add_u32_e32 v30, s6, v23
	v_add_u32_e32 v28, s3, v0
	v_ashrrev_i32_e32 v31, 31, v30
	v_ashrrev_i32_e32 v29, 31, v28
	v_lshlrev_b64 v[30:31], 12, v[30:31]
	v_lshlrev_b64 v[28:29], 12, v[28:29]
	v_lshl_add_u64 v[30:31], v[26:27], 0, v[30:31]
	v_lshl_add_u64 v[28:29], v[26:27], 0, v[28:29]
	global_load_dword v110, v[30:31], off
	global_load_dword v111, v[28:29], off
	v_mad_u64_u32 v[136:137], s[10:11], v23, s77, v[6:7]
	v_mad_u64_u32 v[138:139], s[10:11], v0, s77, v[6:7]
	s_add_i32 s11, s9, 24
	s_add_i32 s10, s8, 24
	v_or_b32_e32 v23, s11, v2
	v_or_b32_e32 v0, s10, v3
	s_add_i32 s9, s9, 28
	s_add_i32 s8, s8, 28
	s_cmp_lg_u32 s7, 0
	s_waitcnt vmcnt(1)
	v_add_u32_e32 v30, s6, v23
	v_add_u32_e32 v28, s3, v0
	v_ashrrev_i32_e32 v31, 31, v30
	v_ashrrev_i32_e32 v29, 31, v28
	v_lshlrev_b64 v[30:31], 12, v[30:31]
	v_lshlrev_b64 v[28:29], 12, v[28:29]
	v_lshl_add_u64 v[30:31], v[26:27], 0, v[30:31]
	v_lshl_add_u64 v[28:29], v[26:27], 0, v[28:29]
	global_load_dword v112, v[30:31], off
	global_load_dword v113, v[28:29], off
	v_mad_u64_u32 v[140:141], s[10:11], v23, s77, v[6:7]
	v_mad_u64_u32 v[142:143], s[10:11], v0, s77, v[6:7]
	v_or_b32_e32 v23, s9, v2
	v_or_b32_e32 v0, s8, v3
	s_waitcnt vmcnt(1)
	v_add_u32_e32 v30, s6, v23
	v_add_u32_e32 v28, s3, v0
	v_ashrrev_i32_e32 v31, 31, v30
	v_ashrrev_i32_e32 v29, 31, v28
	v_lshlrev_b64 v[30:31], 12, v[30:31]
	v_lshlrev_b64 v[28:29], 12, v[28:29]
	v_lshl_add_u64 v[30:31], v[26:27], 0, v[30:31]
	v_lshl_add_u64 v[28:29], v[26:27], 0, v[28:29]
	global_load_dword v114, v[30:31], off
	global_load_dword v115, v[28:29], off
	v_mad_u64_u32 v[144:145], s[8:9], v23, s77, v[6:7]
	v_mad_u64_u32 v[146:147], s[8:9], v0, s77, v[6:7]
	s_waitcnt vmcnt(1)
	s_lshl_b32 s9, s5, 1
	s_lshl_b32 s8, s2, 1
	v_or_b32_e32 v23, s9, v2
	v_or_b32_e32 v0, s8, v3
	v_add_u32_e32 v30, s6, v23
	v_add_u32_e32 v28, s3, v0
	v_ashrrev_i32_e32 v31, 31, v30
	v_ashrrev_i32_e32 v29, 31, v28
	v_lshlrev_b64 v[30:31], 12, v[30:31]
	v_lshlrev_b64 v[28:29], 12, v[28:29]
	v_lshl_add_u64 v[30:31], v[26:27], 0, v[30:31]
	v_lshl_add_u64 v[28:29], v[26:27], 0, v[28:29]
	global_load_dword v148, v[30:31], off
	global_load_dword v149, v[28:29], off
	v_mad_u64_u32 v[164:165], s[10:11], v23, s77, v[6:7]
	v_mad_u64_u32 v[166:167], s[10:11], v0, s77, v[6:7]
	s_add_i32 s11, s9, 4
	s_add_i32 s10, s8, 4
	v_or_b32_e32 v23, s11, v2
	v_or_b32_e32 v0, s10, v3
	s_add_i32 s5, s5, 16
	s_add_i32 s2, s2, 16
	s_add_i32 s7, s7, -16
	s_waitcnt vmcnt(1)
	v_add_u32_e32 v30, s6, v23
	v_add_u32_e32 v28, s3, v0
	v_ashrrev_i32_e32 v31, 31, v30
	v_ashrrev_i32_e32 v29, 31, v28
	v_lshlrev_b64 v[30:31], 12, v[30:31]
	v_lshlrev_b64 v[28:29], 12, v[28:29]
	v_lshl_add_u64 v[30:31], v[26:27], 0, v[30:31]
	v_lshl_add_u64 v[28:29], v[26:27], 0, v[28:29]
	global_load_dword v150, v[30:31], off
	global_load_dword v151, v[28:29], off
	v_mad_u64_u32 v[168:169], s[10:11], v23, s77, v[6:7]
	v_mad_u64_u32 v[170:171], s[10:11], v0, s77, v[6:7]
	s_add_i32 s11, s9, 8
	s_add_i32 s10, s8, 8
	v_or_b32_e32 v23, s11, v2
	v_or_b32_e32 v0, s10, v3
	s_waitcnt vmcnt(1)
	v_add_u32_e32 v30, s6, v23
	v_add_u32_e32 v28, s3, v0
	v_ashrrev_i32_e32 v31, 31, v30
	v_ashrrev_i32_e32 v29, 31, v28
	v_lshlrev_b64 v[30:31], 12, v[30:31]
	v_lshlrev_b64 v[28:29], 12, v[28:29]
	v_lshl_add_u64 v[30:31], v[26:27], 0, v[30:31]
	v_lshl_add_u64 v[28:29], v[26:27], 0, v[28:29]
	global_load_dword v152, v[30:31], off
	global_load_dword v153, v[28:29], off
	v_mad_u64_u32 v[172:173], s[10:11], v23, s77, v[6:7]
	v_mad_u64_u32 v[174:175], s[10:11], v0, s77, v[6:7]
	s_add_i32 s11, s9, 12
	s_add_i32 s10, s8, 12
	v_or_b32_e32 v23, s11, v2
	v_or_b32_e32 v0, s10, v3
	s_waitcnt vmcnt(1)
	v_add_u32_e32 v30, s6, v23
	v_add_u32_e32 v28, s3, v0
	v_ashrrev_i32_e32 v31, 31, v30
	v_ashrrev_i32_e32 v29, 31, v28
	v_lshlrev_b64 v[30:31], 12, v[30:31]
	v_lshlrev_b64 v[28:29], 12, v[28:29]
	v_lshl_add_u64 v[30:31], v[26:27], 0, v[30:31]
	v_lshl_add_u64 v[28:29], v[26:27], 0, v[28:29]
	global_load_dword v154, v[30:31], off
	global_load_dword v155, v[28:29], off
	v_mad_u64_u32 v[176:177], s[10:11], v23, s77, v[6:7]
	v_mad_u64_u32 v[178:179], s[10:11], v0, s77, v[6:7]
	s_add_i32 s11, s9, 16
	s_add_i32 s10, s8, 16
	v_or_b32_e32 v23, s11, v2
	v_or_b32_e32 v0, s10, v3
	s_waitcnt vmcnt(1)
	v_add_u32_e32 v30, s6, v23
	v_add_u32_e32 v28, s3, v0
	v_ashrrev_i32_e32 v31, 31, v30
	v_ashrrev_i32_e32 v29, 31, v28
	v_lshlrev_b64 v[30:31], 12, v[30:31]
	v_lshlrev_b64 v[28:29], 12, v[28:29]
	v_lshl_add_u64 v[30:31], v[26:27], 0, v[30:31]
	v_lshl_add_u64 v[28:29], v[26:27], 0, v[28:29]
	global_load_dword v156, v[30:31], off
	global_load_dword v157, v[28:29], off
	v_mad_u64_u32 v[180:181], s[10:11], v23, s77, v[6:7]
	v_mad_u64_u32 v[182:183], s[10:11], v0, s77, v[6:7]
	s_add_i32 s11, s9, 20
	s_add_i32 s10, s8, 20
	v_or_b32_e32 v23, s11, v2
	v_or_b32_e32 v0, s10, v3
	s_waitcnt vmcnt(1)
	v_add_u32_e32 v30, s6, v23
	v_add_u32_e32 v28, s3, v0
	v_ashrrev_i32_e32 v31, 31, v30
	v_ashrrev_i32_e32 v29, 31, v28
	v_lshlrev_b64 v[30:31], 12, v[30:31]
	v_lshlrev_b64 v[28:29], 12, v[28:29]
	v_lshl_add_u64 v[30:31], v[26:27], 0, v[30:31]
	v_lshl_add_u64 v[28:29], v[26:27], 0, v[28:29]
	global_load_dword v158, v[30:31], off
	global_load_dword v159, v[28:29], off
	v_mad_u64_u32 v[184:185], s[10:11], v23, s77, v[6:7]
	v_mad_u64_u32 v[186:187], s[10:11], v0, s77, v[6:7]
	s_add_i32 s11, s9, 24
	s_add_i32 s10, s8, 24
	v_or_b32_e32 v23, s11, v2
	v_or_b32_e32 v0, s10, v3
	s_add_i32 s9, s9, 28
	s_add_i32 s8, s8, 28
	s_cmp_lg_u32 s7, 0
	s_waitcnt vmcnt(1)
	v_add_u32_e32 v30, s6, v23
	v_add_u32_e32 v28, s3, v0
	v_ashrrev_i32_e32 v31, 31, v30
	v_ashrrev_i32_e32 v29, 31, v28
	v_lshlrev_b64 v[30:31], 12, v[30:31]
	v_lshlrev_b64 v[28:29], 12, v[28:29]
	v_lshl_add_u64 v[30:31], v[26:27], 0, v[30:31]
	v_lshl_add_u64 v[28:29], v[26:27], 0, v[28:29]
	global_load_dword v160, v[30:31], off
	global_load_dword v161, v[28:29], off
	v_mad_u64_u32 v[188:189], s[10:11], v23, s77, v[6:7]
	v_mad_u64_u32 v[190:191], s[10:11], v0, s77, v[6:7]
	v_or_b32_e32 v23, s9, v2
	v_or_b32_e32 v0, s8, v3
	s_waitcnt vmcnt(1)
	v_add_u32_e32 v30, s6, v23
	v_add_u32_e32 v28, s3, v0
	v_ashrrev_i32_e32 v31, 31, v30
	v_ashrrev_i32_e32 v29, 31, v28
	v_lshlrev_b64 v[30:31], 12, v[30:31]
	v_lshlrev_b64 v[28:29], 12, v[28:29]
	v_lshl_add_u64 v[30:31], v[26:27], 0, v[30:31]
	v_lshl_add_u64 v[28:29], v[26:27], 0, v[28:29]
	global_load_dword v162, v[30:31], off
	global_load_dword v163, v[28:29], off
	v_mad_u64_u32 v[192:193], s[8:9], v23, s77, v[6:7]
	v_mad_u64_u32 v[196:197], s[8:9], v0, s77, v[6:7]
	s_waitcnt vmcnt(1)
	s_waitcnt vmcnt(0)
	ds_write_b32 v116, v100
	ds_write_b32 v118, v101
	ds_write_b32 v120, v102
	ds_write_b32 v122, v103
	ds_write_b32 v124, v104
	ds_write_b32 v126, v105
	ds_write_b32 v128, v106
	ds_write_b32 v130, v107
	ds_write_b32 v132, v108
	ds_write_b32 v134, v109
	ds_write_b32 v136, v110
	ds_write_b32 v138, v111
	ds_write_b32 v140, v112
	ds_write_b32 v142, v113
	ds_write_b32 v144, v114
	ds_write_b32 v146, v115
	ds_write_b32 v164, v148
	ds_write_b32 v166, v149
	ds_write_b32 v168, v150
	ds_write_b32 v170, v151
	ds_write_b32 v172, v152
	ds_write_b32 v174, v153
	ds_write_b32 v176, v154
	ds_write_b32 v178, v155
	ds_write_b32 v180, v156
	ds_write_b32 v182, v157
	ds_write_b32 v184, v158
	ds_write_b32 v186, v159
	ds_write_b32 v188, v160
	ds_write_b32 v190, v161
	ds_write_b32 v192, v162
	ds_write_b32 v196, v163
	s_cbranch_scc1 .LBB0_819
	s_mov_b32 s7, s4
	s_lshl_b64 s[2:3], s[6:7], 1
	s_add_u32 s0, s0, s2
	s_addc_u32 s1, s1, s3
	v_mov_b32_e32 v0, v47
	v_mov_b32_e32 v26, v46
	v_mov_b32_e32 v28, v45
	v_mov_b32_e32 v30, v44

.LBB0_824:
	s_lshl_b32 s8, s5, 1
	s_lshl_b32 s7, s3, 1
	v_or_b32_e32 v23, s8, v2
	v_or_b32_e32 v0, s7, v3
	v_add_u32_e32 v28, s0, v23
	v_add_u32_e32 v25, s2, v0
	v_mad_u64_u32 v[28:29], s[10:11], v28, s61, v[26:27]
	v_mad_u64_u32 v[30:31], s[10:11], v25, s61, v[26:27]
	global_load_dword v100, v[28:29], off
	global_load_dword v101, v[30:31], off
	v_mad_u64_u32 v[116:117], s[10:11], v23, s77, v[6:7]
	v_mad_u64_u32 v[118:119], s[10:11], v0, s77, v[6:7]
	s_add_i32 s10, s8, 4
	s_add_i32 s9, s7, 4
	v_or_b32_e32 v23, s10, v2
	v_or_b32_e32 v0, s9, v3
	s_add_i32 s9, s7, 8
	s_add_i32 s5, s5, 16
	s_add_i32 s3, s3, 16
	s_add_i32 s6, s6, -16
	s_waitcnt vmcnt(1)
	v_add_u32_e32 v28, s0, v23
	v_add_u32_e32 v25, s2, v0
	v_mad_u64_u32 v[28:29], s[10:11], v28, s61, v[26:27]
	v_mad_u64_u32 v[30:31], s[10:11], v25, s61, v[26:27]
	global_load_dword v102, v[28:29], off
	global_load_dword v103, v[30:31], off
	v_mad_u64_u32 v[120:121], s[10:11], v23, s77, v[6:7]
	v_mad_u64_u32 v[122:123], s[10:11], v0, s77, v[6:7]
	s_add_i32 s10, s8, 8
	s_nop 0
	v_or_b32_e32 v23, s10, v2
	v_or_b32_e32 v0, s9, v3
	s_add_i32 s9, s7, 12
	s_waitcnt vmcnt(1)
	v_add_u32_e32 v28, s0, v23
	v_add_u32_e32 v25, s2, v0
	v_mad_u64_u32 v[28:29], s[10:11], v28, s61, v[26:27]
	v_mad_u64_u32 v[30:31], s[10:11], v25, s61, v[26:27]
	global_load_dword v104, v[28:29], off
	global_load_dword v105, v[30:31], off
	v_mad_u64_u32 v[124:125], s[10:11], v23, s77, v[6:7]
	v_mad_u64_u32 v[126:127], s[10:11], v0, s77, v[6:7]
	s_add_i32 s10, s8, 12
	s_nop 0
	v_or_b32_e32 v23, s10, v2
	v_or_b32_e32 v0, s9, v3
	s_add_i32 s9, s7, 16
	s_waitcnt vmcnt(1)
	v_add_u32_e32 v28, s0, v23
	v_add_u32_e32 v25, s2, v0
	v_mad_u64_u32 v[28:29], s[10:11], v28, s61, v[26:27]
	v_mad_u64_u32 v[30:31], s[10:11], v25, s61, v[26:27]
	global_load_dword v106, v[28:29], off
	global_load_dword v107, v[30:31], off
	v_mad_u64_u32 v[128:129], s[10:11], v23, s77, v[6:7]
	v_mad_u64_u32 v[130:131], s[10:11], v0, s77, v[6:7]
	s_add_i32 s10, s8, 16
	s_nop 0
	v_or_b32_e32 v23, s10, v2
	v_or_b32_e32 v0, s9, v3
	s_add_i32 s9, s7, 20
	s_waitcnt vmcnt(1)
	v_add_u32_e32 v28, s0, v23
	v_add_u32_e32 v25, s2, v0
	v_mad_u64_u32 v[28:29], s[10:11], v28, s61, v[26:27]
	v_mad_u64_u32 v[30:31], s[10:11], v25, s61, v[26:27]
	global_load_dword v108, v[28:29], off
	global_load_dword v109, v[30:31], off
	v_mad_u64_u32 v[132:133], s[10:11], v23, s77, v[6:7]
	v_mad_u64_u32 v[134:135], s[10:11], v0, s77, v[6:7]
	s_add_i32 s10, s8, 20
	s_nop 0
	v_or_b32_e32 v23, s10, v2
	v_or_b32_e32 v0, s9, v3
	s_add_i32 s9, s7, 24
	s_add_i32 s7, s7, 28
	s_waitcnt vmcnt(1)
	v_add_u32_e32 v28, s0, v23
	v_add_u32_e32 v25, s2, v0
	v_mad_u64_u32 v[28:29], s[10:11], v28, s61, v[26:27]
	v_mad_u64_u32 v[30:31], s[10:11], v25, s61, v[26:27]
	global_load_dword v110, v[28:29], off
	global_load_dword v111, v[30:31], off
	v_mad_u64_u32 v[136:137], s[10:11], v23, s77, v[6:7]
	v_mad_u64_u32 v[138:139], s[10:11], v0, s77, v[6:7]
	s_add_i32 s10, s8, 24
	s_nop 0
	v_or_b32_e32 v23, s10, v2
	v_or_b32_e32 v0, s9, v3
	s_add_i32 s8, s8, 28
	s_cmp_lg_u32 s6, 0
	s_waitcnt vmcnt(1)
	v_add_u32_e32 v28, s0, v23
	v_add_u32_e32 v25, s2, v0
	v_mad_u64_u32 v[28:29], s[10:11], v28, s61, v[26:27]
	v_mad_u64_u32 v[30:31], s[10:11], v25, s61, v[26:27]
	global_load_dword v112, v[28:29], off
	global_load_dword v113, v[30:31], off
	v_mad_u64_u32 v[140:141], s[10:11], v23, s77, v[6:7]
	v_or_b32_e32 v23, s8, v2
	v_mad_u64_u32 v[142:143], s[10:11], v0, s77, v[6:7]
	v_or_b32_e32 v0, s7, v3
	s_waitcnt vmcnt(1)
	v_add_u32_e32 v28, s0, v23
	v_add_u32_e32 v25, s2, v0
	v_mad_u64_u32 v[28:29], s[8:9], v28, s61, v[26:27]
	v_mad_u64_u32 v[30:31], s[8:9], v25, s61, v[26:27]
	global_load_dword v114, v[28:29], off
	global_load_dword v115, v[30:31], off
	v_mad_u64_u32 v[144:145], s[8:9], v23, s77, v[6:7]
	v_mad_u64_u32 v[146:147], s[8:9], v0, s77, v[6:7]
	s_waitcnt vmcnt(1)
	s_lshl_b32 s8, s5, 1
	s_lshl_b32 s7, s3, 1
	v_or_b32_e32 v23, s8, v2
	v_or_b32_e32 v0, s7, v3
	v_add_u32_e32 v28, s0, v23
	v_add_u32_e32 v25, s2, v0
	v_mad_u64_u32 v[28:29], s[10:11], v28, s61, v[26:27]
	v_mad_u64_u32 v[30:31], s[10:11], v25, s61, v[26:27]
	global_load_dword v148, v[28:29], off
	global_load_dword v149, v[30:31], off
	v_mad_u64_u32 v[164:165], s[10:11], v23, s77, v[6:7]
	v_mad_u64_u32 v[166:167], s[10:11], v0, s77, v[6:7]
	s_add_i32 s10, s8, 4
	s_add_i32 s9, s7, 4
	v_or_b32_e32 v23, s10, v2
	v_or_b32_e32 v0, s9, v3
	s_add_i32 s9, s7, 8
	s_add_i32 s5, s5, 16
	s_add_i32 s3, s3, 16
	s_add_i32 s6, s6, -16
	s_waitcnt vmcnt(1)
	v_add_u32_e32 v28, s0, v23
	v_add_u32_e32 v25, s2, v0
	v_mad_u64_u32 v[28:29], s[10:11], v28, s61, v[26:27]
	v_mad_u64_u32 v[30:31], s[10:11], v25, s61, v[26:27]
	global_load_dword v150, v[28:29], off
	global_load_dword v151, v[30:31], off
	v_mad_u64_u32 v[168:169], s[10:11], v23, s77, v[6:7]
	v_mad_u64_u32 v[170:171], s[10:11], v0, s77, v[6:7]
	s_add_i32 s10, s8, 8
	s_nop 0
	v_or_b32_e32 v23, s10, v2
	v_or_b32_e32 v0, s9, v3
	s_add_i32 s9, s7, 12
	s_waitcnt vmcnt(1)
	v_add_u32_e32 v28, s0, v23
	v_add_u32_e32 v25, s2, v0
	v_mad_u64_u32 v[28:29], s[10:11], v28, s61, v[26:27]
	v_mad_u64_u32 v[30:31], s[10:11], v25, s61, v[26:27]
	global_load_dword v152, v[28:29], off
	global_load_dword v153, v[30:31], off
	v_mad_u64_u32 v[172:173], s[10:11], v23, s77, v[6:7]
	v_mad_u64_u32 v[174:175], s[10:11], v0, s77, v[6:7]
	s_add_i32 s10, s8, 12
	s_nop 0
	v_or_b32_e32 v23, s10, v2
	v_or_b32_e32 v0, s9, v3
	s_add_i32 s9, s7, 16
	s_waitcnt vmcnt(1)
	v_add_u32_e32 v28, s0, v23
	v_add_u32_e32 v25, s2, v0
	v_mad_u64_u32 v[28:29], s[10:11], v28, s61, v[26:27]
	v_mad_u64_u32 v[30:31], s[10:11], v25, s61, v[26:27]
	global_load_dword v154, v[28:29], off
	global_load_dword v155, v[30:31], off
	v_mad_u64_u32 v[176:177], s[10:11], v23, s77, v[6:7]
	v_mad_u64_u32 v[178:179], s[10:11], v0, s77, v[6:7]
	s_add_i32 s10, s8, 16
	s_nop 0
	v_or_b32_e32 v23, s10, v2
	v_or_b32_e32 v0, s9, v3
	s_add_i32 s9, s7, 20
	s_waitcnt vmcnt(1)
	v_add_u32_e32 v28, s0, v23
	v_add_u32_e32 v25, s2, v0
	v_mad_u64_u32 v[28:29], s[10:11], v28, s61, v[26:27]
	v_mad_u64_u32 v[30:31], s[10:11], v25, s61, v[26:27]
	global_load_dword v156, v[28:29], off
	global_load_dword v157, v[30:31], off
	v_mad_u64_u32 v[180:181], s[10:11], v23, s77, v[6:7]
	v_mad_u64_u32 v[182:183], s[10:11], v0, s77, v[6:7]
	s_add_i32 s10, s8, 20
	s_nop 0
	v_or_b32_e32 v23, s10, v2
	v_or_b32_e32 v0, s9, v3
	s_add_i32 s9, s7, 24
	s_add_i32 s7, s7, 28
	s_waitcnt vmcnt(1)
	v_add_u32_e32 v28, s0, v23
	v_add_u32_e32 v25, s2, v0
	v_mad_u64_u32 v[28:29], s[10:11], v28, s61, v[26:27]
	v_mad_u64_u32 v[30:31], s[10:11], v25, s61, v[26:27]
	global_load_dword v158, v[28:29], off
	global_load_dword v159, v[30:31], off
	v_mad_u64_u32 v[184:185], s[10:11], v23, s77, v[6:7]
	v_mad_u64_u32 v[186:187], s[10:11], v0, s77, v[6:7]
	s_add_i32 s10, s8, 24
	s_nop 0
	v_or_b32_e32 v23, s10, v2
	v_or_b32_e32 v0, s9, v3
	s_add_i32 s8, s8, 28
	s_cmp_lg_u32 s6, 0
	s_waitcnt vmcnt(1)
	v_add_u32_e32 v28, s0, v23
	v_add_u32_e32 v25, s2, v0
	v_mad_u64_u32 v[28:29], s[10:11], v28, s61, v[26:27]
	v_mad_u64_u32 v[30:31], s[10:11], v25, s61, v[26:27]
	global_load_dword v160, v[28:29], off
	global_load_dword v161, v[30:31], off
	v_mad_u64_u32 v[188:189], s[10:11], v23, s77, v[6:7]
	v_or_b32_e32 v23, s8, v2
	v_mad_u64_u32 v[190:191], s[10:11], v0, s77, v[6:7]
	v_or_b32_e32 v0, s7, v3
	s_waitcnt vmcnt(1)
	v_add_u32_e32 v28, s0, v23
	v_add_u32_e32 v25, s2, v0
	v_mad_u64_u32 v[28:29], s[8:9], v28, s61, v[26:27]
	v_mad_u64_u32 v[30:31], s[8:9], v25, s61, v[26:27]
	global_load_dword v162, v[28:29], off
	global_load_dword v163, v[30:31], off
	v_mad_u64_u32 v[192:193], s[8:9], v23, s77, v[6:7]
	v_mad_u64_u32 v[196:197], s[8:9], v0, s77, v[6:7]
	s_waitcnt vmcnt(1)
	s_waitcnt vmcnt(0)
	ds_write_b32 v116, v100
	ds_write_b32 v118, v101
	ds_write_b32 v120, v102
	ds_write_b32 v122, v103
	ds_write_b32 v124, v104
	ds_write_b32 v126, v105
	ds_write_b32 v128, v106
	ds_write_b32 v130, v107
	ds_write_b32 v132, v108
	ds_write_b32 v134, v109
	ds_write_b32 v136, v110
	ds_write_b32 v138, v111
	ds_write_b32 v140, v112
	ds_write_b32 v142, v113
	ds_write_b32 v144, v114
	ds_write_b32 v146, v115
	ds_write_b32 v164, v148
	ds_write_b32 v166, v149
	ds_write_b32 v168, v150
	ds_write_b32 v170, v151
	ds_write_b32 v172, v152
	ds_write_b32 v174, v153
	ds_write_b32 v176, v154
	ds_write_b32 v178, v155
	ds_write_b32 v180, v156
	ds_write_b32 v182, v157
	ds_write_b32 v184, v158
	ds_write_b32 v186, v159
	ds_write_b32 v188, v160
	ds_write_b32 v190, v161
	ds_write_b32 v192, v162
	ds_write_b32 v196, v163
	s_cbranch_scc1 .LBB0_824
	s_mulk_i32 s1, 0x6000
	s_add_u32 s1, s50, s1
	s_addc_u32 s2, s51, 0
	s_lshl_b32 s0, s0, 1
	s_add_u32 s0, s1, s0
	s_addc_u32 s1, s2, 0
	v_mov_b32_e32 v0, v51
	v_mov_b32_e32 v26, v50
	v_mov_b32_e32 v28, v49
	v_mov_b32_e32 v30, v48

.LBB0_829:
	s_lshl_b32 s8, s5, 1
	s_lshl_b32 s7, s2, 1
	v_or_b32_e32 v25, s8, v2
	v_or_b32_e32 v23, s7, v3
	v_add_u32_e32 v0, s1, v25
	v_add_u32_e32 v28, s3, v23
	v_mov_b32_e32 v29, v1
	v_lshlrev_b64 v[30:31], 14, v[0:1]
	v_lshlrev_b64 v[28:29], 14, v[28:29]
	v_lshl_add_u64 v[30:31], v[26:27], 0, v[30:31]
	v_lshl_add_u64 v[28:29], v[26:27], 0, v[28:29]
	global_load_dword v100, v[30:31], off
	global_load_dword v101, v[28:29], off
	v_mad_u64_u32 v[116:117], s[10:11], v25, s77, v[6:7]
	v_mad_u64_u32 v[118:119], s[10:11], v23, s77, v[6:7]
	s_add_i32 s10, s8, 4
	s_add_i32 s9, s7, 4
	v_or_b32_e32 v25, s10, v2
	v_or_b32_e32 v23, s9, v3
	v_mov_b32_e32 v29, v1
	s_add_i32 s9, s7, 8
	s_add_i32 s5, s5, 16
	s_add_i32 s2, s2, 16
	s_add_i32 s6, s6, -16
	s_waitcnt vmcnt(1)
	v_add_u32_e32 v0, s1, v25
	v_add_u32_e32 v28, s3, v23
	v_lshlrev_b64 v[30:31], 14, v[0:1]
	v_lshlrev_b64 v[28:29], 14, v[28:29]
	v_lshl_add_u64 v[30:31], v[26:27], 0, v[30:31]
	v_lshl_add_u64 v[28:29], v[26:27], 0, v[28:29]
	global_load_dword v102, v[30:31], off
	global_load_dword v103, v[28:29], off
	v_mad_u64_u32 v[120:121], s[10:11], v25, s77, v[6:7]
	v_mad_u64_u32 v[122:123], s[10:11], v23, s77, v[6:7]
	s_add_i32 s10, s8, 8
	s_nop 0
	v_or_b32_e32 v25, s10, v2
	v_or_b32_e32 v23, s9, v3
	v_mov_b32_e32 v29, v1
	s_add_i32 s9, s7, 12
	s_waitcnt vmcnt(1)
	v_add_u32_e32 v0, s1, v25
	v_add_u32_e32 v28, s3, v23
	v_lshlrev_b64 v[30:31], 14, v[0:1]
	v_lshlrev_b64 v[28:29], 14, v[28:29]
	v_lshl_add_u64 v[30:31], v[26:27], 0, v[30:31]
	v_lshl_add_u64 v[28:29], v[26:27], 0, v[28:29]
	global_load_dword v104, v[30:31], off
	global_load_dword v105, v[28:29], off
	v_mad_u64_u32 v[124:125], s[10:11], v25, s77, v[6:7]
	v_mad_u64_u32 v[126:127], s[10:11], v23, s77, v[6:7]
	s_add_i32 s10, s8, 12
	s_nop 0
	v_or_b32_e32 v25, s10, v2
	v_or_b32_e32 v23, s9, v3
	v_mov_b32_e32 v29, v1
	s_add_i32 s9, s7, 16
	s_waitcnt vmcnt(1)
	v_add_u32_e32 v0, s1, v25
	v_add_u32_e32 v28, s3, v23
	v_lshlrev_b64 v[30:31], 14, v[0:1]
	v_lshlrev_b64 v[28:29], 14, v[28:29]
	v_lshl_add_u64 v[30:31], v[26:27], 0, v[30:31]
	v_lshl_add_u64 v[28:29], v[26:27], 0, v[28:29]
	global_load_dword v106, v[30:31], off
	global_load_dword v107, v[28:29], off
	v_mad_u64_u32 v[128:129], s[10:11], v25, s77, v[6:7]
	v_mad_u64_u32 v[130:131], s[10:11], v23, s77, v[6:7]
	s_add_i32 s10, s8, 16
	s_nop 0
	v_or_b32_e32 v25, s10, v2
	v_or_b32_e32 v23, s9, v3
	v_mov_b32_e32 v29, v1
	s_add_i32 s9, s7, 20
	s_waitcnt vmcnt(1)
	v_add_u32_e32 v0, s1, v25
	v_add_u32_e32 v28, s3, v23
	v_lshlrev_b64 v[30:31], 14, v[0:1]
	v_lshlrev_b64 v[28:29], 14, v[28:29]
	v_lshl_add_u64 v[30:31], v[26:27], 0, v[30:31]
	v_lshl_add_u64 v[28:29], v[26:27], 0, v[28:29]
	global_load_dword v108, v[30:31], off
	global_load_dword v109, v[28:29], off
	v_mad_u64_u32 v[132:133], s[10:11], v25, s77, v[6:7]
	v_mad_u64_u32 v[134:135], s[10:11], v23, s77, v[6:7]
	s_add_i32 s10, s8, 20
	s_nop 0
	v_or_b32_e32 v25, s10, v2
	v_or_b32_e32 v23, s9, v3
	v_mov_b32_e32 v29, v1
	s_add_i32 s9, s7, 24
	s_add_i32 s7, s7, 28
	s_waitcnt vmcnt(1)
	v_add_u32_e32 v0, s1, v25
	v_add_u32_e32 v28, s3, v23
	v_lshlrev_b64 v[30:31], 14, v[0:1]
	v_lshlrev_b64 v[28:29], 14, v[28:29]
	v_lshl_add_u64 v[30:31], v[26:27], 0, v[30:31]
	v_lshl_add_u64 v[28:29], v[26:27], 0, v[28:29]
	global_load_dword v110, v[30:31], off
	global_load_dword v111, v[28:29], off
	v_mad_u64_u32 v[136:137], s[10:11], v25, s77, v[6:7]
	v_mad_u64_u32 v[138:139], s[10:11], v23, s77, v[6:7]
	s_add_i32 s10, s8, 24
	s_nop 0
	v_or_b32_e32 v25, s10, v2
	v_or_b32_e32 v23, s9, v3
	v_mov_b32_e32 v29, v1
	s_add_i32 s8, s8, 28
	s_cmp_lg_u32 s6, 0
	s_waitcnt vmcnt(1)
	v_add_u32_e32 v0, s1, v25
	v_add_u32_e32 v28, s3, v23
	v_lshlrev_b64 v[30:31], 14, v[0:1]
	v_lshlrev_b64 v[28:29], 14, v[28:29]
	v_lshl_add_u64 v[30:31], v[26:27], 0, v[30:31]
	v_lshl_add_u64 v[28:29], v[26:27], 0, v[28:29]
	global_load_dword v112, v[30:31], off
	global_load_dword v113, v[28:29], off
	v_mad_u64_u32 v[140:141], s[10:11], v25, s77, v[6:7]
	v_or_b32_e32 v25, s8, v2
	v_mad_u64_u32 v[142:143], s[10:11], v23, s77, v[6:7]
	v_or_b32_e32 v23, s7, v3
	v_mov_b32_e32 v29, v1
	s_waitcnt vmcnt(1)
	v_add_u32_e32 v0, s1, v25
	v_add_u32_e32 v28, s3, v23
	v_lshlrev_b64 v[30:31], 14, v[0:1]
	v_lshlrev_b64 v[28:29], 14, v[28:29]
	v_lshl_add_u64 v[30:31], v[26:27], 0, v[30:31]
	v_lshl_add_u64 v[28:29], v[26:27], 0, v[28:29]
	global_load_dword v114, v[30:31], off
	global_load_dword v115, v[28:29], off
	v_mad_u64_u32 v[144:145], s[8:9], v25, s77, v[6:7]
	v_mad_u64_u32 v[146:147], s[8:9], v23, s77, v[6:7]
	s_waitcnt vmcnt(1)
	s_lshl_b32 s8, s5, 1
	s_lshl_b32 s7, s2, 1
	v_or_b32_e32 v25, s8, v2
	v_or_b32_e32 v23, s7, v3
	v_add_u32_e32 v0, s1, v25
	v_add_u32_e32 v28, s3, v23
	v_mov_b32_e32 v29, v1
	v_lshlrev_b64 v[30:31], 14, v[0:1]
	v_lshlrev_b64 v[28:29], 14, v[28:29]
	v_lshl_add_u64 v[30:31], v[26:27], 0, v[30:31]
	v_lshl_add_u64 v[28:29], v[26:27], 0, v[28:29]
	global_load_dword v148, v[30:31], off
	global_load_dword v149, v[28:29], off
	v_mad_u64_u32 v[164:165], s[10:11], v25, s77, v[6:7]
	v_mad_u64_u32 v[166:167], s[10:11], v23, s77, v[6:7]
	s_add_i32 s10, s8, 4
	s_add_i32 s9, s7, 4
	v_or_b32_e32 v25, s10, v2
	v_or_b32_e32 v23, s9, v3
	v_mov_b32_e32 v29, v1
	s_add_i32 s9, s7, 8
	s_add_i32 s5, s5, 16
	s_add_i32 s2, s2, 16
	s_add_i32 s6, s6, -16
	s_waitcnt vmcnt(1)
	v_add_u32_e32 v0, s1, v25
	v_add_u32_e32 v28, s3, v23
	v_lshlrev_b64 v[30:31], 14, v[0:1]
	v_lshlrev_b64 v[28:29], 14, v[28:29]
	v_lshl_add_u64 v[30:31], v[26:27], 0, v[30:31]
	v_lshl_add_u64 v[28:29], v[26:27], 0, v[28:29]
	global_load_dword v150, v[30:31], off
	global_load_dword v151, v[28:29], off
	v_mad_u64_u32 v[168:169], s[10:11], v25, s77, v[6:7]
	v_mad_u64_u32 v[170:171], s[10:11], v23, s77, v[6:7]
	s_add_i32 s10, s8, 8
	s_nop 0
	v_or_b32_e32 v25, s10, v2
	v_or_b32_e32 v23, s9, v3
	v_mov_b32_e32 v29, v1
	s_add_i32 s9, s7, 12
	s_waitcnt vmcnt(1)
	v_add_u32_e32 v0, s1, v25
	v_add_u32_e32 v28, s3, v23
	v_lshlrev_b64 v[30:31], 14, v[0:1]
	v_lshlrev_b64 v[28:29], 14, v[28:29]
	v_lshl_add_u64 v[30:31], v[26:27], 0, v[30:31]
	v_lshl_add_u64 v[28:29], v[26:27], 0, v[28:29]
	global_load_dword v152, v[30:31], off
	global_load_dword v153, v[28:29], off
	v_mad_u64_u32 v[172:173], s[10:11], v25, s77, v[6:7]
	v_mad_u64_u32 v[174:175], s[10:11], v23, s77, v[6:7]
	s_add_i32 s10, s8, 12
	s_nop 0
	v_or_b32_e32 v25, s10, v2
	v_or_b32_e32 v23, s9, v3
	v_mov_b32_e32 v29, v1
	s_add_i32 s9, s7, 16
	s_waitcnt vmcnt(1)
	v_add_u32_e32 v0, s1, v25
	v_add_u32_e32 v28, s3, v23
	v_lshlrev_b64 v[30:31], 14, v[0:1]
	v_lshlrev_b64 v[28:29], 14, v[28:29]
	v_lshl_add_u64 v[30:31], v[26:27], 0, v[30:31]
	v_lshl_add_u64 v[28:29], v[26:27], 0, v[28:29]
	global_load_dword v154, v[30:31], off
	global_load_dword v155, v[28:29], off
	v_mad_u64_u32 v[176:177], s[10:11], v25, s77, v[6:7]
	v_mad_u64_u32 v[178:179], s[10:11], v23, s77, v[6:7]
	s_add_i32 s10, s8, 16
	s_nop 0
	v_or_b32_e32 v25, s10, v2
	v_or_b32_e32 v23, s9, v3
	v_mov_b32_e32 v29, v1
	s_add_i32 s9, s7, 20
	s_waitcnt vmcnt(1)
	v_add_u32_e32 v0, s1, v25
	v_add_u32_e32 v28, s3, v23
	v_lshlrev_b64 v[30:31], 14, v[0:1]
	v_lshlrev_b64 v[28:29], 14, v[28:29]
	v_lshl_add_u64 v[30:31], v[26:27], 0, v[30:31]
	v_lshl_add_u64 v[28:29], v[26:27], 0, v[28:29]
	global_load_dword v156, v[30:31], off
	global_load_dword v157, v[28:29], off
	v_mad_u64_u32 v[180:181], s[10:11], v25, s77, v[6:7]
	v_mad_u64_u32 v[182:183], s[10:11], v23, s77, v[6:7]
	s_add_i32 s10, s8, 20
	s_nop 0
	v_or_b32_e32 v25, s10, v2
	v_or_b32_e32 v23, s9, v3
	v_mov_b32_e32 v29, v1
	s_add_i32 s9, s7, 24
	s_add_i32 s7, s7, 28
	s_waitcnt vmcnt(1)
	v_add_u32_e32 v0, s1, v25
	v_add_u32_e32 v28, s3, v23
	v_lshlrev_b64 v[30:31], 14, v[0:1]
	v_lshlrev_b64 v[28:29], 14, v[28:29]
	v_lshl_add_u64 v[30:31], v[26:27], 0, v[30:31]
	v_lshl_add_u64 v[28:29], v[26:27], 0, v[28:29]
	global_load_dword v158, v[30:31], off
	global_load_dword v159, v[28:29], off
	v_mad_u64_u32 v[184:185], s[10:11], v25, s77, v[6:7]
	v_mad_u64_u32 v[186:187], s[10:11], v23, s77, v[6:7]
	s_add_i32 s10, s8, 24
	s_nop 0
	v_or_b32_e32 v25, s10, v2
	v_or_b32_e32 v23, s9, v3
	v_mov_b32_e32 v29, v1
	s_add_i32 s8, s8, 28
	s_cmp_lg_u32 s6, 0
	s_waitcnt vmcnt(1)
	v_add_u32_e32 v0, s1, v25
	v_add_u32_e32 v28, s3, v23
	v_lshlrev_b64 v[30:31], 14, v[0:1]
	v_lshlrev_b64 v[28:29], 14, v[28:29]
	v_lshl_add_u64 v[30:31], v[26:27], 0, v[30:31]
	v_lshl_add_u64 v[28:29], v[26:27], 0, v[28:29]
	global_load_dword v160, v[30:31], off
	global_load_dword v161, v[28:29], off
	v_mad_u64_u32 v[188:189], s[10:11], v25, s77, v[6:7]
	v_or_b32_e32 v25, s8, v2
	v_mad_u64_u32 v[190:191], s[10:11], v23, s77, v[6:7]
	v_or_b32_e32 v23, s7, v3
	v_mov_b32_e32 v29, v1
	s_waitcnt vmcnt(1)
	v_add_u32_e32 v0, s1, v25
	v_add_u32_e32 v28, s3, v23
	v_lshlrev_b64 v[30:31], 14, v[0:1]
	v_lshlrev_b64 v[28:29], 14, v[28:29]
	v_lshl_add_u64 v[30:31], v[26:27], 0, v[30:31]
	v_lshl_add_u64 v[28:29], v[26:27], 0, v[28:29]
	global_load_dword v162, v[30:31], off
	global_load_dword v163, v[28:29], off
	v_mad_u64_u32 v[192:193], s[8:9], v25, s77, v[6:7]
	v_mad_u64_u32 v[196:197], s[8:9], v23, s77, v[6:7]
	s_waitcnt vmcnt(1)
	s_waitcnt vmcnt(0)
	ds_write_b32 v116, v100
	ds_write_b32 v118, v101
	ds_write_b32 v120, v102
	ds_write_b32 v122, v103
	ds_write_b32 v124, v104
	ds_write_b32 v126, v105
	ds_write_b32 v128, v106
	ds_write_b32 v130, v107
	ds_write_b32 v132, v108
	ds_write_b32 v134, v109
	ds_write_b32 v136, v110
	ds_write_b32 v138, v111
	ds_write_b32 v140, v112
	ds_write_b32 v142, v113
	ds_write_b32 v144, v114
	ds_write_b32 v146, v115
	ds_write_b32 v164, v148
	ds_write_b32 v166, v149
	ds_write_b32 v168, v150
	ds_write_b32 v170, v151
	ds_write_b32 v172, v152
	ds_write_b32 v174, v153
	ds_write_b32 v176, v154
	ds_write_b32 v178, v155
	ds_write_b32 v180, v156
	ds_write_b32 v182, v157
	ds_write_b32 v184, v158
	ds_write_b32 v186, v159
	ds_write_b32 v188, v160
	ds_write_b32 v190, v161
	ds_write_b32 v192, v162
	ds_write_b32 v196, v163
	s_cbranch_scc1 .LBB0_829
	v_readlane_b32 s8, v249, 0
	s_lshl_b32 s0, s0, 11
	v_readlane_b32 s14, v249, 6
	v_readlane_b32 s15, v249, 7
	s_add_u32 s0, s14, s0
	s_addc_u32 s2, s15, 0
	s_lshl_b32 s1, s1, 1
	s_add_u32 s0, s0, s1
	s_addc_u32 s1, s2, 0
	s_add_u32 s0, s0, 0x680000
	s_addc_u32 s1, s1, 0
	v_mov_b32_e32 v0, v39
	v_mov_b32_e32 v26, v38
	v_mov_b32_e32 v28, v37
	v_mov_b32_e32 v30, v36
	v_readlane_b32 s9, v249, 1
	v_readlane_b32 s10, v249, 2
	v_readlane_b32 s11, v249, 3
	v_readlane_b32 s12, v249, 4
	v_readlane_b32 s13, v249, 5

.LBB0_834:
	s_lshl_b32 s9, s3, 1
	s_lshl_b32 s8, s2, 1
	v_or_b32_e32 v23, s9, v2
	v_or_b32_e32 v0, s8, v3
	v_add_u32_e32 v28, s0, v23
	v_add_u32_e32 v25, s1, v0
	v_mad_i64_i32 v[28:29], s[10:11], v28, s62, v[26:27]
	v_mad_i64_i32 v[30:31], s[10:11], v25, s62, v[26:27]
	global_load_dword v100, v[28:29], off
	global_load_dword v101, v[30:31], off
	v_mad_u64_u32 v[116:117], s[10:11], v23, s77, v[6:7]
	v_mad_u64_u32 v[118:119], s[10:11], v0, s77, v[6:7]
	s_add_i32 s11, s9, 4
	s_add_i32 s10, s8, 4
	v_or_b32_e32 v23, s11, v2
	v_or_b32_e32 v0, s10, v3
	s_add_i32 s3, s3, 16
	s_add_i32 s2, s2, 16
	s_add_i32 s5, s5, -16
	s_waitcnt vmcnt(1)
	v_add_u32_e32 v28, s0, v23
	v_add_u32_e32 v25, s1, v0
	v_mad_i64_i32 v[28:29], s[10:11], v28, s62, v[26:27]
	v_mad_i64_i32 v[30:31], s[10:11], v25, s62, v[26:27]
	global_load_dword v102, v[28:29], off
	global_load_dword v103, v[30:31], off
	v_mad_u64_u32 v[120:121], s[10:11], v23, s77, v[6:7]
	v_mad_u64_u32 v[122:123], s[10:11], v0, s77, v[6:7]
	s_add_i32 s11, s9, 8
	s_add_i32 s10, s8, 8
	v_or_b32_e32 v23, s11, v2
	v_or_b32_e32 v0, s10, v3
	s_waitcnt vmcnt(1)
	v_add_u32_e32 v28, s0, v23
	v_add_u32_e32 v25, s1, v0
	v_mad_i64_i32 v[28:29], s[10:11], v28, s62, v[26:27]
	v_mad_i64_i32 v[30:31], s[10:11], v25, s62, v[26:27]
	global_load_dword v104, v[28:29], off
	global_load_dword v105, v[30:31], off
	v_mad_u64_u32 v[124:125], s[10:11], v23, s77, v[6:7]
	v_mad_u64_u32 v[126:127], s[10:11], v0, s77, v[6:7]
	s_add_i32 s11, s9, 12
	s_add_i32 s10, s8, 12
	v_or_b32_e32 v23, s11, v2
	v_or_b32_e32 v0, s10, v3
	s_waitcnt vmcnt(1)
	v_add_u32_e32 v28, s0, v23
	v_add_u32_e32 v25, s1, v0
	v_mad_i64_i32 v[28:29], s[10:11], v28, s62, v[26:27]
	v_mad_i64_i32 v[30:31], s[10:11], v25, s62, v[26:27]
	global_load_dword v106, v[28:29], off
	global_load_dword v107, v[30:31], off
	v_mad_u64_u32 v[128:129], s[10:11], v23, s77, v[6:7]
	v_mad_u64_u32 v[130:131], s[10:11], v0, s77, v[6:7]
	s_add_i32 s11, s9, 16
	s_add_i32 s10, s8, 16
	v_or_b32_e32 v23, s11, v2
	v_or_b32_e32 v0, s10, v3
	s_waitcnt vmcnt(1)
	v_add_u32_e32 v28, s0, v23
	v_add_u32_e32 v25, s1, v0
	v_mad_i64_i32 v[28:29], s[10:11], v28, s62, v[26:27]
	v_mad_i64_i32 v[30:31], s[10:11], v25, s62, v[26:27]
	global_load_dword v108, v[28:29], off
	global_load_dword v109, v[30:31], off
	v_mad_u64_u32 v[132:133], s[10:11], v23, s77, v[6:7]
	v_mad_u64_u32 v[134:135], s[10:11], v0, s77, v[6:7]
	s_add_i32 s11, s9, 20
	s_add_i32 s10, s8, 20
	v_or_b32_e32 v23, s11, v2
	v_or_b32_e32 v0, s10, v3
	s_waitcnt vmcnt(1)
	v_add_u32_e32 v28, s0, v23
	v_add_u32_e32 v25, s1, v0
	v_mad_i64_i32 v[28:29], s[10:11], v28, s62, v[26:27]
	v_mad_i64_i32 v[30:31], s[10:11], v25, s62, v[26:27]
	global_load_dword v110, v[28:29], off
	global_load_dword v111, v[30:31], off
	v_mad_u64_u32 v[136:137], s[10:11], v23, s77, v[6:7]
	v_mad_u64_u32 v[138:139], s[10:11], v0, s77, v[6:7]
	s_add_i32 s11, s9, 24
	s_add_i32 s10, s8, 24
	v_or_b32_e32 v23, s11, v2
	v_or_b32_e32 v0, s10, v3
	s_add_i32 s9, s9, 28
	s_add_i32 s8, s8, 28
	s_cmp_lg_u32 s5, 0
	s_waitcnt vmcnt(1)
	v_add_u32_e32 v28, s0, v23
	v_add_u32_e32 v25, s1, v0
	v_mad_i64_i32 v[28:29], s[10:11], v28, s62, v[26:27]
	v_mad_i64_i32 v[30:31], s[10:11], v25, s62, v[26:27]
	global_load_dword v112, v[28:29], off
	global_load_dword v113, v[30:31], off
	v_mad_u64_u32 v[140:141], s[10:11], v23, s77, v[6:7]
	v_or_b32_e32 v23, s9, v2
	v_mad_u64_u32 v[142:143], s[10:11], v0, s77, v[6:7]
	v_or_b32_e32 v0, s8, v3
	s_waitcnt vmcnt(1)
	v_add_u32_e32 v28, s0, v23
	v_add_u32_e32 v25, s1, v0
	v_mad_i64_i32 v[28:29], s[8:9], v28, s62, v[26:27]
	v_mad_i64_i32 v[30:31], s[8:9], v25, s62, v[26:27]
	global_load_dword v114, v[28:29], off
	global_load_dword v115, v[30:31], off
	v_mad_u64_u32 v[144:145], s[8:9], v23, s77, v[6:7]
	v_mad_u64_u32 v[146:147], s[8:9], v0, s77, v[6:7]
	s_waitcnt vmcnt(1)
	s_lshl_b32 s9, s3, 1
	s_lshl_b32 s8, s2, 1
	v_or_b32_e32 v23, s9, v2
	v_or_b32_e32 v0, s8, v3
	v_add_u32_e32 v28, s0, v23
	v_add_u32_e32 v25, s1, v0
	v_mad_i64_i32 v[28:29], s[10:11], v28, s62, v[26:27]
	v_mad_i64_i32 v[30:31], s[10:11], v25, s62, v[26:27]
	global_load_dword v148, v[28:29], off
	global_load_dword v149, v[30:31], off
	v_mad_u64_u32 v[164:165], s[10:11], v23, s77, v[6:7]
	v_mad_u64_u32 v[166:167], s[10:11], v0, s77, v[6:7]
	s_add_i32 s11, s9, 4
	s_add_i32 s10, s8, 4
	v_or_b32_e32 v23, s11, v2
	v_or_b32_e32 v0, s10, v3
	s_add_i32 s3, s3, 16
	s_add_i32 s2, s2, 16
	s_add_i32 s5, s5, -16
	s_waitcnt vmcnt(1)
	v_add_u32_e32 v28, s0, v23
	v_add_u32_e32 v25, s1, v0
	v_mad_i64_i32 v[28:29], s[10:11], v28, s62, v[26:27]
	v_mad_i64_i32 v[30:31], s[10:11], v25, s62, v[26:27]
	global_load_dword v150, v[28:29], off
	global_load_dword v151, v[30:31], off
	v_mad_u64_u32 v[168:169], s[10:11], v23, s77, v[6:7]
	v_mad_u64_u32 v[170:171], s[10:11], v0, s77, v[6:7]
	s_add_i32 s11, s9, 8
	s_add_i32 s10, s8, 8
	v_or_b32_e32 v23, s11, v2
	v_or_b32_e32 v0, s10, v3
	s_waitcnt vmcnt(1)
	v_add_u32_e32 v28, s0, v23
	v_add_u32_e32 v25, s1, v0
	v_mad_i64_i32 v[28:29], s[10:11], v28, s62, v[26:27]
	v_mad_i64_i32 v[30:31], s[10:11], v25, s62, v[26:27]
	global_load_dword v152, v[28:29], off
	global_load_dword v153, v[30:31], off
	v_mad_u64_u32 v[172:173], s[10:11], v23, s77, v[6:7]
	v_mad_u64_u32 v[174:175], s[10:11], v0, s77, v[6:7]
	s_add_i32 s11, s9, 12
	s_add_i32 s10, s8, 12
	v_or_b32_e32 v23, s11, v2
	v_or_b32_e32 v0, s10, v3
	s_waitcnt vmcnt(1)
	v_add_u32_e32 v28, s0, v23
	v_add_u32_e32 v25, s1, v0
	v_mad_i64_i32 v[28:29], s[10:11], v28, s62, v[26:27]
	v_mad_i64_i32 v[30:31], s[10:11], v25, s62, v[26:27]
	global_load_dword v154, v[28:29], off
	global_load_dword v155, v[30:31], off
	v_mad_u64_u32 v[176:177], s[10:11], v23, s77, v[6:7]
	v_mad_u64_u32 v[178:179], s[10:11], v0, s77, v[6:7]
	s_add_i32 s11, s9, 16
	s_add_i32 s10, s8, 16
	v_or_b32_e32 v23, s11, v2
	v_or_b32_e32 v0, s10, v3
	s_waitcnt vmcnt(1)
	v_add_u32_e32 v28, s0, v23
	v_add_u32_e32 v25, s1, v0
	v_mad_i64_i32 v[28:29], s[10:11], v28, s62, v[26:27]
	v_mad_i64_i32 v[30:31], s[10:11], v25, s62, v[26:27]
	global_load_dword v156, v[28:29], off
	global_load_dword v157, v[30:31], off
	v_mad_u64_u32 v[180:181], s[10:11], v23, s77, v[6:7]
	v_mad_u64_u32 v[182:183], s[10:11], v0, s77, v[6:7]
	s_add_i32 s11, s9, 20
	s_add_i32 s10, s8, 20
	v_or_b32_e32 v23, s11, v2
	v_or_b32_e32 v0, s10, v3
	s_waitcnt vmcnt(1)
	v_add_u32_e32 v28, s0, v23
	v_add_u32_e32 v25, s1, v0
	v_mad_i64_i32 v[28:29], s[10:11], v28, s62, v[26:27]
	v_mad_i64_i32 v[30:31], s[10:11], v25, s62, v[26:27]
	global_load_dword v158, v[28:29], off
	global_load_dword v159, v[30:31], off
	v_mad_u64_u32 v[184:185], s[10:11], v23, s77, v[6:7]
	v_mad_u64_u32 v[186:187], s[10:11], v0, s77, v[6:7]
	s_add_i32 s11, s9, 24
	s_add_i32 s10, s8, 24
	v_or_b32_e32 v23, s11, v2
	v_or_b32_e32 v0, s10, v3
	s_add_i32 s9, s9, 28
	s_add_i32 s8, s8, 28
	s_cmp_lg_u32 s5, 0
	s_waitcnt vmcnt(1)
	v_add_u32_e32 v28, s0, v23
	v_add_u32_e32 v25, s1, v0
	v_mad_i64_i32 v[28:29], s[10:11], v28, s62, v[26:27]
	v_mad_i64_i32 v[30:31], s[10:11], v25, s62, v[26:27]
	global_load_dword v160, v[28:29], off
	global_load_dword v161, v[30:31], off
	v_mad_u64_u32 v[188:189], s[10:11], v23, s77, v[6:7]
	v_or_b32_e32 v23, s9, v2
	v_mad_u64_u32 v[190:191], s[10:11], v0, s77, v[6:7]
	v_or_b32_e32 v0, s8, v3
	s_waitcnt vmcnt(1)
	v_add_u32_e32 v28, s0, v23
	v_add_u32_e32 v25, s1, v0
	v_mad_i64_i32 v[28:29], s[8:9], v28, s62, v[26:27]
	v_mad_i64_i32 v[30:31], s[8:9], v25, s62, v[26:27]
	global_load_dword v162, v[28:29], off
	global_load_dword v163, v[30:31], off
	v_mad_u64_u32 v[192:193], s[8:9], v23, s77, v[6:7]
	v_mad_u64_u32 v[196:197], s[8:9], v0, s77, v[6:7]
	s_waitcnt vmcnt(1)
	s_waitcnt vmcnt(0)
	ds_write_b32 v116, v100
	ds_write_b32 v118, v101
	ds_write_b32 v120, v102
	ds_write_b32 v122, v103
	ds_write_b32 v124, v104
	ds_write_b32 v126, v105
	ds_write_b32 v128, v106
	ds_write_b32 v130, v107
	ds_write_b32 v132, v108
	ds_write_b32 v134, v109
	ds_write_b32 v136, v110
	ds_write_b32 v138, v111
	ds_write_b32 v140, v112
	ds_write_b32 v142, v113
	ds_write_b32 v144, v114
	ds_write_b32 v146, v115
	ds_write_b32 v164, v148
	ds_write_b32 v166, v149
	ds_write_b32 v168, v150
	ds_write_b32 v170, v151
	ds_write_b32 v172, v152
	ds_write_b32 v174, v153
	ds_write_b32 v176, v154
	ds_write_b32 v178, v155
	ds_write_b32 v180, v156
	ds_write_b32 v182, v157
	ds_write_b32 v184, v158
	ds_write_b32 v186, v159
	ds_write_b32 v188, v160
	ds_write_b32 v190, v161
	ds_write_b32 v192, v162
	ds_write_b32 v196, v163
	s_cbranch_scc1 .LBB0_834
	v_readlane_b32 s8, v249, 0
	s_lshl_b64 s[2:3], s[6:7], 11
	v_readlane_b32 s14, v249, 6
	v_readlane_b32 s15, v249, 7
	s_add_u32 s2, s14, s2
	s_addc_u32 s3, s15, s3
	s_ashr_i32 s1, s0, 31
	s_lshl_b64 s[0:1], s[0:1], 1
	s_add_u32 s0, s2, s0
	s_addc_u32 s1, s3, s1
	v_mov_b32_e32 v0, v39
	v_mov_b32_e32 v26, v38
	v_mov_b32_e32 v28, v37
	v_mov_b32_e32 v30, v36
	v_readlane_b32 s9, v249, 1
	v_readlane_b32 s10, v249, 2
	v_readlane_b32 s11, v249, 3
	v_readlane_b32 s12, v249, 4
	v_readlane_b32 s13, v249, 5
	s_branch .LBB0_778
